# v14 + s_setprio raise during the MFMA section and late accumulator zeroing in the hand-written GEMM bodies
# speedup vs baseline: 1.0068x; 1.0068x over previous
; #define LAS __attribute__((address_space(3)))
;     ...
;   const int nk = (nk_part < 0) ? (K >> 5) : nk_part;
;   const int lrow = tid >> 2, lpc = tid & 3;
;   const int lch = lpc ^ ((0x78 >> (((lrow >> 2) & 3) * 2)) & 3);
;   const u16* ga = A + (size_t)(m0 + lrow) * lda + kbeg + lch * 8;
;   const u16* gb = Bt + (size_t)(n0 + lrow) * K + kbeg + lch * 8;
;   const size_t ga1 = (size_t)64 * lda, gb1 = (size_t)64 * K;
;   const unsigned lds0 = (unsigned)(uintptr_t)(LAS char*)smem + (unsigned)__builtin_amdgcn_readfirstlane(wid) * 1024u;
;     ...
;   __syncthreads();
;   G2_STAGE(0); G2_STAGE(1);
; DEVI void run_phase(const Params& p, int ph, char* smem) {
;     ...
;           const int u_ = t - 512, tl_ = u_ / 11, q_ = u_ - tl_ * 11;
;           gemm_tile256<EPI_RESID_ATOMIC>(p, hb, DFF, Bt, DFF, (64 + (tl_ & 1)) * 256, (tl_ >> 1) * 128, nullptr, 0, smem, q_ * 256, 8, q_);
.LBB0_42:
	s_cmpk_gt_i32 s38, 0x1ff
	s_mov_b64 s[2:3], -1
	s_cbranch_scc0 .LBB0_116
	s_sub_i32 s46, s38, 512
	s_mul_i32 s45, s46, 373
	s_lshr_b32 s45, s45, 12
	s_mul_i32 s47, s45, 11
	s_sub_i32 s47, s46, s47
	s_lshr_b32 s42, s45, 1
	s_and_b32 s45, s45, 1
	s_add_i32 s45, s45, 64
	s_cmp_lt_u32 s45, 64
	s_cselect_b32 s44, 1, 0
	v_readlane_b32 s2, v250, 5
	v_readlane_b32 s3, v250, 6
	v_readlane_b32 s46, v254, 62
	s_mul_i32 s40, s45, 0x160000
	s_add_u32 s4, s2, s40
	s_addc_u32 s5, s3, 0
	s_add_u32 s4, s4, 0xef40000
	s_addc_u32 s5, s5, 0
	s_mul_i32 s40, s46, 0x580000
	s_mul_i32 s41, s42, 0xb0000
	s_add_i32 s40, s40, s41
	s_add_u32 s10, s2, s40
	s_addc_u32 s11, s3, 0
	s_add_u32 s10, s10, 0x19a00000
	s_addc_u32 s11, s11, 0
	s_mul_i32 s40, s47, 512
	s_add_u32 s4, s4, s40
	s_addc_u32 s5, s5, 0
	s_mul_i32 s40, s47, 1024
	s_add_u32 s10, s10, s40
	s_addc_u32 s11, s11, 0
	s_movk_i32 s39, 0x78
	v_lshrrev_b32_e32 v0, 2, v145
	v_and_b32_e32 v131, 3, v145
	v_bfe_u32 v136, v145, 4, 2
	v_lshlrev_b32_e32 v136, 1, v136
	v_lshrrev_b32_e64 v136, v136, s39
	v_and_b32_e32 v136, 3, v136
	v_xor_b32_e32 v131, v131, v136
	v_lshlrev_b32_e32 v131, 4, v131
	s_movk_i32 s41, 0x1600
	v_mad_u32_u24 v0, v0, s41, v131
	v_bfe_u32 v137, v145, 2, 1
	s_movk_i32 s41, 0x15c0
	v_mul_u32_u24_e32 v136, s41, v137
	v_sub_u32_e32 v136, v0, v136
	v_mov_b32_e32 v137, 0
	v_lshl_add_u64 v[134:135], s[10:11], 0, v[136:137]
	v_bfe_u32 v137, v145, 2, 1
	s_mul_i32 s41, s44, 0x15c0
	v_mul_u32_u24_e32 v136, s41, v137
	v_sub_u32_e32 v0, v0, v136
	s_lshl_b32 s12, s44, 6
	s_add_i32 s12, s12, 64
	s_mov_b32 s13, 0
	v_lshl_add_u64 v[132:133], s[4:5], 0, v[0:1]
	v_bfe_u32 v136, v145, 2, 2
	v_lshlrev_b32_e32 v136, 1, v136
	v_lshrrev_b32_e64 v136, v136, s39
	v_and_b32_e32 v136, 3, v136
	v_bfe_u32 v137, v145, 4, 2
	v_xor_b32_e32 v136, v136, v137
	v_lshlrev_b32_e32 v136, 4, v136
	v_and_b32_e32 v131, 15, v145
	v_lshl_or_b32 v136, v131, 6, v136
	v_bfe_u32 v137, v145, 6, 1
	v_lshl_or_b32 v137, v137, 12, v136
	v_lshrrev_b32_e32 v0, 7, v145
	v_lshl_or_b32 v136, v0, 13, v136
	v_and_b32_e32 v140, 1, v131
	v_lshl_or_b32 v131, v0, 7, v131
	v_bfe_u32 v0, v145, 4, 2
	v_lshlrev_b32_e32 v0, 3, v0
	v_bfe_u32 v141, v145, 6, 1
	s_lshl_b32 s40, s45, 19
	s_lshl_b32 s41, s42, 8
	s_add_i32 s40, s40, s41
	s_add_u32 s4, s2, s40
	s_addc_u32 s5, s3, 0
	s_add_u32 s4, s4, 0x4200000
	s_addc_u32 s5, s5, 0
	v_lshlrev_b32_e32 v138, 11, v131
	v_lshl_add_u32 v138, v141, 7, v138
	v_bfe_u32 v139, v145, 4, 1
	v_lshl_add_u32 v138, v139, 5, v138
	v_bfe_u32 v139, v145, 5, 1
	v_lshl_add_u32 v138, v139, 4, v138
	v_mov_b32_e32 v139, 0
	v_lshl_add_u64 v[138:139], s[4:5], 0, v[138:139]
	s_and_b32 s40, s45, 1
	s_lshl_b32 s40, s40, 20
	s_lshl_b32 s41, s47, 21
	s_add_i32 s40, s40, s41
	s_lshl_b32 s41, s42, 9
	s_add_i32 s40, s40, s41
	s_add_u32 s10, s2, s40
	s_addc_u32 s11, s3, 0
	s_add_u32 s10, s10, 0x1dcc0000
	s_addc_u32 s11, s11, 0
	v_lshlrev_b32_e32 v140, 12, v131
	v_lshl_add_u32 v140, v141, 8, v140
	v_lshl_add_u32 v140, v0, 1, v140
	v_mov_b32_e32 v141, 0
	v_lshl_add_u64 v[140:141], s[10:11], 0, v[140:141]
	s_mov_b32 s2, 0x58000
	s_mov_b32 s3, 0
	v_lshrrev_b32_e32 v0, 6, v145
	v_lshlrev_b32_e32 v0, 10, v0
	s_nop 0
	v_readfirstlane_b32 s46, v0
	s_mov_b32 s43, m0
	s_mov_b32 s4, 128
	s_mov_b32 s5, 0
	s_barrier
	s_add_i32 s42, s46, 0x0
	s_mov_b32 m0, s42
	v_lshl_add_u64 v[142:143], v[132:133], 0, s[2:3]
	global_load_lds_dwordx4 v[132:133], off
	s_addk_i32 m0, 0x1000
	s_nop 0
	global_load_lds_dwordx4 v[142:143], off
	v_lshl_add_u64 v[142:143], v[142:143], 0, s[2:3]
	s_addk_i32 m0, 0x1000
	s_nop 0
	global_load_lds_dwordx4 v[142:143], off
	v_lshl_add_u64 v[142:143], v[142:143], 0, s[2:3]
	s_addk_i32 m0, 0x1000
	s_nop 0
	global_load_lds_dwordx4 v[142:143], off
	s_addk_i32 m0, 0x1000
	v_lshl_add_u64 v[142:143], v[134:135], 0, s[2:3]
	s_nop 0
	global_load_lds_dwordx4 v[134:135], off
	s_addk_i32 m0, 0x1000
	v_lshl_add_u64 v[132:133], v[132:133], 0, s[12:13]
	s_nop 0
	global_load_lds_dwordx4 v[142:143], off
	v_lshl_add_u64 v[134:135], v[134:135], 0, s[4:5]
	s_nop 0
	s_add_i32 s42, s46, 0x6000
	s_mov_b32 m0, s42
	v_lshl_add_u64 v[142:143], v[132:133], 0, s[2:3]
	global_load_lds_dwordx4 v[132:133], off
	s_addk_i32 m0, 0x1000
	s_nop 0
	global_load_lds_dwordx4 v[142:143], off
	v_lshl_add_u64 v[142:143], v[142:143], 0, s[2:3]
	s_addk_i32 m0, 0x1000
	s_nop 0
	global_load_lds_dwordx4 v[142:143], off
	v_lshl_add_u64 v[142:143], v[142:143], 0, s[2:3]
	s_addk_i32 m0, 0x1000
	s_nop 0
	global_load_lds_dwordx4 v[142:143], off
	s_addk_i32 m0, 0x1000
	v_lshl_add_u64 v[142:143], v[134:135], 0, s[2:3]
	s_nop 0
	global_load_lds_dwordx4 v[134:135], off
	s_addk_i32 m0, 0x1000
	v_lshl_add_u64 v[132:133], v[132:133], 0, s[12:13]
	s_nop 0
	global_load_lds_dwordx4 v[142:143], off
	v_lshl_add_u64 v[134:135], v[134:135], 0, s[4:5]
	s_nop 0
	s_add_i32 s42, s46, 0xc000
	s_mov_b32 m0, s42
	v_lshl_add_u64 v[142:143], v[132:133], 0, s[2:3]
	global_load_lds_dwordx4 v[132:133], off
	s_addk_i32 m0, 0x1000
	s_nop 0
	global_load_lds_dwordx4 v[142:143], off
	v_lshl_add_u64 v[142:143], v[142:143], 0, s[2:3]
	s_addk_i32 m0, 0x1000
	s_nop 0
	global_load_lds_dwordx4 v[142:143], off
	v_lshl_add_u64 v[142:143], v[142:143], 0, s[2:3]
	s_addk_i32 m0, 0x1000
	s_nop 0
	global_load_lds_dwordx4 v[142:143], off
	s_addk_i32 m0, 0x1000
	v_lshl_add_u64 v[142:143], v[134:135], 0, s[2:3]
	s_nop 0
	global_load_lds_dwordx4 v[134:135], off
	s_addk_i32 m0, 0x1000
	v_lshl_add_u64 v[132:133], v[132:133], 0, s[12:13]
	s_nop 0
	global_load_lds_dwordx4 v[142:143], off
	v_lshl_add_u64 v[134:135], v[134:135], 0, s[4:5]
	s_nop 0
	v_mov_b32_e32 v2, 0
	v_mov_b32_e32 v3, 0
	v_mov_b32_e32 v4, 0
	v_mov_b32_e32 v5, 0
	v_mov_b32_e32 v6, 0
; #define LAS __attribute__((address_space(3)))
;     ...
;   f32x4 acc[4][8];
; #pragma unroll
;   for (int i = 0; i < 4; i++)
; #pragma unroll
;     for (int j = 0; j < 8; j++) acc[i][j] = (f32x4){0.f, 0.f, 0.f, 0.f};
;   const int nk = (nk_part < 0) ? (K >> 5) : nk_part;
;   const int lrow = tid >> 2, lpc = tid & 3;
;   const int lch = lpc ^ ((0x78 >> (((lrow >> 2) & 3) * 2)) & 3);
;   const u16* ga = A + (size_t)(m0 + lrow) * lda + kbeg + lch * 8;
;   const u16* gb = Bt + (size_t)(n0 + lrow) * K + kbeg + lch * 8;
;   const size_t ga1 = (size_t)64 * lda, gb1 = (size_t)64 * K;
;   const unsigned lds0 = (unsigned)(uintptr_t)(LAS char*)smem + (unsigned)__builtin_amdgcn_readfirstlane(wid) * 1024u;
;     ...
;   __syncthreads();
;   G2_STAGE(0); G2_STAGE(1);
;   const int fsw = (0x78 >> (((r16 >> 2) & 3) * 2)) & 3;
;   const int aoff = (wm * 128 + r16) * 64 + ((quad ^ fsw) << 4);
;   const int boff = 16384 + (wn * 64 + r16) * 64 + ((quad ^ fsw) << 4);
;   for (int kt = 0; kt < nk; kt++) {
;     if (kt + 1 < nk) asm volatile("s_waitcnt vmcnt(6)" ::: "memory");
;     else asm volatile("s_waitcnt vmcnt(0)" ::: "memory");
;     __builtin_amdgcn_s_barrier();
;     asm volatile("" ::: "memory");
;     if (kt + 2 < nk) G2_STAGE(kt + 2);
;     const char* cS = smem + (kt % 3) * 24576;
;     bf16x8 xa[8], wb[4];
; #pragma unroll
;     for (int f = 0; f < 8; f++) xa[f] = *(const bf16x8*)(cS + aoff + f * 1024);
; #pragma unroll
;     for (int f = 0; f < 4; f++) wb[f] = *(const bf16x8*)(cS + boff + f * 1024);
; #pragma unroll
;     for (int nf = 0; nf < 4; nf++)
; #pragma unroll
;       for (int mf = 0; mf < 8; mf++)
;         acc[nf][mf] = __builtin_amdgcn_mfma_f32_16x16x32_bf16(wb[nf], xa[mf], acc[nf][mf], 0, 0, 0);
	v_mov_b32_e32 v7, 0
	v_mov_b32_e32 v8, 0
	v_mov_b32_e32 v9, 0
	v_mov_b32_e32 v10, 0
	v_mov_b32_e32 v11, 0
	v_mov_b32_e32 v12, 0
	v_mov_b32_e32 v13, 0
	v_mov_b32_e32 v14, 0
	v_mov_b32_e32 v15, 0
	v_mov_b32_e32 v16, 0
	v_mov_b32_e32 v17, 0
	v_mov_b32_e32 v18, 0
	v_mov_b32_e32 v19, 0
	v_mov_b32_e32 v20, 0
	v_mov_b32_e32 v21, 0
	v_mov_b32_e32 v22, 0
	v_mov_b32_e32 v23, 0
	v_mov_b32_e32 v24, 0
	v_mov_b32_e32 v25, 0
	v_mov_b32_e32 v26, 0
	v_mov_b32_e32 v27, 0
	v_mov_b32_e32 v28, 0
	v_mov_b32_e32 v29, 0
	v_mov_b32_e32 v30, 0
	v_mov_b32_e32 v31, 0
	v_mov_b32_e32 v32, 0
	v_mov_b32_e32 v33, 0
	v_mov_b32_e32 v34, 0
	v_mov_b32_e32 v35, 0
	v_mov_b32_e32 v36, 0
	v_mov_b32_e32 v37, 0
	v_mov_b32_e32 v38, 0
	v_mov_b32_e32 v39, 0
	v_mov_b32_e32 v40, 0
	v_mov_b32_e32 v41, 0
	v_mov_b32_e32 v42, 0
	v_mov_b32_e32 v43, 0
	v_mov_b32_e32 v44, 0
	v_mov_b32_e32 v45, 0
	v_mov_b32_e32 v46, 0
	v_mov_b32_e32 v47, 0
	v_mov_b32_e32 v48, 0
	v_mov_b32_e32 v49, 0
	v_mov_b32_e32 v50, 0
	v_mov_b32_e32 v51, 0
	v_mov_b32_e32 v52, 0
	v_mov_b32_e32 v53, 0
	v_mov_b32_e32 v54, 0
	v_mov_b32_e32 v55, 0
	v_mov_b32_e32 v56, 0
	v_mov_b32_e32 v57, 0
	v_mov_b32_e32 v58, 0
	v_mov_b32_e32 v59, 0
	v_mov_b32_e32 v60, 0
	v_mov_b32_e32 v61, 0
	v_mov_b32_e32 v62, 0
	v_mov_b32_e32 v63, 0
	v_mov_b32_e32 v64, 0
	v_mov_b32_e32 v65, 0
	v_mov_b32_e32 v66, 0
	v_mov_b32_e32 v67, 0
	v_mov_b32_e32 v68, 0
	v_mov_b32_e32 v69, 0
	v_mov_b32_e32 v70, 0
	v_mov_b32_e32 v71, 0
	v_mov_b32_e32 v72, 0
	v_mov_b32_e32 v73, 0
	v_mov_b32_e32 v74, 0
	v_mov_b32_e32 v75, 0
	v_mov_b32_e32 v76, 0
	v_mov_b32_e32 v77, 0
	v_mov_b32_e32 v78, 0
	v_mov_b32_e32 v79, 0
	v_mov_b32_e32 v80, 0
	v_mov_b32_e32 v81, 0
	v_mov_b32_e32 v82, 0
	v_mov_b32_e32 v83, 0
	v_mov_b32_e32 v84, 0
	v_mov_b32_e32 v85, 0
	v_mov_b32_e32 v86, 0
	v_mov_b32_e32 v87, 0
	v_mov_b32_e32 v88, 0
	v_mov_b32_e32 v89, 0
	v_mov_b32_e32 v90, 0
	v_mov_b32_e32 v91, 0
	v_mov_b32_e32 v92, 0
	v_mov_b32_e32 v93, 0
	v_mov_b32_e32 v94, 0
	v_mov_b32_e32 v95, 0
	v_mov_b32_e32 v96, 0
	v_mov_b32_e32 v97, 0
	v_mov_b32_e32 v98, 0
	v_mov_b32_e32 v99, 0
	v_mov_b32_e32 v100, 0
	v_mov_b32_e32 v101, 0
	v_mov_b32_e32 v102, 0
	v_mov_b32_e32 v103, 0
	v_mov_b32_e32 v104, 0
	v_mov_b32_e32 v105, 0
	v_mov_b32_e32 v106, 0
	v_mov_b32_e32 v107, 0
	v_mov_b32_e32 v108, 0
	v_mov_b32_e32 v109, 0
	v_mov_b32_e32 v110, 0
	v_mov_b32_e32 v111, 0
	v_mov_b32_e32 v112, 0
	v_mov_b32_e32 v113, 0
	v_mov_b32_e32 v114, 0
	v_mov_b32_e32 v115, 0
	v_mov_b32_e32 v116, 0
	v_mov_b32_e32 v117, 0
	v_mov_b32_e32 v118, 0
	v_mov_b32_e32 v119, 0
	v_mov_b32_e32 v120, 0
	v_mov_b32_e32 v121, 0
	v_mov_b32_e32 v122, 0
	v_mov_b32_e32 v123, 0
	v_mov_b32_e32 v124, 0
	v_mov_b32_e32 v125, 0
	v_mov_b32_e32 v126, 0
	v_mov_b32_e32 v127, 0
	v_mov_b32_e32 v128, 0
	v_mov_b32_e32 v129, 0
	s_waitcnt vmcnt(12)
	s_barrier
	ds_read_b128 v[146:149], v136 offset:0
	ds_read_b128 v[152:155], v136 offset:1024
	ds_read_b128 v[156:159], v136 offset:2048
	ds_read_b128 v[162:165], v136 offset:3072
	ds_read_b128 v[166:169], v136 offset:4096
	ds_read_b128 v[170:173], v136 offset:5120
	ds_read_b128 v[176:179], v136 offset:6144
	ds_read_b128 v[180:183], v136 offset:7168
	ds_read_b128 v[184:187], v137 offset:16384
	ds_read_b128 v[188:191], v137 offset:17408
	ds_read_b128 v[192:195], v137 offset:18432
	ds_read_b128 v[196:199], v137 offset:19456
	s_movk_i32 s40, 0x6000
	s_mov_b32 s41, 0
	s_movk_i32 s39, 2
.Lta11_loop:
	s_waitcnt vmcnt(6) lgkmcnt(0)
	s_barrier
	s_setprio 1
	v_add_u32_e32 v144, s40, v136
	v_mfma_f32_16x16x32_bf16 v[126:129], v[184:187], v[146:149], v[126:129]
	ds_read_b128 v[200:203], v144 offset:0
	v_mfma_f32_16x16x32_bf16 v[122:125], v[184:187], v[152:155], v[122:125]
	ds_read_b128 v[204:207], v144 offset:1024
	v_mfma_f32_16x16x32_bf16 v[118:121], v[184:187], v[156:159], v[118:121]
	ds_read_b128 v[208:211], v144 offset:2048
	v_mfma_f32_16x16x32_bf16 v[114:117], v[184:187], v[162:165], v[114:117]
	ds_read_b128 v[212:215], v144 offset:3072
	v_mfma_f32_16x16x32_bf16 v[110:113], v[184:187], v[166:169], v[110:113]
	ds_read_b128 v[216:219], v144 offset:4096
	v_mfma_f32_16x16x32_bf16 v[106:109], v[184:187], v[170:173], v[106:109]
	ds_read_b128 v[220:223], v144 offset:5120
	v_mfma_f32_16x16x32_bf16 v[102:105], v[184:187], v[176:179], v[102:105]
	ds_read_b128 v[224:227], v144 offset:6144
	v_mfma_f32_16x16x32_bf16 v[98:101], v[184:187], v[180:183], v[98:101]
	ds_read_b128 v[228:231], v144 offset:7168
	v_mfma_f32_16x16x32_bf16 v[94:97], v[188:191], v[146:149], v[94:97]
	v_add_u32_e32 v144, s40, v137
	v_mfma_f32_16x16x32_bf16 v[90:93], v[188:191], v[152:155], v[90:93]
	v_mfma_f32_16x16x32_bf16 v[86:89], v[188:191], v[156:159], v[86:89]
	ds_read_b128 v[232:235], v144 offset:16384
	v_mfma_f32_16x16x32_bf16 v[82:85], v[188:191], v[162:165], v[82:85]
	ds_read_b128 v[236:239], v144 offset:17408
	v_mfma_f32_16x16x32_bf16 v[78:81], v[188:191], v[166:169], v[78:81]
	ds_read_b128 v[240:243], v144 offset:18432
	v_mfma_f32_16x16x32_bf16 v[74:77], v[188:191], v[170:173], v[74:77]
	ds_read_b128 v[244:247], v144 offset:19456
	s_add_i32 s42, s46, s41
	v_mfma_f32_16x16x32_bf16 v[70:73], v[188:191], v[176:179], v[70:73]
	s_mov_b32 m0, s42
	v_lshl_add_u64 v[142:143], v[132:133], 0, s[2:3]
	v_mfma_f32_16x16x32_bf16 v[66:69], v[188:191], v[180:183], v[66:69]
	global_load_lds_dwordx4 v[132:133], off
	s_addk_i32 m0, 0x1000
	v_mfma_f32_16x16x32_bf16 v[62:65], v[192:195], v[146:149], v[62:65]
	v_mfma_f32_16x16x32_bf16 v[58:61], v[192:195], v[152:155], v[58:61]
	v_mfma_f32_16x16x32_bf16 v[54:57], v[192:195], v[156:159], v[54:57]
	global_load_lds_dwordx4 v[142:143], off
	v_lshl_add_u64 v[142:143], v[142:143], 0, s[2:3]
	s_addk_i32 m0, 0x1000
	v_mfma_f32_16x16x32_bf16 v[50:53], v[192:195], v[162:165], v[50:53]
;     ...
;   for (int kt = 0; kt < nk; kt++) {
;     if (kt + 1 < nk) asm volatile("s_waitcnt vmcnt(6)" ::: "memory");
;     else asm volatile("s_waitcnt vmcnt(0)" ::: "memory");
;     __builtin_amdgcn_s_barrier();
;     asm volatile("" ::: "memory");
;     if (kt + 2 < nk) G2_STAGE(kt + 2);
;     const char* cS = smem + (kt % 3) * 24576;
;     bf16x8 xa[8], wb[4];
; #pragma unroll
;     for (int f = 0; f < 8; f++) xa[f] = *(const bf16x8*)(cS + aoff + f * 1024);
; #pragma unroll
;     for (int f = 0; f < 4; f++) wb[f] = *(const bf16x8*)(cS + boff + f * 1024);
; #pragma unroll
;     for (int nf = 0; nf < 4; nf++)
; #pragma unroll
;       for (int mf = 0; mf < 8; mf++)
;         acc[nf][mf] = __builtin_amdgcn_mfma_f32_16x16x32_bf16(wb[nf], xa[mf], acc[nf][mf], 0, 0, 0);
	v_mfma_f32_16x16x32_bf16 v[46:49], v[192:195], v[166:169], v[46:49]
	v_mfma_f32_16x16x32_bf16 v[42:45], v[192:195], v[170:173], v[42:45]
	global_load_lds_dwordx4 v[142:143], off
	v_lshl_add_u64 v[142:143], v[142:143], 0, s[2:3]
	s_addk_i32 m0, 0x1000
	v_mfma_f32_16x16x32_bf16 v[38:41], v[192:195], v[176:179], v[38:41]
	v_mfma_f32_16x16x32_bf16 v[34:37], v[192:195], v[180:183], v[34:37]
	v_mfma_f32_16x16x32_bf16 v[30:33], v[196:199], v[146:149], v[30:33]
	global_load_lds_dwordx4 v[142:143], off
	s_addk_i32 m0, 0x1000
	v_lshl_add_u64 v[142:143], v[134:135], 0, s[2:3]
	v_mfma_f32_16x16x32_bf16 v[26:29], v[196:199], v[152:155], v[26:29]
	v_mfma_f32_16x16x32_bf16 v[22:25], v[196:199], v[156:159], v[22:25]
	v_mfma_f32_16x16x32_bf16 v[18:21], v[196:199], v[162:165], v[18:21]
	global_load_lds_dwordx4 v[134:135], off
	s_addk_i32 m0, 0x1000
	v_lshl_add_u64 v[132:133], v[132:133], 0, s[12:13]
	v_mfma_f32_16x16x32_bf16 v[14:17], v[196:199], v[166:169], v[14:17]
	v_mfma_f32_16x16x32_bf16 v[10:13], v[196:199], v[170:173], v[10:13]
	v_mfma_f32_16x16x32_bf16 v[6:9], v[196:199], v[176:179], v[6:9]
	global_load_lds_dwordx4 v[142:143], off
	v_lshl_add_u64 v[134:135], v[134:135], 0, s[4:5]
	v_mfma_f32_16x16x32_bf16 v[2:5], v[196:199], v[180:183], v[2:5]
	s_setprio 0
	s_mov_b32 s41, s40
	s_add_i32 s40, s40, 0x6000
	s_cmp_eq_u32 s40, 0x12000
	s_cselect_b32 s40, 0, s40
	s_waitcnt vmcnt(6) lgkmcnt(0)
	s_barrier
	s_setprio 1
	v_add_u32_e32 v144, s40, v136
	v_mfma_f32_16x16x32_bf16 v[126:129], v[232:235], v[200:203], v[126:129]
	ds_read_b128 v[146:149], v144 offset:0
	v_mfma_f32_16x16x32_bf16 v[122:125], v[232:235], v[204:207], v[122:125]
	ds_read_b128 v[152:155], v144 offset:1024
	v_mfma_f32_16x16x32_bf16 v[118:121], v[232:235], v[208:211], v[118:121]
	ds_read_b128 v[156:159], v144 offset:2048
	v_mfma_f32_16x16x32_bf16 v[114:117], v[232:235], v[212:215], v[114:117]
	ds_read_b128 v[162:165], v144 offset:3072
	v_mfma_f32_16x16x32_bf16 v[110:113], v[232:235], v[216:219], v[110:113]
	ds_read_b128 v[166:169], v144 offset:4096
	v_mfma_f32_16x16x32_bf16 v[106:109], v[232:235], v[220:223], v[106:109]
	ds_read_b128 v[170:173], v144 offset:5120
	v_mfma_f32_16x16x32_bf16 v[102:105], v[232:235], v[224:227], v[102:105]
	ds_read_b128 v[176:179], v144 offset:6144
	v_mfma_f32_16x16x32_bf16 v[98:101], v[232:235], v[228:231], v[98:101]
	ds_read_b128 v[180:183], v144 offset:7168
	v_mfma_f32_16x16x32_bf16 v[94:97], v[236:239], v[200:203], v[94:97]
	v_add_u32_e32 v144, s40, v137
	v_mfma_f32_16x16x32_bf16 v[90:93], v[236:239], v[204:207], v[90:93]
	v_mfma_f32_16x16x32_bf16 v[86:89], v[236:239], v[208:211], v[86:89]
	ds_read_b128 v[184:187], v144 offset:16384
	v_mfma_f32_16x16x32_bf16 v[82:85], v[236:239], v[212:215], v[82:85]
	ds_read_b128 v[188:191], v144 offset:17408
	v_mfma_f32_16x16x32_bf16 v[78:81], v[236:239], v[216:219], v[78:81]
	ds_read_b128 v[192:195], v144 offset:18432
	v_mfma_f32_16x16x32_bf16 v[74:77], v[236:239], v[220:223], v[74:77]
	ds_read_b128 v[196:199], v144 offset:19456
	s_add_i32 s42, s46, s41
	v_mfma_f32_16x16x32_bf16 v[70:73], v[236:239], v[224:227], v[70:73]
	s_mov_b32 m0, s42
	v_lshl_add_u64 v[142:143], v[132:133], 0, s[2:3]
	v_mfma_f32_16x16x32_bf16 v[66:69], v[236:239], v[228:231], v[66:69]
	global_load_lds_dwordx4 v[132:133], off
	s_addk_i32 m0, 0x1000
	v_mfma_f32_16x16x32_bf16 v[62:65], v[240:243], v[200:203], v[62:65]
	v_mfma_f32_16x16x32_bf16 v[58:61], v[240:243], v[204:207], v[58:61]
	v_mfma_f32_16x16x32_bf16 v[54:57], v[240:243], v[208:211], v[54:57]
	global_load_lds_dwordx4 v[142:143], off
	v_lshl_add_u64 v[142:143], v[142:143], 0, s[2:3]
	s_addk_i32 m0, 0x1000
	v_mfma_f32_16x16x32_bf16 v[50:53], v[240:243], v[212:215], v[50:53]
	v_mfma_f32_16x16x32_bf16 v[46:49], v[240:243], v[216:219], v[46:49]
	v_mfma_f32_16x16x32_bf16 v[42:45], v[240:243], v[220:223], v[42:45]
	global_load_lds_dwordx4 v[142:143], off
	v_lshl_add_u64 v[142:143], v[142:143], 0, s[2:3]
	s_addk_i32 m0, 0x1000
	v_mfma_f32_16x16x32_bf16 v[38:41], v[240:243], v[224:227], v[38:41]
	v_mfma_f32_16x16x32_bf16 v[34:37], v[240:243], v[228:231], v[34:37]
	v_mfma_f32_16x16x32_bf16 v[30:33], v[244:247], v[200:203], v[30:33]
	global_load_lds_dwordx4 v[142:143], off
	s_addk_i32 m0, 0x1000
	v_lshl_add_u64 v[142:143], v[134:135], 0, s[2:3]
	v_mfma_f32_16x16x32_bf16 v[26:29], v[244:247], v[204:207], v[26:29]
	v_mfma_f32_16x16x32_bf16 v[22:25], v[244:247], v[208:211], v[22:25]
	v_mfma_f32_16x16x32_bf16 v[18:21], v[244:247], v[212:215], v[18:21]
	global_load_lds_dwordx4 v[134:135], off
	s_addk_i32 m0, 0x1000
	v_lshl_add_u64 v[132:133], v[132:133], 0, s[12:13]
	v_mfma_f32_16x16x32_bf16 v[14:17], v[244:247], v[216:219], v[14:17]
	v_mfma_f32_16x16x32_bf16 v[10:13], v[244:247], v[220:223], v[10:13]
	v_mfma_f32_16x16x32_bf16 v[6:9], v[244:247], v[224:227], v[6:9]
	global_load_lds_dwordx4 v[142:143], off
	v_lshl_add_u64 v[134:135], v[134:135], 0, s[4:5]
	v_mfma_f32_16x16x32_bf16 v[2:5], v[244:247], v[228:231], v[2:5]
	s_setprio 0
	s_mov_b32 s41, s40
	s_add_i32 s40, s40, 0x6000
	s_cmp_eq_u32 s40, 0x12000
	s_cselect_b32 s40, 0, s40
	s_sub_i32 s39, s39, 1
	s_cmp_lg_u32 s39, 0
	s_cbranch_scc1 .Lta11_loop
	s_waitcnt vmcnt(6) lgkmcnt(0)
	s_barrier
;     ...
;   for (int kt = 0; kt < nk; kt++) {
;     if (kt + 1 < nk) asm volatile("s_waitcnt vmcnt(6)" ::: "memory");
;     else asm volatile("s_waitcnt vmcnt(0)" ::: "memory");
;     __builtin_amdgcn_s_barrier();
;     asm volatile("" ::: "memory");
;     if (kt + 2 < nk) G2_STAGE(kt + 2);
;     const char* cS = smem + (kt % 3) * 24576;
;     bf16x8 xa[8], wb[4];
; #pragma unroll
;     for (int f = 0; f < 8; f++) xa[f] = *(const bf16x8*)(cS + aoff + f * 1024);
; #pragma unroll
;     for (int f = 0; f < 4; f++) wb[f] = *(const bf16x8*)(cS + boff + f * 1024);
; #pragma unroll
;     for (int nf = 0; nf < 4; nf++)
; #pragma unroll
;       for (int mf = 0; mf < 8; mf++)
;         acc[nf][mf] = __builtin_amdgcn_mfma_f32_16x16x32_bf16(wb[nf], xa[mf], acc[nf][mf], 0, 0, 0);
	s_setprio 1
	v_add_u32_e32 v144, s40, v136
	v_mfma_f32_16x16x32_bf16 v[126:129], v[184:187], v[146:149], v[126:129]
	ds_read_b128 v[200:203], v144 offset:0
	v_mfma_f32_16x16x32_bf16 v[122:125], v[184:187], v[152:155], v[122:125]
	ds_read_b128 v[204:207], v144 offset:1024
	v_mfma_f32_16x16x32_bf16 v[118:121], v[184:187], v[156:159], v[118:121]
	ds_read_b128 v[208:211], v144 offset:2048
	v_mfma_f32_16x16x32_bf16 v[114:117], v[184:187], v[162:165], v[114:117]
	ds_read_b128 v[212:215], v144 offset:3072
	v_mfma_f32_16x16x32_bf16 v[110:113], v[184:187], v[166:169], v[110:113]
	ds_read_b128 v[216:219], v144 offset:4096
	v_mfma_f32_16x16x32_bf16 v[106:109], v[184:187], v[170:173], v[106:109]
	ds_read_b128 v[220:223], v144 offset:5120
	v_mfma_f32_16x16x32_bf16 v[102:105], v[184:187], v[176:179], v[102:105]
	ds_read_b128 v[224:227], v144 offset:6144
	v_mfma_f32_16x16x32_bf16 v[98:101], v[184:187], v[180:183], v[98:101]
	ds_read_b128 v[228:231], v144 offset:7168
	v_mfma_f32_16x16x32_bf16 v[94:97], v[188:191], v[146:149], v[94:97]
	v_add_u32_e32 v144, s40, v137
	v_mfma_f32_16x16x32_bf16 v[90:93], v[188:191], v[152:155], v[90:93]
	v_mfma_f32_16x16x32_bf16 v[86:89], v[188:191], v[156:159], v[86:89]
	ds_read_b128 v[232:235], v144 offset:16384
	v_mfma_f32_16x16x32_bf16 v[82:85], v[188:191], v[162:165], v[82:85]
	ds_read_b128 v[236:239], v144 offset:17408
	v_mfma_f32_16x16x32_bf16 v[78:81], v[188:191], v[166:169], v[78:81]
	ds_read_b128 v[240:243], v144 offset:18432
	v_mfma_f32_16x16x32_bf16 v[74:77], v[188:191], v[170:173], v[74:77]
	ds_read_b128 v[244:247], v144 offset:19456
	s_add_i32 s42, s46, s41
	v_mfma_f32_16x16x32_bf16 v[70:73], v[188:191], v[176:179], v[70:73]
	s_mov_b32 m0, s42
	v_lshl_add_u64 v[142:143], v[132:133], 0, s[2:3]
	v_mfma_f32_16x16x32_bf16 v[66:69], v[188:191], v[180:183], v[66:69]
	global_load_lds_dwordx4 v[132:133], off
	s_addk_i32 m0, 0x1000
	v_mfma_f32_16x16x32_bf16 v[62:65], v[192:195], v[146:149], v[62:65]
	v_mfma_f32_16x16x32_bf16 v[58:61], v[192:195], v[152:155], v[58:61]
	v_mfma_f32_16x16x32_bf16 v[54:57], v[192:195], v[156:159], v[54:57]
	global_load_lds_dwordx4 v[142:143], off
	v_lshl_add_u64 v[142:143], v[142:143], 0, s[2:3]
	s_addk_i32 m0, 0x1000
	v_mfma_f32_16x16x32_bf16 v[50:53], v[192:195], v[162:165], v[50:53]
	v_mfma_f32_16x16x32_bf16 v[46:49], v[192:195], v[166:169], v[46:49]
	v_mfma_f32_16x16x32_bf16 v[42:45], v[192:195], v[170:173], v[42:45]
	global_load_lds_dwordx4 v[142:143], off
	v_lshl_add_u64 v[142:143], v[142:143], 0, s[2:3]
	s_addk_i32 m0, 0x1000
	v_mfma_f32_16x16x32_bf16 v[38:41], v[192:195], v[176:179], v[38:41]
	v_mfma_f32_16x16x32_bf16 v[34:37], v[192:195], v[180:183], v[34:37]
	v_mfma_f32_16x16x32_bf16 v[30:33], v[196:199], v[146:149], v[30:33]
	global_load_lds_dwordx4 v[142:143], off
	s_addk_i32 m0, 0x1000
	v_lshl_add_u64 v[142:143], v[134:135], 0, s[2:3]
	v_mfma_f32_16x16x32_bf16 v[26:29], v[196:199], v[152:155], v[26:29]
	v_mfma_f32_16x16x32_bf16 v[22:25], v[196:199], v[156:159], v[22:25]
	v_mfma_f32_16x16x32_bf16 v[18:21], v[196:199], v[162:165], v[18:21]
	global_load_lds_dwordx4 v[134:135], off
	s_addk_i32 m0, 0x1000
	v_lshl_add_u64 v[132:133], v[132:133], 0, s[12:13]
	v_mfma_f32_16x16x32_bf16 v[14:17], v[196:199], v[166:169], v[14:17]
	v_mfma_f32_16x16x32_bf16 v[10:13], v[196:199], v[170:173], v[10:13]
	v_mfma_f32_16x16x32_bf16 v[6:9], v[196:199], v[176:179], v[6:9]
	global_load_lds_dwordx4 v[142:143], off
	v_lshl_add_u64 v[134:135], v[134:135], 0, s[4:5]
	v_mfma_f32_16x16x32_bf16 v[2:5], v[196:199], v[180:183], v[2:5]
	s_setprio 0
	s_mov_b32 s41, s40
	s_add_i32 s40, s40, 0x6000
	s_cmp_eq_u32 s40, 0x12000
	s_cselect_b32 s40, 0, s40
	s_waitcnt vmcnt(6) lgkmcnt(0)
	s_barrier
	s_setprio 1
	v_add_u32_e32 v144, s40, v136
	v_mfma_f32_16x16x32_bf16 v[126:129], v[232:235], v[200:203], v[126:129]
	ds_read_b128 v[146:149], v144 offset:0
	v_mfma_f32_16x16x32_bf16 v[122:125], v[232:235], v[204:207], v[122:125]
	ds_read_b128 v[152:155], v144 offset:1024
	v_mfma_f32_16x16x32_bf16 v[118:121], v[232:235], v[208:211], v[118:121]
	ds_read_b128 v[156:159], v144 offset:2048
	v_mfma_f32_16x16x32_bf16 v[114:117], v[232:235], v[212:215], v[114:117]
	ds_read_b128 v[162:165], v144 offset:3072
	v_mfma_f32_16x16x32_bf16 v[110:113], v[232:235], v[216:219], v[110:113]
	ds_read_b128 v[166:169], v144 offset:4096
	v_mfma_f32_16x16x32_bf16 v[106:109], v[232:235], v[220:223], v[106:109]
	ds_read_b128 v[170:173], v144 offset:5120
	v_mfma_f32_16x16x32_bf16 v[102:105], v[232:235], v[224:227], v[102:105]
	ds_read_b128 v[176:179], v144 offset:6144
	v_mfma_f32_16x16x32_bf16 v[98:101], v[232:235], v[228:231], v[98:101]
	ds_read_b128 v[180:183], v144 offset:7168
	v_mfma_f32_16x16x32_bf16 v[94:97], v[236:239], v[200:203], v[94:97]
	v_add_u32_e32 v144, s40, v137
	v_mfma_f32_16x16x32_bf16 v[90:93], v[236:239], v[204:207], v[90:93]
	v_mfma_f32_16x16x32_bf16 v[86:89], v[236:239], v[208:211], v[86:89]
	ds_read_b128 v[184:187], v144 offset:16384
	v_mfma_f32_16x16x32_bf16 v[82:85], v[236:239], v[212:215], v[82:85]
	ds_read_b128 v[188:191], v144 offset:17408
	v_mfma_f32_16x16x32_bf16 v[78:81], v[236:239], v[216:219], v[78:81]
	ds_read_b128 v[192:195], v144 offset:18432
	v_mfma_f32_16x16x32_bf16 v[74:77], v[236:239], v[220:223], v[74:77]
	ds_read_b128 v[196:199], v144 offset:19456
	v_mfma_f32_16x16x32_bf16 v[70:73], v[236:239], v[224:227], v[70:73]
	v_mfma_f32_16x16x32_bf16 v[66:69], v[236:239], v[228:231], v[66:69]
	v_mfma_f32_16x16x32_bf16 v[62:65], v[240:243], v[200:203], v[62:65]
	v_mfma_f32_16x16x32_bf16 v[58:61], v[240:243], v[204:207], v[58:61]
	v_mfma_f32_16x16x32_bf16 v[54:57], v[240:243], v[208:211], v[54:57]
	v_mfma_f32_16x16x32_bf16 v[50:53], v[240:243], v[212:215], v[50:53]
	v_mfma_f32_16x16x32_bf16 v[46:49], v[240:243], v[216:219], v[46:49]
	v_mfma_f32_16x16x32_bf16 v[42:45], v[240:243], v[220:223], v[42:45]
	v_mfma_f32_16x16x32_bf16 v[38:41], v[240:243], v[224:227], v[38:41]
	v_mfma_f32_16x16x32_bf16 v[34:37], v[240:243], v[228:231], v[34:37]
	v_mfma_f32_16x16x32_bf16 v[30:33], v[244:247], v[200:203], v[30:33]
	v_mfma_f32_16x16x32_bf16 v[26:29], v[244:247], v[204:207], v[26:29]
	v_mfma_f32_16x16x32_bf16 v[22:25], v[244:247], v[208:211], v[22:25]
	v_mfma_f32_16x16x32_bf16 v[18:21], v[244:247], v[212:215], v[18:21]
	v_mfma_f32_16x16x32_bf16 v[14:17], v[244:247], v[216:219], v[14:17]
	v_mfma_f32_16x16x32_bf16 v[10:13], v[244:247], v[220:223], v[10:13]
	v_mfma_f32_16x16x32_bf16 v[6:9], v[244:247], v[224:227], v[6:9]
	v_mfma_f32_16x16x32_bf16 v[2:5], v[244:247], v[228:231], v[2:5]
	s_setprio 0
	s_mov_b32 s41, s40
	s_add_i32 s40, s40, 0x6000
	s_cmp_eq_u32 s40, 0x12000
	s_cselect_b32 s40, 0, s40
	s_waitcnt vmcnt(0) lgkmcnt(0)
	s_barrier
; DEVI float blo(unsigned u) { return __uint_as_float(u << 16); }
; DEVI float bhi(unsigned u) { return __uint_as_float(u & 0xffff0000u); }
;     ...
;   for (int kt = 0; kt < nk; kt++) {
;     if (kt + 1 < nk) asm volatile("s_waitcnt vmcnt(6)" ::: "memory");
;     else asm volatile("s_waitcnt vmcnt(0)" ::: "memory");
;     __builtin_amdgcn_s_barrier();
;     asm volatile("" ::: "memory");
;     if (kt + 2 < nk) G2_STAGE(kt + 2);
;     const char* cS = smem + (kt % 3) * 24576;
;     bf16x8 xa[8], wb[4];
; #pragma unroll
;     for (int f = 0; f < 8; f++) xa[f] = *(const bf16x8*)(cS + aoff + f * 1024);
; #pragma unroll
;     for (int f = 0; f < 4; f++) wb[f] = *(const bf16x8*)(cS + boff + f * 1024);
; #pragma unroll
;     for (int nf = 0; nf < 4; nf++)
; #pragma unroll
;       for (int mf = 0; mf < 8; mf++)
;         acc[nf][mf] = __builtin_amdgcn_mfma_f32_16x16x32_bf16(wb[nf], xa[mf], acc[nf][mf], 0, 0, 0);
;     ...
;         const int col = n0 + wn * 64 + nf * 16 + quad * 4;
;         f32x4 a = acc[nf][mf];
;         if (EPI == EPI_RESID || EPI == EPI_RESID_ATOMIC) {
;           f32x4 x = a;
;           if (EPI == EPI_RESID || kpart == 0) {
;             const u32x2 xr = *(const u32x2*)((const u16*)(p.ws + WS_XB) + (size_t)row * 1024 + col);
;             x[0] += ALPHA * blo(xr[0]); x[1] += ALPHA * bhi(xr[0]); x[2] += ALPHA * blo(xr[1]); x[3] += ALPHA * bhi(xr[1]);
;           }
;           if (EPI == EPI_RESID) *(f32x4*)((float*)(p.ws + WS_XF) + (size_t)row * 1024 + col) = x;
;           else *(f32x4*)((float*)(p.ws + WS_SLAB) + ((size_t)kpart * 512 + (row - T_P)) * 1024 + col) = x;
	s_setprio 1
	v_add_u32_e32 v144, s40, v136
	v_mfma_f32_16x16x32_bf16 v[126:129], v[184:187], v[146:149], v[126:129]
	ds_read_b128 v[200:203], v144 offset:0
	v_mfma_f32_16x16x32_bf16 v[122:125], v[184:187], v[152:155], v[122:125]
	ds_read_b128 v[204:207], v144 offset:1024
	v_mfma_f32_16x16x32_bf16 v[118:121], v[184:187], v[156:159], v[118:121]
	ds_read_b128 v[208:211], v144 offset:2048
	v_mfma_f32_16x16x32_bf16 v[114:117], v[184:187], v[162:165], v[114:117]
	ds_read_b128 v[212:215], v144 offset:3072
	v_mfma_f32_16x16x32_bf16 v[110:113], v[184:187], v[166:169], v[110:113]
	ds_read_b128 v[216:219], v144 offset:4096
	v_mfma_f32_16x16x32_bf16 v[106:109], v[184:187], v[170:173], v[106:109]
	ds_read_b128 v[220:223], v144 offset:5120
	v_mfma_f32_16x16x32_bf16 v[102:105], v[184:187], v[176:179], v[102:105]
	ds_read_b128 v[224:227], v144 offset:6144
	v_mfma_f32_16x16x32_bf16 v[98:101], v[184:187], v[180:183], v[98:101]
	ds_read_b128 v[228:231], v144 offset:7168
	v_mfma_f32_16x16x32_bf16 v[94:97], v[188:191], v[146:149], v[94:97]
	v_add_u32_e32 v144, s40, v137
	v_mfma_f32_16x16x32_bf16 v[90:93], v[188:191], v[152:155], v[90:93]
	v_mfma_f32_16x16x32_bf16 v[86:89], v[188:191], v[156:159], v[86:89]
	ds_read_b128 v[232:235], v144 offset:16384
	v_mfma_f32_16x16x32_bf16 v[82:85], v[188:191], v[162:165], v[82:85]
	ds_read_b128 v[236:239], v144 offset:17408
	v_mfma_f32_16x16x32_bf16 v[78:81], v[188:191], v[166:169], v[78:81]
	ds_read_b128 v[240:243], v144 offset:18432
	v_mfma_f32_16x16x32_bf16 v[74:77], v[188:191], v[170:173], v[74:77]
	ds_read_b128 v[244:247], v144 offset:19456
	v_mfma_f32_16x16x32_bf16 v[70:73], v[188:191], v[176:179], v[70:73]
	v_mfma_f32_16x16x32_bf16 v[66:69], v[188:191], v[180:183], v[66:69]
	v_mfma_f32_16x16x32_bf16 v[62:65], v[192:195], v[146:149], v[62:65]
	v_mfma_f32_16x16x32_bf16 v[58:61], v[192:195], v[152:155], v[58:61]
	v_mfma_f32_16x16x32_bf16 v[54:57], v[192:195], v[156:159], v[54:57]
	v_mfma_f32_16x16x32_bf16 v[50:53], v[192:195], v[162:165], v[50:53]
	v_mfma_f32_16x16x32_bf16 v[46:49], v[192:195], v[166:169], v[46:49]
	v_mfma_f32_16x16x32_bf16 v[42:45], v[192:195], v[170:173], v[42:45]
	v_mfma_f32_16x16x32_bf16 v[38:41], v[192:195], v[176:179], v[38:41]
	v_mfma_f32_16x16x32_bf16 v[34:37], v[192:195], v[180:183], v[34:37]
	v_mfma_f32_16x16x32_bf16 v[30:33], v[196:199], v[146:149], v[30:33]
	v_mfma_f32_16x16x32_bf16 v[26:29], v[196:199], v[152:155], v[26:29]
	v_mfma_f32_16x16x32_bf16 v[22:25], v[196:199], v[156:159], v[22:25]
	v_mfma_f32_16x16x32_bf16 v[18:21], v[196:199], v[162:165], v[18:21]
	v_mfma_f32_16x16x32_bf16 v[14:17], v[196:199], v[166:169], v[14:17]
	v_mfma_f32_16x16x32_bf16 v[10:13], v[196:199], v[170:173], v[10:13]
	v_mfma_f32_16x16x32_bf16 v[6:9], v[196:199], v[176:179], v[6:9]
	v_mfma_f32_16x16x32_bf16 v[2:5], v[196:199], v[180:183], v[2:5]
	s_setprio 0
	s_mov_b32 s41, s40
	s_add_i32 s40, s40, 0x6000
	s_cmp_eq_u32 s40, 0x12000
	s_cselect_b32 s40, 0, s40
	s_mov_b32 s4, 0x8000
	s_mov_b32 s5, 0
	s_mov_b32 s10, 0x10000
	s_mov_b32 s11, 0
	s_mov_b32 s44, 0x3fd744fd
	s_waitcnt lgkmcnt(0)
	v_mfma_f32_16x16x32_bf16 v[126:129], v[232:235], v[200:203], v[126:129]
	v_mfma_f32_16x16x32_bf16 v[122:125], v[232:235], v[204:207], v[122:125]
	v_mfma_f32_16x16x32_bf16 v[118:121], v[232:235], v[208:211], v[118:121]
	v_mfma_f32_16x16x32_bf16 v[114:117], v[232:235], v[212:215], v[114:117]
	v_mfma_f32_16x16x32_bf16 v[110:113], v[232:235], v[216:219], v[110:113]
	v_mfma_f32_16x16x32_bf16 v[106:109], v[232:235], v[220:223], v[106:109]
	v_mfma_f32_16x16x32_bf16 v[102:105], v[232:235], v[224:227], v[102:105]
	v_mfma_f32_16x16x32_bf16 v[98:101], v[232:235], v[228:231], v[98:101]
	v_mfma_f32_16x16x32_bf16 v[94:97], v[236:239], v[200:203], v[94:97]
	v_mfma_f32_16x16x32_bf16 v[90:93], v[236:239], v[204:207], v[90:93]
	v_mfma_f32_16x16x32_bf16 v[86:89], v[236:239], v[208:211], v[86:89]
	v_mfma_f32_16x16x32_bf16 v[82:85], v[236:239], v[212:215], v[82:85]
	v_mfma_f32_16x16x32_bf16 v[78:81], v[236:239], v[216:219], v[78:81]
	v_mfma_f32_16x16x32_bf16 v[74:77], v[236:239], v[220:223], v[74:77]
	v_mfma_f32_16x16x32_bf16 v[70:73], v[236:239], v[224:227], v[70:73]
	v_mfma_f32_16x16x32_bf16 v[66:69], v[236:239], v[228:231], v[66:69]
	v_mfma_f32_16x16x32_bf16 v[62:65], v[240:243], v[200:203], v[62:65]
	v_mfma_f32_16x16x32_bf16 v[58:61], v[240:243], v[204:207], v[58:61]
	v_mfma_f32_16x16x32_bf16 v[54:57], v[240:243], v[208:211], v[54:57]
	v_mfma_f32_16x16x32_bf16 v[50:53], v[240:243], v[212:215], v[50:53]
	v_mfma_f32_16x16x32_bf16 v[46:49], v[240:243], v[216:219], v[46:49]
	v_mfma_f32_16x16x32_bf16 v[42:45], v[240:243], v[220:223], v[42:45]
	v_mfma_f32_16x16x32_bf16 v[38:41], v[240:243], v[224:227], v[38:41]
	v_mfma_f32_16x16x32_bf16 v[34:37], v[240:243], v[228:231], v[34:37]
	v_mfma_f32_16x16x32_bf16 v[30:33], v[244:247], v[200:203], v[30:33]
	v_mfma_f32_16x16x32_bf16 v[26:29], v[244:247], v[204:207], v[26:29]
	v_mfma_f32_16x16x32_bf16 v[22:25], v[244:247], v[208:211], v[22:25]
	v_mfma_f32_16x16x32_bf16 v[18:21], v[244:247], v[212:215], v[18:21]
	v_mfma_f32_16x16x32_bf16 v[14:17], v[244:247], v[216:219], v[14:17]
	v_mfma_f32_16x16x32_bf16 v[10:13], v[244:247], v[220:223], v[10:13]
	v_mfma_f32_16x16x32_bf16 v[6:9], v[244:247], v[224:227], v[6:9]
	v_mfma_f32_16x16x32_bf16 v[2:5], v[244:247], v[228:231], v[2:5]
	s_mov_b32 m0, s43
	s_cmp_eq_u32 s47, 0
	s_cbranch_scc1 .Lta11_first
; DEVI float blo(unsigned u) { return __uint_as_float(u << 16); }
; DEVI float bhi(unsigned u) { return __uint_as_float(u & 0xffff0000u); }
;     ...
;         const int col = n0 + wn * 64 + nf * 16 + quad * 4;
;         f32x4 a = acc[nf][mf];
;         if (EPI == EPI_RESID || EPI == EPI_RESID_ATOMIC) {
;           f32x4 x = a;
;           if (EPI == EPI_RESID || kpart == 0) {
;             const u32x2 xr = *(const u32x2*)((const u16*)(p.ws + WS_XB) + (size_t)row * 1024 + col);
;             x[0] += ALPHA * blo(xr[0]); x[1] += ALPHA * bhi(xr[0]); x[2] += ALPHA * blo(xr[1]); x[3] += ALPHA * bhi(xr[1]);
;           }
;           if (EPI == EPI_RESID) *(f32x4*)((float*)(p.ws + WS_XF) + (size_t)row * 1024 + col) = x;
;           else *(f32x4*)((float*)(p.ws + WS_SLAB) + ((size_t)kpart * 512 + (row - T_P)) * 1024 + col) = x;
	s_nop 7
	global_store_dwordx4 v[140:141], v[126:129], off offset:0
	global_store_dwordx4 v[140:141], v[94:97], off offset:64
	global_store_dwordx4 v[140:141], v[62:65], off offset:128
	global_store_dwordx4 v[140:141], v[30:33], off offset:192
	v_lshl_add_u64 v[140:141], v[140:141], 0, s[10:11]
	global_store_dwordx4 v[140:141], v[122:125], off offset:0
	global_store_dwordx4 v[140:141], v[90:93], off offset:64
	global_store_dwordx4 v[140:141], v[58:61], off offset:128
	global_store_dwordx4 v[140:141], v[26:29], off offset:192
	v_lshl_add_u64 v[140:141], v[140:141], 0, s[10:11]
	global_store_dwordx4 v[140:141], v[118:121], off offset:0
	global_store_dwordx4 v[140:141], v[86:89], off offset:64
	global_store_dwordx4 v[140:141], v[54:57], off offset:128
	global_store_dwordx4 v[140:141], v[22:25], off offset:192
	v_lshl_add_u64 v[140:141], v[140:141], 0, s[10:11]
	global_store_dwordx4 v[140:141], v[114:117], off offset:0
	global_store_dwordx4 v[140:141], v[82:85], off offset:64
	global_store_dwordx4 v[140:141], v[50:53], off offset:128
	global_store_dwordx4 v[140:141], v[18:21], off offset:192
	v_lshl_add_u64 v[140:141], v[140:141], 0, s[10:11]
	global_store_dwordx4 v[140:141], v[110:113], off offset:0
	global_store_dwordx4 v[140:141], v[78:81], off offset:64
	global_store_dwordx4 v[140:141], v[46:49], off offset:128
	global_store_dwordx4 v[140:141], v[14:17], off offset:192
	v_lshl_add_u64 v[140:141], v[140:141], 0, s[10:11]
	global_store_dwordx4 v[140:141], v[106:109], off offset:0
	global_store_dwordx4 v[140:141], v[74:77], off offset:64
	global_store_dwordx4 v[140:141], v[42:45], off offset:128
	global_store_dwordx4 v[140:141], v[10:13], off offset:192
	v_lshl_add_u64 v[140:141], v[140:141], 0, s[10:11]
	global_store_dwordx4 v[140:141], v[102:105], off offset:0
	global_store_dwordx4 v[140:141], v[70:73], off offset:64
	global_store_dwordx4 v[140:141], v[38:41], off offset:128
	global_store_dwordx4 v[140:141], v[6:9], off offset:192
	v_lshl_add_u64 v[140:141], v[140:141], 0, s[10:11]
	global_store_dwordx4 v[140:141], v[98:101], off offset:0
	global_store_dwordx4 v[140:141], v[66:69], off offset:64
	global_store_dwordx4 v[140:141], v[34:37], off offset:128
	global_store_dwordx4 v[140:141], v[2:5], off offset:192
	s_branch .LBB0_41

; #define LAS __attribute__((address_space(3)))
; DEVI int xcd_first_tile() { return (blockIdx.x & 7) * (gridDim.x >> 3) + (blockIdx.x >> 3); }
;     ...
;   const int nk = (nk_part < 0) ? (K >> 5) : nk_part;
;   const int lrow = tid >> 2, lpc = tid & 3;
;   const int lch = lpc ^ ((0x78 >> (((lrow >> 2) & 3) * 2)) & 3);
;   const u16* ga = A + (size_t)(m0 + lrow) * lda + kbeg + lch * 8;
;   const u16* gb = Bt + (size_t)(n0 + lrow) * K + kbeg + lch * 8;
;   const size_t ga1 = (size_t)64 * lda, gb1 = (size_t)64 * K;
;   const unsigned lds0 = (unsigned)(uintptr_t)(LAS char*)smem + (unsigned)__builtin_amdgcn_readfirstlane(wid) * 1024u;
;     ...
;   __syncthreads();
;   G2_STAGE(0); G2_STAGE(1);
;   const int fsw = (0x78 >> (((r16 >> 2) & 3) * 2)) & 3;
;   const int aoff = (wm * 128 + r16) * 64 + ((quad ^ fsw) << 4);
;   const int boff = 16384 + (wn * 64 + r16) * 64 + ((quad ^ fsw) << 4);
; DEVI void run_phase(const Params& p, int ph, char* smem) {
;     ...
;       for (int t = xcd_first_tile(); t < 512 + 16 * 11; t += xcd_tile_step()) {
;         if (t < 512) {
;           int mt_, nt_; tile_coords(t, 64, 8, mt_, nt_);
;           gemm_tile256<EPI_RESID>(p, hb, DFF, Bt, DFF, mt_ * 256, nt_ * 128, nullptr, 0, smem);
.LBB0_116:
	s_and_b64 vcc, exec, s[2:3]
	s_cbranch_vccz .LBB0_41
	s_lshr_b32 s45, s38, 6
	s_and_b32 s46, s38, 63
	s_lshr_b32 s42, s46, 3
	s_and_b32 s46, s46, 7
	s_lshl_b32 s45, s45, 3
	s_add_i32 s45, s45, s46
	s_cmp_lt_u32 s45, 64
	s_cselect_b32 s44, 1, 0
	v_readlane_b32 s2, v250, 5
	v_readlane_b32 s3, v250, 6
	v_readlane_b32 s46, v254, 62
	s_mul_i32 s40, s45, 0x160000
	s_add_u32 s4, s2, s40
	s_addc_u32 s5, s3, 0
	s_add_u32 s4, s4, 0xef40000
	s_addc_u32 s5, s5, 0
	s_mul_i32 s40, s46, 0x580000
	s_mul_i32 s41, s42, 0xb0000
	s_add_i32 s40, s40, s41
	s_add_u32 s10, s2, s40
	s_addc_u32 s11, s3, 0
	s_add_u32 s10, s10, 0x19a00000
	s_addc_u32 s11, s11, 0
	s_movk_i32 s39, 0x78
	v_lshrrev_b32_e32 v0, 2, v145
	v_and_b32_e32 v131, 3, v145
	v_bfe_u32 v136, v145, 4, 2
	v_lshlrev_b32_e32 v136, 1, v136
	v_lshrrev_b32_e64 v136, v136, s39
	v_and_b32_e32 v136, 3, v136
	v_xor_b32_e32 v131, v131, v136
	v_lshlrev_b32_e32 v131, 4, v131
	s_movk_i32 s41, 0x1600
	v_mad_u32_u24 v0, v0, s41, v131
	v_bfe_u32 v137, v145, 2, 1
	s_movk_i32 s41, 0x15c0
	v_mul_u32_u24_e32 v136, s41, v137
	v_sub_u32_e32 v136, v0, v136
	v_mov_b32_e32 v137, 0
	v_lshl_add_u64 v[134:135], s[10:11], 0, v[136:137]
	v_bfe_u32 v137, v145, 2, 1
	s_mul_i32 s41, s44, 0x15c0
	v_mul_u32_u24_e32 v136, s41, v137
	v_sub_u32_e32 v0, v0, v136
	s_lshl_b32 s12, s44, 6
	s_add_i32 s12, s12, 64
	s_mov_b32 s13, 0
	v_lshl_add_u64 v[132:133], s[4:5], 0, v[0:1]
	v_bfe_u32 v136, v145, 2, 2
	v_lshlrev_b32_e32 v136, 1, v136
	v_lshrrev_b32_e64 v136, v136, s39
	v_and_b32_e32 v136, 3, v136
	v_bfe_u32 v137, v145, 4, 2
	v_xor_b32_e32 v136, v136, v137
	v_lshlrev_b32_e32 v136, 4, v136
	v_and_b32_e32 v131, 15, v145
	v_lshl_or_b32 v136, v131, 6, v136
	v_bfe_u32 v137, v145, 6, 1
	v_lshl_or_b32 v137, v137, 12, v136
	v_lshrrev_b32_e32 v0, 7, v145
	v_lshl_or_b32 v136, v0, 13, v136
	v_and_b32_e32 v140, 1, v131
	v_lshl_or_b32 v131, v0, 7, v131
	v_bfe_u32 v0, v145, 4, 2
	v_lshlrev_b32_e32 v0, 3, v0
	v_bfe_u32 v141, v145, 6, 1
	s_lshl_b32 s40, s45, 19
	s_lshl_b32 s41, s42, 9
	s_add_i32 s40, s40, s41
	s_add_u32 s4, s2, s40
	s_addc_u32 s5, s3, 0
	s_add_u32 s4, s4, 0x4200000
	s_addc_u32 s5, s5, 0
	v_lshlrev_b32_e32 v138, 11, v131
	v_lshl_add_u32 v138, v141, 8, v138
	v_bfe_u32 v139, v145, 4, 1
	v_lshl_add_u32 v138, v139, 5, v138
	v_bfe_u32 v139, v145, 5, 1
	v_lshl_add_u32 v138, v139, 4, v138
	s_movk_i32 s41, 1984
	v_mul_u32_u24_e32 v139, s41, v140
	v_sub_u32_e32 v138, v138, v139
	v_mov_b32_e32 v139, 0
	v_lshl_add_u64 v[138:139], s[4:5], 0, v[138:139]
	s_lshl_b32 s40, s45, 20
	s_lshl_b32 s41, s42, 9
	s_add_i32 s40, s40, s41
	s_add_u32 s10, s2, s40
	s_addc_u32 s11, s3, 0
	v_lshlrev_b32_e32 v140, 12, v131
	v_lshl_add_u32 v140, v141, 8, v140
	v_lshl_add_u32 v140, v0, 1, v140
	v_mov_b32_e32 v141, 0
	v_lshl_add_u64 v[140:141], s[10:11], 0, v[140:141]
	s_mov_b32 s2, 0x58000
	s_mov_b32 s3, 0
	v_lshrrev_b32_e32 v0, 6, v145
	v_lshlrev_b32_e32 v0, 10, v0
	s_nop 0
	v_readfirstlane_b32 s46, v0
	s_mov_b32 s43, m0
	s_mov_b32 s4, 128
	s_mov_b32 s5, 0
	s_barrier
	s_add_i32 s42, s46, 0x0
	s_mov_b32 m0, s42
	v_lshl_add_u64 v[142:143], v[132:133], 0, s[2:3]
	global_load_lds_dwordx4 v[132:133], off
	s_addk_i32 m0, 0x1000
	s_nop 0
	global_load_lds_dwordx4 v[142:143], off
	v_lshl_add_u64 v[142:143], v[142:143], 0, s[2:3]
	s_addk_i32 m0, 0x1000
	s_nop 0
	global_load_lds_dwordx4 v[142:143], off
	v_lshl_add_u64 v[142:143], v[142:143], 0, s[2:3]
	s_addk_i32 m0, 0x1000
	s_nop 0
	global_load_lds_dwordx4 v[142:143], off
	s_addk_i32 m0, 0x1000
	v_lshl_add_u64 v[142:143], v[134:135], 0, s[2:3]
	s_nop 0
	global_load_lds_dwordx4 v[134:135], off
	s_addk_i32 m0, 0x1000
	v_lshl_add_u64 v[132:133], v[132:133], 0, s[12:13]
	s_nop 0
	global_load_lds_dwordx4 v[142:143], off
	v_lshl_add_u64 v[134:135], v[134:135], 0, s[4:5]
	s_nop 0
	s_add_i32 s42, s46, 0x6000
	s_mov_b32 m0, s42
	v_lshl_add_u64 v[142:143], v[132:133], 0, s[2:3]
	global_load_lds_dwordx4 v[132:133], off
	s_addk_i32 m0, 0x1000
	s_nop 0
	global_load_lds_dwordx4 v[142:143], off
	v_lshl_add_u64 v[142:143], v[142:143], 0, s[2:3]
	s_addk_i32 m0, 0x1000
	s_nop 0
	global_load_lds_dwordx4 v[142:143], off
	v_lshl_add_u64 v[142:143], v[142:143], 0, s[2:3]
	s_addk_i32 m0, 0x1000
	s_nop 0
	global_load_lds_dwordx4 v[142:143], off
	s_addk_i32 m0, 0x1000
	v_lshl_add_u64 v[142:143], v[134:135], 0, s[2:3]
	s_nop 0
	global_load_lds_dwordx4 v[134:135], off
	s_addk_i32 m0, 0x1000
	v_lshl_add_u64 v[132:133], v[132:133], 0, s[12:13]
	s_nop 0
	global_load_lds_dwordx4 v[142:143], off
	v_lshl_add_u64 v[134:135], v[134:135], 0, s[4:5]
	s_nop 0
	s_add_i32 s42, s46, 0xc000
	s_mov_b32 m0, s42
	v_lshl_add_u64 v[142:143], v[132:133], 0, s[2:3]
	global_load_lds_dwordx4 v[132:133], off
	s_addk_i32 m0, 0x1000
	s_nop 0
	global_load_lds_dwordx4 v[142:143], off
	v_lshl_add_u64 v[142:143], v[142:143], 0, s[2:3]
	s_addk_i32 m0, 0x1000
	s_nop 0
	global_load_lds_dwordx4 v[142:143], off
	v_lshl_add_u64 v[142:143], v[142:143], 0, s[2:3]
	s_addk_i32 m0, 0x1000
	s_nop 0
	global_load_lds_dwordx4 v[142:143], off
	s_addk_i32 m0, 0x1000
	v_lshl_add_u64 v[142:143], v[134:135], 0, s[2:3]
	s_nop 0
	global_load_lds_dwordx4 v[134:135], off
	s_addk_i32 m0, 0x1000
	v_lshl_add_u64 v[132:133], v[132:133], 0, s[12:13]
	s_nop 0
	global_load_lds_dwordx4 v[142:143], off
	v_lshl_add_u64 v[134:135], v[134:135], 0, s[4:5]
	s_nop 0
	v_mov_b32_e32 v2, 0
	v_mov_b32_e32 v3, 0
	v_mov_b32_e32 v4, 0
	v_mov_b32_e32 v5, 0
	v_mov_b32_e32 v6, 0
	v_mov_b32_e32 v7, 0
	v_mov_b32_e32 v8, 0
	v_mov_b32_e32 v9, 0
	v_mov_b32_e32 v10, 0
	v_mov_b32_e32 v11, 0
	v_mov_b32_e32 v12, 0
	v_mov_b32_e32 v13, 0
	v_mov_b32_e32 v14, 0
	v_mov_b32_e32 v15, 0
	v_mov_b32_e32 v16, 0
	v_mov_b32_e32 v17, 0
; #define LAS __attribute__((address_space(3)))
;     ...
;   f32x4 acc[4][8];
; #pragma unroll
;   for (int i = 0; i < 4; i++)
; #pragma unroll
;     for (int j = 0; j < 8; j++) acc[i][j] = (f32x4){0.f, 0.f, 0.f, 0.f};
;   const int nk = (nk_part < 0) ? (K >> 5) : nk_part;
;   const int lrow = tid >> 2, lpc = tid & 3;
;   const int lch = lpc ^ ((0x78 >> (((lrow >> 2) & 3) * 2)) & 3);
;   const u16* ga = A + (size_t)(m0 + lrow) * lda + kbeg + lch * 8;
;   const u16* gb = Bt + (size_t)(n0 + lrow) * K + kbeg + lch * 8;
;   const size_t ga1 = (size_t)64 * lda, gb1 = (size_t)64 * K;
;   const unsigned lds0 = (unsigned)(uintptr_t)(LAS char*)smem + (unsigned)__builtin_amdgcn_readfirstlane(wid) * 1024u;
;     ...
;   __syncthreads();
;   G2_STAGE(0); G2_STAGE(1);
;   const int fsw = (0x78 >> (((r16 >> 2) & 3) * 2)) & 3;
;   const int aoff = (wm * 128 + r16) * 64 + ((quad ^ fsw) << 4);
;   const int boff = 16384 + (wn * 64 + r16) * 64 + ((quad ^ fsw) << 4);
;   for (int kt = 0; kt < nk; kt++) {
;     if (kt + 1 < nk) asm volatile("s_waitcnt vmcnt(6)" ::: "memory");
;     else asm volatile("s_waitcnt vmcnt(0)" ::: "memory");
;     __builtin_amdgcn_s_barrier();
;     asm volatile("" ::: "memory");
;     if (kt + 2 < nk) G2_STAGE(kt + 2);
;     const char* cS = smem + (kt % 3) * 24576;
;     bf16x8 xa[8], wb[4];
; #pragma unroll
;     for (int f = 0; f < 8; f++) xa[f] = *(const bf16x8*)(cS + aoff + f * 1024);
; #pragma unroll
;     for (int f = 0; f < 4; f++) wb[f] = *(const bf16x8*)(cS + boff + f * 1024);
; #pragma unroll
;     for (int nf = 0; nf < 4; nf++)
; #pragma unroll
;       for (int mf = 0; mf < 8; mf++)
;         acc[nf][mf] = __builtin_amdgcn_mfma_f32_16x16x32_bf16(wb[nf], xa[mf], acc[nf][mf], 0, 0, 0);
	v_mov_b32_e32 v18, 0
	v_mov_b32_e32 v19, 0
	v_mov_b32_e32 v20, 0
	v_mov_b32_e32 v21, 0
	v_mov_b32_e32 v22, 0
	v_mov_b32_e32 v23, 0
	v_mov_b32_e32 v24, 0
	v_mov_b32_e32 v25, 0
	v_mov_b32_e32 v26, 0
	v_mov_b32_e32 v27, 0
	v_mov_b32_e32 v28, 0
	v_mov_b32_e32 v29, 0
	v_mov_b32_e32 v30, 0
	v_mov_b32_e32 v31, 0
	v_mov_b32_e32 v32, 0
	v_mov_b32_e32 v33, 0
	v_mov_b32_e32 v34, 0
	v_mov_b32_e32 v35, 0
	v_mov_b32_e32 v36, 0
	v_mov_b32_e32 v37, 0
	v_mov_b32_e32 v38, 0
	v_mov_b32_e32 v39, 0
	v_mov_b32_e32 v40, 0
	v_mov_b32_e32 v41, 0
	v_mov_b32_e32 v42, 0
	v_mov_b32_e32 v43, 0
	v_mov_b32_e32 v44, 0
	v_mov_b32_e32 v45, 0
	v_mov_b32_e32 v46, 0
	v_mov_b32_e32 v47, 0
	v_mov_b32_e32 v48, 0
	v_mov_b32_e32 v49, 0
	v_mov_b32_e32 v50, 0
	v_mov_b32_e32 v51, 0
	v_mov_b32_e32 v52, 0
	v_mov_b32_e32 v53, 0
	v_mov_b32_e32 v54, 0
	v_mov_b32_e32 v55, 0
	v_mov_b32_e32 v56, 0
	v_mov_b32_e32 v57, 0
	v_mov_b32_e32 v58, 0
	v_mov_b32_e32 v59, 0
	v_mov_b32_e32 v60, 0
	v_mov_b32_e32 v61, 0
	v_mov_b32_e32 v62, 0
	v_mov_b32_e32 v63, 0
	v_mov_b32_e32 v64, 0
	v_mov_b32_e32 v65, 0
	v_mov_b32_e32 v66, 0
	v_mov_b32_e32 v67, 0
	v_mov_b32_e32 v68, 0
	v_mov_b32_e32 v69, 0
	v_mov_b32_e32 v70, 0
	v_mov_b32_e32 v71, 0
	v_mov_b32_e32 v72, 0
	v_mov_b32_e32 v73, 0
	v_mov_b32_e32 v74, 0
	v_mov_b32_e32 v75, 0
	v_mov_b32_e32 v76, 0
	v_mov_b32_e32 v77, 0
	v_mov_b32_e32 v78, 0
	v_mov_b32_e32 v79, 0
	v_mov_b32_e32 v80, 0
	v_mov_b32_e32 v81, 0
	v_mov_b32_e32 v82, 0
	v_mov_b32_e32 v83, 0
	v_mov_b32_e32 v84, 0
	v_mov_b32_e32 v85, 0
	v_mov_b32_e32 v86, 0
	v_mov_b32_e32 v87, 0
	v_mov_b32_e32 v88, 0
	v_mov_b32_e32 v89, 0
	v_mov_b32_e32 v90, 0
	v_mov_b32_e32 v91, 0
	v_mov_b32_e32 v92, 0
	v_mov_b32_e32 v93, 0
	v_mov_b32_e32 v94, 0
	v_mov_b32_e32 v95, 0
	v_mov_b32_e32 v96, 0
	v_mov_b32_e32 v97, 0
	v_mov_b32_e32 v98, 0
	v_mov_b32_e32 v99, 0
	v_mov_b32_e32 v100, 0
	v_mov_b32_e32 v101, 0
	v_mov_b32_e32 v102, 0
	v_mov_b32_e32 v103, 0
	v_mov_b32_e32 v104, 0
	v_mov_b32_e32 v105, 0
	v_mov_b32_e32 v106, 0
	v_mov_b32_e32 v107, 0
	v_mov_b32_e32 v108, 0
	v_mov_b32_e32 v109, 0
	v_mov_b32_e32 v110, 0
	v_mov_b32_e32 v111, 0
	v_mov_b32_e32 v112, 0
	v_mov_b32_e32 v113, 0
	v_mov_b32_e32 v114, 0
	v_mov_b32_e32 v115, 0
	v_mov_b32_e32 v116, 0
	v_mov_b32_e32 v117, 0
	v_mov_b32_e32 v118, 0
	v_mov_b32_e32 v119, 0
	v_mov_b32_e32 v120, 0
	v_mov_b32_e32 v121, 0
	v_mov_b32_e32 v122, 0
	v_mov_b32_e32 v123, 0
	v_mov_b32_e32 v124, 0
	v_mov_b32_e32 v125, 0
	v_mov_b32_e32 v126, 0
	v_mov_b32_e32 v127, 0
	v_mov_b32_e32 v128, 0
	v_mov_b32_e32 v129, 0
	s_waitcnt vmcnt(12)
	s_barrier
	ds_read_b128 v[146:149], v136 offset:0
	ds_read_b128 v[152:155], v136 offset:1024
	ds_read_b128 v[156:159], v136 offset:2048
	ds_read_b128 v[162:165], v136 offset:3072
	ds_read_b128 v[166:169], v136 offset:4096
	ds_read_b128 v[170:173], v136 offset:5120
	ds_read_b128 v[176:179], v136 offset:6144
	ds_read_b128 v[180:183], v136 offset:7168
	ds_read_b128 v[184:187], v137 offset:16384
	ds_read_b128 v[188:191], v137 offset:17408
	ds_read_b128 v[192:195], v137 offset:18432
	ds_read_b128 v[196:199], v137 offset:19456
	s_movk_i32 s40, 0x6000
	s_mov_b32 s41, 0
	s_movk_i32 s39, 42
.Lt11_loop:
	s_waitcnt vmcnt(6) lgkmcnt(0)
	s_barrier
	s_setprio 1
	v_add_u32_e32 v144, s40, v136
	v_mfma_f32_16x16x32_bf16 v[126:129], v[184:187], v[146:149], v[126:129]
	ds_read_b128 v[200:203], v144 offset:0
	v_mfma_f32_16x16x32_bf16 v[122:125], v[184:187], v[152:155], v[122:125]
	ds_read_b128 v[204:207], v144 offset:1024
	v_mfma_f32_16x16x32_bf16 v[118:121], v[184:187], v[156:159], v[118:121]
	ds_read_b128 v[208:211], v144 offset:2048
	v_mfma_f32_16x16x32_bf16 v[114:117], v[184:187], v[162:165], v[114:117]
	ds_read_b128 v[212:215], v144 offset:3072
	v_mfma_f32_16x16x32_bf16 v[110:113], v[184:187], v[166:169], v[110:113]
	ds_read_b128 v[216:219], v144 offset:4096
	v_mfma_f32_16x16x32_bf16 v[106:109], v[184:187], v[170:173], v[106:109]
	ds_read_b128 v[220:223], v144 offset:5120
	v_mfma_f32_16x16x32_bf16 v[102:105], v[184:187], v[176:179], v[102:105]
	ds_read_b128 v[224:227], v144 offset:6144
	v_mfma_f32_16x16x32_bf16 v[98:101], v[184:187], v[180:183], v[98:101]
	ds_read_b128 v[228:231], v144 offset:7168
	v_mfma_f32_16x16x32_bf16 v[94:97], v[188:191], v[146:149], v[94:97]
	v_add_u32_e32 v144, s40, v137
	v_mfma_f32_16x16x32_bf16 v[90:93], v[188:191], v[152:155], v[90:93]
	v_mfma_f32_16x16x32_bf16 v[86:89], v[188:191], v[156:159], v[86:89]
	ds_read_b128 v[232:235], v144 offset:16384
	v_mfma_f32_16x16x32_bf16 v[82:85], v[188:191], v[162:165], v[82:85]
	ds_read_b128 v[236:239], v144 offset:17408
	v_mfma_f32_16x16x32_bf16 v[78:81], v[188:191], v[166:169], v[78:81]
	ds_read_b128 v[240:243], v144 offset:18432
	v_mfma_f32_16x16x32_bf16 v[74:77], v[188:191], v[170:173], v[74:77]
	ds_read_b128 v[244:247], v144 offset:19456
	s_add_i32 s42, s46, s41
	v_mfma_f32_16x16x32_bf16 v[70:73], v[188:191], v[176:179], v[70:73]
	s_mov_b32 m0, s42
	v_lshl_add_u64 v[142:143], v[132:133], 0, s[2:3]
	v_mfma_f32_16x16x32_bf16 v[66:69], v[188:191], v[180:183], v[66:69]
	global_load_lds_dwordx4 v[132:133], off
	s_addk_i32 m0, 0x1000
	v_mfma_f32_16x16x32_bf16 v[62:65], v[192:195], v[146:149], v[62:65]
	v_mfma_f32_16x16x32_bf16 v[58:61], v[192:195], v[152:155], v[58:61]
	v_mfma_f32_16x16x32_bf16 v[54:57], v[192:195], v[156:159], v[54:57]
	global_load_lds_dwordx4 v[142:143], off
	v_lshl_add_u64 v[142:143], v[142:143], 0, s[2:3]
	s_addk_i32 m0, 0x1000
	v_mfma_f32_16x16x32_bf16 v[50:53], v[192:195], v[162:165], v[50:53]
	v_mfma_f32_16x16x32_bf16 v[46:49], v[192:195], v[166:169], v[46:49]
	v_mfma_f32_16x16x32_bf16 v[42:45], v[192:195], v[170:173], v[42:45]
	global_load_lds_dwordx4 v[142:143], off
	v_lshl_add_u64 v[142:143], v[142:143], 0, s[2:3]
	s_addk_i32 m0, 0x1000
	v_mfma_f32_16x16x32_bf16 v[38:41], v[192:195], v[176:179], v[38:41]
	v_mfma_f32_16x16x32_bf16 v[34:37], v[192:195], v[180:183], v[34:37]
	v_mfma_f32_16x16x32_bf16 v[30:33], v[196:199], v[146:149], v[30:33]
	global_load_lds_dwordx4 v[142:143], off
	s_addk_i32 m0, 0x1000
	v_lshl_add_u64 v[142:143], v[134:135], 0, s[2:3]
	v_mfma_f32_16x16x32_bf16 v[26:29], v[196:199], v[152:155], v[26:29]
	v_mfma_f32_16x16x32_bf16 v[22:25], v[196:199], v[156:159], v[22:25]
	v_mfma_f32_16x16x32_bf16 v[18:21], v[196:199], v[162:165], v[18:21]
	global_load_lds_dwordx4 v[134:135], off
	s_addk_i32 m0, 0x1000
	v_lshl_add_u64 v[132:133], v[132:133], 0, s[12:13]
	v_mfma_f32_16x16x32_bf16 v[14:17], v[196:199], v[166:169], v[14:17]
	v_mfma_f32_16x16x32_bf16 v[10:13], v[196:199], v[170:173], v[10:13]
	v_mfma_f32_16x16x32_bf16 v[6:9], v[196:199], v[176:179], v[6:9]
	global_load_lds_dwordx4 v[142:143], off
	v_lshl_add_u64 v[134:135], v[134:135], 0, s[4:5]
	v_mfma_f32_16x16x32_bf16 v[2:5], v[196:199], v[180:183], v[2:5]
	s_setprio 0
	s_mov_b32 s41, s40
	s_add_i32 s40, s40, 0x6000
	s_cmp_eq_u32 s40, 0x12000
	s_cselect_b32 s40, 0, s40
	s_waitcnt vmcnt(6) lgkmcnt(0)
	s_barrier
;     ...
;   for (int kt = 0; kt < nk; kt++) {
;     if (kt + 1 < nk) asm volatile("s_waitcnt vmcnt(6)" ::: "memory");
;     else asm volatile("s_waitcnt vmcnt(0)" ::: "memory");
;     __builtin_amdgcn_s_barrier();
;     asm volatile("" ::: "memory");
;     if (kt + 2 < nk) G2_STAGE(kt + 2);
;     const char* cS = smem + (kt % 3) * 24576;
;     bf16x8 xa[8], wb[4];
; #pragma unroll
;     for (int f = 0; f < 8; f++) xa[f] = *(const bf16x8*)(cS + aoff + f * 1024);
; #pragma unroll
;     for (int f = 0; f < 4; f++) wb[f] = *(const bf16x8*)(cS + boff + f * 1024);
; #pragma unroll
;     for (int nf = 0; nf < 4; nf++)
; #pragma unroll
;       for (int mf = 0; mf < 8; mf++)
;         acc[nf][mf] = __builtin_amdgcn_mfma_f32_16x16x32_bf16(wb[nf], xa[mf], acc[nf][mf], 0, 0, 0);
	s_setprio 1
	v_add_u32_e32 v144, s40, v136
	v_mfma_f32_16x16x32_bf16 v[126:129], v[232:235], v[200:203], v[126:129]
	ds_read_b128 v[146:149], v144 offset:0
	v_mfma_f32_16x16x32_bf16 v[122:125], v[232:235], v[204:207], v[122:125]
	ds_read_b128 v[152:155], v144 offset:1024
	v_mfma_f32_16x16x32_bf16 v[118:121], v[232:235], v[208:211], v[118:121]
	ds_read_b128 v[156:159], v144 offset:2048
	v_mfma_f32_16x16x32_bf16 v[114:117], v[232:235], v[212:215], v[114:117]
	ds_read_b128 v[162:165], v144 offset:3072
	v_mfma_f32_16x16x32_bf16 v[110:113], v[232:235], v[216:219], v[110:113]
	ds_read_b128 v[166:169], v144 offset:4096
	v_mfma_f32_16x16x32_bf16 v[106:109], v[232:235], v[220:223], v[106:109]
	ds_read_b128 v[170:173], v144 offset:5120
	v_mfma_f32_16x16x32_bf16 v[102:105], v[232:235], v[224:227], v[102:105]
	ds_read_b128 v[176:179], v144 offset:6144
	v_mfma_f32_16x16x32_bf16 v[98:101], v[232:235], v[228:231], v[98:101]
	ds_read_b128 v[180:183], v144 offset:7168
	v_mfma_f32_16x16x32_bf16 v[94:97], v[236:239], v[200:203], v[94:97]
	v_add_u32_e32 v144, s40, v137
	v_mfma_f32_16x16x32_bf16 v[90:93], v[236:239], v[204:207], v[90:93]
	v_mfma_f32_16x16x32_bf16 v[86:89], v[236:239], v[208:211], v[86:89]
	ds_read_b128 v[184:187], v144 offset:16384
	v_mfma_f32_16x16x32_bf16 v[82:85], v[236:239], v[212:215], v[82:85]
	ds_read_b128 v[188:191], v144 offset:17408
	v_mfma_f32_16x16x32_bf16 v[78:81], v[236:239], v[216:219], v[78:81]
	ds_read_b128 v[192:195], v144 offset:18432
	v_mfma_f32_16x16x32_bf16 v[74:77], v[236:239], v[220:223], v[74:77]
	ds_read_b128 v[196:199], v144 offset:19456
	s_add_i32 s42, s46, s41
	v_mfma_f32_16x16x32_bf16 v[70:73], v[236:239], v[224:227], v[70:73]
	s_mov_b32 m0, s42
	v_lshl_add_u64 v[142:143], v[132:133], 0, s[2:3]
	v_mfma_f32_16x16x32_bf16 v[66:69], v[236:239], v[228:231], v[66:69]
	global_load_lds_dwordx4 v[132:133], off
	s_addk_i32 m0, 0x1000
	v_mfma_f32_16x16x32_bf16 v[62:65], v[240:243], v[200:203], v[62:65]
	v_mfma_f32_16x16x32_bf16 v[58:61], v[240:243], v[204:207], v[58:61]
	v_mfma_f32_16x16x32_bf16 v[54:57], v[240:243], v[208:211], v[54:57]
	global_load_lds_dwordx4 v[142:143], off
	v_lshl_add_u64 v[142:143], v[142:143], 0, s[2:3]
	s_addk_i32 m0, 0x1000
	v_mfma_f32_16x16x32_bf16 v[50:53], v[240:243], v[212:215], v[50:53]
	v_mfma_f32_16x16x32_bf16 v[46:49], v[240:243], v[216:219], v[46:49]
	v_mfma_f32_16x16x32_bf16 v[42:45], v[240:243], v[220:223], v[42:45]
	global_load_lds_dwordx4 v[142:143], off
	v_lshl_add_u64 v[142:143], v[142:143], 0, s[2:3]
	s_addk_i32 m0, 0x1000
	v_mfma_f32_16x16x32_bf16 v[38:41], v[240:243], v[224:227], v[38:41]
	v_mfma_f32_16x16x32_bf16 v[34:37], v[240:243], v[228:231], v[34:37]
	v_mfma_f32_16x16x32_bf16 v[30:33], v[244:247], v[200:203], v[30:33]
	global_load_lds_dwordx4 v[142:143], off
	s_addk_i32 m0, 0x1000
	v_lshl_add_u64 v[142:143], v[134:135], 0, s[2:3]
	v_mfma_f32_16x16x32_bf16 v[26:29], v[244:247], v[204:207], v[26:29]
	v_mfma_f32_16x16x32_bf16 v[22:25], v[244:247], v[208:211], v[22:25]
	v_mfma_f32_16x16x32_bf16 v[18:21], v[244:247], v[212:215], v[18:21]
	global_load_lds_dwordx4 v[134:135], off
	s_addk_i32 m0, 0x1000
	v_lshl_add_u64 v[132:133], v[132:133], 0, s[12:13]
	v_mfma_f32_16x16x32_bf16 v[14:17], v[244:247], v[216:219], v[14:17]
	v_mfma_f32_16x16x32_bf16 v[10:13], v[244:247], v[220:223], v[10:13]
	v_mfma_f32_16x16x32_bf16 v[6:9], v[244:247], v[224:227], v[6:9]
	global_load_lds_dwordx4 v[142:143], off
	v_lshl_add_u64 v[134:135], v[134:135], 0, s[4:5]
	v_mfma_f32_16x16x32_bf16 v[2:5], v[244:247], v[228:231], v[2:5]
	s_setprio 0
	s_mov_b32 s41, s40
	s_add_i32 s40, s40, 0x6000
	s_cmp_eq_u32 s40, 0x12000
	s_cselect_b32 s40, 0, s40
	s_sub_i32 s39, s39, 1
	s_cmp_lg_u32 s39, 0
	s_cbranch_scc1 .Lt11_loop
	s_waitcnt vmcnt(6) lgkmcnt(0)
	s_barrier
	s_setprio 1
	v_add_u32_e32 v144, s40, v136
	v_mfma_f32_16x16x32_bf16 v[126:129], v[184:187], v[146:149], v[126:129]
	ds_read_b128 v[200:203], v144 offset:0
	v_mfma_f32_16x16x32_bf16 v[122:125], v[184:187], v[152:155], v[122:125]
	ds_read_b128 v[204:207], v144 offset:1024
	v_mfma_f32_16x16x32_bf16 v[118:121], v[184:187], v[156:159], v[118:121]
	ds_read_b128 v[208:211], v144 offset:2048
	v_mfma_f32_16x16x32_bf16 v[114:117], v[184:187], v[162:165], v[114:117]
	ds_read_b128 v[212:215], v144 offset:3072
	v_mfma_f32_16x16x32_bf16 v[110:113], v[184:187], v[166:169], v[110:113]
	ds_read_b128 v[216:219], v144 offset:4096
	v_mfma_f32_16x16x32_bf16 v[106:109], v[184:187], v[170:173], v[106:109]
	ds_read_b128 v[220:223], v144 offset:5120
	v_mfma_f32_16x16x32_bf16 v[102:105], v[184:187], v[176:179], v[102:105]
	ds_read_b128 v[224:227], v144 offset:6144
	v_mfma_f32_16x16x32_bf16 v[98:101], v[184:187], v[180:183], v[98:101]
	ds_read_b128 v[228:231], v144 offset:7168
	v_mfma_f32_16x16x32_bf16 v[94:97], v[188:191], v[146:149], v[94:97]
	v_add_u32_e32 v144, s40, v137
	v_mfma_f32_16x16x32_bf16 v[90:93], v[188:191], v[152:155], v[90:93]
	v_mfma_f32_16x16x32_bf16 v[86:89], v[188:191], v[156:159], v[86:89]
	ds_read_b128 v[232:235], v144 offset:16384
	v_mfma_f32_16x16x32_bf16 v[82:85], v[188:191], v[162:165], v[82:85]
	ds_read_b128 v[236:239], v144 offset:17408
	v_mfma_f32_16x16x32_bf16 v[78:81], v[188:191], v[166:169], v[78:81]
	ds_read_b128 v[240:243], v144 offset:18432
	v_mfma_f32_16x16x32_bf16 v[74:77], v[188:191], v[170:173], v[74:77]
	ds_read_b128 v[244:247], v144 offset:19456
	s_add_i32 s42, s46, s41
	v_mfma_f32_16x16x32_bf16 v[70:73], v[188:191], v[176:179], v[70:73]
	s_mov_b32 m0, s42
	v_lshl_add_u64 v[142:143], v[132:133], 0, s[2:3]
	v_mfma_f32_16x16x32_bf16 v[66:69], v[188:191], v[180:183], v[66:69]
	global_load_lds_dwordx4 v[132:133], off
	s_addk_i32 m0, 0x1000
;     ...
;   for (int kt = 0; kt < nk; kt++) {
;     if (kt + 1 < nk) asm volatile("s_waitcnt vmcnt(6)" ::: "memory");
;     else asm volatile("s_waitcnt vmcnt(0)" ::: "memory");
;     __builtin_amdgcn_s_barrier();
;     asm volatile("" ::: "memory");
;     if (kt + 2 < nk) G2_STAGE(kt + 2);
;     const char* cS = smem + (kt % 3) * 24576;
;     bf16x8 xa[8], wb[4];
; #pragma unroll
;     for (int f = 0; f < 8; f++) xa[f] = *(const bf16x8*)(cS + aoff + f * 1024);
; #pragma unroll
;     for (int f = 0; f < 4; f++) wb[f] = *(const bf16x8*)(cS + boff + f * 1024);
; #pragma unroll
;     for (int nf = 0; nf < 4; nf++)
; #pragma unroll
;       for (int mf = 0; mf < 8; mf++)
;         acc[nf][mf] = __builtin_amdgcn_mfma_f32_16x16x32_bf16(wb[nf], xa[mf], acc[nf][mf], 0, 0, 0);
	v_mfma_f32_16x16x32_bf16 v[62:65], v[192:195], v[146:149], v[62:65]
	v_mfma_f32_16x16x32_bf16 v[58:61], v[192:195], v[152:155], v[58:61]
	v_mfma_f32_16x16x32_bf16 v[54:57], v[192:195], v[156:159], v[54:57]
	global_load_lds_dwordx4 v[142:143], off
	v_lshl_add_u64 v[142:143], v[142:143], 0, s[2:3]
	s_addk_i32 m0, 0x1000
	v_mfma_f32_16x16x32_bf16 v[50:53], v[192:195], v[162:165], v[50:53]
	v_mfma_f32_16x16x32_bf16 v[46:49], v[192:195], v[166:169], v[46:49]
	v_mfma_f32_16x16x32_bf16 v[42:45], v[192:195], v[170:173], v[42:45]
	global_load_lds_dwordx4 v[142:143], off
	v_lshl_add_u64 v[142:143], v[142:143], 0, s[2:3]
	s_addk_i32 m0, 0x1000
	v_mfma_f32_16x16x32_bf16 v[38:41], v[192:195], v[176:179], v[38:41]
	v_mfma_f32_16x16x32_bf16 v[34:37], v[192:195], v[180:183], v[34:37]
	v_mfma_f32_16x16x32_bf16 v[30:33], v[196:199], v[146:149], v[30:33]
	global_load_lds_dwordx4 v[142:143], off
	s_addk_i32 m0, 0x1000
	v_lshl_add_u64 v[142:143], v[134:135], 0, s[2:3]
	v_mfma_f32_16x16x32_bf16 v[26:29], v[196:199], v[152:155], v[26:29]
	v_mfma_f32_16x16x32_bf16 v[22:25], v[196:199], v[156:159], v[22:25]
	v_mfma_f32_16x16x32_bf16 v[18:21], v[196:199], v[162:165], v[18:21]
	global_load_lds_dwordx4 v[134:135], off
	s_addk_i32 m0, 0x1000
	v_lshl_add_u64 v[132:133], v[132:133], 0, s[12:13]
	v_mfma_f32_16x16x32_bf16 v[14:17], v[196:199], v[166:169], v[14:17]
	v_mfma_f32_16x16x32_bf16 v[10:13], v[196:199], v[170:173], v[10:13]
	v_mfma_f32_16x16x32_bf16 v[6:9], v[196:199], v[176:179], v[6:9]
	global_load_lds_dwordx4 v[142:143], off
	v_lshl_add_u64 v[134:135], v[134:135], 0, s[4:5]
	v_mfma_f32_16x16x32_bf16 v[2:5], v[196:199], v[180:183], v[2:5]
	s_setprio 0
	s_mov_b32 s41, s40
	s_add_i32 s40, s40, 0x6000
	s_cmp_eq_u32 s40, 0x12000
	s_cselect_b32 s40, 0, s40
	s_waitcnt vmcnt(6) lgkmcnt(0)
	s_barrier
	s_setprio 1
	v_add_u32_e32 v144, s40, v136
	v_mfma_f32_16x16x32_bf16 v[126:129], v[232:235], v[200:203], v[126:129]
	ds_read_b128 v[146:149], v144 offset:0
	v_mfma_f32_16x16x32_bf16 v[122:125], v[232:235], v[204:207], v[122:125]
	ds_read_b128 v[152:155], v144 offset:1024
	v_mfma_f32_16x16x32_bf16 v[118:121], v[232:235], v[208:211], v[118:121]
	ds_read_b128 v[156:159], v144 offset:2048
	v_mfma_f32_16x16x32_bf16 v[114:117], v[232:235], v[212:215], v[114:117]
	ds_read_b128 v[162:165], v144 offset:3072
	v_mfma_f32_16x16x32_bf16 v[110:113], v[232:235], v[216:219], v[110:113]
	ds_read_b128 v[166:169], v144 offset:4096
	v_mfma_f32_16x16x32_bf16 v[106:109], v[232:235], v[220:223], v[106:109]
	ds_read_b128 v[170:173], v144 offset:5120
	v_mfma_f32_16x16x32_bf16 v[102:105], v[232:235], v[224:227], v[102:105]
	ds_read_b128 v[176:179], v144 offset:6144
	v_mfma_f32_16x16x32_bf16 v[98:101], v[232:235], v[228:231], v[98:101]
	ds_read_b128 v[180:183], v144 offset:7168
	v_mfma_f32_16x16x32_bf16 v[94:97], v[236:239], v[200:203], v[94:97]
	v_add_u32_e32 v144, s40, v137
	v_mfma_f32_16x16x32_bf16 v[90:93], v[236:239], v[204:207], v[90:93]
	v_mfma_f32_16x16x32_bf16 v[86:89], v[236:239], v[208:211], v[86:89]
	ds_read_b128 v[184:187], v144 offset:16384
	v_mfma_f32_16x16x32_bf16 v[82:85], v[236:239], v[212:215], v[82:85]
	ds_read_b128 v[188:191], v144 offset:17408
	v_mfma_f32_16x16x32_bf16 v[78:81], v[236:239], v[216:219], v[78:81]
	ds_read_b128 v[192:195], v144 offset:18432
	v_mfma_f32_16x16x32_bf16 v[74:77], v[236:239], v[220:223], v[74:77]
	ds_read_b128 v[196:199], v144 offset:19456
	v_mfma_f32_16x16x32_bf16 v[70:73], v[236:239], v[224:227], v[70:73]
	v_mfma_f32_16x16x32_bf16 v[66:69], v[236:239], v[228:231], v[66:69]
	v_mfma_f32_16x16x32_bf16 v[62:65], v[240:243], v[200:203], v[62:65]
	v_mfma_f32_16x16x32_bf16 v[58:61], v[240:243], v[204:207], v[58:61]
	v_mfma_f32_16x16x32_bf16 v[54:57], v[240:243], v[208:211], v[54:57]
	v_mfma_f32_16x16x32_bf16 v[50:53], v[240:243], v[212:215], v[50:53]
	v_mfma_f32_16x16x32_bf16 v[46:49], v[240:243], v[216:219], v[46:49]
	v_mfma_f32_16x16x32_bf16 v[42:45], v[240:243], v[220:223], v[42:45]
	v_mfma_f32_16x16x32_bf16 v[38:41], v[240:243], v[224:227], v[38:41]
	v_mfma_f32_16x16x32_bf16 v[34:37], v[240:243], v[228:231], v[34:37]
	v_mfma_f32_16x16x32_bf16 v[30:33], v[244:247], v[200:203], v[30:33]
	v_mfma_f32_16x16x32_bf16 v[26:29], v[244:247], v[204:207], v[26:29]
	v_mfma_f32_16x16x32_bf16 v[22:25], v[244:247], v[208:211], v[22:25]
	v_mfma_f32_16x16x32_bf16 v[18:21], v[244:247], v[212:215], v[18:21]
	v_mfma_f32_16x16x32_bf16 v[14:17], v[244:247], v[216:219], v[14:17]
	v_mfma_f32_16x16x32_bf16 v[10:13], v[244:247], v[220:223], v[10:13]
	v_mfma_f32_16x16x32_bf16 v[6:9], v[244:247], v[224:227], v[6:9]
	v_mfma_f32_16x16x32_bf16 v[2:5], v[244:247], v[228:231], v[2:5]
	s_setprio 0
	s_mov_b32 s41, s40
	s_add_i32 s40, s40, 0x6000
	s_cmp_eq_u32 s40, 0x12000
	s_cselect_b32 s40, 0, s40
	s_waitcnt vmcnt(0) lgkmcnt(0)
	s_barrier
; DEVI float blo(unsigned u) { return __uint_as_float(u << 16); }
; DEVI float bhi(unsigned u) { return __uint_as_float(u & 0xffff0000u); }
;     ...
;   for (int kt = 0; kt < nk; kt++) {
;     if (kt + 1 < nk) asm volatile("s_waitcnt vmcnt(6)" ::: "memory");
;     else asm volatile("s_waitcnt vmcnt(0)" ::: "memory");
;     __builtin_amdgcn_s_barrier();
;     asm volatile("" ::: "memory");
;     if (kt + 2 < nk) G2_STAGE(kt + 2);
;     const char* cS = smem + (kt % 3) * 24576;
;     bf16x8 xa[8], wb[4];
; #pragma unroll
;     for (int f = 0; f < 8; f++) xa[f] = *(const bf16x8*)(cS + aoff + f * 1024);
; #pragma unroll
;     for (int f = 0; f < 4; f++) wb[f] = *(const bf16x8*)(cS + boff + f * 1024);
; #pragma unroll
;     for (int nf = 0; nf < 4; nf++)
; #pragma unroll
;       for (int mf = 0; mf < 8; mf++)
;         acc[nf][mf] = __builtin_amdgcn_mfma_f32_16x16x32_bf16(wb[nf], xa[mf], acc[nf][mf], 0, 0, 0);
;     ...
;         if (EPI == EPI_RESID || EPI == EPI_RESID_ATOMIC) {
;           f32x4 x = a;
;           if (EPI == EPI_RESID || kpart == 0) {
;             const u32x2 xr = *(const u32x2*)((const u16*)(p.ws + WS_XB) + (size_t)row * 1024 + col);
;             x[0] += ALPHA * blo(xr[0]); x[1] += ALPHA * bhi(xr[0]); x[2] += ALPHA * blo(xr[1]); x[3] += ALPHA * bhi(xr[1]);
;           }
;           if (EPI == EPI_RESID) *(f32x4*)((float*)(p.ws + WS_XF) + (size_t)row * 1024 + col) = x;
	s_setprio 1
	v_add_u32_e32 v144, s40, v136
	v_mfma_f32_16x16x32_bf16 v[126:129], v[184:187], v[146:149], v[126:129]
	ds_read_b128 v[200:203], v144 offset:0
	v_mfma_f32_16x16x32_bf16 v[122:125], v[184:187], v[152:155], v[122:125]
	ds_read_b128 v[204:207], v144 offset:1024
	v_mfma_f32_16x16x32_bf16 v[118:121], v[184:187], v[156:159], v[118:121]
	ds_read_b128 v[208:211], v144 offset:2048
	v_mfma_f32_16x16x32_bf16 v[114:117], v[184:187], v[162:165], v[114:117]
	ds_read_b128 v[212:215], v144 offset:3072
	v_mfma_f32_16x16x32_bf16 v[110:113], v[184:187], v[166:169], v[110:113]
	ds_read_b128 v[216:219], v144 offset:4096
	v_mfma_f32_16x16x32_bf16 v[106:109], v[184:187], v[170:173], v[106:109]
	ds_read_b128 v[220:223], v144 offset:5120
	v_mfma_f32_16x16x32_bf16 v[102:105], v[184:187], v[176:179], v[102:105]
	ds_read_b128 v[224:227], v144 offset:6144
	v_mfma_f32_16x16x32_bf16 v[98:101], v[184:187], v[180:183], v[98:101]
	ds_read_b128 v[228:231], v144 offset:7168
	v_mfma_f32_16x16x32_bf16 v[94:97], v[188:191], v[146:149], v[94:97]
	v_add_u32_e32 v144, s40, v137
	v_mfma_f32_16x16x32_bf16 v[90:93], v[188:191], v[152:155], v[90:93]
	v_mfma_f32_16x16x32_bf16 v[86:89], v[188:191], v[156:159], v[86:89]
	ds_read_b128 v[232:235], v144 offset:16384
	v_mfma_f32_16x16x32_bf16 v[82:85], v[188:191], v[162:165], v[82:85]
	ds_read_b128 v[236:239], v144 offset:17408
	v_mfma_f32_16x16x32_bf16 v[78:81], v[188:191], v[166:169], v[78:81]
	ds_read_b128 v[240:243], v144 offset:18432
	v_mfma_f32_16x16x32_bf16 v[74:77], v[188:191], v[170:173], v[74:77]
	ds_read_b128 v[244:247], v144 offset:19456
	v_mfma_f32_16x16x32_bf16 v[70:73], v[188:191], v[176:179], v[70:73]
	v_mfma_f32_16x16x32_bf16 v[66:69], v[188:191], v[180:183], v[66:69]
	v_mfma_f32_16x16x32_bf16 v[62:65], v[192:195], v[146:149], v[62:65]
	v_mfma_f32_16x16x32_bf16 v[58:61], v[192:195], v[152:155], v[58:61]
	v_mfma_f32_16x16x32_bf16 v[54:57], v[192:195], v[156:159], v[54:57]
	v_mfma_f32_16x16x32_bf16 v[50:53], v[192:195], v[162:165], v[50:53]
	v_mfma_f32_16x16x32_bf16 v[46:49], v[192:195], v[166:169], v[46:49]
	v_mfma_f32_16x16x32_bf16 v[42:45], v[192:195], v[170:173], v[42:45]
	v_mfma_f32_16x16x32_bf16 v[38:41], v[192:195], v[176:179], v[38:41]
	v_mfma_f32_16x16x32_bf16 v[34:37], v[192:195], v[180:183], v[34:37]
	v_mfma_f32_16x16x32_bf16 v[30:33], v[196:199], v[146:149], v[30:33]
	v_mfma_f32_16x16x32_bf16 v[26:29], v[196:199], v[152:155], v[26:29]
	v_mfma_f32_16x16x32_bf16 v[22:25], v[196:199], v[156:159], v[22:25]
	v_mfma_f32_16x16x32_bf16 v[18:21], v[196:199], v[162:165], v[18:21]
	v_mfma_f32_16x16x32_bf16 v[14:17], v[196:199], v[166:169], v[14:17]
	v_mfma_f32_16x16x32_bf16 v[10:13], v[196:199], v[170:173], v[10:13]
	v_mfma_f32_16x16x32_bf16 v[6:9], v[196:199], v[176:179], v[6:9]
	v_mfma_f32_16x16x32_bf16 v[2:5], v[196:199], v[180:183], v[2:5]
	s_setprio 0
	s_mov_b32 s41, s40
	s_add_i32 s40, s40, 0x6000
	s_cmp_eq_u32 s40, 0x12000
	s_cselect_b32 s40, 0, s40
	s_mov_b32 s4, 0x8000
	s_mov_b32 s5, 0
	s_mov_b32 s10, 0x10000
	s_mov_b32 s11, 0
	s_mov_b32 s44, 0x3fd744fd
	s_waitcnt lgkmcnt(0)
	v_mfma_f32_16x16x32_bf16 v[126:129], v[232:235], v[200:203], v[126:129]
	v_mfma_f32_16x16x32_bf16 v[122:125], v[232:235], v[204:207], v[122:125]
	v_mfma_f32_16x16x32_bf16 v[118:121], v[232:235], v[208:211], v[118:121]
	v_mfma_f32_16x16x32_bf16 v[114:117], v[232:235], v[212:215], v[114:117]
	v_mfma_f32_16x16x32_bf16 v[110:113], v[232:235], v[216:219], v[110:113]
	global_load_dwordx4 v[146:149], v[138:139], off offset:0
	v_mfma_f32_16x16x32_bf16 v[106:109], v[232:235], v[220:223], v[106:109]
	v_mfma_f32_16x16x32_bf16 v[102:105], v[232:235], v[224:227], v[102:105]
	global_load_dwordx4 v[152:155], v[138:139], off offset:128
	v_mfma_f32_16x16x32_bf16 v[98:101], v[232:235], v[228:231], v[98:101]
	v_lshl_add_u64 v[138:139], v[138:139], 0, s[4:5]
	v_mfma_f32_16x16x32_bf16 v[94:97], v[236:239], v[200:203], v[94:97]
	global_load_dwordx4 v[156:159], v[138:139], off offset:0
	v_mfma_f32_16x16x32_bf16 v[90:93], v[236:239], v[204:207], v[90:93]
	v_mfma_f32_16x16x32_bf16 v[86:89], v[236:239], v[208:211], v[86:89]
	global_load_dwordx4 v[162:165], v[138:139], off offset:128
	v_mfma_f32_16x16x32_bf16 v[82:85], v[236:239], v[212:215], v[82:85]
	v_lshl_add_u64 v[138:139], v[138:139], 0, s[4:5]
	v_mfma_f32_16x16x32_bf16 v[78:81], v[236:239], v[216:219], v[78:81]
	global_load_dwordx4 v[166:169], v[138:139], off offset:0
	v_mfma_f32_16x16x32_bf16 v[74:77], v[236:239], v[220:223], v[74:77]
	v_mfma_f32_16x16x32_bf16 v[70:73], v[236:239], v[224:227], v[70:73]
	global_load_dwordx4 v[170:173], v[138:139], off offset:128
	v_mfma_f32_16x16x32_bf16 v[66:69], v[236:239], v[228:231], v[66:69]
	v_lshl_add_u64 v[138:139], v[138:139], 0, s[4:5]
	v_mfma_f32_16x16x32_bf16 v[62:65], v[240:243], v[200:203], v[62:65]
	global_load_dwordx4 v[176:179], v[138:139], off offset:0
	v_mfma_f32_16x16x32_bf16 v[58:61], v[240:243], v[204:207], v[58:61]
	v_mfma_f32_16x16x32_bf16 v[54:57], v[240:243], v[208:211], v[54:57]
	global_load_dwordx4 v[180:183], v[138:139], off offset:128
	v_mfma_f32_16x16x32_bf16 v[50:53], v[240:243], v[212:215], v[50:53]
	v_lshl_add_u64 v[138:139], v[138:139], 0, s[4:5]
	v_mfma_f32_16x16x32_bf16 v[46:49], v[240:243], v[216:219], v[46:49]
	global_load_dwordx4 v[184:187], v[138:139], off offset:0
	v_mfma_f32_16x16x32_bf16 v[42:45], v[240:243], v[220:223], v[42:45]
	v_mfma_f32_16x16x32_bf16 v[38:41], v[240:243], v[224:227], v[38:41]
	global_load_dwordx4 v[188:191], v[138:139], off offset:128
	v_mfma_f32_16x16x32_bf16 v[34:37], v[240:243], v[228:231], v[34:37]
	v_lshl_add_u64 v[138:139], v[138:139], 0, s[4:5]
	v_mfma_f32_16x16x32_bf16 v[30:33], v[244:247], v[200:203], v[30:33]
	global_load_dwordx4 v[192:195], v[138:139], off offset:0
	v_mfma_f32_16x16x32_bf16 v[26:29], v[244:247], v[204:207], v[26:29]
	v_mfma_f32_16x16x32_bf16 v[22:25], v[244:247], v[208:211], v[22:25]
	global_load_dwordx4 v[196:199], v[138:139], off offset:128
	v_mfma_f32_16x16x32_bf16 v[18:21], v[244:247], v[212:215], v[18:21]
	v_lshl_add_u64 v[138:139], v[138:139], 0, s[4:5]
	v_mfma_f32_16x16x32_bf16 v[14:17], v[244:247], v[216:219], v[14:17]
	v_mfma_f32_16x16x32_bf16 v[10:13], v[244:247], v[220:223], v[10:13]
	v_mfma_f32_16x16x32_bf16 v[6:9], v[244:247], v[224:227], v[6:9]
	v_mfma_f32_16x16x32_bf16 v[2:5], v[244:247], v[228:231], v[2:5]
	s_mov_b32 m0, s43
	global_load_dwordx4 v[200:203], v[138:139], off offset:0
	global_load_dwordx4 v[204:207], v[138:139], off offset:128
	v_lshl_add_u64 v[138:139], v[138:139], 0, s[4:5]
	global_load_dwordx4 v[208:211], v[138:139], off offset:0
	global_load_dwordx4 v[212:215], v[138:139], off offset:128
	v_lshl_add_u64 v[138:139], v[138:139], 0, s[4:5]
	s_nop 7
	s_waitcnt vmcnt(15)
; DEVI float blo(unsigned u) { return __uint_as_float(u << 16); }
; DEVI float bhi(unsigned u) { return __uint_as_float(u & 0xffff0000u); }
;     ...
;         if (EPI == EPI_RESID || EPI == EPI_RESID_ATOMIC) {
;           f32x4 x = a;
;           if (EPI == EPI_RESID || kpart == 0) {
;             const u32x2 xr = *(const u32x2*)((const u16*)(p.ws + WS_XB) + (size_t)row * 1024 + col);
;             x[0] += ALPHA * blo(xr[0]); x[1] += ALPHA * bhi(xr[0]); x[2] += ALPHA * blo(xr[1]); x[3] += ALPHA * bhi(xr[1]);
;           }
;           if (EPI == EPI_RESID) *(f32x4*)((float*)(p.ws + WS_XF) + (size_t)row * 1024 + col) = x;
	v_permlane16_swap_b32_e32 v146, v148
	v_permlane16_swap_b32_e32 v147, v149
	v_lshlrev_b32_e32 v216, 16, v146
	v_and_b32_e32 v146, 0xffff0000, v146
	v_lshlrev_b32_e32 v217, 16, v147
	v_and_b32_e32 v147, 0xffff0000, v147
	v_fmac_f32_e32 v126, s44, v216
	v_fmac_f32_e32 v127, s44, v146
	v_fmac_f32_e32 v128, s44, v217
	v_fmac_f32_e32 v129, s44, v147
	global_store_dwordx4 v[140:141], v[126:129], off offset:0
	v_lshlrev_b32_e32 v216, 16, v148
	v_and_b32_e32 v148, 0xffff0000, v148
	v_lshlrev_b32_e32 v217, 16, v149
	v_and_b32_e32 v149, 0xffff0000, v149
	v_fmac_f32_e32 v94, s44, v216
	v_fmac_f32_e32 v95, s44, v148
	v_fmac_f32_e32 v96, s44, v217
	v_fmac_f32_e32 v97, s44, v149
	global_store_dwordx4 v[140:141], v[94:97], off offset:64
	s_waitcnt vmcnt(16)
	v_permlane16_swap_b32_e32 v152, v154
	v_permlane16_swap_b32_e32 v153, v155
	v_lshlrev_b32_e32 v216, 16, v152
	v_and_b32_e32 v152, 0xffff0000, v152
	v_lshlrev_b32_e32 v217, 16, v153
	v_and_b32_e32 v153, 0xffff0000, v153
	v_fmac_f32_e32 v62, s44, v216
	v_fmac_f32_e32 v63, s44, v152
	v_fmac_f32_e32 v64, s44, v217
	v_fmac_f32_e32 v65, s44, v153
	global_store_dwordx4 v[140:141], v[62:65], off offset:128
	v_lshlrev_b32_e32 v216, 16, v154
	v_and_b32_e32 v154, 0xffff0000, v154
	v_lshlrev_b32_e32 v217, 16, v155
	v_and_b32_e32 v155, 0xffff0000, v155
	v_fmac_f32_e32 v30, s44, v216
	v_fmac_f32_e32 v31, s44, v154
	v_fmac_f32_e32 v32, s44, v217
	v_fmac_f32_e32 v33, s44, v155
	global_store_dwordx4 v[140:141], v[30:33], off offset:192
	v_lshl_add_u64 v[140:141], v[140:141], 0, s[10:11]
	s_waitcnt vmcnt(17)
	v_permlane16_swap_b32_e32 v156, v158
	v_permlane16_swap_b32_e32 v157, v159
	v_lshlrev_b32_e32 v216, 16, v156
	v_and_b32_e32 v156, 0xffff0000, v156
	v_lshlrev_b32_e32 v217, 16, v157
	v_and_b32_e32 v157, 0xffff0000, v157
	v_fmac_f32_e32 v122, s44, v216
	v_fmac_f32_e32 v123, s44, v156
	v_fmac_f32_e32 v124, s44, v217
	v_fmac_f32_e32 v125, s44, v157
	global_store_dwordx4 v[140:141], v[122:125], off offset:0
	v_lshlrev_b32_e32 v216, 16, v158
	v_and_b32_e32 v158, 0xffff0000, v158
	v_lshlrev_b32_e32 v217, 16, v159
	v_and_b32_e32 v159, 0xffff0000, v159
	v_fmac_f32_e32 v90, s44, v216
	v_fmac_f32_e32 v91, s44, v158
	v_fmac_f32_e32 v92, s44, v217
	v_fmac_f32_e32 v93, s44, v159
	global_store_dwordx4 v[140:141], v[90:93], off offset:64
	s_waitcnt vmcnt(18)
	v_permlane16_swap_b32_e32 v162, v164
	v_permlane16_swap_b32_e32 v163, v165
	v_lshlrev_b32_e32 v216, 16, v162
	v_and_b32_e32 v162, 0xffff0000, v162
	v_lshlrev_b32_e32 v217, 16, v163
	v_and_b32_e32 v163, 0xffff0000, v163
	v_fmac_f32_e32 v58, s44, v216
	v_fmac_f32_e32 v59, s44, v162
	v_fmac_f32_e32 v60, s44, v217
	v_fmac_f32_e32 v61, s44, v163
	global_store_dwordx4 v[140:141], v[58:61], off offset:128
	v_lshlrev_b32_e32 v216, 16, v164
	v_and_b32_e32 v164, 0xffff0000, v164
	v_lshlrev_b32_e32 v217, 16, v165
	v_and_b32_e32 v165, 0xffff0000, v165
	v_fmac_f32_e32 v26, s44, v216
	v_fmac_f32_e32 v27, s44, v164
	v_fmac_f32_e32 v28, s44, v217
	v_fmac_f32_e32 v29, s44, v165
	global_store_dwordx4 v[140:141], v[26:29], off offset:192
	v_lshl_add_u64 v[140:141], v[140:141], 0, s[10:11]
	s_waitcnt vmcnt(19)
	v_permlane16_swap_b32_e32 v166, v168
	v_permlane16_swap_b32_e32 v167, v169
	v_lshlrev_b32_e32 v216, 16, v166
	v_and_b32_e32 v166, 0xffff0000, v166
	v_lshlrev_b32_e32 v217, 16, v167
	v_and_b32_e32 v167, 0xffff0000, v167
	v_fmac_f32_e32 v118, s44, v216
	v_fmac_f32_e32 v119, s44, v166
	v_fmac_f32_e32 v120, s44, v217
	v_fmac_f32_e32 v121, s44, v167
	global_store_dwordx4 v[140:141], v[118:121], off offset:0
	v_lshlrev_b32_e32 v216, 16, v168
	v_and_b32_e32 v168, 0xffff0000, v168
	v_lshlrev_b32_e32 v217, 16, v169
	v_and_b32_e32 v169, 0xffff0000, v169
	v_fmac_f32_e32 v86, s44, v216
	v_fmac_f32_e32 v87, s44, v168
	v_fmac_f32_e32 v88, s44, v217
	v_fmac_f32_e32 v89, s44, v169
	global_store_dwordx4 v[140:141], v[86:89], off offset:64
	s_waitcnt vmcnt(20)
	v_permlane16_swap_b32_e32 v170, v172
	v_permlane16_swap_b32_e32 v171, v173
	v_lshlrev_b32_e32 v216, 16, v170
	v_and_b32_e32 v170, 0xffff0000, v170
	v_lshlrev_b32_e32 v217, 16, v171
	v_and_b32_e32 v171, 0xffff0000, v171
	v_fmac_f32_e32 v54, s44, v216
	v_fmac_f32_e32 v55, s44, v170
	v_fmac_f32_e32 v56, s44, v217
	v_fmac_f32_e32 v57, s44, v171
	global_store_dwordx4 v[140:141], v[54:57], off offset:128
	v_lshlrev_b32_e32 v216, 16, v172
	v_and_b32_e32 v172, 0xffff0000, v172
	v_lshlrev_b32_e32 v217, 16, v173
	v_and_b32_e32 v173, 0xffff0000, v173
	v_fmac_f32_e32 v22, s44, v216
	v_fmac_f32_e32 v23, s44, v172
	v_fmac_f32_e32 v24, s44, v217
	v_fmac_f32_e32 v25, s44, v173
	global_store_dwordx4 v[140:141], v[22:25], off offset:192
	v_lshl_add_u64 v[140:141], v[140:141], 0, s[10:11]
	s_waitcnt vmcnt(21)
	v_permlane16_swap_b32_e32 v176, v178
	v_permlane16_swap_b32_e32 v177, v179
	v_lshlrev_b32_e32 v216, 16, v176
	v_and_b32_e32 v176, 0xffff0000, v176
	v_lshlrev_b32_e32 v217, 16, v177
	v_and_b32_e32 v177, 0xffff0000, v177
	v_fmac_f32_e32 v114, s44, v216
	v_fmac_f32_e32 v115, s44, v176
	v_fmac_f32_e32 v116, s44, v217
	v_fmac_f32_e32 v117, s44, v177
	global_store_dwordx4 v[140:141], v[114:117], off offset:0
	v_lshlrev_b32_e32 v216, 16, v178
	v_and_b32_e32 v178, 0xffff0000, v178
	v_lshlrev_b32_e32 v217, 16, v179
	v_and_b32_e32 v179, 0xffff0000, v179
	v_fmac_f32_e32 v82, s44, v216
	v_fmac_f32_e32 v83, s44, v178
	v_fmac_f32_e32 v84, s44, v217
	v_fmac_f32_e32 v85, s44, v179
	global_store_dwordx4 v[140:141], v[82:85], off offset:64
	s_waitcnt vmcnt(22)
; DEVI float blo(unsigned u) { return __uint_as_float(u << 16); }
; DEVI float bhi(unsigned u) { return __uint_as_float(u & 0xffff0000u); }
; DEVI int xcd_first_tile() { return (blockIdx.x & 7) * (gridDim.x >> 3) + (blockIdx.x >> 3); }
;     ...
;         if (EPI == EPI_RESID || EPI == EPI_RESID_ATOMIC) {
;           f32x4 x = a;
;           if (EPI == EPI_RESID || kpart == 0) {
;             const u32x2 xr = *(const u32x2*)((const u16*)(p.ws + WS_XB) + (size_t)row * 1024 + col);
;             x[0] += ALPHA * blo(xr[0]); x[1] += ALPHA * bhi(xr[0]); x[2] += ALPHA * blo(xr[1]); x[3] += ALPHA * bhi(xr[1]);
;           }
;           if (EPI == EPI_RESID) *(f32x4*)((float*)(p.ws + WS_XF) + (size_t)row * 1024 + col) = x;
; DEVI void run_phase(const Params& p, int ph, char* smem) {
;     ...
;       for (int t = xcd_first_tile(); t < 512 + 16 * 11; t += xcd_tile_step()) {
;         if (t < 512) {
;           int mt_, nt_; tile_coords(t, 64, 8, mt_, nt_);
	v_permlane16_swap_b32_e32 v180, v182
	v_permlane16_swap_b32_e32 v181, v183
	v_lshlrev_b32_e32 v216, 16, v180
	v_and_b32_e32 v180, 0xffff0000, v180
	v_lshlrev_b32_e32 v217, 16, v181
	v_and_b32_e32 v181, 0xffff0000, v181
	v_fmac_f32_e32 v50, s44, v216
	v_fmac_f32_e32 v51, s44, v180
	v_fmac_f32_e32 v52, s44, v217
	v_fmac_f32_e32 v53, s44, v181
	global_store_dwordx4 v[140:141], v[50:53], off offset:128
	v_lshlrev_b32_e32 v216, 16, v182
	v_and_b32_e32 v182, 0xffff0000, v182
	v_lshlrev_b32_e32 v217, 16, v183
	v_and_b32_e32 v183, 0xffff0000, v183
	v_fmac_f32_e32 v18, s44, v216
	v_fmac_f32_e32 v19, s44, v182
	v_fmac_f32_e32 v20, s44, v217
	v_fmac_f32_e32 v21, s44, v183
	global_store_dwordx4 v[140:141], v[18:21], off offset:192
	v_lshl_add_u64 v[140:141], v[140:141], 0, s[10:11]
	s_waitcnt vmcnt(23)
	v_permlane16_swap_b32_e32 v184, v186
	v_permlane16_swap_b32_e32 v185, v187
	v_lshlrev_b32_e32 v216, 16, v184
	v_and_b32_e32 v184, 0xffff0000, v184
	v_lshlrev_b32_e32 v217, 16, v185
	v_and_b32_e32 v185, 0xffff0000, v185
	v_fmac_f32_e32 v110, s44, v216
	v_fmac_f32_e32 v111, s44, v184
	v_fmac_f32_e32 v112, s44, v217
	v_fmac_f32_e32 v113, s44, v185
	global_store_dwordx4 v[140:141], v[110:113], off offset:0
	v_lshlrev_b32_e32 v216, 16, v186
	v_and_b32_e32 v186, 0xffff0000, v186
	v_lshlrev_b32_e32 v217, 16, v187
	v_and_b32_e32 v187, 0xffff0000, v187
	v_fmac_f32_e32 v78, s44, v216
	v_fmac_f32_e32 v79, s44, v186
	v_fmac_f32_e32 v80, s44, v217
	v_fmac_f32_e32 v81, s44, v187
	global_store_dwordx4 v[140:141], v[78:81], off offset:64
	s_waitcnt vmcnt(24)
	v_permlane16_swap_b32_e32 v188, v190
	v_permlane16_swap_b32_e32 v189, v191
	v_lshlrev_b32_e32 v216, 16, v188
	v_and_b32_e32 v188, 0xffff0000, v188
	v_lshlrev_b32_e32 v217, 16, v189
	v_and_b32_e32 v189, 0xffff0000, v189
	v_fmac_f32_e32 v46, s44, v216
	v_fmac_f32_e32 v47, s44, v188
	v_fmac_f32_e32 v48, s44, v217
	v_fmac_f32_e32 v49, s44, v189
	global_store_dwordx4 v[140:141], v[46:49], off offset:128
	v_lshlrev_b32_e32 v216, 16, v190
	v_and_b32_e32 v190, 0xffff0000, v190
	v_lshlrev_b32_e32 v217, 16, v191
	v_and_b32_e32 v191, 0xffff0000, v191
	v_fmac_f32_e32 v14, s44, v216
	v_fmac_f32_e32 v15, s44, v190
	v_fmac_f32_e32 v16, s44, v217
	v_fmac_f32_e32 v17, s44, v191
	global_store_dwordx4 v[140:141], v[14:17], off offset:192
	v_lshl_add_u64 v[140:141], v[140:141], 0, s[10:11]
	s_waitcnt vmcnt(25)
	v_permlane16_swap_b32_e32 v192, v194
	v_permlane16_swap_b32_e32 v193, v195
	v_lshlrev_b32_e32 v216, 16, v192
	v_and_b32_e32 v192, 0xffff0000, v192
	v_lshlrev_b32_e32 v217, 16, v193
	v_and_b32_e32 v193, 0xffff0000, v193
	v_fmac_f32_e32 v106, s44, v216
	v_fmac_f32_e32 v107, s44, v192
	v_fmac_f32_e32 v108, s44, v217
	v_fmac_f32_e32 v109, s44, v193
	global_store_dwordx4 v[140:141], v[106:109], off offset:0
	v_lshlrev_b32_e32 v216, 16, v194
	v_and_b32_e32 v194, 0xffff0000, v194
	v_lshlrev_b32_e32 v217, 16, v195
	v_and_b32_e32 v195, 0xffff0000, v195
	v_fmac_f32_e32 v74, s44, v216
	v_fmac_f32_e32 v75, s44, v194
	v_fmac_f32_e32 v76, s44, v217
	v_fmac_f32_e32 v77, s44, v195
	global_store_dwordx4 v[140:141], v[74:77], off offset:64
	s_waitcnt vmcnt(26)
	v_permlane16_swap_b32_e32 v196, v198
	v_permlane16_swap_b32_e32 v197, v199
	v_lshlrev_b32_e32 v216, 16, v196
	v_and_b32_e32 v196, 0xffff0000, v196
	v_lshlrev_b32_e32 v217, 16, v197
	v_and_b32_e32 v197, 0xffff0000, v197
	v_fmac_f32_e32 v42, s44, v216
	v_fmac_f32_e32 v43, s44, v196
	v_fmac_f32_e32 v44, s44, v217
	v_fmac_f32_e32 v45, s44, v197
	global_store_dwordx4 v[140:141], v[42:45], off offset:128
	v_lshlrev_b32_e32 v216, 16, v198
	v_and_b32_e32 v198, 0xffff0000, v198
	v_lshlrev_b32_e32 v217, 16, v199
	v_and_b32_e32 v199, 0xffff0000, v199
	v_fmac_f32_e32 v10, s44, v216
	v_fmac_f32_e32 v11, s44, v198
	v_fmac_f32_e32 v12, s44, v217
	v_fmac_f32_e32 v13, s44, v199
	global_store_dwordx4 v[140:141], v[10:13], off offset:192
	v_lshl_add_u64 v[140:141], v[140:141], 0, s[10:11]
	s_waitcnt vmcnt(27)
	v_permlane16_swap_b32_e32 v200, v202
	v_permlane16_swap_b32_e32 v201, v203
	v_lshlrev_b32_e32 v216, 16, v200
	v_and_b32_e32 v200, 0xffff0000, v200
	v_lshlrev_b32_e32 v217, 16, v201
	v_and_b32_e32 v201, 0xffff0000, v201
	v_fmac_f32_e32 v102, s44, v216
	v_fmac_f32_e32 v103, s44, v200
	v_fmac_f32_e32 v104, s44, v217
	v_fmac_f32_e32 v105, s44, v201
	global_store_dwordx4 v[140:141], v[102:105], off offset:0
	v_lshlrev_b32_e32 v216, 16, v202
	v_and_b32_e32 v202, 0xffff0000, v202
	v_lshlrev_b32_e32 v217, 16, v203
	v_and_b32_e32 v203, 0xffff0000, v203
	v_fmac_f32_e32 v70, s44, v216
	v_fmac_f32_e32 v71, s44, v202
	v_fmac_f32_e32 v72, s44, v217
	v_fmac_f32_e32 v73, s44, v203
	global_store_dwordx4 v[140:141], v[70:73], off offset:64
	s_waitcnt vmcnt(28)
	v_permlane16_swap_b32_e32 v204, v206
	v_permlane16_swap_b32_e32 v205, v207
	v_lshlrev_b32_e32 v216, 16, v204
	v_and_b32_e32 v204, 0xffff0000, v204
	v_lshlrev_b32_e32 v217, 16, v205
	v_and_b32_e32 v205, 0xffff0000, v205
	v_fmac_f32_e32 v38, s44, v216
	v_fmac_f32_e32 v39, s44, v204
	v_fmac_f32_e32 v40, s44, v217
	v_fmac_f32_e32 v41, s44, v205
	global_store_dwordx4 v[140:141], v[38:41], off offset:128
	v_lshlrev_b32_e32 v216, 16, v206
	v_and_b32_e32 v206, 0xffff0000, v206
	v_lshlrev_b32_e32 v217, 16, v207
	v_and_b32_e32 v207, 0xffff0000, v207
	v_fmac_f32_e32 v6, s44, v216
	v_fmac_f32_e32 v7, s44, v206
	v_fmac_f32_e32 v8, s44, v217
	v_fmac_f32_e32 v9, s44, v207
	global_store_dwordx4 v[140:141], v[6:9], off offset:192
	v_lshl_add_u64 v[140:141], v[140:141], 0, s[10:11]
	s_waitcnt vmcnt(29)
	v_permlane16_swap_b32_e32 v208, v210
	v_permlane16_swap_b32_e32 v209, v211
	v_lshlrev_b32_e32 v216, 16, v208
	v_and_b32_e32 v208, 0xffff0000, v208
	v_lshlrev_b32_e32 v217, 16, v209
	v_and_b32_e32 v209, 0xffff0000, v209
	v_fmac_f32_e32 v98, s44, v216
	v_fmac_f32_e32 v99, s44, v208
	v_fmac_f32_e32 v100, s44, v217
	v_fmac_f32_e32 v101, s44, v209
	global_store_dwordx4 v[140:141], v[98:101], off offset:0
	v_lshlrev_b32_e32 v216, 16, v210
	v_and_b32_e32 v210, 0xffff0000, v210
	v_lshlrev_b32_e32 v217, 16, v211
	v_and_b32_e32 v211, 0xffff0000, v211
	v_fmac_f32_e32 v66, s44, v216
	v_fmac_f32_e32 v67, s44, v210
	v_fmac_f32_e32 v68, s44, v217
	v_fmac_f32_e32 v69, s44, v211
	global_store_dwordx4 v[140:141], v[66:69], off offset:64
	s_waitcnt vmcnt(30)
	v_permlane16_swap_b32_e32 v212, v214
	v_permlane16_swap_b32_e32 v213, v215
	v_lshlrev_b32_e32 v216, 16, v212
	v_and_b32_e32 v212, 0xffff0000, v212
	v_lshlrev_b32_e32 v217, 16, v213
	v_and_b32_e32 v213, 0xffff0000, v213
	v_fmac_f32_e32 v34, s44, v216
	v_fmac_f32_e32 v35, s44, v212
	v_fmac_f32_e32 v36, s44, v217
	v_fmac_f32_e32 v37, s44, v213
	global_store_dwordx4 v[140:141], v[34:37], off offset:128
	v_lshlrev_b32_e32 v216, 16, v214
	v_and_b32_e32 v214, 0xffff0000, v214
	v_lshlrev_b32_e32 v217, 16, v215
	v_and_b32_e32 v215, 0xffff0000, v215
	v_fmac_f32_e32 v2, s44, v216
	v_fmac_f32_e32 v3, s44, v214
	v_fmac_f32_e32 v4, s44, v217
	v_fmac_f32_e32 v5, s44, v215
	global_store_dwordx4 v[140:141], v[2:5], off offset:192
	v_readlane_b32 s39, v250, 7
	s_cmpk_lg_u32 s39, 0x200
	s_cbranch_scc1 .LBB0_41
; DEVI int xcd_first_tile() { return (blockIdx.x & 7) * (gridDim.x >> 3) + (blockIdx.x >> 3); }
; DEVI void run_phase(const Params& p, int ph, char* smem) {
;     ...
;       for (int t = xcd_first_tile(); t < 512 + 16 * 11; t += xcd_tile_step()) {
;         if (t < 512) {
;           int mt_, nt_; tile_coords(t, 64, 8, mt_, nt_);
;           gemm_tile256<EPI_RESID>(p, hb, DFF, Bt, DFF, mt_ * 256, nt_ * 128, nullptr, 0, smem);
;         } else {
;           const int u_ = t - 512, tl_ = u_ / 11, q_ = u_ - tl_ * 11;
;           gemm_tile256<EPI_RESID_ATOMIC>(p, hb, DFF, Bt, DFF, (64 + (tl_ & 1)) * 256, (tl_ >> 1) * 128, nullptr, 0, smem, q_ * 256, 8, q_);
;         }
	v_readlane_b32 s40, v250, 0
	s_lshr_b32 s41, s40, 3
	s_and_b32 s40, s40, 7
	s_mul_i32 s40, s40, 22
	s_add_i32 s40, s40, s41
	s_cmp_lt_u32 s41, 22
	s_cselect_b32 s38, s40, 0x4000
	s_branch .LBB0_41

; #define LAS __attribute__((address_space(3)))
; DEVI int xcd_first_tile() { return (blockIdx.x & 7) * (gridDim.x >> 3) + (blockIdx.x >> 3); }
;     ...
;   const int nk = (nk_part < 0) ? (K >> 5) : nk_part;
;   const int lrow = tid >> 2, lpc = tid & 3;
;   const int lch = lpc ^ ((0x78 >> (((lrow >> 2) & 3) * 2)) & 3);
;   const u16* ga = A + (size_t)(m0 + lrow) * lda + kbeg + lch * 8;
;   const u16* gb = Bt + (size_t)(n0 + lrow) * K + kbeg + lch * 8;
;   const size_t ga1 = (size_t)64 * lda, gb1 = (size_t)64 * K;
;   const unsigned lds0 = (unsigned)(uintptr_t)(LAS char*)smem + (unsigned)__builtin_amdgcn_readfirstlane(wid) * 1024u;
;     ...
;   __syncthreads();
;   G2_STAGE(0); G2_STAGE(1);
;   const int fsw = (0x78 >> (((r16 >> 2) & 3) * 2)) & 3;
;   const int aoff = (wm * 128 + r16) * 64 + ((quad ^ fsw) << 4);
;   const int boff = 16384 + (wn * 64 + r16) * 64 + ((quad ^ fsw) << 4);
; DEVI void run_phase(const Params& p, int ph, char* smem) {
;     ...
;       const u16* Bt = (const u16*)(p.ws + WS_WGU) + (size_t)l * 5632 * 1024;
;       for (int t = xcd_first_tile(); t < 66 * 44; t += xcd_tile_step()) {
;         int mt_, nt_; tile_coords(t, 66, 44, mt_, nt_);
;         gemm_tile256<EPI_SWIGLU>(p, xb, 1024, Bt, 1024, mt_ * 256, nt_ * 128, hb, DFF, smem);
.Lt10_crd:
	s_cmp_lt_u32 s41, 64
	s_cselect_b32 s40, 1, 0
	v_readlane_b32 s2, v250, 5
	v_readlane_b32 s3, v250, 6
	v_readlane_b32 s43, v254, 62
	s_mul_i32 s36, s41, 0x80000
	s_add_u32 s10, s2, s36
	s_addc_u32 s11, s3, 0
	s_add_u32 s10, s10, 0x4200000
	s_addc_u32 s11, s11, 0
	s_mul_i32 s36, s43, 0xb00000
	s_mul_i32 s37, s38, 0x40000
	s_add_i32 s36, s36, s37
	s_add_u32 s12, s2, s36
	s_addc_u32 s13, s3, 0
	s_add_u32 s12, s12, 0x16e00000
	s_addc_u32 s13, s13, 0
	s_movk_i32 s9, 0x78
	v_lshrrev_b32_e32 v0, 2, v145
	v_and_b32_e32 v131, 3, v145
	v_bfe_u32 v136, v145, 4, 2
	v_lshlrev_b32_e32 v136, 1, v136
	v_lshrrev_b32_e64 v136, v136, s9
	v_and_b32_e32 v136, 3, v136
	v_xor_b32_e32 v131, v131, v136
	v_lshlrev_b32_e32 v131, 4, v131
	s_movk_i32 s37, 0x800
	v_mad_u32_u24 v0, v0, s37, v131
	v_bfe_u32 v137, v145, 2, 1
	s_movk_i32 s37, 0x7c0
	v_mul_u32_u24_e32 v136, s37, v137
	v_sub_u32_e32 v136, v0, v136
	v_mov_b32_e32 v137, 0
	v_lshl_add_u64 v[134:135], s[12:13], 0, v[136:137]
	v_bfe_u32 v137, v145, 2, 1
	s_mul_i32 s37, s40, 0x7c0
	v_mul_u32_u24_e32 v136, s37, v137
	v_sub_u32_e32 v0, v0, v136
	s_lshl_b32 s14, s40, 6
	s_add_i32 s14, s14, 64
	s_mov_b32 s15, 0
	v_lshl_add_u64 v[132:133], s[10:11], 0, v[0:1]
	v_bfe_u32 v136, v145, 2, 2
	v_lshlrev_b32_e32 v136, 1, v136
	v_lshrrev_b32_e64 v136, v136, s9
	v_and_b32_e32 v136, 3, v136
	v_bfe_u32 v137, v145, 4, 2
	v_xor_b32_e32 v136, v136, v137
	v_lshlrev_b32_e32 v136, 4, v136
	v_and_b32_e32 v131, 15, v145
	v_lshl_or_b32 v136, v131, 6, v136
	v_bfe_u32 v137, v145, 6, 1
	v_lshl_or_b32 v137, v137, 12, v136
	v_lshrrev_b32_e32 v0, 7, v145
	v_lshl_or_b32 v136, v0, 13, v136
	v_and_b32_e32 v140, 1, v131
	v_lshl_or_b32 v131, v0, 7, v131
	v_bfe_u32 v0, v145, 4, 1
	v_lshlrev_b32_e32 v0, 5, v0
	v_bfe_u32 v141, v145, 5, 1
	v_lshl_or_b32 v0, v141, 4, v0
	v_bfe_u32 v141, v145, 6, 1
	s_mul_i32 s36, s41, 0x160000
	s_lshl_b32 s37, s38, 7
	s_lshl_b32 s37, s37, s40
	s_add_i32 s36, s36, s37
	s_add_u32 s12, s2, s36
	s_addc_u32 s13, s3, 0
	s_add_u32 s12, s12, 0xef40000
	s_addc_u32 s13, s13, 0
	s_movk_i32 s37, 5632
	v_mad_u32_u24 v138, v131, s37, v0
	v_lshlrev_b32_e32 v139, 6, v141
	v_lshlrev_b32_e64 v139, s40, v139
	v_add_u32_e32 v138, v138, v139
	s_mul_i32 s37, s40, 5568
	v_mul_u32_u24_e32 v139, s37, v140
	v_sub_u32_e32 v138, v138, v139
	v_mov_b32_e32 v139, 0
	v_lshl_add_u64 v[140:141], s[12:13], 0, v[138:139]
	s_mov_b32 s2, 0x20000
	s_mov_b32 s3, 0
	v_lshrrev_b32_e32 v0, 6, v145
	v_lshlrev_b32_e32 v0, 10, v0
	s_nop 0
	v_readfirstlane_b32 s43, v0
	s_mov_b32 s39, m0
	s_mov_b32 s10, 128
	s_mov_b32 s11, 0
	s_barrier
	s_add_i32 s38, s43, 0x0
	s_mov_b32 m0, s38
	v_lshl_add_u64 v[142:143], v[132:133], 0, s[2:3]
	global_load_lds_dwordx4 v[132:133], off
	s_addk_i32 m0, 0x1000
	s_nop 0
	global_load_lds_dwordx4 v[142:143], off
	v_lshl_add_u64 v[142:143], v[142:143], 0, s[2:3]
	s_addk_i32 m0, 0x1000
	s_nop 0
	global_load_lds_dwordx4 v[142:143], off
	v_lshl_add_u64 v[142:143], v[142:143], 0, s[2:3]
	s_addk_i32 m0, 0x1000
	s_nop 0
	global_load_lds_dwordx4 v[142:143], off
	s_addk_i32 m0, 0x1000
	v_lshl_add_u64 v[142:143], v[134:135], 0, s[2:3]
	s_nop 0
	global_load_lds_dwordx4 v[134:135], off
	s_addk_i32 m0, 0x1000
	v_lshl_add_u64 v[132:133], v[132:133], 0, s[14:15]
	s_nop 0
	global_load_lds_dwordx4 v[142:143], off
	v_lshl_add_u64 v[134:135], v[134:135], 0, s[10:11]
	s_nop 0
	s_add_i32 s38, s43, 0x6000
	s_mov_b32 m0, s38
	v_lshl_add_u64 v[142:143], v[132:133], 0, s[2:3]
	global_load_lds_dwordx4 v[132:133], off
	s_addk_i32 m0, 0x1000
	s_nop 0
	global_load_lds_dwordx4 v[142:143], off
	v_lshl_add_u64 v[142:143], v[142:143], 0, s[2:3]
	s_addk_i32 m0, 0x1000
	s_nop 0
	global_load_lds_dwordx4 v[142:143], off
	v_lshl_add_u64 v[142:143], v[142:143], 0, s[2:3]
	s_addk_i32 m0, 0x1000
	s_nop 0
	global_load_lds_dwordx4 v[142:143], off
	s_addk_i32 m0, 0x1000
	v_lshl_add_u64 v[142:143], v[134:135], 0, s[2:3]
	s_nop 0
	global_load_lds_dwordx4 v[134:135], off
	s_addk_i32 m0, 0x1000
	v_lshl_add_u64 v[132:133], v[132:133], 0, s[14:15]
	s_nop 0
	global_load_lds_dwordx4 v[142:143], off
	v_lshl_add_u64 v[134:135], v[134:135], 0, s[10:11]
	s_nop 0
	s_add_i32 s38, s43, 0xc000
	s_mov_b32 m0, s38
	v_lshl_add_u64 v[142:143], v[132:133], 0, s[2:3]
	global_load_lds_dwordx4 v[132:133], off
	s_addk_i32 m0, 0x1000
	s_nop 0
	global_load_lds_dwordx4 v[142:143], off
	v_lshl_add_u64 v[142:143], v[142:143], 0, s[2:3]
	s_addk_i32 m0, 0x1000
	s_nop 0
	global_load_lds_dwordx4 v[142:143], off
	v_lshl_add_u64 v[142:143], v[142:143], 0, s[2:3]
	s_addk_i32 m0, 0x1000
	s_nop 0
	global_load_lds_dwordx4 v[142:143], off
	s_addk_i32 m0, 0x1000
	v_lshl_add_u64 v[142:143], v[134:135], 0, s[2:3]
	s_nop 0
	global_load_lds_dwordx4 v[134:135], off
	s_addk_i32 m0, 0x1000
	v_lshl_add_u64 v[132:133], v[132:133], 0, s[14:15]
	s_nop 0
	global_load_lds_dwordx4 v[142:143], off
	v_lshl_add_u64 v[134:135], v[134:135], 0, s[10:11]
	s_nop 0
	v_mov_b32_e32 v2, 0
	v_mov_b32_e32 v3, 0
	v_mov_b32_e32 v4, 0
	v_mov_b32_e32 v5, 0
	v_mov_b32_e32 v6, 0
	v_mov_b32_e32 v7, 0
	v_mov_b32_e32 v8, 0
	v_mov_b32_e32 v9, 0
	v_mov_b32_e32 v10, 0
	v_mov_b32_e32 v11, 0
	v_mov_b32_e32 v12, 0
	v_mov_b32_e32 v13, 0
	v_mov_b32_e32 v14, 0
	v_mov_b32_e32 v15, 0
	v_mov_b32_e32 v16, 0
	v_mov_b32_e32 v17, 0
	v_mov_b32_e32 v18, 0
	v_mov_b32_e32 v19, 0
	v_mov_b32_e32 v20, 0
	v_mov_b32_e32 v21, 0
	v_mov_b32_e32 v22, 0
	v_mov_b32_e32 v23, 0
	v_mov_b32_e32 v24, 0
	v_mov_b32_e32 v25, 0
	v_mov_b32_e32 v26, 0
	v_mov_b32_e32 v27, 0
	v_mov_b32_e32 v28, 0
	v_mov_b32_e32 v29, 0
	v_mov_b32_e32 v30, 0
	v_mov_b32_e32 v31, 0
	v_mov_b32_e32 v32, 0
	v_mov_b32_e32 v33, 0
	v_mov_b32_e32 v34, 0
	v_mov_b32_e32 v35, 0
	v_mov_b32_e32 v36, 0
	v_mov_b32_e32 v37, 0
; #define LAS __attribute__((address_space(3)))
;     ...
;   f32x4 acc[4][8];
; #pragma unroll
;   for (int i = 0; i < 4; i++)
; #pragma unroll
;     for (int j = 0; j < 8; j++) acc[i][j] = (f32x4){0.f, 0.f, 0.f, 0.f};
;   const int nk = (nk_part < 0) ? (K >> 5) : nk_part;
;   const int lrow = tid >> 2, lpc = tid & 3;
;   const int lch = lpc ^ ((0x78 >> (((lrow >> 2) & 3) * 2)) & 3);
;   const u16* ga = A + (size_t)(m0 + lrow) * lda + kbeg + lch * 8;
;   const u16* gb = Bt + (size_t)(n0 + lrow) * K + kbeg + lch * 8;
;   const size_t ga1 = (size_t)64 * lda, gb1 = (size_t)64 * K;
;   const unsigned lds0 = (unsigned)(uintptr_t)(LAS char*)smem + (unsigned)__builtin_amdgcn_readfirstlane(wid) * 1024u;
;     ...
;   __syncthreads();
;   G2_STAGE(0); G2_STAGE(1);
;   const int fsw = (0x78 >> (((r16 >> 2) & 3) * 2)) & 3;
;   const int aoff = (wm * 128 + r16) * 64 + ((quad ^ fsw) << 4);
;   const int boff = 16384 + (wn * 64 + r16) * 64 + ((quad ^ fsw) << 4);
;   for (int kt = 0; kt < nk; kt++) {
;     if (kt + 1 < nk) asm volatile("s_waitcnt vmcnt(6)" ::: "memory");
;     else asm volatile("s_waitcnt vmcnt(0)" ::: "memory");
;     __builtin_amdgcn_s_barrier();
;     asm volatile("" ::: "memory");
;     if (kt + 2 < nk) G2_STAGE(kt + 2);
;     const char* cS = smem + (kt % 3) * 24576;
;     bf16x8 xa[8], wb[4];
; #pragma unroll
;     for (int f = 0; f < 8; f++) xa[f] = *(const bf16x8*)(cS + aoff + f * 1024);
; #pragma unroll
;     for (int f = 0; f < 4; f++) wb[f] = *(const bf16x8*)(cS + boff + f * 1024);
; #pragma unroll
;     for (int nf = 0; nf < 4; nf++)
; #pragma unroll
;       for (int mf = 0; mf < 8; mf++)
;         acc[nf][mf] = __builtin_amdgcn_mfma_f32_16x16x32_bf16(wb[nf], xa[mf], acc[nf][mf], 0, 0, 0);
	v_mov_b32_e32 v38, 0
	v_mov_b32_e32 v39, 0
	v_mov_b32_e32 v40, 0
	v_mov_b32_e32 v41, 0
	v_mov_b32_e32 v42, 0
	v_mov_b32_e32 v43, 0
	v_mov_b32_e32 v44, 0
	v_mov_b32_e32 v45, 0
	v_mov_b32_e32 v46, 0
	v_mov_b32_e32 v47, 0
	v_mov_b32_e32 v48, 0
	v_mov_b32_e32 v49, 0
	v_mov_b32_e32 v50, 0
	v_mov_b32_e32 v51, 0
	v_mov_b32_e32 v52, 0
	v_mov_b32_e32 v53, 0
	v_mov_b32_e32 v54, 0
	v_mov_b32_e32 v55, 0
	v_mov_b32_e32 v56, 0
	v_mov_b32_e32 v57, 0
	v_mov_b32_e32 v58, 0
	v_mov_b32_e32 v59, 0
	v_mov_b32_e32 v60, 0
	v_mov_b32_e32 v61, 0
	v_mov_b32_e32 v62, 0
	v_mov_b32_e32 v63, 0
	v_mov_b32_e32 v64, 0
	v_mov_b32_e32 v65, 0
	v_mov_b32_e32 v66, 0
	v_mov_b32_e32 v67, 0
	v_mov_b32_e32 v68, 0
	v_mov_b32_e32 v69, 0
	v_mov_b32_e32 v70, 0
	v_mov_b32_e32 v71, 0
	v_mov_b32_e32 v72, 0
	v_mov_b32_e32 v73, 0
	v_mov_b32_e32 v74, 0
	v_mov_b32_e32 v75, 0
	v_mov_b32_e32 v76, 0
	v_mov_b32_e32 v77, 0
	v_mov_b32_e32 v78, 0
	v_mov_b32_e32 v79, 0
	v_mov_b32_e32 v80, 0
	v_mov_b32_e32 v81, 0
	v_mov_b32_e32 v82, 0
	v_mov_b32_e32 v83, 0
	v_mov_b32_e32 v84, 0
	v_mov_b32_e32 v85, 0
	v_mov_b32_e32 v86, 0
	v_mov_b32_e32 v87, 0
	v_mov_b32_e32 v88, 0
	v_mov_b32_e32 v89, 0
	v_mov_b32_e32 v90, 0
	v_mov_b32_e32 v91, 0
	v_mov_b32_e32 v92, 0
	v_mov_b32_e32 v93, 0
	v_mov_b32_e32 v94, 0
	v_mov_b32_e32 v95, 0
	v_mov_b32_e32 v96, 0
	v_mov_b32_e32 v97, 0
	v_mov_b32_e32 v98, 0
	v_mov_b32_e32 v99, 0
	v_mov_b32_e32 v100, 0
	v_mov_b32_e32 v101, 0
	v_mov_b32_e32 v102, 0
	v_mov_b32_e32 v103, 0
	v_mov_b32_e32 v104, 0
	v_mov_b32_e32 v105, 0
	v_mov_b32_e32 v106, 0
	v_mov_b32_e32 v107, 0
	v_mov_b32_e32 v108, 0
	v_mov_b32_e32 v109, 0
	v_mov_b32_e32 v110, 0
	v_mov_b32_e32 v111, 0
	v_mov_b32_e32 v112, 0
	v_mov_b32_e32 v113, 0
	v_mov_b32_e32 v114, 0
	v_mov_b32_e32 v115, 0
	v_mov_b32_e32 v116, 0
	v_mov_b32_e32 v117, 0
	v_mov_b32_e32 v118, 0
	v_mov_b32_e32 v119, 0
	v_mov_b32_e32 v120, 0
	v_mov_b32_e32 v121, 0
	v_mov_b32_e32 v122, 0
	v_mov_b32_e32 v123, 0
	v_mov_b32_e32 v124, 0
	v_mov_b32_e32 v125, 0
	v_mov_b32_e32 v126, 0
	v_mov_b32_e32 v127, 0
	v_mov_b32_e32 v128, 0
	v_mov_b32_e32 v129, 0
	s_waitcnt vmcnt(12)
	s_barrier
	ds_read_b128 v[146:149], v136 offset:0
	ds_read_b128 v[152:155], v136 offset:1024
	ds_read_b128 v[156:159], v136 offset:2048
	ds_read_b128 v[162:165], v136 offset:3072
	ds_read_b128 v[166:169], v136 offset:4096
	ds_read_b128 v[170:173], v136 offset:5120
	ds_read_b128 v[176:179], v136 offset:6144
	ds_read_b128 v[180:183], v136 offset:7168
	ds_read_b128 v[184:187], v137 offset:16384
	ds_read_b128 v[188:191], v137 offset:17408
	ds_read_b128 v[192:195], v137 offset:18432
	ds_read_b128 v[196:199], v137 offset:19456
	s_movk_i32 s36, 0x6000
	s_mov_b32 s37, 0
	s_movk_i32 s9, 14
.Lt10_loop:
	s_waitcnt vmcnt(6) lgkmcnt(0)
	s_barrier
	s_setprio 1
	v_add_u32_e32 v144, s36, v136
	v_mfma_f32_16x16x32_bf16 v[126:129], v[184:187], v[146:149], v[126:129]
	ds_read_b128 v[200:203], v144 offset:0
	v_mfma_f32_16x16x32_bf16 v[122:125], v[184:187], v[152:155], v[122:125]
	ds_read_b128 v[204:207], v144 offset:1024
	v_mfma_f32_16x16x32_bf16 v[118:121], v[184:187], v[156:159], v[118:121]
	ds_read_b128 v[208:211], v144 offset:2048
	v_mfma_f32_16x16x32_bf16 v[114:117], v[184:187], v[162:165], v[114:117]
	ds_read_b128 v[212:215], v144 offset:3072
	v_mfma_f32_16x16x32_bf16 v[110:113], v[184:187], v[166:169], v[110:113]
	ds_read_b128 v[216:219], v144 offset:4096
	v_mfma_f32_16x16x32_bf16 v[106:109], v[184:187], v[170:173], v[106:109]
	ds_read_b128 v[220:223], v144 offset:5120
	v_mfma_f32_16x16x32_bf16 v[102:105], v[184:187], v[176:179], v[102:105]
	ds_read_b128 v[224:227], v144 offset:6144
	v_mfma_f32_16x16x32_bf16 v[98:101], v[184:187], v[180:183], v[98:101]
	ds_read_b128 v[228:231], v144 offset:7168
	v_mfma_f32_16x16x32_bf16 v[94:97], v[188:191], v[146:149], v[94:97]
	v_add_u32_e32 v144, s36, v137
	v_mfma_f32_16x16x32_bf16 v[90:93], v[188:191], v[152:155], v[90:93]
	v_mfma_f32_16x16x32_bf16 v[86:89], v[188:191], v[156:159], v[86:89]
	ds_read_b128 v[232:235], v144 offset:16384
	v_mfma_f32_16x16x32_bf16 v[82:85], v[188:191], v[162:165], v[82:85]
	ds_read_b128 v[236:239], v144 offset:17408
	v_mfma_f32_16x16x32_bf16 v[78:81], v[188:191], v[166:169], v[78:81]
	ds_read_b128 v[240:243], v144 offset:18432
	v_mfma_f32_16x16x32_bf16 v[74:77], v[188:191], v[170:173], v[74:77]
	ds_read_b128 v[244:247], v144 offset:19456
	s_add_i32 s38, s43, s37
	v_mfma_f32_16x16x32_bf16 v[70:73], v[188:191], v[176:179], v[70:73]
	s_mov_b32 m0, s38
	v_lshl_add_u64 v[142:143], v[132:133], 0, s[2:3]
	v_mfma_f32_16x16x32_bf16 v[66:69], v[188:191], v[180:183], v[66:69]
	global_load_lds_dwordx4 v[132:133], off
	s_addk_i32 m0, 0x1000
	v_mfma_f32_16x16x32_bf16 v[62:65], v[192:195], v[146:149], v[62:65]
	v_mfma_f32_16x16x32_bf16 v[58:61], v[192:195], v[152:155], v[58:61]
	v_mfma_f32_16x16x32_bf16 v[54:57], v[192:195], v[156:159], v[54:57]
	global_load_lds_dwordx4 v[142:143], off
	v_lshl_add_u64 v[142:143], v[142:143], 0, s[2:3]
	s_addk_i32 m0, 0x1000
	v_mfma_f32_16x16x32_bf16 v[50:53], v[192:195], v[162:165], v[50:53]
	v_mfma_f32_16x16x32_bf16 v[46:49], v[192:195], v[166:169], v[46:49]
	v_mfma_f32_16x16x32_bf16 v[42:45], v[192:195], v[170:173], v[42:45]
	global_load_lds_dwordx4 v[142:143], off
	v_lshl_add_u64 v[142:143], v[142:143], 0, s[2:3]
	s_addk_i32 m0, 0x1000
	v_mfma_f32_16x16x32_bf16 v[38:41], v[192:195], v[176:179], v[38:41]
	v_mfma_f32_16x16x32_bf16 v[34:37], v[192:195], v[180:183], v[34:37]
	v_mfma_f32_16x16x32_bf16 v[30:33], v[196:199], v[146:149], v[30:33]
	global_load_lds_dwordx4 v[142:143], off
	s_addk_i32 m0, 0x1000
	v_lshl_add_u64 v[142:143], v[134:135], 0, s[2:3]
	v_mfma_f32_16x16x32_bf16 v[26:29], v[196:199], v[152:155], v[26:29]
	v_mfma_f32_16x16x32_bf16 v[22:25], v[196:199], v[156:159], v[22:25]
	v_mfma_f32_16x16x32_bf16 v[18:21], v[196:199], v[162:165], v[18:21]
	global_load_lds_dwordx4 v[134:135], off
	s_addk_i32 m0, 0x1000
	v_lshl_add_u64 v[132:133], v[132:133], 0, s[14:15]
	v_mfma_f32_16x16x32_bf16 v[14:17], v[196:199], v[166:169], v[14:17]
	v_mfma_f32_16x16x32_bf16 v[10:13], v[196:199], v[170:173], v[10:13]
	v_mfma_f32_16x16x32_bf16 v[6:9], v[196:199], v[176:179], v[6:9]
	global_load_lds_dwordx4 v[142:143], off
	v_lshl_add_u64 v[134:135], v[134:135], 0, s[10:11]
	v_mfma_f32_16x16x32_bf16 v[2:5], v[196:199], v[180:183], v[2:5]
	s_setprio 0
	s_mov_b32 s37, s36
	s_add_i32 s36, s36, 0x6000
	s_cmp_eq_u32 s36, 0x12000
	s_cselect_b32 s36, 0, s36
	s_waitcnt vmcnt(6) lgkmcnt(0)
	s_barrier
;     ...
;   for (int kt = 0; kt < nk; kt++) {
;     if (kt + 1 < nk) asm volatile("s_waitcnt vmcnt(6)" ::: "memory");
;     else asm volatile("s_waitcnt vmcnt(0)" ::: "memory");
;     __builtin_amdgcn_s_barrier();
;     asm volatile("" ::: "memory");
;     if (kt + 2 < nk) G2_STAGE(kt + 2);
;     const char* cS = smem + (kt % 3) * 24576;
;     bf16x8 xa[8], wb[4];
; #pragma unroll
;     for (int f = 0; f < 8; f++) xa[f] = *(const bf16x8*)(cS + aoff + f * 1024);
; #pragma unroll
;     for (int f = 0; f < 4; f++) wb[f] = *(const bf16x8*)(cS + boff + f * 1024);
; #pragma unroll
;     for (int nf = 0; nf < 4; nf++)
; #pragma unroll
;       for (int mf = 0; mf < 8; mf++)
;         acc[nf][mf] = __builtin_amdgcn_mfma_f32_16x16x32_bf16(wb[nf], xa[mf], acc[nf][mf], 0, 0, 0);
	s_setprio 1
	v_add_u32_e32 v144, s36, v136
	v_mfma_f32_16x16x32_bf16 v[126:129], v[232:235], v[200:203], v[126:129]
	ds_read_b128 v[146:149], v144 offset:0
	v_mfma_f32_16x16x32_bf16 v[122:125], v[232:235], v[204:207], v[122:125]
	ds_read_b128 v[152:155], v144 offset:1024
	v_mfma_f32_16x16x32_bf16 v[118:121], v[232:235], v[208:211], v[118:121]
	ds_read_b128 v[156:159], v144 offset:2048
	v_mfma_f32_16x16x32_bf16 v[114:117], v[232:235], v[212:215], v[114:117]
	ds_read_b128 v[162:165], v144 offset:3072
	v_mfma_f32_16x16x32_bf16 v[110:113], v[232:235], v[216:219], v[110:113]
	ds_read_b128 v[166:169], v144 offset:4096
	v_mfma_f32_16x16x32_bf16 v[106:109], v[232:235], v[220:223], v[106:109]
	ds_read_b128 v[170:173], v144 offset:5120
	v_mfma_f32_16x16x32_bf16 v[102:105], v[232:235], v[224:227], v[102:105]
	ds_read_b128 v[176:179], v144 offset:6144
	v_mfma_f32_16x16x32_bf16 v[98:101], v[232:235], v[228:231], v[98:101]
	ds_read_b128 v[180:183], v144 offset:7168
	v_mfma_f32_16x16x32_bf16 v[94:97], v[236:239], v[200:203], v[94:97]
	v_add_u32_e32 v144, s36, v137
	v_mfma_f32_16x16x32_bf16 v[90:93], v[236:239], v[204:207], v[90:93]
	v_mfma_f32_16x16x32_bf16 v[86:89], v[236:239], v[208:211], v[86:89]
	ds_read_b128 v[184:187], v144 offset:16384
	v_mfma_f32_16x16x32_bf16 v[82:85], v[236:239], v[212:215], v[82:85]
	ds_read_b128 v[188:191], v144 offset:17408
	v_mfma_f32_16x16x32_bf16 v[78:81], v[236:239], v[216:219], v[78:81]
	ds_read_b128 v[192:195], v144 offset:18432
	v_mfma_f32_16x16x32_bf16 v[74:77], v[236:239], v[220:223], v[74:77]
	ds_read_b128 v[196:199], v144 offset:19456
	s_add_i32 s38, s43, s37
	v_mfma_f32_16x16x32_bf16 v[70:73], v[236:239], v[224:227], v[70:73]
	s_mov_b32 m0, s38
	v_lshl_add_u64 v[142:143], v[132:133], 0, s[2:3]
	v_mfma_f32_16x16x32_bf16 v[66:69], v[236:239], v[228:231], v[66:69]
	global_load_lds_dwordx4 v[132:133], off
	s_addk_i32 m0, 0x1000
	v_mfma_f32_16x16x32_bf16 v[62:65], v[240:243], v[200:203], v[62:65]
	v_mfma_f32_16x16x32_bf16 v[58:61], v[240:243], v[204:207], v[58:61]
	v_mfma_f32_16x16x32_bf16 v[54:57], v[240:243], v[208:211], v[54:57]
	global_load_lds_dwordx4 v[142:143], off
	v_lshl_add_u64 v[142:143], v[142:143], 0, s[2:3]
	s_addk_i32 m0, 0x1000
	v_mfma_f32_16x16x32_bf16 v[50:53], v[240:243], v[212:215], v[50:53]
	v_mfma_f32_16x16x32_bf16 v[46:49], v[240:243], v[216:219], v[46:49]
	v_mfma_f32_16x16x32_bf16 v[42:45], v[240:243], v[220:223], v[42:45]
	global_load_lds_dwordx4 v[142:143], off
	v_lshl_add_u64 v[142:143], v[142:143], 0, s[2:3]
	s_addk_i32 m0, 0x1000
	v_mfma_f32_16x16x32_bf16 v[38:41], v[240:243], v[224:227], v[38:41]
	v_mfma_f32_16x16x32_bf16 v[34:37], v[240:243], v[228:231], v[34:37]
	v_mfma_f32_16x16x32_bf16 v[30:33], v[244:247], v[200:203], v[30:33]
	global_load_lds_dwordx4 v[142:143], off
	s_addk_i32 m0, 0x1000
	v_lshl_add_u64 v[142:143], v[134:135], 0, s[2:3]
	v_mfma_f32_16x16x32_bf16 v[26:29], v[244:247], v[204:207], v[26:29]
	v_mfma_f32_16x16x32_bf16 v[22:25], v[244:247], v[208:211], v[22:25]
	v_mfma_f32_16x16x32_bf16 v[18:21], v[244:247], v[212:215], v[18:21]
	global_load_lds_dwordx4 v[134:135], off
	s_addk_i32 m0, 0x1000
	v_lshl_add_u64 v[132:133], v[132:133], 0, s[14:15]
	v_mfma_f32_16x16x32_bf16 v[14:17], v[244:247], v[216:219], v[14:17]
	v_mfma_f32_16x16x32_bf16 v[10:13], v[244:247], v[220:223], v[10:13]
	v_mfma_f32_16x16x32_bf16 v[6:9], v[244:247], v[224:227], v[6:9]
	global_load_lds_dwordx4 v[142:143], off
	v_lshl_add_u64 v[134:135], v[134:135], 0, s[10:11]
	v_mfma_f32_16x16x32_bf16 v[2:5], v[244:247], v[228:231], v[2:5]
	s_setprio 0
	s_mov_b32 s37, s36
	s_add_i32 s36, s36, 0x6000
	s_cmp_eq_u32 s36, 0x12000
	s_cselect_b32 s36, 0, s36
	s_sub_i32 s9, s9, 1
	s_cmp_lg_u32 s9, 0
	s_cbranch_scc1 .Lt10_loop
	s_waitcnt vmcnt(6) lgkmcnt(0)
	s_barrier
	s_setprio 1
	v_add_u32_e32 v144, s36, v136
	v_mfma_f32_16x16x32_bf16 v[126:129], v[184:187], v[146:149], v[126:129]
	ds_read_b128 v[200:203], v144 offset:0
	v_mfma_f32_16x16x32_bf16 v[122:125], v[184:187], v[152:155], v[122:125]
	ds_read_b128 v[204:207], v144 offset:1024
	v_mfma_f32_16x16x32_bf16 v[118:121], v[184:187], v[156:159], v[118:121]
	ds_read_b128 v[208:211], v144 offset:2048
	v_mfma_f32_16x16x32_bf16 v[114:117], v[184:187], v[162:165], v[114:117]
	ds_read_b128 v[212:215], v144 offset:3072
	v_mfma_f32_16x16x32_bf16 v[110:113], v[184:187], v[166:169], v[110:113]
	ds_read_b128 v[216:219], v144 offset:4096
	v_mfma_f32_16x16x32_bf16 v[106:109], v[184:187], v[170:173], v[106:109]
	ds_read_b128 v[220:223], v144 offset:5120
	v_mfma_f32_16x16x32_bf16 v[102:105], v[184:187], v[176:179], v[102:105]
	ds_read_b128 v[224:227], v144 offset:6144
	v_mfma_f32_16x16x32_bf16 v[98:101], v[184:187], v[180:183], v[98:101]
	ds_read_b128 v[228:231], v144 offset:7168
	v_mfma_f32_16x16x32_bf16 v[94:97], v[188:191], v[146:149], v[94:97]
	v_add_u32_e32 v144, s36, v137
	v_mfma_f32_16x16x32_bf16 v[90:93], v[188:191], v[152:155], v[90:93]
	v_mfma_f32_16x16x32_bf16 v[86:89], v[188:191], v[156:159], v[86:89]
	ds_read_b128 v[232:235], v144 offset:16384
	v_mfma_f32_16x16x32_bf16 v[82:85], v[188:191], v[162:165], v[82:85]
	ds_read_b128 v[236:239], v144 offset:17408
	v_mfma_f32_16x16x32_bf16 v[78:81], v[188:191], v[166:169], v[78:81]
	ds_read_b128 v[240:243], v144 offset:18432
	v_mfma_f32_16x16x32_bf16 v[74:77], v[188:191], v[170:173], v[74:77]
	ds_read_b128 v[244:247], v144 offset:19456
	s_add_i32 s38, s43, s37
	v_mfma_f32_16x16x32_bf16 v[70:73], v[188:191], v[176:179], v[70:73]
	s_mov_b32 m0, s38
	v_lshl_add_u64 v[142:143], v[132:133], 0, s[2:3]
	v_mfma_f32_16x16x32_bf16 v[66:69], v[188:191], v[180:183], v[66:69]
	global_load_lds_dwordx4 v[132:133], off
	s_addk_i32 m0, 0x1000
;     ...
;   for (int kt = 0; kt < nk; kt++) {
;     if (kt + 1 < nk) asm volatile("s_waitcnt vmcnt(6)" ::: "memory");
;     else asm volatile("s_waitcnt vmcnt(0)" ::: "memory");
;     __builtin_amdgcn_s_barrier();
;     asm volatile("" ::: "memory");
;     if (kt + 2 < nk) G2_STAGE(kt + 2);
;     const char* cS = smem + (kt % 3) * 24576;
;     bf16x8 xa[8], wb[4];
; #pragma unroll
;     for (int f = 0; f < 8; f++) xa[f] = *(const bf16x8*)(cS + aoff + f * 1024);
; #pragma unroll
;     for (int f = 0; f < 4; f++) wb[f] = *(const bf16x8*)(cS + boff + f * 1024);
; #pragma unroll
;     for (int nf = 0; nf < 4; nf++)
; #pragma unroll
;       for (int mf = 0; mf < 8; mf++)
;         acc[nf][mf] = __builtin_amdgcn_mfma_f32_16x16x32_bf16(wb[nf], xa[mf], acc[nf][mf], 0, 0, 0);
	v_mfma_f32_16x16x32_bf16 v[62:65], v[192:195], v[146:149], v[62:65]
	v_mfma_f32_16x16x32_bf16 v[58:61], v[192:195], v[152:155], v[58:61]
	v_mfma_f32_16x16x32_bf16 v[54:57], v[192:195], v[156:159], v[54:57]
	global_load_lds_dwordx4 v[142:143], off
	v_lshl_add_u64 v[142:143], v[142:143], 0, s[2:3]
	s_addk_i32 m0, 0x1000
	v_mfma_f32_16x16x32_bf16 v[50:53], v[192:195], v[162:165], v[50:53]
	v_mfma_f32_16x16x32_bf16 v[46:49], v[192:195], v[166:169], v[46:49]
	v_mfma_f32_16x16x32_bf16 v[42:45], v[192:195], v[170:173], v[42:45]
	global_load_lds_dwordx4 v[142:143], off
	v_lshl_add_u64 v[142:143], v[142:143], 0, s[2:3]
	s_addk_i32 m0, 0x1000
	v_mfma_f32_16x16x32_bf16 v[38:41], v[192:195], v[176:179], v[38:41]
	v_mfma_f32_16x16x32_bf16 v[34:37], v[192:195], v[180:183], v[34:37]
	v_mfma_f32_16x16x32_bf16 v[30:33], v[196:199], v[146:149], v[30:33]
	global_load_lds_dwordx4 v[142:143], off
	s_addk_i32 m0, 0x1000
	v_lshl_add_u64 v[142:143], v[134:135], 0, s[2:3]
	v_mfma_f32_16x16x32_bf16 v[26:29], v[196:199], v[152:155], v[26:29]
	v_mfma_f32_16x16x32_bf16 v[22:25], v[196:199], v[156:159], v[22:25]
	v_mfma_f32_16x16x32_bf16 v[18:21], v[196:199], v[162:165], v[18:21]
	global_load_lds_dwordx4 v[134:135], off
	s_addk_i32 m0, 0x1000
	v_lshl_add_u64 v[132:133], v[132:133], 0, s[14:15]
	v_mfma_f32_16x16x32_bf16 v[14:17], v[196:199], v[166:169], v[14:17]
	v_mfma_f32_16x16x32_bf16 v[10:13], v[196:199], v[170:173], v[10:13]
	v_mfma_f32_16x16x32_bf16 v[6:9], v[196:199], v[176:179], v[6:9]
	global_load_lds_dwordx4 v[142:143], off
	v_lshl_add_u64 v[134:135], v[134:135], 0, s[10:11]
	v_mfma_f32_16x16x32_bf16 v[2:5], v[196:199], v[180:183], v[2:5]
	s_setprio 0
	s_mov_b32 s37, s36
	s_add_i32 s36, s36, 0x6000
	s_cmp_eq_u32 s36, 0x12000
	s_cselect_b32 s36, 0, s36
	s_waitcnt vmcnt(6) lgkmcnt(0)
	s_barrier
	s_setprio 1
	v_add_u32_e32 v144, s36, v136
	v_mfma_f32_16x16x32_bf16 v[126:129], v[232:235], v[200:203], v[126:129]
	ds_read_b128 v[146:149], v144 offset:0
	v_mfma_f32_16x16x32_bf16 v[122:125], v[232:235], v[204:207], v[122:125]
	ds_read_b128 v[152:155], v144 offset:1024
	v_mfma_f32_16x16x32_bf16 v[118:121], v[232:235], v[208:211], v[118:121]
	ds_read_b128 v[156:159], v144 offset:2048
	v_mfma_f32_16x16x32_bf16 v[114:117], v[232:235], v[212:215], v[114:117]
	ds_read_b128 v[162:165], v144 offset:3072
	v_mfma_f32_16x16x32_bf16 v[110:113], v[232:235], v[216:219], v[110:113]
	ds_read_b128 v[166:169], v144 offset:4096
	v_mfma_f32_16x16x32_bf16 v[106:109], v[232:235], v[220:223], v[106:109]
	ds_read_b128 v[170:173], v144 offset:5120
	v_mfma_f32_16x16x32_bf16 v[102:105], v[232:235], v[224:227], v[102:105]
	ds_read_b128 v[176:179], v144 offset:6144
	v_mfma_f32_16x16x32_bf16 v[98:101], v[232:235], v[228:231], v[98:101]
	ds_read_b128 v[180:183], v144 offset:7168
	v_mfma_f32_16x16x32_bf16 v[94:97], v[236:239], v[200:203], v[94:97]
	v_add_u32_e32 v144, s36, v137
	v_mfma_f32_16x16x32_bf16 v[90:93], v[236:239], v[204:207], v[90:93]
	v_mfma_f32_16x16x32_bf16 v[86:89], v[236:239], v[208:211], v[86:89]
	ds_read_b128 v[184:187], v144 offset:16384
	v_mfma_f32_16x16x32_bf16 v[82:85], v[236:239], v[212:215], v[82:85]
	ds_read_b128 v[188:191], v144 offset:17408
	v_mfma_f32_16x16x32_bf16 v[78:81], v[236:239], v[216:219], v[78:81]
	ds_read_b128 v[192:195], v144 offset:18432
	v_mfma_f32_16x16x32_bf16 v[74:77], v[236:239], v[220:223], v[74:77]
	ds_read_b128 v[196:199], v144 offset:19456
	v_mfma_f32_16x16x32_bf16 v[70:73], v[236:239], v[224:227], v[70:73]
	v_mfma_f32_16x16x32_bf16 v[66:69], v[236:239], v[228:231], v[66:69]
	v_mfma_f32_16x16x32_bf16 v[62:65], v[240:243], v[200:203], v[62:65]
	v_mfma_f32_16x16x32_bf16 v[58:61], v[240:243], v[204:207], v[58:61]
	v_mfma_f32_16x16x32_bf16 v[54:57], v[240:243], v[208:211], v[54:57]
	v_mfma_f32_16x16x32_bf16 v[50:53], v[240:243], v[212:215], v[50:53]
	v_mfma_f32_16x16x32_bf16 v[46:49], v[240:243], v[216:219], v[46:49]
	v_mfma_f32_16x16x32_bf16 v[42:45], v[240:243], v[220:223], v[42:45]
	v_mfma_f32_16x16x32_bf16 v[38:41], v[240:243], v[224:227], v[38:41]
	v_mfma_f32_16x16x32_bf16 v[34:37], v[240:243], v[228:231], v[34:37]
	v_mfma_f32_16x16x32_bf16 v[30:33], v[244:247], v[200:203], v[30:33]
	v_mfma_f32_16x16x32_bf16 v[26:29], v[244:247], v[204:207], v[26:29]
	v_mfma_f32_16x16x32_bf16 v[22:25], v[244:247], v[208:211], v[22:25]
	v_mfma_f32_16x16x32_bf16 v[18:21], v[244:247], v[212:215], v[18:21]
	v_mfma_f32_16x16x32_bf16 v[14:17], v[244:247], v[216:219], v[14:17]
	v_mfma_f32_16x16x32_bf16 v[10:13], v[244:247], v[220:223], v[10:13]
	v_mfma_f32_16x16x32_bf16 v[6:9], v[244:247], v[224:227], v[6:9]
	v_mfma_f32_16x16x32_bf16 v[2:5], v[244:247], v[228:231], v[2:5]
	s_setprio 0
	s_mov_b32 s37, s36
	s_add_i32 s36, s36, 0x6000
	s_cmp_eq_u32 s36, 0x12000
	s_cselect_b32 s36, 0, s36
	s_waitcnt vmcnt(0) lgkmcnt(0)
	s_barrier
; DEVI unsigned pack2(float a, float b) { return __builtin_bit_cast(unsigned, __builtin_convertvector((f32x2_t){a, b}, bf16x2_t)); }
; DEVI float siluf_(float x) { return x * __builtin_amdgcn_rcpf(1.f + __expf(-x)); }
;     ...
;   for (int kt = 0; kt < nk; kt++) {
;     if (kt + 1 < nk) asm volatile("s_waitcnt vmcnt(6)" ::: "memory");
;     else asm volatile("s_waitcnt vmcnt(0)" ::: "memory");
;     __builtin_amdgcn_s_barrier();
;     asm volatile("" ::: "memory");
;     if (kt + 2 < nk) G2_STAGE(kt + 2);
;     const char* cS = smem + (kt % 3) * 24576;
;     bf16x8 xa[8], wb[4];
; #pragma unroll
;     for (int f = 0; f < 8; f++) xa[f] = *(const bf16x8*)(cS + aoff + f * 1024);
; #pragma unroll
;     for (int f = 0; f < 4; f++) wb[f] = *(const bf16x8*)(cS + boff + f * 1024);
; #pragma unroll
;     for (int nf = 0; nf < 4; nf++)
; #pragma unroll
;       for (int mf = 0; mf < 8; mf++)
;         acc[nf][mf] = __builtin_amdgcn_mfma_f32_16x16x32_bf16(wb[nf], xa[mf], acc[nf][mf], 0, 0, 0);
;     ...
;     if (EPI == EPI_SWIGLU) {
; #pragma unroll
;       for (int nf = 0; nf < 2; nf++) {
;         const int hcol = (n0 >> 1) + wn * 32 + nf * 16 + quad * 4;
;         f32x4 g = acc[nf][mf], u = acc[nf + 2][mf];
;         u32x2 pk;
;         pk[0] = pack2(siluf_(g[0]) * u[0], siluf_(g[1]) * u[1]);
;         pk[1] = pack2(siluf_(g[2]) * u[2], siluf_(g[3]) * u[3]);
;         *(u32x2*)(outb + (size_t)row * DFF + hcol) = pk;
;       }
	s_setprio 1
	v_add_u32_e32 v144, s36, v136
	v_mfma_f32_16x16x32_bf16 v[126:129], v[184:187], v[146:149], v[126:129]
	ds_read_b128 v[200:203], v144 offset:0
	v_mfma_f32_16x16x32_bf16 v[122:125], v[184:187], v[152:155], v[122:125]
	ds_read_b128 v[204:207], v144 offset:1024
	v_mfma_f32_16x16x32_bf16 v[118:121], v[184:187], v[156:159], v[118:121]
	ds_read_b128 v[208:211], v144 offset:2048
	v_mfma_f32_16x16x32_bf16 v[114:117], v[184:187], v[162:165], v[114:117]
	ds_read_b128 v[212:215], v144 offset:3072
	v_mfma_f32_16x16x32_bf16 v[110:113], v[184:187], v[166:169], v[110:113]
	ds_read_b128 v[216:219], v144 offset:4096
	v_mfma_f32_16x16x32_bf16 v[106:109], v[184:187], v[170:173], v[106:109]
	ds_read_b128 v[220:223], v144 offset:5120
	v_mfma_f32_16x16x32_bf16 v[102:105], v[184:187], v[176:179], v[102:105]
	ds_read_b128 v[224:227], v144 offset:6144
	v_mfma_f32_16x16x32_bf16 v[98:101], v[184:187], v[180:183], v[98:101]
	ds_read_b128 v[228:231], v144 offset:7168
	v_mfma_f32_16x16x32_bf16 v[94:97], v[188:191], v[146:149], v[94:97]
	v_add_u32_e32 v144, s36, v137
	v_mfma_f32_16x16x32_bf16 v[90:93], v[188:191], v[152:155], v[90:93]
	v_mfma_f32_16x16x32_bf16 v[86:89], v[188:191], v[156:159], v[86:89]
	ds_read_b128 v[232:235], v144 offset:16384
	v_mfma_f32_16x16x32_bf16 v[82:85], v[188:191], v[162:165], v[82:85]
	ds_read_b128 v[236:239], v144 offset:17408
	v_mfma_f32_16x16x32_bf16 v[78:81], v[188:191], v[166:169], v[78:81]
	ds_read_b128 v[240:243], v144 offset:18432
	v_mfma_f32_16x16x32_bf16 v[74:77], v[188:191], v[170:173], v[74:77]
	ds_read_b128 v[244:247], v144 offset:19456
	v_mfma_f32_16x16x32_bf16 v[70:73], v[188:191], v[176:179], v[70:73]
	v_mfma_f32_16x16x32_bf16 v[66:69], v[188:191], v[180:183], v[66:69]
	v_mfma_f32_16x16x32_bf16 v[62:65], v[192:195], v[146:149], v[62:65]
	v_mfma_f32_16x16x32_bf16 v[58:61], v[192:195], v[152:155], v[58:61]
	v_mfma_f32_16x16x32_bf16 v[54:57], v[192:195], v[156:159], v[54:57]
	v_mfma_f32_16x16x32_bf16 v[50:53], v[192:195], v[162:165], v[50:53]
	v_mfma_f32_16x16x32_bf16 v[46:49], v[192:195], v[166:169], v[46:49]
	v_mfma_f32_16x16x32_bf16 v[42:45], v[192:195], v[170:173], v[42:45]
	v_mfma_f32_16x16x32_bf16 v[38:41], v[192:195], v[176:179], v[38:41]
	v_mfma_f32_16x16x32_bf16 v[34:37], v[192:195], v[180:183], v[34:37]
	v_mfma_f32_16x16x32_bf16 v[30:33], v[196:199], v[146:149], v[30:33]
	v_mfma_f32_16x16x32_bf16 v[26:29], v[196:199], v[152:155], v[26:29]
	v_mfma_f32_16x16x32_bf16 v[22:25], v[196:199], v[156:159], v[22:25]
	v_mfma_f32_16x16x32_bf16 v[18:21], v[196:199], v[162:165], v[18:21]
	v_mfma_f32_16x16x32_bf16 v[14:17], v[196:199], v[166:169], v[14:17]
	v_mfma_f32_16x16x32_bf16 v[10:13], v[196:199], v[170:173], v[10:13]
	v_mfma_f32_16x16x32_bf16 v[6:9], v[196:199], v[176:179], v[6:9]
	v_mfma_f32_16x16x32_bf16 v[2:5], v[196:199], v[180:183], v[2:5]
	s_setprio 0
	s_mov_b32 s37, s36
	s_add_i32 s36, s36, 0x6000
	s_cmp_eq_u32 s36, 0x12000
	s_cselect_b32 s36, 0, s36
	s_waitcnt lgkmcnt(0)
	v_mfma_f32_16x16x32_bf16 v[126:129], v[232:235], v[200:203], v[126:129]
	v_mfma_f32_16x16x32_bf16 v[122:125], v[232:235], v[204:207], v[122:125]
	v_mfma_f32_16x16x32_bf16 v[118:121], v[232:235], v[208:211], v[118:121]
	v_mfma_f32_16x16x32_bf16 v[114:117], v[232:235], v[212:215], v[114:117]
	v_mfma_f32_16x16x32_bf16 v[110:113], v[232:235], v[216:219], v[110:113]
	v_mfma_f32_16x16x32_bf16 v[106:109], v[232:235], v[220:223], v[106:109]
	v_mfma_f32_16x16x32_bf16 v[102:105], v[232:235], v[224:227], v[102:105]
	v_mfma_f32_16x16x32_bf16 v[98:101], v[232:235], v[228:231], v[98:101]
	v_mfma_f32_16x16x32_bf16 v[94:97], v[236:239], v[200:203], v[94:97]
	v_mfma_f32_16x16x32_bf16 v[90:93], v[236:239], v[204:207], v[90:93]
	v_mfma_f32_16x16x32_bf16 v[86:89], v[236:239], v[208:211], v[86:89]
	v_mfma_f32_16x16x32_bf16 v[82:85], v[236:239], v[212:215], v[82:85]
	v_mfma_f32_16x16x32_bf16 v[78:81], v[236:239], v[216:219], v[78:81]
	v_mfma_f32_16x16x32_bf16 v[74:77], v[236:239], v[220:223], v[74:77]
	v_mfma_f32_16x16x32_bf16 v[70:73], v[236:239], v[224:227], v[70:73]
	v_mfma_f32_16x16x32_bf16 v[66:69], v[236:239], v[228:231], v[66:69]
	v_mfma_f32_16x16x32_bf16 v[62:65], v[240:243], v[200:203], v[62:65]
	v_mfma_f32_16x16x32_bf16 v[58:61], v[240:243], v[204:207], v[58:61]
	v_mfma_f32_16x16x32_bf16 v[54:57], v[240:243], v[208:211], v[54:57]
	v_mfma_f32_16x16x32_bf16 v[50:53], v[240:243], v[212:215], v[50:53]
	v_mfma_f32_16x16x32_bf16 v[46:49], v[240:243], v[216:219], v[46:49]
	v_mfma_f32_16x16x32_bf16 v[42:45], v[240:243], v[220:223], v[42:45]
	v_mfma_f32_16x16x32_bf16 v[38:41], v[240:243], v[224:227], v[38:41]
	v_mfma_f32_16x16x32_bf16 v[34:37], v[240:243], v[228:231], v[34:37]
	v_mfma_f32_16x16x32_bf16 v[30:33], v[244:247], v[200:203], v[30:33]
	v_mfma_f32_16x16x32_bf16 v[26:29], v[244:247], v[204:207], v[26:29]
	v_mfma_f32_16x16x32_bf16 v[22:25], v[244:247], v[208:211], v[22:25]
	v_mfma_f32_16x16x32_bf16 v[18:21], v[244:247], v[212:215], v[18:21]
	v_mfma_f32_16x16x32_bf16 v[14:17], v[244:247], v[216:219], v[14:17]
	v_mfma_f32_16x16x32_bf16 v[10:13], v[244:247], v[220:223], v[10:13]
	v_mfma_f32_16x16x32_bf16 v[6:9], v[244:247], v[224:227], v[6:9]
	v_mfma_f32_16x16x32_bf16 v[2:5], v[244:247], v[228:231], v[2:5]
	s_mov_b32 m0, s39
	s_mov_b32 s10, 0x16000
	s_mov_b32 s11, 0
	s_mov_b32 s40, 0xbfb8aa3b
	s_nop 7
	v_mul_f32_e32 v216, s40, v126
	v_mul_f32_e32 v217, s40, v127
	v_mul_f32_e32 v218, s40, v128
	v_mul_f32_e32 v219, s40, v129
	v_exp_f32_e32 v216, v216
	v_exp_f32_e32 v217, v217
	v_exp_f32_e32 v218, v218
	v_exp_f32_e32 v219, v219
	v_add_f32_e32 v216, 1.0, v216
	v_add_f32_e32 v217, 1.0, v217
	v_add_f32_e32 v218, 1.0, v218
	v_add_f32_e32 v219, 1.0, v219
; DEVI unsigned pack2(float a, float b) { return __builtin_bit_cast(unsigned, __builtin_convertvector((f32x2_t){a, b}, bf16x2_t)); }
; DEVI float siluf_(float x) { return x * __builtin_amdgcn_rcpf(1.f + __expf(-x)); }
;     ...
;     if (EPI == EPI_SWIGLU) {
; #pragma unroll
;       for (int nf = 0; nf < 2; nf++) {
;         const int hcol = (n0 >> 1) + wn * 32 + nf * 16 + quad * 4;
;         f32x4 g = acc[nf][mf], u = acc[nf + 2][mf];
;         u32x2 pk;
;         pk[0] = pack2(siluf_(g[0]) * u[0], siluf_(g[1]) * u[1]);
;         pk[1] = pack2(siluf_(g[2]) * u[2], siluf_(g[3]) * u[3]);
;         *(u32x2*)(outb + (size_t)row * DFF + hcol) = pk;
;       }
	v_rcp_f32_e32 v216, v216
	v_rcp_f32_e32 v217, v217
	v_rcp_f32_e32 v218, v218
	v_rcp_f32_e32 v219, v219
	v_mul_f32_e32 v126, v126, v216
	v_mul_f32_e32 v127, v127, v217
	v_mul_f32_e32 v128, v128, v218
	v_mul_f32_e32 v129, v129, v219
	v_mul_f32_e32 v126, v126, v62
	v_mul_f32_e32 v127, v127, v63
	v_mul_f32_e32 v128, v128, v64
	v_mul_f32_e32 v129, v129, v65
	v_mul_f32_e32 v220, s40, v94
	v_mul_f32_e32 v221, s40, v95
	v_mul_f32_e32 v222, s40, v96
	v_mul_f32_e32 v223, s40, v97
	v_exp_f32_e32 v220, v220
	v_exp_f32_e32 v221, v221
	v_exp_f32_e32 v222, v222
	v_exp_f32_e32 v223, v223
	v_add_f32_e32 v220, 1.0, v220
	v_add_f32_e32 v221, 1.0, v221
	v_add_f32_e32 v222, 1.0, v222
	v_add_f32_e32 v223, 1.0, v223
	v_rcp_f32_e32 v220, v220
	v_rcp_f32_e32 v221, v221
	v_rcp_f32_e32 v222, v222
	v_rcp_f32_e32 v223, v223
	v_mul_f32_e32 v94, v94, v220
	v_mul_f32_e32 v95, v95, v221
	v_mul_f32_e32 v96, v96, v222
	v_mul_f32_e32 v97, v97, v223
	v_mul_f32_e32 v94, v94, v30
	v_mul_f32_e32 v95, v95, v31
	v_mul_f32_e32 v96, v96, v32
	v_mul_f32_e32 v97, v97, v33
	v_cvt_pk_bf16_f32 v126, v126, v127
	v_cvt_pk_bf16_f32 v127, v128, v129
	v_cvt_pk_bf16_f32 v128, v94, v95
	v_cvt_pk_bf16_f32 v129, v96, v97
	s_nop 1
	v_permlane16_swap_b32_e32 v126, v128
	v_permlane16_swap_b32_e32 v127, v129
	global_store_dwordx4 v[140:141], v[126:129], off
	v_lshl_add_u64 v[140:141], v[140:141], 0, s[10:11]
	v_mul_f32_e32 v216, s40, v122
	v_mul_f32_e32 v217, s40, v123
	v_mul_f32_e32 v218, s40, v124
	v_mul_f32_e32 v219, s40, v125
	v_exp_f32_e32 v216, v216
	v_exp_f32_e32 v217, v217
	v_exp_f32_e32 v218, v218
	v_exp_f32_e32 v219, v219
	v_add_f32_e32 v216, 1.0, v216
	v_add_f32_e32 v217, 1.0, v217
	v_add_f32_e32 v218, 1.0, v218
	v_add_f32_e32 v219, 1.0, v219
	v_rcp_f32_e32 v216, v216
	v_rcp_f32_e32 v217, v217
	v_rcp_f32_e32 v218, v218
	v_rcp_f32_e32 v219, v219
	v_mul_f32_e32 v122, v122, v216
	v_mul_f32_e32 v123, v123, v217
	v_mul_f32_e32 v124, v124, v218
	v_mul_f32_e32 v125, v125, v219
	v_mul_f32_e32 v122, v122, v58
	v_mul_f32_e32 v123, v123, v59
	v_mul_f32_e32 v124, v124, v60
	v_mul_f32_e32 v125, v125, v61
	v_mul_f32_e32 v220, s40, v90
	v_mul_f32_e32 v221, s40, v91
	v_mul_f32_e32 v222, s40, v92
	v_mul_f32_e32 v223, s40, v93
	v_exp_f32_e32 v220, v220
	v_exp_f32_e32 v221, v221
	v_exp_f32_e32 v222, v222
	v_exp_f32_e32 v223, v223
	v_add_f32_e32 v220, 1.0, v220
	v_add_f32_e32 v221, 1.0, v221
	v_add_f32_e32 v222, 1.0, v222
	v_add_f32_e32 v223, 1.0, v223
	v_rcp_f32_e32 v220, v220
	v_rcp_f32_e32 v221, v221
	v_rcp_f32_e32 v222, v222
	v_rcp_f32_e32 v223, v223
	v_mul_f32_e32 v90, v90, v220
	v_mul_f32_e32 v91, v91, v221
	v_mul_f32_e32 v92, v92, v222
	v_mul_f32_e32 v93, v93, v223
	v_mul_f32_e32 v90, v90, v26
	v_mul_f32_e32 v91, v91, v27
	v_mul_f32_e32 v92, v92, v28
	v_mul_f32_e32 v93, v93, v29
	v_cvt_pk_bf16_f32 v122, v122, v123
	v_cvt_pk_bf16_f32 v123, v124, v125
	v_cvt_pk_bf16_f32 v124, v90, v91
	v_cvt_pk_bf16_f32 v125, v92, v93
	s_nop 1
	v_permlane16_swap_b32_e32 v122, v124
	v_permlane16_swap_b32_e32 v123, v125
	global_store_dwordx4 v[140:141], v[122:125], off
	v_lshl_add_u64 v[140:141], v[140:141], 0, s[10:11]
	v_mul_f32_e32 v216, s40, v118
	v_mul_f32_e32 v217, s40, v119
	v_mul_f32_e32 v218, s40, v120
	v_mul_f32_e32 v219, s40, v121
	v_exp_f32_e32 v216, v216
	v_exp_f32_e32 v217, v217
	v_exp_f32_e32 v218, v218
	v_exp_f32_e32 v219, v219
	v_add_f32_e32 v216, 1.0, v216
	v_add_f32_e32 v217, 1.0, v217
	v_add_f32_e32 v218, 1.0, v218
	v_add_f32_e32 v219, 1.0, v219
	v_rcp_f32_e32 v216, v216
	v_rcp_f32_e32 v217, v217
	v_rcp_f32_e32 v218, v218
	v_rcp_f32_e32 v219, v219
	v_mul_f32_e32 v118, v118, v216
	v_mul_f32_e32 v119, v119, v217
	v_mul_f32_e32 v120, v120, v218
	v_mul_f32_e32 v121, v121, v219
	v_mul_f32_e32 v118, v118, v54
	v_mul_f32_e32 v119, v119, v55
	v_mul_f32_e32 v120, v120, v56
	v_mul_f32_e32 v121, v121, v57
	v_mul_f32_e32 v220, s40, v86
	v_mul_f32_e32 v221, s40, v87
	v_mul_f32_e32 v222, s40, v88
	v_mul_f32_e32 v223, s40, v89
	v_exp_f32_e32 v220, v220
	v_exp_f32_e32 v221, v221
	v_exp_f32_e32 v222, v222
	v_exp_f32_e32 v223, v223
	v_add_f32_e32 v220, 1.0, v220
	v_add_f32_e32 v221, 1.0, v221
	v_add_f32_e32 v222, 1.0, v222
	v_add_f32_e32 v223, 1.0, v223
	v_rcp_f32_e32 v220, v220
	v_rcp_f32_e32 v221, v221
	v_rcp_f32_e32 v222, v222
	v_rcp_f32_e32 v223, v223
	v_mul_f32_e32 v86, v86, v220
	v_mul_f32_e32 v87, v87, v221
	v_mul_f32_e32 v88, v88, v222
	v_mul_f32_e32 v89, v89, v223
	v_mul_f32_e32 v86, v86, v22
	v_mul_f32_e32 v87, v87, v23
	v_mul_f32_e32 v88, v88, v24
	v_mul_f32_e32 v89, v89, v25
	v_cvt_pk_bf16_f32 v118, v118, v119
	v_cvt_pk_bf16_f32 v119, v120, v121
	v_cvt_pk_bf16_f32 v120, v86, v87
	v_cvt_pk_bf16_f32 v121, v88, v89
	s_nop 1
	v_permlane16_swap_b32_e32 v118, v120
	v_permlane16_swap_b32_e32 v119, v121
	global_store_dwordx4 v[140:141], v[118:121], off
	v_lshl_add_u64 v[140:141], v[140:141], 0, s[10:11]
	v_mul_f32_e32 v216, s40, v114
	v_mul_f32_e32 v217, s40, v115
	v_mul_f32_e32 v218, s40, v116
	v_mul_f32_e32 v219, s40, v117
	v_exp_f32_e32 v216, v216
	v_exp_f32_e32 v217, v217
	v_exp_f32_e32 v218, v218
	v_exp_f32_e32 v219, v219
	v_add_f32_e32 v216, 1.0, v216
	v_add_f32_e32 v217, 1.0, v217
	v_add_f32_e32 v218, 1.0, v218
	v_add_f32_e32 v219, 1.0, v219
	v_rcp_f32_e32 v216, v216
	v_rcp_f32_e32 v217, v217
	v_rcp_f32_e32 v218, v218
	v_rcp_f32_e32 v219, v219
	v_mul_f32_e32 v114, v114, v216
	v_mul_f32_e32 v115, v115, v217
	v_mul_f32_e32 v116, v116, v218
	v_mul_f32_e32 v117, v117, v219
	v_mul_f32_e32 v114, v114, v50
	v_mul_f32_e32 v115, v115, v51
	v_mul_f32_e32 v116, v116, v52
	v_mul_f32_e32 v117, v117, v53
	v_mul_f32_e32 v220, s40, v82
	v_mul_f32_e32 v221, s40, v83
	v_mul_f32_e32 v222, s40, v84
	v_mul_f32_e32 v223, s40, v85
; DEVI unsigned pack2(float a, float b) { return __builtin_bit_cast(unsigned, __builtin_convertvector((f32x2_t){a, b}, bf16x2_t)); }
; DEVI float siluf_(float x) { return x * __builtin_amdgcn_rcpf(1.f + __expf(-x)); }
;     ...
;     if (EPI == EPI_SWIGLU) {
; #pragma unroll
;       for (int nf = 0; nf < 2; nf++) {
;         const int hcol = (n0 >> 1) + wn * 32 + nf * 16 + quad * 4;
;         f32x4 g = acc[nf][mf], u = acc[nf + 2][mf];
;         u32x2 pk;
;         pk[0] = pack2(siluf_(g[0]) * u[0], siluf_(g[1]) * u[1]);
;         pk[1] = pack2(siluf_(g[2]) * u[2], siluf_(g[3]) * u[3]);
;         *(u32x2*)(outb + (size_t)row * DFF + hcol) = pk;
;       }
	v_exp_f32_e32 v220, v220
	v_exp_f32_e32 v221, v221
	v_exp_f32_e32 v222, v222
	v_exp_f32_e32 v223, v223
	v_add_f32_e32 v220, 1.0, v220
	v_add_f32_e32 v221, 1.0, v221
	v_add_f32_e32 v222, 1.0, v222
	v_add_f32_e32 v223, 1.0, v223
	v_rcp_f32_e32 v220, v220
	v_rcp_f32_e32 v221, v221
	v_rcp_f32_e32 v222, v222
	v_rcp_f32_e32 v223, v223
	v_mul_f32_e32 v82, v82, v220
	v_mul_f32_e32 v83, v83, v221
	v_mul_f32_e32 v84, v84, v222
	v_mul_f32_e32 v85, v85, v223
	v_mul_f32_e32 v82, v82, v18
	v_mul_f32_e32 v83, v83, v19
	v_mul_f32_e32 v84, v84, v20
	v_mul_f32_e32 v85, v85, v21
	v_cvt_pk_bf16_f32 v114, v114, v115
	v_cvt_pk_bf16_f32 v115, v116, v117
	v_cvt_pk_bf16_f32 v116, v82, v83
	v_cvt_pk_bf16_f32 v117, v84, v85
	s_nop 1
	v_permlane16_swap_b32_e32 v114, v116
	v_permlane16_swap_b32_e32 v115, v117
	global_store_dwordx4 v[140:141], v[114:117], off
	v_lshl_add_u64 v[140:141], v[140:141], 0, s[10:11]
	v_mul_f32_e32 v216, s40, v110
	v_mul_f32_e32 v217, s40, v111
	v_mul_f32_e32 v218, s40, v112
	v_mul_f32_e32 v219, s40, v113
	v_exp_f32_e32 v216, v216
	v_exp_f32_e32 v217, v217
	v_exp_f32_e32 v218, v218
	v_exp_f32_e32 v219, v219
	v_add_f32_e32 v216, 1.0, v216
	v_add_f32_e32 v217, 1.0, v217
	v_add_f32_e32 v218, 1.0, v218
	v_add_f32_e32 v219, 1.0, v219
	v_rcp_f32_e32 v216, v216
	v_rcp_f32_e32 v217, v217
	v_rcp_f32_e32 v218, v218
	v_rcp_f32_e32 v219, v219
	v_mul_f32_e32 v110, v110, v216
	v_mul_f32_e32 v111, v111, v217
	v_mul_f32_e32 v112, v112, v218
	v_mul_f32_e32 v113, v113, v219
	v_mul_f32_e32 v110, v110, v46
	v_mul_f32_e32 v111, v111, v47
	v_mul_f32_e32 v112, v112, v48
	v_mul_f32_e32 v113, v113, v49
	v_mul_f32_e32 v220, s40, v78
	v_mul_f32_e32 v221, s40, v79
	v_mul_f32_e32 v222, s40, v80
	v_mul_f32_e32 v223, s40, v81
	v_exp_f32_e32 v220, v220
	v_exp_f32_e32 v221, v221
	v_exp_f32_e32 v222, v222
	v_exp_f32_e32 v223, v223
	v_add_f32_e32 v220, 1.0, v220
	v_add_f32_e32 v221, 1.0, v221
	v_add_f32_e32 v222, 1.0, v222
	v_add_f32_e32 v223, 1.0, v223
	v_rcp_f32_e32 v220, v220
	v_rcp_f32_e32 v221, v221
	v_rcp_f32_e32 v222, v222
	v_rcp_f32_e32 v223, v223
	v_mul_f32_e32 v78, v78, v220
	v_mul_f32_e32 v79, v79, v221
	v_mul_f32_e32 v80, v80, v222
	v_mul_f32_e32 v81, v81, v223
	v_mul_f32_e32 v78, v78, v14
	v_mul_f32_e32 v79, v79, v15
	v_mul_f32_e32 v80, v80, v16
	v_mul_f32_e32 v81, v81, v17
	v_cvt_pk_bf16_f32 v110, v110, v111
	v_cvt_pk_bf16_f32 v111, v112, v113
	v_cvt_pk_bf16_f32 v112, v78, v79
	v_cvt_pk_bf16_f32 v113, v80, v81
	s_nop 1
	v_permlane16_swap_b32_e32 v110, v112
	v_permlane16_swap_b32_e32 v111, v113
	global_store_dwordx4 v[140:141], v[110:113], off
	v_lshl_add_u64 v[140:141], v[140:141], 0, s[10:11]
	v_mul_f32_e32 v216, s40, v106
	v_mul_f32_e32 v217, s40, v107
	v_mul_f32_e32 v218, s40, v108
	v_mul_f32_e32 v219, s40, v109
	v_exp_f32_e32 v216, v216
	v_exp_f32_e32 v217, v217
	v_exp_f32_e32 v218, v218
	v_exp_f32_e32 v219, v219
	v_add_f32_e32 v216, 1.0, v216
	v_add_f32_e32 v217, 1.0, v217
	v_add_f32_e32 v218, 1.0, v218
	v_add_f32_e32 v219, 1.0, v219
	v_rcp_f32_e32 v216, v216
	v_rcp_f32_e32 v217, v217
	v_rcp_f32_e32 v218, v218
	v_rcp_f32_e32 v219, v219
	v_mul_f32_e32 v106, v106, v216
	v_mul_f32_e32 v107, v107, v217
	v_mul_f32_e32 v108, v108, v218
	v_mul_f32_e32 v109, v109, v219
	v_mul_f32_e32 v106, v106, v42
	v_mul_f32_e32 v107, v107, v43
	v_mul_f32_e32 v108, v108, v44
	v_mul_f32_e32 v109, v109, v45
	v_mul_f32_e32 v220, s40, v74
	v_mul_f32_e32 v221, s40, v75
	v_mul_f32_e32 v222, s40, v76
	v_mul_f32_e32 v223, s40, v77
	v_exp_f32_e32 v220, v220
	v_exp_f32_e32 v221, v221
	v_exp_f32_e32 v222, v222
	v_exp_f32_e32 v223, v223
	v_add_f32_e32 v220, 1.0, v220
	v_add_f32_e32 v221, 1.0, v221
	v_add_f32_e32 v222, 1.0, v222
	v_add_f32_e32 v223, 1.0, v223
	v_rcp_f32_e32 v220, v220
	v_rcp_f32_e32 v221, v221
	v_rcp_f32_e32 v222, v222
	v_rcp_f32_e32 v223, v223
	v_mul_f32_e32 v74, v74, v220
	v_mul_f32_e32 v75, v75, v221
	v_mul_f32_e32 v76, v76, v222
	v_mul_f32_e32 v77, v77, v223
	v_mul_f32_e32 v74, v74, v10
; DEVI unsigned pack2(float a, float b) { return __builtin_bit_cast(unsigned, __builtin_convertvector((f32x2_t){a, b}, bf16x2_t)); }
; DEVI float siluf_(float x) { return x * __builtin_amdgcn_rcpf(1.f + __expf(-x)); }
; DEVI int xcd_first_tile() { return (blockIdx.x & 7) * (gridDim.x >> 3) + (blockIdx.x >> 3); }
;     ...
;     if (EPI == EPI_SWIGLU) {
; #pragma unroll
;       for (int nf = 0; nf < 2; nf++) {
;         const int hcol = (n0 >> 1) + wn * 32 + nf * 16 + quad * 4;
;         f32x4 g = acc[nf][mf], u = acc[nf + 2][mf];
;         u32x2 pk;
;         pk[0] = pack2(siluf_(g[0]) * u[0], siluf_(g[1]) * u[1]);
;         pk[1] = pack2(siluf_(g[2]) * u[2], siluf_(g[3]) * u[3]);
;         *(u32x2*)(outb + (size_t)row * DFF + hcol) = pk;
;       }
; DEVI void run_phase(const Params& p, int ph, char* smem) {
;     ...
;       for (int t = xcd_first_tile(); t < 66 * 44; t += xcd_tile_step()) {
;         int mt_, nt_; tile_coords(t, 66, 44, mt_, nt_);
;         gemm_tile256<EPI_SWIGLU>(p, xb, 1024, Bt, 1024, mt_ * 256, nt_ * 128, hb, DFF, smem);
	v_mul_f32_e32 v75, v75, v11
	v_mul_f32_e32 v76, v76, v12
	v_mul_f32_e32 v77, v77, v13
	v_cvt_pk_bf16_f32 v106, v106, v107
	v_cvt_pk_bf16_f32 v107, v108, v109
	v_cvt_pk_bf16_f32 v108, v74, v75
	v_cvt_pk_bf16_f32 v109, v76, v77
	s_nop 1
	v_permlane16_swap_b32_e32 v106, v108
	v_permlane16_swap_b32_e32 v107, v109
	global_store_dwordx4 v[140:141], v[106:109], off
	v_lshl_add_u64 v[140:141], v[140:141], 0, s[10:11]
	v_mul_f32_e32 v216, s40, v102
	v_mul_f32_e32 v217, s40, v103
	v_mul_f32_e32 v218, s40, v104
	v_mul_f32_e32 v219, s40, v105
	v_exp_f32_e32 v216, v216
	v_exp_f32_e32 v217, v217
	v_exp_f32_e32 v218, v218
	v_exp_f32_e32 v219, v219
	v_add_f32_e32 v216, 1.0, v216
	v_add_f32_e32 v217, 1.0, v217
	v_add_f32_e32 v218, 1.0, v218
	v_add_f32_e32 v219, 1.0, v219
	v_rcp_f32_e32 v216, v216
	v_rcp_f32_e32 v217, v217
	v_rcp_f32_e32 v218, v218
	v_rcp_f32_e32 v219, v219
	v_mul_f32_e32 v102, v102, v216
	v_mul_f32_e32 v103, v103, v217
	v_mul_f32_e32 v104, v104, v218
	v_mul_f32_e32 v105, v105, v219
	v_mul_f32_e32 v102, v102, v38
	v_mul_f32_e32 v103, v103, v39
	v_mul_f32_e32 v104, v104, v40
	v_mul_f32_e32 v105, v105, v41
	v_mul_f32_e32 v220, s40, v70
	v_mul_f32_e32 v221, s40, v71
	v_mul_f32_e32 v222, s40, v72
	v_mul_f32_e32 v223, s40, v73
	v_exp_f32_e32 v220, v220
	v_exp_f32_e32 v221, v221
	v_exp_f32_e32 v222, v222
	v_exp_f32_e32 v223, v223
	v_add_f32_e32 v220, 1.0, v220
	v_add_f32_e32 v221, 1.0, v221
	v_add_f32_e32 v222, 1.0, v222
	v_add_f32_e32 v223, 1.0, v223
	v_rcp_f32_e32 v220, v220
	v_rcp_f32_e32 v221, v221
	v_rcp_f32_e32 v222, v222
	v_rcp_f32_e32 v223, v223
	v_mul_f32_e32 v70, v70, v220
	v_mul_f32_e32 v71, v71, v221
	v_mul_f32_e32 v72, v72, v222
	v_mul_f32_e32 v73, v73, v223
	v_mul_f32_e32 v70, v70, v6
	v_mul_f32_e32 v71, v71, v7
	v_mul_f32_e32 v72, v72, v8
	v_mul_f32_e32 v73, v73, v9
	v_cvt_pk_bf16_f32 v102, v102, v103
	v_cvt_pk_bf16_f32 v103, v104, v105
	v_cvt_pk_bf16_f32 v104, v70, v71
	v_cvt_pk_bf16_f32 v105, v72, v73
	s_nop 1
	v_permlane16_swap_b32_e32 v102, v104
	v_permlane16_swap_b32_e32 v103, v105
	global_store_dwordx4 v[140:141], v[102:105], off
	v_lshl_add_u64 v[140:141], v[140:141], 0, s[10:11]
	v_mul_f32_e32 v216, s40, v98
	v_mul_f32_e32 v217, s40, v99
	v_mul_f32_e32 v218, s40, v100
	v_mul_f32_e32 v219, s40, v101
	v_exp_f32_e32 v216, v216
	v_exp_f32_e32 v217, v217
	v_exp_f32_e32 v218, v218
	v_exp_f32_e32 v219, v219
	v_add_f32_e32 v216, 1.0, v216
	v_add_f32_e32 v217, 1.0, v217
	v_add_f32_e32 v218, 1.0, v218
	v_add_f32_e32 v219, 1.0, v219
	v_rcp_f32_e32 v216, v216
	v_rcp_f32_e32 v217, v217
	v_rcp_f32_e32 v218, v218
	v_rcp_f32_e32 v219, v219
	v_mul_f32_e32 v98, v98, v216
	v_mul_f32_e32 v99, v99, v217
	v_mul_f32_e32 v100, v100, v218
	v_mul_f32_e32 v101, v101, v219
	v_mul_f32_e32 v98, v98, v34
	v_mul_f32_e32 v99, v99, v35
	v_mul_f32_e32 v100, v100, v36
	v_mul_f32_e32 v101, v101, v37
	v_mul_f32_e32 v220, s40, v66
	v_mul_f32_e32 v221, s40, v67
	v_mul_f32_e32 v222, s40, v68
	v_mul_f32_e32 v223, s40, v69
	v_exp_f32_e32 v220, v220
	v_exp_f32_e32 v221, v221
	v_exp_f32_e32 v222, v222
	v_exp_f32_e32 v223, v223
	v_add_f32_e32 v220, 1.0, v220
	v_add_f32_e32 v221, 1.0, v221
	v_add_f32_e32 v222, 1.0, v222
	v_add_f32_e32 v223, 1.0, v223
	v_rcp_f32_e32 v220, v220
	v_rcp_f32_e32 v221, v221
	v_rcp_f32_e32 v222, v222
	v_rcp_f32_e32 v223, v223
	v_mul_f32_e32 v66, v66, v220
	v_mul_f32_e32 v67, v67, v221
	v_mul_f32_e32 v68, v68, v222
	v_mul_f32_e32 v69, v69, v223
	v_mul_f32_e32 v66, v66, v2
	v_mul_f32_e32 v67, v67, v3
	v_mul_f32_e32 v68, v68, v4
	v_mul_f32_e32 v69, v69, v5
	v_cvt_pk_bf16_f32 v98, v98, v99
	v_cvt_pk_bf16_f32 v99, v100, v101
	v_cvt_pk_bf16_f32 v100, v66, v67
	v_cvt_pk_bf16_f32 v101, v68, v69
	s_nop 1
	v_permlane16_swap_b32_e32 v98, v100
	v_permlane16_swap_b32_e32 v99, v101
	global_store_dwordx4 v[140:141], v[98:101], off
	v_readlane_b32 s42, v250, 7
	s_add_i32 s8, s8, s42
	s_cmpk_gt_i32 s8, 0xb57
	s_cbranch_scc0 .LBB0_124
	s_branch .LBB0_131

; #define LAS __attribute__((address_space(3)))
;     ...
;   const int nk = (nk_part < 0) ? (K >> 5) : nk_part;
;   const int lrow = tid >> 2, lpc = tid & 3;
;   const int lch = lpc ^ ((0x78 >> (((lrow >> 2) & 3) * 2)) & 3);
;   const u16* ga = A + (size_t)(m0 + lrow) * lda + kbeg + lch * 8;
;   const u16* gb = Bt + (size_t)(n0 + lrow) * K + kbeg + lch * 8;
;   const size_t ga1 = (size_t)64 * lda, gb1 = (size_t)64 * K;
;   const unsigned lds0 = (unsigned)(uintptr_t)(LAS char*)smem + (unsigned)__builtin_amdgcn_readfirstlane(wid) * 1024u;
;     ...
;   __syncthreads();
;   G2_STAGE(0); G2_STAGE(1);
;   const int fsw = (0x78 >> (((r16 >> 2) & 3) * 2)) & 3;
;   const int aoff = (wm * 128 + r16) * 64 + ((quad ^ fsw) << 4);
;   const int boff = 16384 + (wn * 64 + r16) * 64 + ((quad ^ fsw) << 4);
; DEVI void run_phase(const Params& p, int ph, char* smem) {
;     ...
;           const int u_ = t - 512, tl_ = u_ / 2, q_ = u_ - tl_ * 2;
;           gemm_tile256<EPI_RESID_ATOMIC>(p, ox, 256, Bt, 256, (64 + (tl_ & 1)) * 256, (tl_ >> 1) * 128, nullptr, 0, smem, q_ * 128, 4, q_);
.LBB0_147:
	s_cmpk_gt_i32 s38, 0x1ff
	s_mov_b64 s[2:3], -1
	s_cbranch_scc0 .LBB0_208
	s_sub_i32 s98, s38, 512
	s_lshr_b32 s41, s98, 1
	s_and_b32 s99, s98, 1
	s_lshr_b32 s13, s41, 1
	s_and_b32 s41, s41, 1
	s_add_i32 s41, s41, 64
	v_readlane_b32 s2, v250, 5
	v_readlane_b32 s3, v250, 6
	v_readlane_b32 s98, v254, 62
	s_mul_i32 s1, s41, 0x20000
	s_add_u32 s4, s2, s1
	s_addc_u32 s5, s3, 0
	s_add_u32 s4, s4, 0xe700000
	s_addc_u32 s5, s5, 0
	s_mul_i32 s1, s98, 0x80000
	s_mul_i32 s12, s13, 0x10000
	s_add_i32 s1, s1, s12
	s_add_u32 s8, s2, s1
	s_addc_u32 s9, s3, 0
	s_add_u32 s8, s8, 0x16c00000
	s_addc_u32 s9, s9, 0
	s_mul_i32 s1, s99, 256
	s_add_u32 s4, s4, s1
	s_addc_u32 s5, s5, 0
	s_mul_i32 s1, s99, 512
	s_add_u32 s8, s8, s1
	s_addc_u32 s9, s9, 0
	s_movk_i32 s0, 0x78
	v_lshrrev_b32_e32 v0, 2, v145
	v_and_b32_e32 v131, 3, v145
	v_bfe_u32 v136, v145, 4, 2
	v_lshlrev_b32_e32 v136, 1, v136
	v_lshrrev_b32_e64 v136, v136, s0
	v_and_b32_e32 v136, 3, v136
	v_xor_b32_e32 v131, v131, v136
	v_lshlrev_b32_e32 v131, 4, v131
	s_movk_i32 s12, 0x200
	v_mad_u32_u24 v0, v0, s12, v131
	v_bfe_u32 v137, v145, 2, 1
	s_movk_i32 s12, 0x1c0
	v_mul_u32_u24_e32 v136, s12, v137
	v_sub_u32_e32 v136, v0, v136
	v_mov_b32_e32 v137, 0
	v_lshl_add_u64 v[134:135], s[8:9], 0, v[136:137]
	v_bfe_u32 v137, v145, 2, 1
	s_mov_b32 s10, 64
	s_mov_b32 s11, 0
	v_lshl_add_u64 v[132:133], s[4:5], 0, v[0:1]
	v_bfe_u32 v136, v145, 2, 2
	v_lshlrev_b32_e32 v136, 1, v136
	v_lshrrev_b32_e64 v136, v136, s0
	v_and_b32_e32 v136, 3, v136
	v_bfe_u32 v137, v145, 4, 2
	v_xor_b32_e32 v136, v136, v137
	v_lshlrev_b32_e32 v136, 4, v136
	v_and_b32_e32 v131, 15, v145
	v_lshl_or_b32 v136, v131, 6, v136
	v_bfe_u32 v137, v145, 6, 1
	v_lshl_or_b32 v137, v137, 12, v136
	v_lshrrev_b32_e32 v0, 7, v145
	v_lshl_or_b32 v136, v0, 13, v136
	v_and_b32_e32 v140, 1, v131
	v_lshl_or_b32 v131, v0, 7, v131
	v_bfe_u32 v0, v145, 4, 2
	v_lshlrev_b32_e32 v0, 3, v0
	v_bfe_u32 v141, v145, 6, 1
	s_lshl_b32 s1, s41, 19
	s_lshl_b32 s12, s13, 8
	s_add_i32 s1, s1, s12
	s_add_u32 s4, s2, s1
	s_addc_u32 s5, s3, 0
	s_add_u32 s4, s4, 0x4200000
	s_addc_u32 s5, s5, 0
	v_lshlrev_b32_e32 v138, 11, v131
	v_lshl_add_u32 v138, v141, 7, v138
	v_bfe_u32 v139, v145, 4, 1
	v_lshl_add_u32 v138, v139, 5, v138
	v_bfe_u32 v139, v145, 5, 1
	v_lshl_add_u32 v138, v139, 4, v138
	v_mov_b32_e32 v139, 0
	v_lshl_add_u64 v[138:139], s[4:5], 0, v[138:139]
	s_and_b32 s1, s41, 1
	s_lshl_b32 s1, s1, 20
	s_lshl_b32 s12, s99, 21
	s_add_i32 s1, s1, s12
	s_lshl_b32 s12, s13, 9
	s_add_i32 s1, s1, s12
	s_add_u32 s8, s2, s1
	s_addc_u32 s9, s3, 0
	s_add_u32 s8, s8, 0x1dcc0000
	s_addc_u32 s9, s9, 0
	v_lshlrev_b32_e32 v140, 12, v131
	v_lshl_add_u32 v140, v141, 8, v140
	v_lshl_add_u32 v140, v0, 1, v140
	v_mov_b32_e32 v141, 0
	v_lshl_add_u64 v[140:141], s[8:9], 0, v[140:141]
	s_mov_b32 s2, 0x8000
	s_mov_b32 s3, 0
	v_lshrrev_b32_e32 v0, 6, v145
	v_lshlrev_b32_e32 v0, 10, v0
	s_nop 0
	v_readfirstlane_b32 s98, v0
	s_mov_b32 s39, m0
	s_mov_b32 s4, 128
	s_mov_b32 s5, 0
	s_barrier
	s_add_i32 s13, s98, 0x0
	s_mov_b32 m0, s13
	v_lshl_add_u64 v[142:143], v[132:133], 0, s[2:3]
	global_load_lds_dwordx4 v[132:133], off
	s_addk_i32 m0, 0x1000
	s_nop 0
	global_load_lds_dwordx4 v[142:143], off
	v_lshl_add_u64 v[142:143], v[142:143], 0, s[2:3]
	s_addk_i32 m0, 0x1000
	s_nop 0
	global_load_lds_dwordx4 v[142:143], off
	v_lshl_add_u64 v[142:143], v[142:143], 0, s[2:3]
	s_addk_i32 m0, 0x1000
	s_nop 0
	global_load_lds_dwordx4 v[142:143], off
	s_addk_i32 m0, 0x1000
	v_lshl_add_u64 v[142:143], v[134:135], 0, s[2:3]
	s_nop 0
	global_load_lds_dwordx4 v[134:135], off
	s_addk_i32 m0, 0x1000
	v_lshl_add_u64 v[132:133], v[132:133], 0, s[10:11]
	s_nop 0
	global_load_lds_dwordx4 v[142:143], off
	v_lshl_add_u64 v[134:135], v[134:135], 0, s[4:5]
	s_nop 0
	s_add_i32 s13, s98, 0x6000
	s_mov_b32 m0, s13
	v_lshl_add_u64 v[142:143], v[132:133], 0, s[2:3]
	global_load_lds_dwordx4 v[132:133], off
	s_addk_i32 m0, 0x1000
	s_nop 0
	global_load_lds_dwordx4 v[142:143], off
	v_lshl_add_u64 v[142:143], v[142:143], 0, s[2:3]
	s_addk_i32 m0, 0x1000
	s_nop 0
	global_load_lds_dwordx4 v[142:143], off
	v_lshl_add_u64 v[142:143], v[142:143], 0, s[2:3]
	s_addk_i32 m0, 0x1000
	s_nop 0
	global_load_lds_dwordx4 v[142:143], off
	s_addk_i32 m0, 0x1000
	v_lshl_add_u64 v[142:143], v[134:135], 0, s[2:3]
	s_nop 0
	global_load_lds_dwordx4 v[134:135], off
	s_addk_i32 m0, 0x1000
	v_lshl_add_u64 v[132:133], v[132:133], 0, s[10:11]
	s_nop 0
	global_load_lds_dwordx4 v[142:143], off
	v_lshl_add_u64 v[134:135], v[134:135], 0, s[4:5]
	s_nop 0
	s_add_i32 s13, s98, 0xc000
	s_mov_b32 m0, s13
	v_lshl_add_u64 v[142:143], v[132:133], 0, s[2:3]
	global_load_lds_dwordx4 v[132:133], off
	s_addk_i32 m0, 0x1000
	s_nop 0
	global_load_lds_dwordx4 v[142:143], off
	v_lshl_add_u64 v[142:143], v[142:143], 0, s[2:3]
	s_addk_i32 m0, 0x1000
	s_nop 0
	global_load_lds_dwordx4 v[142:143], off
	v_lshl_add_u64 v[142:143], v[142:143], 0, s[2:3]
	s_addk_i32 m0, 0x1000
	s_nop 0
	global_load_lds_dwordx4 v[142:143], off
	s_addk_i32 m0, 0x1000
	v_lshl_add_u64 v[142:143], v[134:135], 0, s[2:3]
	s_nop 0
	global_load_lds_dwordx4 v[134:135], off
	s_addk_i32 m0, 0x1000
	v_lshl_add_u64 v[132:133], v[132:133], 0, s[10:11]
	s_nop 0
	global_load_lds_dwordx4 v[142:143], off
	v_lshl_add_u64 v[134:135], v[134:135], 0, s[4:5]
	s_nop 0
	v_mov_b32_e32 v2, 0
	v_mov_b32_e32 v3, 0
	v_mov_b32_e32 v4, 0
	v_mov_b32_e32 v5, 0
	v_mov_b32_e32 v6, 0
	v_mov_b32_e32 v7, 0
	v_mov_b32_e32 v8, 0
	v_mov_b32_e32 v9, 0
	v_mov_b32_e32 v10, 0
	v_mov_b32_e32 v11, 0
	v_mov_b32_e32 v12, 0
	v_mov_b32_e32 v13, 0
	v_mov_b32_e32 v14, 0
	v_mov_b32_e32 v15, 0
	v_mov_b32_e32 v16, 0
	v_mov_b32_e32 v17, 0
	v_mov_b32_e32 v18, 0
; #define LAS __attribute__((address_space(3)))
;     ...
;   f32x4 acc[4][8];
; #pragma unroll
;   for (int i = 0; i < 4; i++)
; #pragma unroll
;     for (int j = 0; j < 8; j++) acc[i][j] = (f32x4){0.f, 0.f, 0.f, 0.f};
;   const int nk = (nk_part < 0) ? (K >> 5) : nk_part;
;   const int lrow = tid >> 2, lpc = tid & 3;
;   const int lch = lpc ^ ((0x78 >> (((lrow >> 2) & 3) * 2)) & 3);
;   const u16* ga = A + (size_t)(m0 + lrow) * lda + kbeg + lch * 8;
;   const u16* gb = Bt + (size_t)(n0 + lrow) * K + kbeg + lch * 8;
;   const size_t ga1 = (size_t)64 * lda, gb1 = (size_t)64 * K;
;   const unsigned lds0 = (unsigned)(uintptr_t)(LAS char*)smem + (unsigned)__builtin_amdgcn_readfirstlane(wid) * 1024u;
;     ...
;   __syncthreads();
;   G2_STAGE(0); G2_STAGE(1);
;   const int fsw = (0x78 >> (((r16 >> 2) & 3) * 2)) & 3;
;   const int aoff = (wm * 128 + r16) * 64 + ((quad ^ fsw) << 4);
;   const int boff = 16384 + (wn * 64 + r16) * 64 + ((quad ^ fsw) << 4);
;   for (int kt = 0; kt < nk; kt++) {
;     if (kt + 1 < nk) asm volatile("s_waitcnt vmcnt(6)" ::: "memory");
;     else asm volatile("s_waitcnt vmcnt(0)" ::: "memory");
;     __builtin_amdgcn_s_barrier();
;     asm volatile("" ::: "memory");
;     if (kt + 2 < nk) G2_STAGE(kt + 2);
;     const char* cS = smem + (kt % 3) * 24576;
;     bf16x8 xa[8], wb[4];
; #pragma unroll
;     for (int f = 0; f < 8; f++) xa[f] = *(const bf16x8*)(cS + aoff + f * 1024);
; #pragma unroll
;     for (int f = 0; f < 4; f++) wb[f] = *(const bf16x8*)(cS + boff + f * 1024);
; #pragma unroll
;     for (int nf = 0; nf < 4; nf++)
; #pragma unroll
;       for (int mf = 0; mf < 8; mf++)
;         acc[nf][mf] = __builtin_amdgcn_mfma_f32_16x16x32_bf16(wb[nf], xa[mf], acc[nf][mf], 0, 0, 0);
;   }
	v_mov_b32_e32 v19, 0
	v_mov_b32_e32 v20, 0
	v_mov_b32_e32 v21, 0
	v_mov_b32_e32 v22, 0
	v_mov_b32_e32 v23, 0
	v_mov_b32_e32 v24, 0
	v_mov_b32_e32 v25, 0
	v_mov_b32_e32 v26, 0
	v_mov_b32_e32 v27, 0
	v_mov_b32_e32 v28, 0
	v_mov_b32_e32 v29, 0
	v_mov_b32_e32 v30, 0
	v_mov_b32_e32 v31, 0
	v_mov_b32_e32 v32, 0
	v_mov_b32_e32 v33, 0
	v_mov_b32_e32 v34, 0
	v_mov_b32_e32 v35, 0
	v_mov_b32_e32 v36, 0
	v_mov_b32_e32 v37, 0
	v_mov_b32_e32 v38, 0
	v_mov_b32_e32 v39, 0
	v_mov_b32_e32 v40, 0
	v_mov_b32_e32 v41, 0
	v_mov_b32_e32 v42, 0
	v_mov_b32_e32 v43, 0
	v_mov_b32_e32 v44, 0
	v_mov_b32_e32 v45, 0
	v_mov_b32_e32 v46, 0
	v_mov_b32_e32 v47, 0
	v_mov_b32_e32 v48, 0
	v_mov_b32_e32 v49, 0
	v_mov_b32_e32 v50, 0
	v_mov_b32_e32 v51, 0
	v_mov_b32_e32 v52, 0
	v_mov_b32_e32 v53, 0
	v_mov_b32_e32 v54, 0
	v_mov_b32_e32 v55, 0
	v_mov_b32_e32 v56, 0
	v_mov_b32_e32 v57, 0
	v_mov_b32_e32 v58, 0
	v_mov_b32_e32 v59, 0
	v_mov_b32_e32 v60, 0
	v_mov_b32_e32 v61, 0
	v_mov_b32_e32 v62, 0
	v_mov_b32_e32 v63, 0
	v_mov_b32_e32 v64, 0
	v_mov_b32_e32 v65, 0
	v_mov_b32_e32 v66, 0
	v_mov_b32_e32 v67, 0
	v_mov_b32_e32 v68, 0
	v_mov_b32_e32 v69, 0
	v_mov_b32_e32 v70, 0
	v_mov_b32_e32 v71, 0
	v_mov_b32_e32 v72, 0
	v_mov_b32_e32 v73, 0
	v_mov_b32_e32 v74, 0
	v_mov_b32_e32 v75, 0
	v_mov_b32_e32 v76, 0
	v_mov_b32_e32 v77, 0
	v_mov_b32_e32 v78, 0
	v_mov_b32_e32 v79, 0
	v_mov_b32_e32 v80, 0
	v_mov_b32_e32 v81, 0
	v_mov_b32_e32 v82, 0
	v_mov_b32_e32 v83, 0
	v_mov_b32_e32 v84, 0
	v_mov_b32_e32 v85, 0
	v_mov_b32_e32 v86, 0
	v_mov_b32_e32 v87, 0
	v_mov_b32_e32 v88, 0
	v_mov_b32_e32 v89, 0
	v_mov_b32_e32 v90, 0
	v_mov_b32_e32 v91, 0
	v_mov_b32_e32 v92, 0
	v_mov_b32_e32 v93, 0
	v_mov_b32_e32 v94, 0
	v_mov_b32_e32 v95, 0
	v_mov_b32_e32 v96, 0
	v_mov_b32_e32 v97, 0
	v_mov_b32_e32 v98, 0
	v_mov_b32_e32 v99, 0
	v_mov_b32_e32 v100, 0
	v_mov_b32_e32 v101, 0
	v_mov_b32_e32 v102, 0
	v_mov_b32_e32 v103, 0
	v_mov_b32_e32 v104, 0
	v_mov_b32_e32 v105, 0
	v_mov_b32_e32 v106, 0
	v_mov_b32_e32 v107, 0
	v_mov_b32_e32 v108, 0
	v_mov_b32_e32 v109, 0
	v_mov_b32_e32 v110, 0
	v_mov_b32_e32 v111, 0
	v_mov_b32_e32 v112, 0
	v_mov_b32_e32 v113, 0
	v_mov_b32_e32 v114, 0
	v_mov_b32_e32 v115, 0
	v_mov_b32_e32 v116, 0
	v_mov_b32_e32 v117, 0
	v_mov_b32_e32 v118, 0
	v_mov_b32_e32 v119, 0
	v_mov_b32_e32 v120, 0
	v_mov_b32_e32 v121, 0
	v_mov_b32_e32 v122, 0
	v_mov_b32_e32 v123, 0
	v_mov_b32_e32 v124, 0
	v_mov_b32_e32 v125, 0
	v_mov_b32_e32 v126, 0
	v_mov_b32_e32 v127, 0
	v_mov_b32_e32 v128, 0
	v_mov_b32_e32 v129, 0
	s_waitcnt vmcnt(12)
	s_barrier
	ds_read_b128 v[146:149], v136 offset:0
	ds_read_b128 v[152:155], v136 offset:1024
	ds_read_b128 v[156:159], v136 offset:2048
	ds_read_b128 v[162:165], v136 offset:3072
	ds_read_b128 v[166:169], v136 offset:4096
	ds_read_b128 v[170:173], v136 offset:5120
	ds_read_b128 v[176:179], v136 offset:6144
	ds_read_b128 v[180:183], v136 offset:7168
	ds_read_b128 v[184:187], v137 offset:16384
	ds_read_b128 v[188:191], v137 offset:17408
	ds_read_b128 v[192:195], v137 offset:18432
	ds_read_b128 v[196:199], v137 offset:19456
	s_movk_i32 s1, 0x6000
	s_mov_b32 s12, 0
	s_waitcnt vmcnt(6) lgkmcnt(0)
	s_barrier
	s_setprio 1
	v_add_u32_e32 v144, s1, v136
	v_mfma_f32_16x16x32_bf16 v[126:129], v[184:187], v[146:149], v[126:129]
	ds_read_b128 v[200:203], v144 offset:0
	v_mfma_f32_16x16x32_bf16 v[122:125], v[184:187], v[152:155], v[122:125]
	ds_read_b128 v[204:207], v144 offset:1024
	v_mfma_f32_16x16x32_bf16 v[118:121], v[184:187], v[156:159], v[118:121]
	ds_read_b128 v[208:211], v144 offset:2048
	v_mfma_f32_16x16x32_bf16 v[114:117], v[184:187], v[162:165], v[114:117]
	ds_read_b128 v[212:215], v144 offset:3072
	v_mfma_f32_16x16x32_bf16 v[110:113], v[184:187], v[166:169], v[110:113]
	ds_read_b128 v[216:219], v144 offset:4096
	v_mfma_f32_16x16x32_bf16 v[106:109], v[184:187], v[170:173], v[106:109]
	ds_read_b128 v[220:223], v144 offset:5120
	v_mfma_f32_16x16x32_bf16 v[102:105], v[184:187], v[176:179], v[102:105]
	ds_read_b128 v[224:227], v144 offset:6144
	v_mfma_f32_16x16x32_bf16 v[98:101], v[184:187], v[180:183], v[98:101]
	ds_read_b128 v[228:231], v144 offset:7168
	v_mfma_f32_16x16x32_bf16 v[94:97], v[188:191], v[146:149], v[94:97]
	v_add_u32_e32 v144, s1, v137
	v_mfma_f32_16x16x32_bf16 v[90:93], v[188:191], v[152:155], v[90:93]
	v_mfma_f32_16x16x32_bf16 v[86:89], v[188:191], v[156:159], v[86:89]
	ds_read_b128 v[232:235], v144 offset:16384
	v_mfma_f32_16x16x32_bf16 v[82:85], v[188:191], v[162:165], v[82:85]
	ds_read_b128 v[236:239], v144 offset:17408
	v_mfma_f32_16x16x32_bf16 v[78:81], v[188:191], v[166:169], v[78:81]
	ds_read_b128 v[240:243], v144 offset:18432
	v_mfma_f32_16x16x32_bf16 v[74:77], v[188:191], v[170:173], v[74:77]
	ds_read_b128 v[244:247], v144 offset:19456
	s_add_i32 s13, s98, s12
	v_mfma_f32_16x16x32_bf16 v[70:73], v[188:191], v[176:179], v[70:73]
	s_mov_b32 m0, s13
	v_lshl_add_u64 v[142:143], v[132:133], 0, s[2:3]
	v_mfma_f32_16x16x32_bf16 v[66:69], v[188:191], v[180:183], v[66:69]
	global_load_lds_dwordx4 v[132:133], off
	s_addk_i32 m0, 0x1000
	v_mfma_f32_16x16x32_bf16 v[62:65], v[192:195], v[146:149], v[62:65]
	v_mfma_f32_16x16x32_bf16 v[58:61], v[192:195], v[152:155], v[58:61]
	v_mfma_f32_16x16x32_bf16 v[54:57], v[192:195], v[156:159], v[54:57]
	global_load_lds_dwordx4 v[142:143], off
	v_lshl_add_u64 v[142:143], v[142:143], 0, s[2:3]
	s_addk_i32 m0, 0x1000
	v_mfma_f32_16x16x32_bf16 v[50:53], v[192:195], v[162:165], v[50:53]
	v_mfma_f32_16x16x32_bf16 v[46:49], v[192:195], v[166:169], v[46:49]
	v_mfma_f32_16x16x32_bf16 v[42:45], v[192:195], v[170:173], v[42:45]
	global_load_lds_dwordx4 v[142:143], off
	v_lshl_add_u64 v[142:143], v[142:143], 0, s[2:3]
	s_addk_i32 m0, 0x1000
	v_mfma_f32_16x16x32_bf16 v[38:41], v[192:195], v[176:179], v[38:41]
	v_mfma_f32_16x16x32_bf16 v[34:37], v[192:195], v[180:183], v[34:37]
	v_mfma_f32_16x16x32_bf16 v[30:33], v[196:199], v[146:149], v[30:33]
	global_load_lds_dwordx4 v[142:143], off
	s_addk_i32 m0, 0x1000
	v_lshl_add_u64 v[142:143], v[134:135], 0, s[2:3]
	v_mfma_f32_16x16x32_bf16 v[26:29], v[196:199], v[152:155], v[26:29]
	v_mfma_f32_16x16x32_bf16 v[22:25], v[196:199], v[156:159], v[22:25]
	v_mfma_f32_16x16x32_bf16 v[18:21], v[196:199], v[162:165], v[18:21]
	global_load_lds_dwordx4 v[134:135], off
	s_addk_i32 m0, 0x1000
	v_lshl_add_u64 v[132:133], v[132:133], 0, s[10:11]
	v_mfma_f32_16x16x32_bf16 v[14:17], v[196:199], v[166:169], v[14:17]
	v_mfma_f32_16x16x32_bf16 v[10:13], v[196:199], v[170:173], v[10:13]
	v_mfma_f32_16x16x32_bf16 v[6:9], v[196:199], v[176:179], v[6:9]
	global_load_lds_dwordx4 v[142:143], off
	v_lshl_add_u64 v[134:135], v[134:135], 0, s[4:5]
	v_mfma_f32_16x16x32_bf16 v[2:5], v[196:199], v[180:183], v[2:5]
	s_setprio 0
	s_mov_b32 s12, s1
	s_add_i32 s1, s1, 0x6000
	s_cmp_eq_u32 s1, 0x12000
	s_cselect_b32 s1, 0, s1
	s_waitcnt vmcnt(6) lgkmcnt(0)
	s_barrier
;     ...
;   for (int kt = 0; kt < nk; kt++) {
;     if (kt + 1 < nk) asm volatile("s_waitcnt vmcnt(6)" ::: "memory");
;     else asm volatile("s_waitcnt vmcnt(0)" ::: "memory");
;     __builtin_amdgcn_s_barrier();
;     asm volatile("" ::: "memory");
;     if (kt + 2 < nk) G2_STAGE(kt + 2);
;     const char* cS = smem + (kt % 3) * 24576;
;     bf16x8 xa[8], wb[4];
; #pragma unroll
;     for (int f = 0; f < 8; f++) xa[f] = *(const bf16x8*)(cS + aoff + f * 1024);
; #pragma unroll
;     for (int f = 0; f < 4; f++) wb[f] = *(const bf16x8*)(cS + boff + f * 1024);
; #pragma unroll
;     for (int nf = 0; nf < 4; nf++)
; #pragma unroll
;       for (int mf = 0; mf < 8; mf++)
;         acc[nf][mf] = __builtin_amdgcn_mfma_f32_16x16x32_bf16(wb[nf], xa[mf], acc[nf][mf], 0, 0, 0);
;   }
	s_setprio 1
	v_add_u32_e32 v144, s1, v136
	v_mfma_f32_16x16x32_bf16 v[126:129], v[232:235], v[200:203], v[126:129]
	ds_read_b128 v[146:149], v144 offset:0
	v_mfma_f32_16x16x32_bf16 v[122:125], v[232:235], v[204:207], v[122:125]
	ds_read_b128 v[152:155], v144 offset:1024
	v_mfma_f32_16x16x32_bf16 v[118:121], v[232:235], v[208:211], v[118:121]
	ds_read_b128 v[156:159], v144 offset:2048
	v_mfma_f32_16x16x32_bf16 v[114:117], v[232:235], v[212:215], v[114:117]
	ds_read_b128 v[162:165], v144 offset:3072
	v_mfma_f32_16x16x32_bf16 v[110:113], v[232:235], v[216:219], v[110:113]
	ds_read_b128 v[166:169], v144 offset:4096
	v_mfma_f32_16x16x32_bf16 v[106:109], v[232:235], v[220:223], v[106:109]
	ds_read_b128 v[170:173], v144 offset:5120
	v_mfma_f32_16x16x32_bf16 v[102:105], v[232:235], v[224:227], v[102:105]
	ds_read_b128 v[176:179], v144 offset:6144
	v_mfma_f32_16x16x32_bf16 v[98:101], v[232:235], v[228:231], v[98:101]
	ds_read_b128 v[180:183], v144 offset:7168
	v_mfma_f32_16x16x32_bf16 v[94:97], v[236:239], v[200:203], v[94:97]
	v_add_u32_e32 v144, s1, v137
	v_mfma_f32_16x16x32_bf16 v[90:93], v[236:239], v[204:207], v[90:93]
	v_mfma_f32_16x16x32_bf16 v[86:89], v[236:239], v[208:211], v[86:89]
	ds_read_b128 v[184:187], v144 offset:16384
	v_mfma_f32_16x16x32_bf16 v[82:85], v[236:239], v[212:215], v[82:85]
	ds_read_b128 v[188:191], v144 offset:17408
	v_mfma_f32_16x16x32_bf16 v[78:81], v[236:239], v[216:219], v[78:81]
	ds_read_b128 v[192:195], v144 offset:18432
	v_mfma_f32_16x16x32_bf16 v[74:77], v[236:239], v[220:223], v[74:77]
	ds_read_b128 v[196:199], v144 offset:19456
	v_mfma_f32_16x16x32_bf16 v[70:73], v[236:239], v[224:227], v[70:73]
	v_mfma_f32_16x16x32_bf16 v[66:69], v[236:239], v[228:231], v[66:69]
	v_mfma_f32_16x16x32_bf16 v[62:65], v[240:243], v[200:203], v[62:65]
	v_mfma_f32_16x16x32_bf16 v[58:61], v[240:243], v[204:207], v[58:61]
	v_mfma_f32_16x16x32_bf16 v[54:57], v[240:243], v[208:211], v[54:57]
	v_mfma_f32_16x16x32_bf16 v[50:53], v[240:243], v[212:215], v[50:53]
	v_mfma_f32_16x16x32_bf16 v[46:49], v[240:243], v[216:219], v[46:49]
	v_mfma_f32_16x16x32_bf16 v[42:45], v[240:243], v[220:223], v[42:45]
	v_mfma_f32_16x16x32_bf16 v[38:41], v[240:243], v[224:227], v[38:41]
	v_mfma_f32_16x16x32_bf16 v[34:37], v[240:243], v[228:231], v[34:37]
	v_mfma_f32_16x16x32_bf16 v[30:33], v[244:247], v[200:203], v[30:33]
	v_mfma_f32_16x16x32_bf16 v[26:29], v[244:247], v[204:207], v[26:29]
	v_mfma_f32_16x16x32_bf16 v[22:25], v[244:247], v[208:211], v[22:25]
	v_mfma_f32_16x16x32_bf16 v[18:21], v[244:247], v[212:215], v[18:21]
	v_mfma_f32_16x16x32_bf16 v[14:17], v[244:247], v[216:219], v[14:17]
	v_mfma_f32_16x16x32_bf16 v[10:13], v[244:247], v[220:223], v[10:13]
	v_mfma_f32_16x16x32_bf16 v[6:9], v[244:247], v[224:227], v[6:9]
	v_mfma_f32_16x16x32_bf16 v[2:5], v[244:247], v[228:231], v[2:5]
	s_setprio 0
	s_mov_b32 s12, s1
	s_add_i32 s1, s1, 0x6000
	s_cmp_eq_u32 s1, 0x12000
	s_cselect_b32 s1, 0, s1
	s_waitcnt vmcnt(0) lgkmcnt(0)
	s_barrier
	s_setprio 1
	v_add_u32_e32 v144, s1, v136
	v_mfma_f32_16x16x32_bf16 v[126:129], v[184:187], v[146:149], v[126:129]
	ds_read_b128 v[200:203], v144 offset:0
	v_mfma_f32_16x16x32_bf16 v[122:125], v[184:187], v[152:155], v[122:125]
	ds_read_b128 v[204:207], v144 offset:1024
	v_mfma_f32_16x16x32_bf16 v[118:121], v[184:187], v[156:159], v[118:121]
	ds_read_b128 v[208:211], v144 offset:2048
	v_mfma_f32_16x16x32_bf16 v[114:117], v[184:187], v[162:165], v[114:117]
	ds_read_b128 v[212:215], v144 offset:3072
	v_mfma_f32_16x16x32_bf16 v[110:113], v[184:187], v[166:169], v[110:113]
	ds_read_b128 v[216:219], v144 offset:4096
	v_mfma_f32_16x16x32_bf16 v[106:109], v[184:187], v[170:173], v[106:109]
	ds_read_b128 v[220:223], v144 offset:5120
	v_mfma_f32_16x16x32_bf16 v[102:105], v[184:187], v[176:179], v[102:105]
	ds_read_b128 v[224:227], v144 offset:6144
	v_mfma_f32_16x16x32_bf16 v[98:101], v[184:187], v[180:183], v[98:101]
	ds_read_b128 v[228:231], v144 offset:7168
	v_mfma_f32_16x16x32_bf16 v[94:97], v[188:191], v[146:149], v[94:97]
	v_add_u32_e32 v144, s1, v137
	v_mfma_f32_16x16x32_bf16 v[90:93], v[188:191], v[152:155], v[90:93]
	v_mfma_f32_16x16x32_bf16 v[86:89], v[188:191], v[156:159], v[86:89]
	ds_read_b128 v[232:235], v144 offset:16384
	v_mfma_f32_16x16x32_bf16 v[82:85], v[188:191], v[162:165], v[82:85]
	ds_read_b128 v[236:239], v144 offset:17408
	v_mfma_f32_16x16x32_bf16 v[78:81], v[188:191], v[166:169], v[78:81]
	ds_read_b128 v[240:243], v144 offset:18432
	v_mfma_f32_16x16x32_bf16 v[74:77], v[188:191], v[170:173], v[74:77]
	ds_read_b128 v[244:247], v144 offset:19456
	v_mfma_f32_16x16x32_bf16 v[70:73], v[188:191], v[176:179], v[70:73]
	v_mfma_f32_16x16x32_bf16 v[66:69], v[188:191], v[180:183], v[66:69]
	v_mfma_f32_16x16x32_bf16 v[62:65], v[192:195], v[146:149], v[62:65]
	v_mfma_f32_16x16x32_bf16 v[58:61], v[192:195], v[152:155], v[58:61]
	v_mfma_f32_16x16x32_bf16 v[54:57], v[192:195], v[156:159], v[54:57]
	v_mfma_f32_16x16x32_bf16 v[50:53], v[192:195], v[162:165], v[50:53]
	v_mfma_f32_16x16x32_bf16 v[46:49], v[192:195], v[166:169], v[46:49]
	v_mfma_f32_16x16x32_bf16 v[42:45], v[192:195], v[170:173], v[42:45]
	v_mfma_f32_16x16x32_bf16 v[38:41], v[192:195], v[176:179], v[38:41]
	v_mfma_f32_16x16x32_bf16 v[34:37], v[192:195], v[180:183], v[34:37]
	v_mfma_f32_16x16x32_bf16 v[30:33], v[196:199], v[146:149], v[30:33]
	v_mfma_f32_16x16x32_bf16 v[26:29], v[196:199], v[152:155], v[26:29]
	v_mfma_f32_16x16x32_bf16 v[22:25], v[196:199], v[156:159], v[22:25]
	v_mfma_f32_16x16x32_bf16 v[18:21], v[196:199], v[162:165], v[18:21]
	v_mfma_f32_16x16x32_bf16 v[14:17], v[196:199], v[166:169], v[14:17]
	v_mfma_f32_16x16x32_bf16 v[10:13], v[196:199], v[170:173], v[10:13]
	v_mfma_f32_16x16x32_bf16 v[6:9], v[196:199], v[176:179], v[6:9]
	v_mfma_f32_16x16x32_bf16 v[2:5], v[196:199], v[180:183], v[2:5]
	s_setprio 0
	s_mov_b32 s12, s1
	s_add_i32 s1, s1, 0x6000
	s_cmp_eq_u32 s1, 0x12000
	s_cselect_b32 s1, 0, s1
	s_mov_b32 s4, 0x8000
	s_mov_b32 s5, 0
	s_mov_b32 s8, 0x10000
	s_mov_b32 s9, 0
	s_mov_b32 s40, 0x3fd744fd
	s_waitcnt lgkmcnt(0)
; DEVI float blo(unsigned u) { return __uint_as_float(u << 16); }
; DEVI float bhi(unsigned u) { return __uint_as_float(u & 0xffff0000u); }
;     ...
;     for (int nf = 0; nf < 4; nf++)
; #pragma unroll
;       for (int mf = 0; mf < 8; mf++)
;         acc[nf][mf] = __builtin_amdgcn_mfma_f32_16x16x32_bf16(wb[nf], xa[mf], acc[nf][mf], 0, 0, 0);
;     ...
;         if (EPI == EPI_RESID || EPI == EPI_RESID_ATOMIC) {
;           f32x4 x = a;
;           if (EPI == EPI_RESID || kpart == 0) {
;             const u32x2 xr = *(const u32x2*)((const u16*)(p.ws + WS_XB) + (size_t)row * 1024 + col);
;             x[0] += ALPHA * blo(xr[0]); x[1] += ALPHA * bhi(xr[0]); x[2] += ALPHA * blo(xr[1]); x[3] += ALPHA * bhi(xr[1]);
;           }
;           if (EPI == EPI_RESID) *(f32x4*)((float*)(p.ws + WS_XF) + (size_t)row * 1024 + col) = x;
;           else *(f32x4*)((float*)(p.ws + WS_SLAB) + ((size_t)kpart * 512 + (row - T_P)) * 1024 + col) = x;
	v_mfma_f32_16x16x32_bf16 v[126:129], v[232:235], v[200:203], v[126:129]
	v_mfma_f32_16x16x32_bf16 v[122:125], v[232:235], v[204:207], v[122:125]
	v_mfma_f32_16x16x32_bf16 v[118:121], v[232:235], v[208:211], v[118:121]
	v_mfma_f32_16x16x32_bf16 v[114:117], v[232:235], v[212:215], v[114:117]
	v_mfma_f32_16x16x32_bf16 v[110:113], v[232:235], v[216:219], v[110:113]
	v_mfma_f32_16x16x32_bf16 v[106:109], v[232:235], v[220:223], v[106:109]
	v_mfma_f32_16x16x32_bf16 v[102:105], v[232:235], v[224:227], v[102:105]
	v_mfma_f32_16x16x32_bf16 v[98:101], v[232:235], v[228:231], v[98:101]
	v_mfma_f32_16x16x32_bf16 v[94:97], v[236:239], v[200:203], v[94:97]
	v_mfma_f32_16x16x32_bf16 v[90:93], v[236:239], v[204:207], v[90:93]
	v_mfma_f32_16x16x32_bf16 v[86:89], v[236:239], v[208:211], v[86:89]
	v_mfma_f32_16x16x32_bf16 v[82:85], v[236:239], v[212:215], v[82:85]
	v_mfma_f32_16x16x32_bf16 v[78:81], v[236:239], v[216:219], v[78:81]
	v_mfma_f32_16x16x32_bf16 v[74:77], v[236:239], v[220:223], v[74:77]
	v_mfma_f32_16x16x32_bf16 v[70:73], v[236:239], v[224:227], v[70:73]
	v_mfma_f32_16x16x32_bf16 v[66:69], v[236:239], v[228:231], v[66:69]
	v_mfma_f32_16x16x32_bf16 v[62:65], v[240:243], v[200:203], v[62:65]
	v_mfma_f32_16x16x32_bf16 v[58:61], v[240:243], v[204:207], v[58:61]
	v_mfma_f32_16x16x32_bf16 v[54:57], v[240:243], v[208:211], v[54:57]
	v_mfma_f32_16x16x32_bf16 v[50:53], v[240:243], v[212:215], v[50:53]
	v_mfma_f32_16x16x32_bf16 v[46:49], v[240:243], v[216:219], v[46:49]
	v_mfma_f32_16x16x32_bf16 v[42:45], v[240:243], v[220:223], v[42:45]
	v_mfma_f32_16x16x32_bf16 v[38:41], v[240:243], v[224:227], v[38:41]
	v_mfma_f32_16x16x32_bf16 v[34:37], v[240:243], v[228:231], v[34:37]
	v_mfma_f32_16x16x32_bf16 v[30:33], v[244:247], v[200:203], v[30:33]
	v_mfma_f32_16x16x32_bf16 v[26:29], v[244:247], v[204:207], v[26:29]
	v_mfma_f32_16x16x32_bf16 v[22:25], v[244:247], v[208:211], v[22:25]
	v_mfma_f32_16x16x32_bf16 v[18:21], v[244:247], v[212:215], v[18:21]
	v_mfma_f32_16x16x32_bf16 v[14:17], v[244:247], v[216:219], v[14:17]
	v_mfma_f32_16x16x32_bf16 v[10:13], v[244:247], v[220:223], v[10:13]
	v_mfma_f32_16x16x32_bf16 v[6:9], v[244:247], v[224:227], v[6:9]
	v_mfma_f32_16x16x32_bf16 v[2:5], v[244:247], v[228:231], v[2:5]
	s_mov_b32 m0, s39
	s_cmp_eq_u32 s99, 0
	s_cbranch_scc1 .Lta8_first
	s_nop 7
	global_store_dwordx4 v[140:141], v[126:129], off offset:0
	global_store_dwordx4 v[140:141], v[94:97], off offset:64
	global_store_dwordx4 v[140:141], v[62:65], off offset:128
	global_store_dwordx4 v[140:141], v[30:33], off offset:192
	v_lshl_add_u64 v[140:141], v[140:141], 0, s[8:9]
	global_store_dwordx4 v[140:141], v[122:125], off offset:0
	global_store_dwordx4 v[140:141], v[90:93], off offset:64
	global_store_dwordx4 v[140:141], v[58:61], off offset:128
	global_store_dwordx4 v[140:141], v[26:29], off offset:192
	v_lshl_add_u64 v[140:141], v[140:141], 0, s[8:9]
	global_store_dwordx4 v[140:141], v[118:121], off offset:0
	global_store_dwordx4 v[140:141], v[86:89], off offset:64
	global_store_dwordx4 v[140:141], v[54:57], off offset:128
	global_store_dwordx4 v[140:141], v[22:25], off offset:192
	v_lshl_add_u64 v[140:141], v[140:141], 0, s[8:9]
	global_store_dwordx4 v[140:141], v[114:117], off offset:0
	global_store_dwordx4 v[140:141], v[82:85], off offset:64
	global_store_dwordx4 v[140:141], v[50:53], off offset:128
	global_store_dwordx4 v[140:141], v[18:21], off offset:192
	v_lshl_add_u64 v[140:141], v[140:141], 0, s[8:9]
	global_store_dwordx4 v[140:141], v[110:113], off offset:0
	global_store_dwordx4 v[140:141], v[78:81], off offset:64
	global_store_dwordx4 v[140:141], v[46:49], off offset:128
	global_store_dwordx4 v[140:141], v[14:17], off offset:192
	v_lshl_add_u64 v[140:141], v[140:141], 0, s[8:9]
	global_store_dwordx4 v[140:141], v[106:109], off offset:0
	global_store_dwordx4 v[140:141], v[74:77], off offset:64
	global_store_dwordx4 v[140:141], v[42:45], off offset:128
	global_store_dwordx4 v[140:141], v[10:13], off offset:192
	v_lshl_add_u64 v[140:141], v[140:141], 0, s[8:9]
	global_store_dwordx4 v[140:141], v[102:105], off offset:0
	global_store_dwordx4 v[140:141], v[70:73], off offset:64
	global_store_dwordx4 v[140:141], v[38:41], off offset:128
	global_store_dwordx4 v[140:141], v[6:9], off offset:192
	v_lshl_add_u64 v[140:141], v[140:141], 0, s[8:9]
	global_store_dwordx4 v[140:141], v[98:101], off offset:0
	global_store_dwordx4 v[140:141], v[66:69], off offset:64
	global_store_dwordx4 v[140:141], v[34:37], off offset:128
	global_store_dwordx4 v[140:141], v[2:5], off offset:192
	s_branch .LBB0_146

; #define LAS __attribute__((address_space(3)))
;     ...
;   const int nk = (nk_part < 0) ? (K >> 5) : nk_part;
;   const int lrow = tid >> 2, lpc = tid & 3;
;   const int lch = lpc ^ ((0x78 >> (((lrow >> 2) & 3) * 2)) & 3);
;   const u16* ga = A + (size_t)(m0 + lrow) * lda + kbeg + lch * 8;
;   const u16* gb = Bt + (size_t)(n0 + lrow) * K + kbeg + lch * 8;
;   const size_t ga1 = (size_t)64 * lda, gb1 = (size_t)64 * K;
;   const unsigned lds0 = (unsigned)(uintptr_t)(LAS char*)smem + (unsigned)__builtin_amdgcn_readfirstlane(wid) * 1024u;
;     ...
;   __syncthreads();
;   G2_STAGE(0); G2_STAGE(1);
.LBB0_208:
	s_and_b64 vcc, exec, s[2:3]
	s_cbranch_vccz .LBB0_146
	s_lshr_b32 s45, s38, 6
	s_and_b32 s46, s38, 63
	s_lshr_b32 s42, s46, 3
	s_and_b32 s46, s46, 7
	s_lshl_b32 s45, s45, 3
	s_add_i32 s45, s45, s46
	v_readlane_b32 s2, v250, 5
	v_readlane_b32 s3, v250, 6
	v_readlane_b32 s46, v254, 62
	s_mul_i32 s40, s45, 0x20000
	s_add_u32 s4, s2, s40
	s_addc_u32 s5, s3, 0
	s_add_u32 s4, s4, 0xe700000
	s_addc_u32 s5, s5, 0
	s_mul_i32 s40, s46, 0x80000
	s_mul_i32 s41, s42, 0x10000
	s_add_i32 s40, s40, s41
	s_add_u32 s10, s2, s40
	s_addc_u32 s11, s3, 0
	s_add_u32 s10, s10, 0x16c00000
	s_addc_u32 s11, s11, 0
	s_movk_i32 s39, 0x78
	v_lshrrev_b32_e32 v0, 2, v145
	v_and_b32_e32 v131, 3, v145
	v_bfe_u32 v136, v145, 4, 2
	v_lshlrev_b32_e32 v136, 1, v136
	v_lshrrev_b32_e64 v136, v136, s39
	v_and_b32_e32 v136, 3, v136
	v_xor_b32_e32 v131, v131, v136
	v_lshlrev_b32_e32 v131, 4, v131
	s_movk_i32 s41, 0x200
	v_mad_u32_u24 v0, v0, s41, v131
	v_bfe_u32 v137, v145, 2, 1
	s_movk_i32 s41, 0x1c0
	v_mul_u32_u24_e32 v136, s41, v137
	v_sub_u32_e32 v136, v0, v136
	v_mov_b32_e32 v137, 0
	v_lshl_add_u64 v[134:135], s[10:11], 0, v[136:137]
	v_bfe_u32 v137, v145, 2, 1
	s_mov_b32 s12, 64
	s_mov_b32 s13, 0
	v_lshl_add_u64 v[132:133], s[4:5], 0, v[0:1]
	v_bfe_u32 v136, v145, 2, 2
	v_lshlrev_b32_e32 v136, 1, v136
	v_lshrrev_b32_e64 v136, v136, s39
	v_and_b32_e32 v136, 3, v136
	v_bfe_u32 v137, v145, 4, 2
	v_xor_b32_e32 v136, v136, v137
	v_lshlrev_b32_e32 v136, 4, v136
	v_and_b32_e32 v131, 15, v145
	v_lshl_or_b32 v136, v131, 6, v136
	v_bfe_u32 v137, v145, 6, 1
	v_lshl_or_b32 v137, v137, 12, v136
	v_lshrrev_b32_e32 v0, 7, v145
	v_lshl_or_b32 v136, v0, 13, v136
	v_and_b32_e32 v140, 1, v131
	v_lshl_or_b32 v131, v0, 7, v131
	v_bfe_u32 v0, v145, 4, 2
	v_lshlrev_b32_e32 v0, 3, v0
	v_bfe_u32 v141, v145, 6, 1
	s_lshl_b32 s40, s45, 19
	s_lshl_b32 s41, s42, 8
	s_add_i32 s40, s40, s41
	s_add_u32 s4, s2, s40
	s_addc_u32 s5, s3, 0
	s_add_u32 s4, s4, 0x4200000
	s_addc_u32 s5, s5, 0
	v_lshlrev_b32_e32 v138, 11, v131
	v_lshl_add_u32 v138, v141, 7, v138
	v_bfe_u32 v139, v145, 4, 1
	v_lshl_add_u32 v138, v139, 5, v138
	v_bfe_u32 v139, v145, 5, 1
	v_lshl_add_u32 v138, v139, 4, v138
	v_mov_b32_e32 v139, 0
	v_lshl_add_u64 v[138:139], s[4:5], 0, v[138:139]
	s_lshl_b32 s40, s45, 20
	s_lshl_b32 s41, s42, 9
	s_add_i32 s40, s40, s41
	s_add_u32 s10, s2, s40
	s_addc_u32 s11, s3, 0
	v_lshlrev_b32_e32 v140, 12, v131
	v_lshl_add_u32 v140, v141, 8, v140
	v_lshl_add_u32 v140, v0, 1, v140
	v_mov_b32_e32 v141, 0
	v_lshl_add_u64 v[140:141], s[10:11], 0, v[140:141]
	s_mov_b32 s2, 0x8000
	s_mov_b32 s3, 0
	v_lshrrev_b32_e32 v0, 6, v145
	v_lshlrev_b32_e32 v0, 10, v0
	s_nop 0
	v_readfirstlane_b32 s46, v0
	s_mov_b32 s43, m0
	s_mov_b32 s4, 128
	s_mov_b32 s5, 0
	s_barrier
	s_add_i32 s42, s46, 0x0
	s_mov_b32 m0, s42
	v_lshl_add_u64 v[142:143], v[132:133], 0, s[2:3]
	global_load_lds_dwordx4 v[132:133], off
	s_addk_i32 m0, 0x1000
	s_nop 0
	global_load_lds_dwordx4 v[142:143], off
	v_lshl_add_u64 v[142:143], v[142:143], 0, s[2:3]
	s_addk_i32 m0, 0x1000
	s_nop 0
	global_load_lds_dwordx4 v[142:143], off
	v_lshl_add_u64 v[142:143], v[142:143], 0, s[2:3]
	s_addk_i32 m0, 0x1000
	s_nop 0
	global_load_lds_dwordx4 v[142:143], off
	s_addk_i32 m0, 0x1000
	v_lshl_add_u64 v[142:143], v[134:135], 0, s[2:3]
	s_nop 0
	global_load_lds_dwordx4 v[134:135], off
	s_addk_i32 m0, 0x1000
	v_lshl_add_u64 v[132:133], v[132:133], 0, s[12:13]
	s_nop 0
	global_load_lds_dwordx4 v[142:143], off
	v_lshl_add_u64 v[134:135], v[134:135], 0, s[4:5]
	s_nop 0
	s_add_i32 s42, s46, 0x6000
	s_mov_b32 m0, s42
	v_lshl_add_u64 v[142:143], v[132:133], 0, s[2:3]
	global_load_lds_dwordx4 v[132:133], off
	s_addk_i32 m0, 0x1000
	s_nop 0
	global_load_lds_dwordx4 v[142:143], off
	v_lshl_add_u64 v[142:143], v[142:143], 0, s[2:3]
	s_addk_i32 m0, 0x1000
	s_nop 0
	global_load_lds_dwordx4 v[142:143], off
	v_lshl_add_u64 v[142:143], v[142:143], 0, s[2:3]
	s_addk_i32 m0, 0x1000
	s_nop 0
	global_load_lds_dwordx4 v[142:143], off
	s_addk_i32 m0, 0x1000
	v_lshl_add_u64 v[142:143], v[134:135], 0, s[2:3]
	s_nop 0
	global_load_lds_dwordx4 v[134:135], off
	s_addk_i32 m0, 0x1000
	v_lshl_add_u64 v[132:133], v[132:133], 0, s[12:13]
	s_nop 0
	global_load_lds_dwordx4 v[142:143], off
	v_lshl_add_u64 v[134:135], v[134:135], 0, s[4:5]
	s_nop 0
	s_add_i32 s42, s46, 0xc000
	s_mov_b32 m0, s42
	v_lshl_add_u64 v[142:143], v[132:133], 0, s[2:3]
	global_load_lds_dwordx4 v[132:133], off
	s_addk_i32 m0, 0x1000
	s_nop 0
	global_load_lds_dwordx4 v[142:143], off
	v_lshl_add_u64 v[142:143], v[142:143], 0, s[2:3]
	s_addk_i32 m0, 0x1000
	s_nop 0
	global_load_lds_dwordx4 v[142:143], off
	v_lshl_add_u64 v[142:143], v[142:143], 0, s[2:3]
	s_addk_i32 m0, 0x1000
	s_nop 0
	global_load_lds_dwordx4 v[142:143], off
	s_addk_i32 m0, 0x1000
	v_lshl_add_u64 v[142:143], v[134:135], 0, s[2:3]
	s_nop 0
	global_load_lds_dwordx4 v[134:135], off
	s_addk_i32 m0, 0x1000
	v_lshl_add_u64 v[132:133], v[132:133], 0, s[12:13]
	s_nop 0
	global_load_lds_dwordx4 v[142:143], off
	v_lshl_add_u64 v[134:135], v[134:135], 0, s[4:5]
	s_nop 0
	v_mov_b32_e32 v2, 0
	v_mov_b32_e32 v3, 0
	v_mov_b32_e32 v4, 0
	v_mov_b32_e32 v5, 0
	v_mov_b32_e32 v6, 0
	v_mov_b32_e32 v7, 0
	v_mov_b32_e32 v8, 0
	v_mov_b32_e32 v9, 0
	v_mov_b32_e32 v10, 0
	v_mov_b32_e32 v11, 0
	v_mov_b32_e32 v12, 0
	v_mov_b32_e32 v13, 0
	v_mov_b32_e32 v14, 0
	v_mov_b32_e32 v15, 0
	v_mov_b32_e32 v16, 0
	v_mov_b32_e32 v17, 0
	v_mov_b32_e32 v18, 0
	v_mov_b32_e32 v19, 0
	v_mov_b32_e32 v20, 0
	v_mov_b32_e32 v21, 0
	v_mov_b32_e32 v22, 0
	v_mov_b32_e32 v23, 0
	v_mov_b32_e32 v24, 0
	v_mov_b32_e32 v25, 0
	v_mov_b32_e32 v26, 0
	v_mov_b32_e32 v27, 0
	v_mov_b32_e32 v28, 0
	v_mov_b32_e32 v29, 0
; #define LAS __attribute__((address_space(3)))
;     ...
;   f32x4 acc[4][8];
; #pragma unroll
;   for (int i = 0; i < 4; i++)
; #pragma unroll
;     for (int j = 0; j < 8; j++) acc[i][j] = (f32x4){0.f, 0.f, 0.f, 0.f};
;   const int nk = (nk_part < 0) ? (K >> 5) : nk_part;
;   const int lrow = tid >> 2, lpc = tid & 3;
;   const int lch = lpc ^ ((0x78 >> (((lrow >> 2) & 3) * 2)) & 3);
;   const u16* ga = A + (size_t)(m0 + lrow) * lda + kbeg + lch * 8;
;   const u16* gb = Bt + (size_t)(n0 + lrow) * K + kbeg + lch * 8;
;   const size_t ga1 = (size_t)64 * lda, gb1 = (size_t)64 * K;
;   const unsigned lds0 = (unsigned)(uintptr_t)(LAS char*)smem + (unsigned)__builtin_amdgcn_readfirstlane(wid) * 1024u;
;     ...
;   __syncthreads();
;   G2_STAGE(0); G2_STAGE(1);
;   const int fsw = (0x78 >> (((r16 >> 2) & 3) * 2)) & 3;
;   const int aoff = (wm * 128 + r16) * 64 + ((quad ^ fsw) << 4);
;   const int boff = 16384 + (wn * 64 + r16) * 64 + ((quad ^ fsw) << 4);
;   for (int kt = 0; kt < nk; kt++) {
;     if (kt + 1 < nk) asm volatile("s_waitcnt vmcnt(6)" ::: "memory");
;     else asm volatile("s_waitcnt vmcnt(0)" ::: "memory");
;     __builtin_amdgcn_s_barrier();
;     asm volatile("" ::: "memory");
;     if (kt + 2 < nk) G2_STAGE(kt + 2);
;     const char* cS = smem + (kt % 3) * 24576;
;     bf16x8 xa[8], wb[4];
; #pragma unroll
;     for (int f = 0; f < 8; f++) xa[f] = *(const bf16x8*)(cS + aoff + f * 1024);
; #pragma unroll
;     for (int f = 0; f < 4; f++) wb[f] = *(const bf16x8*)(cS + boff + f * 1024);
; #pragma unroll
;     for (int nf = 0; nf < 4; nf++)
; #pragma unroll
;       for (int mf = 0; mf < 8; mf++)
;         acc[nf][mf] = __builtin_amdgcn_mfma_f32_16x16x32_bf16(wb[nf], xa[mf], acc[nf][mf], 0, 0, 0);
;   }
	v_mov_b32_e32 v30, 0
	v_mov_b32_e32 v31, 0
	v_mov_b32_e32 v32, 0
	v_mov_b32_e32 v33, 0
	v_mov_b32_e32 v34, 0
	v_mov_b32_e32 v35, 0
	v_mov_b32_e32 v36, 0
	v_mov_b32_e32 v37, 0
	v_mov_b32_e32 v38, 0
	v_mov_b32_e32 v39, 0
	v_mov_b32_e32 v40, 0
	v_mov_b32_e32 v41, 0
	v_mov_b32_e32 v42, 0
	v_mov_b32_e32 v43, 0
	v_mov_b32_e32 v44, 0
	v_mov_b32_e32 v45, 0
	v_mov_b32_e32 v46, 0
	v_mov_b32_e32 v47, 0
	v_mov_b32_e32 v48, 0
	v_mov_b32_e32 v49, 0
	v_mov_b32_e32 v50, 0
	v_mov_b32_e32 v51, 0
	v_mov_b32_e32 v52, 0
	v_mov_b32_e32 v53, 0
	v_mov_b32_e32 v54, 0
	v_mov_b32_e32 v55, 0
	v_mov_b32_e32 v56, 0
	v_mov_b32_e32 v57, 0
	v_mov_b32_e32 v58, 0
	v_mov_b32_e32 v59, 0
	v_mov_b32_e32 v60, 0
	v_mov_b32_e32 v61, 0
	v_mov_b32_e32 v62, 0
	v_mov_b32_e32 v63, 0
	v_mov_b32_e32 v64, 0
	v_mov_b32_e32 v65, 0
	v_mov_b32_e32 v66, 0
	v_mov_b32_e32 v67, 0
	v_mov_b32_e32 v68, 0
	v_mov_b32_e32 v69, 0
	v_mov_b32_e32 v70, 0
	v_mov_b32_e32 v71, 0
	v_mov_b32_e32 v72, 0
	v_mov_b32_e32 v73, 0
	v_mov_b32_e32 v74, 0
	v_mov_b32_e32 v75, 0
	v_mov_b32_e32 v76, 0
	v_mov_b32_e32 v77, 0
	v_mov_b32_e32 v78, 0
	v_mov_b32_e32 v79, 0
	v_mov_b32_e32 v80, 0
	v_mov_b32_e32 v81, 0
	v_mov_b32_e32 v82, 0
	v_mov_b32_e32 v83, 0
	v_mov_b32_e32 v84, 0
	v_mov_b32_e32 v85, 0
	v_mov_b32_e32 v86, 0
	v_mov_b32_e32 v87, 0
	v_mov_b32_e32 v88, 0
	v_mov_b32_e32 v89, 0
	v_mov_b32_e32 v90, 0
	v_mov_b32_e32 v91, 0
	v_mov_b32_e32 v92, 0
	v_mov_b32_e32 v93, 0
	v_mov_b32_e32 v94, 0
	v_mov_b32_e32 v95, 0
	v_mov_b32_e32 v96, 0
	v_mov_b32_e32 v97, 0
	v_mov_b32_e32 v98, 0
	v_mov_b32_e32 v99, 0
	v_mov_b32_e32 v100, 0
	v_mov_b32_e32 v101, 0
	v_mov_b32_e32 v102, 0
	v_mov_b32_e32 v103, 0
	v_mov_b32_e32 v104, 0
	v_mov_b32_e32 v105, 0
	v_mov_b32_e32 v106, 0
	v_mov_b32_e32 v107, 0
	v_mov_b32_e32 v108, 0
	v_mov_b32_e32 v109, 0
	v_mov_b32_e32 v110, 0
	v_mov_b32_e32 v111, 0
	v_mov_b32_e32 v112, 0
	v_mov_b32_e32 v113, 0
	v_mov_b32_e32 v114, 0
	v_mov_b32_e32 v115, 0
	v_mov_b32_e32 v116, 0
	v_mov_b32_e32 v117, 0
	v_mov_b32_e32 v118, 0
	v_mov_b32_e32 v119, 0
	v_mov_b32_e32 v120, 0
	v_mov_b32_e32 v121, 0
	v_mov_b32_e32 v122, 0
	v_mov_b32_e32 v123, 0
	v_mov_b32_e32 v124, 0
	v_mov_b32_e32 v125, 0
	v_mov_b32_e32 v126, 0
	v_mov_b32_e32 v127, 0
	v_mov_b32_e32 v128, 0
	v_mov_b32_e32 v129, 0
	s_waitcnt vmcnt(12)
	s_barrier
	ds_read_b128 v[146:149], v136 offset:0
	ds_read_b128 v[152:155], v136 offset:1024
	ds_read_b128 v[156:159], v136 offset:2048
	ds_read_b128 v[162:165], v136 offset:3072
	ds_read_b128 v[166:169], v136 offset:4096
	ds_read_b128 v[170:173], v136 offset:5120
	ds_read_b128 v[176:179], v136 offset:6144
	ds_read_b128 v[180:183], v136 offset:7168
	ds_read_b128 v[184:187], v137 offset:16384
	ds_read_b128 v[188:191], v137 offset:17408
	ds_read_b128 v[192:195], v137 offset:18432
	ds_read_b128 v[196:199], v137 offset:19456
	s_movk_i32 s40, 0x6000
	s_mov_b32 s41, 0
	s_movk_i32 s39, 2
.Lt8_loop:
	s_waitcnt vmcnt(6) lgkmcnt(0)
	s_barrier
	s_setprio 1
	v_add_u32_e32 v144, s40, v136
	v_mfma_f32_16x16x32_bf16 v[126:129], v[184:187], v[146:149], v[126:129]
	ds_read_b128 v[200:203], v144 offset:0
	v_mfma_f32_16x16x32_bf16 v[122:125], v[184:187], v[152:155], v[122:125]
	ds_read_b128 v[204:207], v144 offset:1024
	v_mfma_f32_16x16x32_bf16 v[118:121], v[184:187], v[156:159], v[118:121]
	ds_read_b128 v[208:211], v144 offset:2048
	v_mfma_f32_16x16x32_bf16 v[114:117], v[184:187], v[162:165], v[114:117]
	ds_read_b128 v[212:215], v144 offset:3072
	v_mfma_f32_16x16x32_bf16 v[110:113], v[184:187], v[166:169], v[110:113]
	ds_read_b128 v[216:219], v144 offset:4096
	v_mfma_f32_16x16x32_bf16 v[106:109], v[184:187], v[170:173], v[106:109]
	ds_read_b128 v[220:223], v144 offset:5120
	v_mfma_f32_16x16x32_bf16 v[102:105], v[184:187], v[176:179], v[102:105]
	ds_read_b128 v[224:227], v144 offset:6144
	v_mfma_f32_16x16x32_bf16 v[98:101], v[184:187], v[180:183], v[98:101]
	ds_read_b128 v[228:231], v144 offset:7168
	v_mfma_f32_16x16x32_bf16 v[94:97], v[188:191], v[146:149], v[94:97]
	v_add_u32_e32 v144, s40, v137
	v_mfma_f32_16x16x32_bf16 v[90:93], v[188:191], v[152:155], v[90:93]
	v_mfma_f32_16x16x32_bf16 v[86:89], v[188:191], v[156:159], v[86:89]
	ds_read_b128 v[232:235], v144 offset:16384
	v_mfma_f32_16x16x32_bf16 v[82:85], v[188:191], v[162:165], v[82:85]
	ds_read_b128 v[236:239], v144 offset:17408
	v_mfma_f32_16x16x32_bf16 v[78:81], v[188:191], v[166:169], v[78:81]
	ds_read_b128 v[240:243], v144 offset:18432
	v_mfma_f32_16x16x32_bf16 v[74:77], v[188:191], v[170:173], v[74:77]
	ds_read_b128 v[244:247], v144 offset:19456
	s_add_i32 s42, s46, s41
	v_mfma_f32_16x16x32_bf16 v[70:73], v[188:191], v[176:179], v[70:73]
	s_mov_b32 m0, s42
	v_lshl_add_u64 v[142:143], v[132:133], 0, s[2:3]
	v_mfma_f32_16x16x32_bf16 v[66:69], v[188:191], v[180:183], v[66:69]
	global_load_lds_dwordx4 v[132:133], off
	s_addk_i32 m0, 0x1000
	v_mfma_f32_16x16x32_bf16 v[62:65], v[192:195], v[146:149], v[62:65]
	v_mfma_f32_16x16x32_bf16 v[58:61], v[192:195], v[152:155], v[58:61]
	v_mfma_f32_16x16x32_bf16 v[54:57], v[192:195], v[156:159], v[54:57]
	global_load_lds_dwordx4 v[142:143], off
	v_lshl_add_u64 v[142:143], v[142:143], 0, s[2:3]
	s_addk_i32 m0, 0x1000
	v_mfma_f32_16x16x32_bf16 v[50:53], v[192:195], v[162:165], v[50:53]
	v_mfma_f32_16x16x32_bf16 v[46:49], v[192:195], v[166:169], v[46:49]
	v_mfma_f32_16x16x32_bf16 v[42:45], v[192:195], v[170:173], v[42:45]
	global_load_lds_dwordx4 v[142:143], off
	v_lshl_add_u64 v[142:143], v[142:143], 0, s[2:3]
	s_addk_i32 m0, 0x1000
	v_mfma_f32_16x16x32_bf16 v[38:41], v[192:195], v[176:179], v[38:41]
	v_mfma_f32_16x16x32_bf16 v[34:37], v[192:195], v[180:183], v[34:37]
	v_mfma_f32_16x16x32_bf16 v[30:33], v[196:199], v[146:149], v[30:33]
	global_load_lds_dwordx4 v[142:143], off
	s_addk_i32 m0, 0x1000
	v_lshl_add_u64 v[142:143], v[134:135], 0, s[2:3]
	v_mfma_f32_16x16x32_bf16 v[26:29], v[196:199], v[152:155], v[26:29]
	v_mfma_f32_16x16x32_bf16 v[22:25], v[196:199], v[156:159], v[22:25]
	v_mfma_f32_16x16x32_bf16 v[18:21], v[196:199], v[162:165], v[18:21]
	global_load_lds_dwordx4 v[134:135], off
	s_addk_i32 m0, 0x1000
	v_lshl_add_u64 v[132:133], v[132:133], 0, s[12:13]
	v_mfma_f32_16x16x32_bf16 v[14:17], v[196:199], v[166:169], v[14:17]
	v_mfma_f32_16x16x32_bf16 v[10:13], v[196:199], v[170:173], v[10:13]
	v_mfma_f32_16x16x32_bf16 v[6:9], v[196:199], v[176:179], v[6:9]
	global_load_lds_dwordx4 v[142:143], off
	v_lshl_add_u64 v[134:135], v[134:135], 0, s[4:5]
	v_mfma_f32_16x16x32_bf16 v[2:5], v[196:199], v[180:183], v[2:5]
	s_setprio 0
	s_mov_b32 s41, s40
	s_add_i32 s40, s40, 0x6000
	s_cmp_eq_u32 s40, 0x12000
	s_cselect_b32 s40, 0, s40
	s_waitcnt vmcnt(6) lgkmcnt(0)
	s_barrier
;     ...
;   for (int kt = 0; kt < nk; kt++) {
;     if (kt + 1 < nk) asm volatile("s_waitcnt vmcnt(6)" ::: "memory");
;     else asm volatile("s_waitcnt vmcnt(0)" ::: "memory");
;     __builtin_amdgcn_s_barrier();
;     asm volatile("" ::: "memory");
;     if (kt + 2 < nk) G2_STAGE(kt + 2);
;     const char* cS = smem + (kt % 3) * 24576;
;     bf16x8 xa[8], wb[4];
; #pragma unroll
;     for (int f = 0; f < 8; f++) xa[f] = *(const bf16x8*)(cS + aoff + f * 1024);
; #pragma unroll
;     for (int f = 0; f < 4; f++) wb[f] = *(const bf16x8*)(cS + boff + f * 1024);
; #pragma unroll
;     for (int nf = 0; nf < 4; nf++)
; #pragma unroll
;       for (int mf = 0; mf < 8; mf++)
;         acc[nf][mf] = __builtin_amdgcn_mfma_f32_16x16x32_bf16(wb[nf], xa[mf], acc[nf][mf], 0, 0, 0);
;   }
	s_setprio 1
	v_add_u32_e32 v144, s40, v136
	v_mfma_f32_16x16x32_bf16 v[126:129], v[232:235], v[200:203], v[126:129]
	ds_read_b128 v[146:149], v144 offset:0
	v_mfma_f32_16x16x32_bf16 v[122:125], v[232:235], v[204:207], v[122:125]
	ds_read_b128 v[152:155], v144 offset:1024
	v_mfma_f32_16x16x32_bf16 v[118:121], v[232:235], v[208:211], v[118:121]
	ds_read_b128 v[156:159], v144 offset:2048
	v_mfma_f32_16x16x32_bf16 v[114:117], v[232:235], v[212:215], v[114:117]
	ds_read_b128 v[162:165], v144 offset:3072
	v_mfma_f32_16x16x32_bf16 v[110:113], v[232:235], v[216:219], v[110:113]
	ds_read_b128 v[166:169], v144 offset:4096
	v_mfma_f32_16x16x32_bf16 v[106:109], v[232:235], v[220:223], v[106:109]
	ds_read_b128 v[170:173], v144 offset:5120
	v_mfma_f32_16x16x32_bf16 v[102:105], v[232:235], v[224:227], v[102:105]
	ds_read_b128 v[176:179], v144 offset:6144
	v_mfma_f32_16x16x32_bf16 v[98:101], v[232:235], v[228:231], v[98:101]
	ds_read_b128 v[180:183], v144 offset:7168
	v_mfma_f32_16x16x32_bf16 v[94:97], v[236:239], v[200:203], v[94:97]
	v_add_u32_e32 v144, s40, v137
	v_mfma_f32_16x16x32_bf16 v[90:93], v[236:239], v[204:207], v[90:93]
	v_mfma_f32_16x16x32_bf16 v[86:89], v[236:239], v[208:211], v[86:89]
	ds_read_b128 v[184:187], v144 offset:16384
	v_mfma_f32_16x16x32_bf16 v[82:85], v[236:239], v[212:215], v[82:85]
	ds_read_b128 v[188:191], v144 offset:17408
	v_mfma_f32_16x16x32_bf16 v[78:81], v[236:239], v[216:219], v[78:81]
	ds_read_b128 v[192:195], v144 offset:18432
	v_mfma_f32_16x16x32_bf16 v[74:77], v[236:239], v[220:223], v[74:77]
	ds_read_b128 v[196:199], v144 offset:19456
	s_add_i32 s42, s46, s41
	v_mfma_f32_16x16x32_bf16 v[70:73], v[236:239], v[224:227], v[70:73]
	s_mov_b32 m0, s42
	v_lshl_add_u64 v[142:143], v[132:133], 0, s[2:3]
	v_mfma_f32_16x16x32_bf16 v[66:69], v[236:239], v[228:231], v[66:69]
	global_load_lds_dwordx4 v[132:133], off
	s_addk_i32 m0, 0x1000
	v_mfma_f32_16x16x32_bf16 v[62:65], v[240:243], v[200:203], v[62:65]
	v_mfma_f32_16x16x32_bf16 v[58:61], v[240:243], v[204:207], v[58:61]
	v_mfma_f32_16x16x32_bf16 v[54:57], v[240:243], v[208:211], v[54:57]
	global_load_lds_dwordx4 v[142:143], off
	v_lshl_add_u64 v[142:143], v[142:143], 0, s[2:3]
	s_addk_i32 m0, 0x1000
	v_mfma_f32_16x16x32_bf16 v[50:53], v[240:243], v[212:215], v[50:53]
	v_mfma_f32_16x16x32_bf16 v[46:49], v[240:243], v[216:219], v[46:49]
	v_mfma_f32_16x16x32_bf16 v[42:45], v[240:243], v[220:223], v[42:45]
	global_load_lds_dwordx4 v[142:143], off
	v_lshl_add_u64 v[142:143], v[142:143], 0, s[2:3]
	s_addk_i32 m0, 0x1000
	v_mfma_f32_16x16x32_bf16 v[38:41], v[240:243], v[224:227], v[38:41]
	v_mfma_f32_16x16x32_bf16 v[34:37], v[240:243], v[228:231], v[34:37]
	v_mfma_f32_16x16x32_bf16 v[30:33], v[244:247], v[200:203], v[30:33]
	global_load_lds_dwordx4 v[142:143], off
	s_addk_i32 m0, 0x1000
	v_lshl_add_u64 v[142:143], v[134:135], 0, s[2:3]
	v_mfma_f32_16x16x32_bf16 v[26:29], v[244:247], v[204:207], v[26:29]
	v_mfma_f32_16x16x32_bf16 v[22:25], v[244:247], v[208:211], v[22:25]
	v_mfma_f32_16x16x32_bf16 v[18:21], v[244:247], v[212:215], v[18:21]
	global_load_lds_dwordx4 v[134:135], off
	s_addk_i32 m0, 0x1000
	v_lshl_add_u64 v[132:133], v[132:133], 0, s[12:13]
	v_mfma_f32_16x16x32_bf16 v[14:17], v[244:247], v[216:219], v[14:17]
	v_mfma_f32_16x16x32_bf16 v[10:13], v[244:247], v[220:223], v[10:13]
	v_mfma_f32_16x16x32_bf16 v[6:9], v[244:247], v[224:227], v[6:9]
	global_load_lds_dwordx4 v[142:143], off
	v_lshl_add_u64 v[134:135], v[134:135], 0, s[4:5]
	v_mfma_f32_16x16x32_bf16 v[2:5], v[244:247], v[228:231], v[2:5]
	s_setprio 0
	s_mov_b32 s41, s40
	s_add_i32 s40, s40, 0x6000
	s_cmp_eq_u32 s40, 0x12000
	s_cselect_b32 s40, 0, s40
	s_sub_i32 s39, s39, 1
	s_cmp_lg_u32 s39, 0
	s_cbranch_scc1 .Lt8_loop
	s_waitcnt vmcnt(6) lgkmcnt(0)
	s_barrier
	s_setprio 1
	v_add_u32_e32 v144, s40, v136
	v_mfma_f32_16x16x32_bf16 v[126:129], v[184:187], v[146:149], v[126:129]
	ds_read_b128 v[200:203], v144 offset:0
	v_mfma_f32_16x16x32_bf16 v[122:125], v[184:187], v[152:155], v[122:125]
	ds_read_b128 v[204:207], v144 offset:1024
	v_mfma_f32_16x16x32_bf16 v[118:121], v[184:187], v[156:159], v[118:121]
	ds_read_b128 v[208:211], v144 offset:2048
	v_mfma_f32_16x16x32_bf16 v[114:117], v[184:187], v[162:165], v[114:117]
	ds_read_b128 v[212:215], v144 offset:3072
	v_mfma_f32_16x16x32_bf16 v[110:113], v[184:187], v[166:169], v[110:113]
	ds_read_b128 v[216:219], v144 offset:4096
	v_mfma_f32_16x16x32_bf16 v[106:109], v[184:187], v[170:173], v[106:109]
	ds_read_b128 v[220:223], v144 offset:5120
	v_mfma_f32_16x16x32_bf16 v[102:105], v[184:187], v[176:179], v[102:105]
	ds_read_b128 v[224:227], v144 offset:6144
	v_mfma_f32_16x16x32_bf16 v[98:101], v[184:187], v[180:183], v[98:101]
	ds_read_b128 v[228:231], v144 offset:7168
	v_mfma_f32_16x16x32_bf16 v[94:97], v[188:191], v[146:149], v[94:97]
	v_add_u32_e32 v144, s40, v137
	v_mfma_f32_16x16x32_bf16 v[90:93], v[188:191], v[152:155], v[90:93]
	v_mfma_f32_16x16x32_bf16 v[86:89], v[188:191], v[156:159], v[86:89]
	ds_read_b128 v[232:235], v144 offset:16384
	v_mfma_f32_16x16x32_bf16 v[82:85], v[188:191], v[162:165], v[82:85]
	ds_read_b128 v[236:239], v144 offset:17408
	v_mfma_f32_16x16x32_bf16 v[78:81], v[188:191], v[166:169], v[78:81]
	ds_read_b128 v[240:243], v144 offset:18432
	v_mfma_f32_16x16x32_bf16 v[74:77], v[188:191], v[170:173], v[74:77]
	ds_read_b128 v[244:247], v144 offset:19456
	s_add_i32 s42, s46, s41
	v_mfma_f32_16x16x32_bf16 v[70:73], v[188:191], v[176:179], v[70:73]
	s_mov_b32 m0, s42
	v_lshl_add_u64 v[142:143], v[132:133], 0, s[2:3]
	v_mfma_f32_16x16x32_bf16 v[66:69], v[188:191], v[180:183], v[66:69]
	global_load_lds_dwordx4 v[132:133], off
	s_addk_i32 m0, 0x1000
;     ...
;   for (int kt = 0; kt < nk; kt++) {
;     if (kt + 1 < nk) asm volatile("s_waitcnt vmcnt(6)" ::: "memory");
;     else asm volatile("s_waitcnt vmcnt(0)" ::: "memory");
;     __builtin_amdgcn_s_barrier();
;     asm volatile("" ::: "memory");
;     if (kt + 2 < nk) G2_STAGE(kt + 2);
;     const char* cS = smem + (kt % 3) * 24576;
;     bf16x8 xa[8], wb[4];
; #pragma unroll
;     for (int f = 0; f < 8; f++) xa[f] = *(const bf16x8*)(cS + aoff + f * 1024);
; #pragma unroll
;     for (int f = 0; f < 4; f++) wb[f] = *(const bf16x8*)(cS + boff + f * 1024);
; #pragma unroll
;     for (int nf = 0; nf < 4; nf++)
; #pragma unroll
;       for (int mf = 0; mf < 8; mf++)
;         acc[nf][mf] = __builtin_amdgcn_mfma_f32_16x16x32_bf16(wb[nf], xa[mf], acc[nf][mf], 0, 0, 0);
;   }
	v_mfma_f32_16x16x32_bf16 v[62:65], v[192:195], v[146:149], v[62:65]
	v_mfma_f32_16x16x32_bf16 v[58:61], v[192:195], v[152:155], v[58:61]
	v_mfma_f32_16x16x32_bf16 v[54:57], v[192:195], v[156:159], v[54:57]
	global_load_lds_dwordx4 v[142:143], off
	v_lshl_add_u64 v[142:143], v[142:143], 0, s[2:3]
	s_addk_i32 m0, 0x1000
	v_mfma_f32_16x16x32_bf16 v[50:53], v[192:195], v[162:165], v[50:53]
	v_mfma_f32_16x16x32_bf16 v[46:49], v[192:195], v[166:169], v[46:49]
	v_mfma_f32_16x16x32_bf16 v[42:45], v[192:195], v[170:173], v[42:45]
	global_load_lds_dwordx4 v[142:143], off
	v_lshl_add_u64 v[142:143], v[142:143], 0, s[2:3]
	s_addk_i32 m0, 0x1000
	v_mfma_f32_16x16x32_bf16 v[38:41], v[192:195], v[176:179], v[38:41]
	v_mfma_f32_16x16x32_bf16 v[34:37], v[192:195], v[180:183], v[34:37]
	v_mfma_f32_16x16x32_bf16 v[30:33], v[196:199], v[146:149], v[30:33]
	global_load_lds_dwordx4 v[142:143], off
	s_addk_i32 m0, 0x1000
	v_lshl_add_u64 v[142:143], v[134:135], 0, s[2:3]
	v_mfma_f32_16x16x32_bf16 v[26:29], v[196:199], v[152:155], v[26:29]
	v_mfma_f32_16x16x32_bf16 v[22:25], v[196:199], v[156:159], v[22:25]
	v_mfma_f32_16x16x32_bf16 v[18:21], v[196:199], v[162:165], v[18:21]
	global_load_lds_dwordx4 v[134:135], off
	s_addk_i32 m0, 0x1000
	v_lshl_add_u64 v[132:133], v[132:133], 0, s[12:13]
	v_mfma_f32_16x16x32_bf16 v[14:17], v[196:199], v[166:169], v[14:17]
	v_mfma_f32_16x16x32_bf16 v[10:13], v[196:199], v[170:173], v[10:13]
	v_mfma_f32_16x16x32_bf16 v[6:9], v[196:199], v[176:179], v[6:9]
	global_load_lds_dwordx4 v[142:143], off
	v_lshl_add_u64 v[134:135], v[134:135], 0, s[4:5]
	v_mfma_f32_16x16x32_bf16 v[2:5], v[196:199], v[180:183], v[2:5]
	s_setprio 0
	s_mov_b32 s41, s40
	s_add_i32 s40, s40, 0x6000
	s_cmp_eq_u32 s40, 0x12000
	s_cselect_b32 s40, 0, s40
	s_waitcnt vmcnt(6) lgkmcnt(0)
	s_barrier
	s_setprio 1
	v_add_u32_e32 v144, s40, v136
	v_mfma_f32_16x16x32_bf16 v[126:129], v[232:235], v[200:203], v[126:129]
	ds_read_b128 v[146:149], v144 offset:0
	v_mfma_f32_16x16x32_bf16 v[122:125], v[232:235], v[204:207], v[122:125]
	ds_read_b128 v[152:155], v144 offset:1024
	v_mfma_f32_16x16x32_bf16 v[118:121], v[232:235], v[208:211], v[118:121]
	ds_read_b128 v[156:159], v144 offset:2048
	v_mfma_f32_16x16x32_bf16 v[114:117], v[232:235], v[212:215], v[114:117]
	ds_read_b128 v[162:165], v144 offset:3072
	v_mfma_f32_16x16x32_bf16 v[110:113], v[232:235], v[216:219], v[110:113]
	ds_read_b128 v[166:169], v144 offset:4096
	v_mfma_f32_16x16x32_bf16 v[106:109], v[232:235], v[220:223], v[106:109]
	ds_read_b128 v[170:173], v144 offset:5120
	v_mfma_f32_16x16x32_bf16 v[102:105], v[232:235], v[224:227], v[102:105]
	ds_read_b128 v[176:179], v144 offset:6144
	v_mfma_f32_16x16x32_bf16 v[98:101], v[232:235], v[228:231], v[98:101]
	ds_read_b128 v[180:183], v144 offset:7168
	v_mfma_f32_16x16x32_bf16 v[94:97], v[236:239], v[200:203], v[94:97]
	v_add_u32_e32 v144, s40, v137
	v_mfma_f32_16x16x32_bf16 v[90:93], v[236:239], v[204:207], v[90:93]
	v_mfma_f32_16x16x32_bf16 v[86:89], v[236:239], v[208:211], v[86:89]
	ds_read_b128 v[184:187], v144 offset:16384
	v_mfma_f32_16x16x32_bf16 v[82:85], v[236:239], v[212:215], v[82:85]
	ds_read_b128 v[188:191], v144 offset:17408
	v_mfma_f32_16x16x32_bf16 v[78:81], v[236:239], v[216:219], v[78:81]
	ds_read_b128 v[192:195], v144 offset:18432
	v_mfma_f32_16x16x32_bf16 v[74:77], v[236:239], v[220:223], v[74:77]
	ds_read_b128 v[196:199], v144 offset:19456
	v_mfma_f32_16x16x32_bf16 v[70:73], v[236:239], v[224:227], v[70:73]
	v_mfma_f32_16x16x32_bf16 v[66:69], v[236:239], v[228:231], v[66:69]
	v_mfma_f32_16x16x32_bf16 v[62:65], v[240:243], v[200:203], v[62:65]
	v_mfma_f32_16x16x32_bf16 v[58:61], v[240:243], v[204:207], v[58:61]
	v_mfma_f32_16x16x32_bf16 v[54:57], v[240:243], v[208:211], v[54:57]
	v_mfma_f32_16x16x32_bf16 v[50:53], v[240:243], v[212:215], v[50:53]
	v_mfma_f32_16x16x32_bf16 v[46:49], v[240:243], v[216:219], v[46:49]
	v_mfma_f32_16x16x32_bf16 v[42:45], v[240:243], v[220:223], v[42:45]
	v_mfma_f32_16x16x32_bf16 v[38:41], v[240:243], v[224:227], v[38:41]
	v_mfma_f32_16x16x32_bf16 v[34:37], v[240:243], v[228:231], v[34:37]
	v_mfma_f32_16x16x32_bf16 v[30:33], v[244:247], v[200:203], v[30:33]
	v_mfma_f32_16x16x32_bf16 v[26:29], v[244:247], v[204:207], v[26:29]
	v_mfma_f32_16x16x32_bf16 v[22:25], v[244:247], v[208:211], v[22:25]
	v_mfma_f32_16x16x32_bf16 v[18:21], v[244:247], v[212:215], v[18:21]
	v_mfma_f32_16x16x32_bf16 v[14:17], v[244:247], v[216:219], v[14:17]
	v_mfma_f32_16x16x32_bf16 v[10:13], v[244:247], v[220:223], v[10:13]
	v_mfma_f32_16x16x32_bf16 v[6:9], v[244:247], v[224:227], v[6:9]
	v_mfma_f32_16x16x32_bf16 v[2:5], v[244:247], v[228:231], v[2:5]
	s_setprio 0
	s_mov_b32 s41, s40
	s_add_i32 s40, s40, 0x6000
	s_cmp_eq_u32 s40, 0x12000
	s_cselect_b32 s40, 0, s40
	s_waitcnt vmcnt(0) lgkmcnt(0)
	s_barrier
; DEVI float blo(unsigned u) { return __uint_as_float(u << 16); }
; DEVI float bhi(unsigned u) { return __uint_as_float(u & 0xffff0000u); }
;     ...
;   for (int kt = 0; kt < nk; kt++) {
;     if (kt + 1 < nk) asm volatile("s_waitcnt vmcnt(6)" ::: "memory");
;     else asm volatile("s_waitcnt vmcnt(0)" ::: "memory");
;     __builtin_amdgcn_s_barrier();
;     asm volatile("" ::: "memory");
;     if (kt + 2 < nk) G2_STAGE(kt + 2);
;     const char* cS = smem + (kt % 3) * 24576;
;     bf16x8 xa[8], wb[4];
; #pragma unroll
;     for (int f = 0; f < 8; f++) xa[f] = *(const bf16x8*)(cS + aoff + f * 1024);
; #pragma unroll
;     for (int f = 0; f < 4; f++) wb[f] = *(const bf16x8*)(cS + boff + f * 1024);
; #pragma unroll
;     for (int nf = 0; nf < 4; nf++)
; #pragma unroll
;       for (int mf = 0; mf < 8; mf++)
;         acc[nf][mf] = __builtin_amdgcn_mfma_f32_16x16x32_bf16(wb[nf], xa[mf], acc[nf][mf], 0, 0, 0);
;   }
;     ...
;         if (EPI == EPI_RESID || EPI == EPI_RESID_ATOMIC) {
;           f32x4 x = a;
;           if (EPI == EPI_RESID || kpart == 0) {
;             const u32x2 xr = *(const u32x2*)((const u16*)(p.ws + WS_XB) + (size_t)row * 1024 + col);
;             x[0] += ALPHA * blo(xr[0]); x[1] += ALPHA * bhi(xr[0]); x[2] += ALPHA * blo(xr[1]); x[3] += ALPHA * bhi(xr[1]);
;           }
;           if (EPI == EPI_RESID) *(f32x4*)((float*)(p.ws + WS_XF) + (size_t)row * 1024 + col) = x;
	s_setprio 1
	v_add_u32_e32 v144, s40, v136
	v_mfma_f32_16x16x32_bf16 v[126:129], v[184:187], v[146:149], v[126:129]
	ds_read_b128 v[200:203], v144 offset:0
	v_mfma_f32_16x16x32_bf16 v[122:125], v[184:187], v[152:155], v[122:125]
	ds_read_b128 v[204:207], v144 offset:1024
	v_mfma_f32_16x16x32_bf16 v[118:121], v[184:187], v[156:159], v[118:121]
	ds_read_b128 v[208:211], v144 offset:2048
	v_mfma_f32_16x16x32_bf16 v[114:117], v[184:187], v[162:165], v[114:117]
	ds_read_b128 v[212:215], v144 offset:3072
	v_mfma_f32_16x16x32_bf16 v[110:113], v[184:187], v[166:169], v[110:113]
	ds_read_b128 v[216:219], v144 offset:4096
	v_mfma_f32_16x16x32_bf16 v[106:109], v[184:187], v[170:173], v[106:109]
	ds_read_b128 v[220:223], v144 offset:5120
	v_mfma_f32_16x16x32_bf16 v[102:105], v[184:187], v[176:179], v[102:105]
	ds_read_b128 v[224:227], v144 offset:6144
	v_mfma_f32_16x16x32_bf16 v[98:101], v[184:187], v[180:183], v[98:101]
	ds_read_b128 v[228:231], v144 offset:7168
	v_mfma_f32_16x16x32_bf16 v[94:97], v[188:191], v[146:149], v[94:97]
	v_add_u32_e32 v144, s40, v137
	v_mfma_f32_16x16x32_bf16 v[90:93], v[188:191], v[152:155], v[90:93]
	v_mfma_f32_16x16x32_bf16 v[86:89], v[188:191], v[156:159], v[86:89]
	ds_read_b128 v[232:235], v144 offset:16384
	v_mfma_f32_16x16x32_bf16 v[82:85], v[188:191], v[162:165], v[82:85]
	ds_read_b128 v[236:239], v144 offset:17408
	v_mfma_f32_16x16x32_bf16 v[78:81], v[188:191], v[166:169], v[78:81]
	ds_read_b128 v[240:243], v144 offset:18432
	v_mfma_f32_16x16x32_bf16 v[74:77], v[188:191], v[170:173], v[74:77]
	ds_read_b128 v[244:247], v144 offset:19456
	v_mfma_f32_16x16x32_bf16 v[70:73], v[188:191], v[176:179], v[70:73]
	v_mfma_f32_16x16x32_bf16 v[66:69], v[188:191], v[180:183], v[66:69]
	v_mfma_f32_16x16x32_bf16 v[62:65], v[192:195], v[146:149], v[62:65]
	v_mfma_f32_16x16x32_bf16 v[58:61], v[192:195], v[152:155], v[58:61]
	v_mfma_f32_16x16x32_bf16 v[54:57], v[192:195], v[156:159], v[54:57]
	v_mfma_f32_16x16x32_bf16 v[50:53], v[192:195], v[162:165], v[50:53]
	v_mfma_f32_16x16x32_bf16 v[46:49], v[192:195], v[166:169], v[46:49]
	v_mfma_f32_16x16x32_bf16 v[42:45], v[192:195], v[170:173], v[42:45]
	v_mfma_f32_16x16x32_bf16 v[38:41], v[192:195], v[176:179], v[38:41]
	v_mfma_f32_16x16x32_bf16 v[34:37], v[192:195], v[180:183], v[34:37]
	v_mfma_f32_16x16x32_bf16 v[30:33], v[196:199], v[146:149], v[30:33]
	v_mfma_f32_16x16x32_bf16 v[26:29], v[196:199], v[152:155], v[26:29]
	v_mfma_f32_16x16x32_bf16 v[22:25], v[196:199], v[156:159], v[22:25]
	v_mfma_f32_16x16x32_bf16 v[18:21], v[196:199], v[162:165], v[18:21]
	v_mfma_f32_16x16x32_bf16 v[14:17], v[196:199], v[166:169], v[14:17]
	v_mfma_f32_16x16x32_bf16 v[10:13], v[196:199], v[170:173], v[10:13]
	v_mfma_f32_16x16x32_bf16 v[6:9], v[196:199], v[176:179], v[6:9]
	v_mfma_f32_16x16x32_bf16 v[2:5], v[196:199], v[180:183], v[2:5]
	s_setprio 0
	s_mov_b32 s41, s40
	s_add_i32 s40, s40, 0x6000
	s_cmp_eq_u32 s40, 0x12000
	s_cselect_b32 s40, 0, s40
	s_mov_b32 s4, 0x8000
	s_mov_b32 s5, 0
	s_mov_b32 s10, 0x10000
	s_mov_b32 s11, 0
	s_mov_b32 s44, 0x3fd744fd
	s_waitcnt lgkmcnt(0)
	v_mfma_f32_16x16x32_bf16 v[126:129], v[232:235], v[200:203], v[126:129]
	v_mfma_f32_16x16x32_bf16 v[122:125], v[232:235], v[204:207], v[122:125]
	v_mfma_f32_16x16x32_bf16 v[118:121], v[232:235], v[208:211], v[118:121]
	v_mfma_f32_16x16x32_bf16 v[114:117], v[232:235], v[212:215], v[114:117]
	v_mfma_f32_16x16x32_bf16 v[110:113], v[232:235], v[216:219], v[110:113]
	global_load_dwordx4 v[146:149], v[138:139], off offset:0
	v_mfma_f32_16x16x32_bf16 v[106:109], v[232:235], v[220:223], v[106:109]
	v_mfma_f32_16x16x32_bf16 v[102:105], v[232:235], v[224:227], v[102:105]
	global_load_dwordx4 v[152:155], v[138:139], off offset:64
	v_mfma_f32_16x16x32_bf16 v[98:101], v[232:235], v[228:231], v[98:101]
	v_lshl_add_u64 v[138:139], v[138:139], 0, s[4:5]
	v_mfma_f32_16x16x32_bf16 v[94:97], v[236:239], v[200:203], v[94:97]
	global_load_dwordx4 v[156:159], v[138:139], off offset:0
	v_mfma_f32_16x16x32_bf16 v[90:93], v[236:239], v[204:207], v[90:93]
	v_mfma_f32_16x16x32_bf16 v[86:89], v[236:239], v[208:211], v[86:89]
	global_load_dwordx4 v[162:165], v[138:139], off offset:64
	v_mfma_f32_16x16x32_bf16 v[82:85], v[236:239], v[212:215], v[82:85]
	v_lshl_add_u64 v[138:139], v[138:139], 0, s[4:5]
	v_mfma_f32_16x16x32_bf16 v[78:81], v[236:239], v[216:219], v[78:81]
	global_load_dwordx4 v[166:169], v[138:139], off offset:0
	v_mfma_f32_16x16x32_bf16 v[74:77], v[236:239], v[220:223], v[74:77]
	v_mfma_f32_16x16x32_bf16 v[70:73], v[236:239], v[224:227], v[70:73]
	global_load_dwordx4 v[170:173], v[138:139], off offset:64
	v_mfma_f32_16x16x32_bf16 v[66:69], v[236:239], v[228:231], v[66:69]
	v_lshl_add_u64 v[138:139], v[138:139], 0, s[4:5]
	v_mfma_f32_16x16x32_bf16 v[62:65], v[240:243], v[200:203], v[62:65]
	global_load_dwordx4 v[176:179], v[138:139], off offset:0
	v_mfma_f32_16x16x32_bf16 v[58:61], v[240:243], v[204:207], v[58:61]
	v_mfma_f32_16x16x32_bf16 v[54:57], v[240:243], v[208:211], v[54:57]
	global_load_dwordx4 v[180:183], v[138:139], off offset:64
	v_mfma_f32_16x16x32_bf16 v[50:53], v[240:243], v[212:215], v[50:53]
	v_lshl_add_u64 v[138:139], v[138:139], 0, s[4:5]
	v_mfma_f32_16x16x32_bf16 v[46:49], v[240:243], v[216:219], v[46:49]
	global_load_dwordx4 v[184:187], v[138:139], off offset:0
	v_mfma_f32_16x16x32_bf16 v[42:45], v[240:243], v[220:223], v[42:45]
	v_mfma_f32_16x16x32_bf16 v[38:41], v[240:243], v[224:227], v[38:41]
	global_load_dwordx4 v[188:191], v[138:139], off offset:64
	v_mfma_f32_16x16x32_bf16 v[34:37], v[240:243], v[228:231], v[34:37]
	v_lshl_add_u64 v[138:139], v[138:139], 0, s[4:5]
	v_mfma_f32_16x16x32_bf16 v[30:33], v[244:247], v[200:203], v[30:33]
	global_load_dwordx4 v[192:195], v[138:139], off offset:0
	v_mfma_f32_16x16x32_bf16 v[26:29], v[244:247], v[204:207], v[26:29]
	v_mfma_f32_16x16x32_bf16 v[22:25], v[244:247], v[208:211], v[22:25]
	global_load_dwordx4 v[196:199], v[138:139], off offset:64
	v_mfma_f32_16x16x32_bf16 v[18:21], v[244:247], v[212:215], v[18:21]
	v_lshl_add_u64 v[138:139], v[138:139], 0, s[4:5]
	v_mfma_f32_16x16x32_bf16 v[14:17], v[244:247], v[216:219], v[14:17]
	v_mfma_f32_16x16x32_bf16 v[10:13], v[244:247], v[220:223], v[10:13]
	v_mfma_f32_16x16x32_bf16 v[6:9], v[244:247], v[224:227], v[6:9]
	v_mfma_f32_16x16x32_bf16 v[2:5], v[244:247], v[228:231], v[2:5]
	s_mov_b32 m0, s43
	global_load_dwordx4 v[200:203], v[138:139], off offset:0
	global_load_dwordx4 v[204:207], v[138:139], off offset:64
	v_lshl_add_u64 v[138:139], v[138:139], 0, s[4:5]
	global_load_dwordx4 v[208:211], v[138:139], off offset:0
	global_load_dwordx4 v[212:215], v[138:139], off offset:64
	v_lshl_add_u64 v[138:139], v[138:139], 0, s[4:5]
	s_nop 7
	s_waitcnt vmcnt(15)
; DEVI float blo(unsigned u) { return __uint_as_float(u << 16); }
; DEVI float bhi(unsigned u) { return __uint_as_float(u & 0xffff0000u); }
;     ...
;         if (EPI == EPI_RESID || EPI == EPI_RESID_ATOMIC) {
;           f32x4 x = a;
;           if (EPI == EPI_RESID || kpart == 0) {
;             const u32x2 xr = *(const u32x2*)((const u16*)(p.ws + WS_XB) + (size_t)row * 1024 + col);
;             x[0] += ALPHA * blo(xr[0]); x[1] += ALPHA * bhi(xr[0]); x[2] += ALPHA * blo(xr[1]); x[3] += ALPHA * bhi(xr[1]);
;           }
;           if (EPI == EPI_RESID) *(f32x4*)((float*)(p.ws + WS_XF) + (size_t)row * 1024 + col) = x;
	v_permlane16_swap_b32_e32 v146, v148
	v_permlane16_swap_b32_e32 v147, v149
	v_lshlrev_b32_e32 v216, 16, v146
	v_and_b32_e32 v146, 0xffff0000, v146
	v_lshlrev_b32_e32 v217, 16, v147
	v_and_b32_e32 v147, 0xffff0000, v147
	v_fmac_f32_e32 v126, s44, v216
	v_fmac_f32_e32 v127, s44, v146
	v_fmac_f32_e32 v128, s44, v217
	v_fmac_f32_e32 v129, s44, v147
	global_store_dwordx4 v[140:141], v[126:129], off offset:0
	v_lshlrev_b32_e32 v216, 16, v148
	v_and_b32_e32 v148, 0xffff0000, v148
	v_lshlrev_b32_e32 v217, 16, v149
	v_and_b32_e32 v149, 0xffff0000, v149
	v_fmac_f32_e32 v94, s44, v216
	v_fmac_f32_e32 v95, s44, v148
	v_fmac_f32_e32 v96, s44, v217
	v_fmac_f32_e32 v97, s44, v149
	global_store_dwordx4 v[140:141], v[94:97], off offset:64
	s_waitcnt vmcnt(16)
	v_permlane16_swap_b32_e32 v152, v154
	v_permlane16_swap_b32_e32 v153, v155
	v_lshlrev_b32_e32 v216, 16, v152
	v_and_b32_e32 v152, 0xffff0000, v152
	v_lshlrev_b32_e32 v217, 16, v153
	v_and_b32_e32 v153, 0xffff0000, v153
	v_fmac_f32_e32 v62, s44, v216
	v_fmac_f32_e32 v63, s44, v152
	v_fmac_f32_e32 v64, s44, v217
	v_fmac_f32_e32 v65, s44, v153
	global_store_dwordx4 v[140:141], v[62:65], off offset:128
	v_lshlrev_b32_e32 v216, 16, v154
	v_and_b32_e32 v154, 0xffff0000, v154
	v_lshlrev_b32_e32 v217, 16, v155
	v_and_b32_e32 v155, 0xffff0000, v155
	v_fmac_f32_e32 v30, s44, v216
	v_fmac_f32_e32 v31, s44, v154
	v_fmac_f32_e32 v32, s44, v217
	v_fmac_f32_e32 v33, s44, v155
	global_store_dwordx4 v[140:141], v[30:33], off offset:192
	v_lshl_add_u64 v[140:141], v[140:141], 0, s[10:11]
	s_waitcnt vmcnt(17)
	v_permlane16_swap_b32_e32 v156, v158
	v_permlane16_swap_b32_e32 v157, v159
	v_lshlrev_b32_e32 v216, 16, v156
	v_and_b32_e32 v156, 0xffff0000, v156
	v_lshlrev_b32_e32 v217, 16, v157
	v_and_b32_e32 v157, 0xffff0000, v157
	v_fmac_f32_e32 v122, s44, v216
	v_fmac_f32_e32 v123, s44, v156
	v_fmac_f32_e32 v124, s44, v217
	v_fmac_f32_e32 v125, s44, v157
	global_store_dwordx4 v[140:141], v[122:125], off offset:0
	v_lshlrev_b32_e32 v216, 16, v158
	v_and_b32_e32 v158, 0xffff0000, v158
	v_lshlrev_b32_e32 v217, 16, v159
	v_and_b32_e32 v159, 0xffff0000, v159
	v_fmac_f32_e32 v90, s44, v216
	v_fmac_f32_e32 v91, s44, v158
	v_fmac_f32_e32 v92, s44, v217
	v_fmac_f32_e32 v93, s44, v159
	global_store_dwordx4 v[140:141], v[90:93], off offset:64
	s_waitcnt vmcnt(18)
	v_permlane16_swap_b32_e32 v162, v164
	v_permlane16_swap_b32_e32 v163, v165
	v_lshlrev_b32_e32 v216, 16, v162
	v_and_b32_e32 v162, 0xffff0000, v162
	v_lshlrev_b32_e32 v217, 16, v163
	v_and_b32_e32 v163, 0xffff0000, v163
	v_fmac_f32_e32 v58, s44, v216
	v_fmac_f32_e32 v59, s44, v162
	v_fmac_f32_e32 v60, s44, v217
	v_fmac_f32_e32 v61, s44, v163
	global_store_dwordx4 v[140:141], v[58:61], off offset:128
	v_lshlrev_b32_e32 v216, 16, v164
	v_and_b32_e32 v164, 0xffff0000, v164
	v_lshlrev_b32_e32 v217, 16, v165
	v_and_b32_e32 v165, 0xffff0000, v165
	v_fmac_f32_e32 v26, s44, v216
	v_fmac_f32_e32 v27, s44, v164
	v_fmac_f32_e32 v28, s44, v217
	v_fmac_f32_e32 v29, s44, v165
	global_store_dwordx4 v[140:141], v[26:29], off offset:192
	v_lshl_add_u64 v[140:141], v[140:141], 0, s[10:11]
	s_waitcnt vmcnt(19)
	v_permlane16_swap_b32_e32 v166, v168
	v_permlane16_swap_b32_e32 v167, v169
	v_lshlrev_b32_e32 v216, 16, v166
	v_and_b32_e32 v166, 0xffff0000, v166
	v_lshlrev_b32_e32 v217, 16, v167
	v_and_b32_e32 v167, 0xffff0000, v167
	v_fmac_f32_e32 v118, s44, v216
	v_fmac_f32_e32 v119, s44, v166
	v_fmac_f32_e32 v120, s44, v217
	v_fmac_f32_e32 v121, s44, v167
	global_store_dwordx4 v[140:141], v[118:121], off offset:0
	v_lshlrev_b32_e32 v216, 16, v168
	v_and_b32_e32 v168, 0xffff0000, v168
	v_lshlrev_b32_e32 v217, 16, v169
	v_and_b32_e32 v169, 0xffff0000, v169
	v_fmac_f32_e32 v86, s44, v216
	v_fmac_f32_e32 v87, s44, v168
	v_fmac_f32_e32 v88, s44, v217
	v_fmac_f32_e32 v89, s44, v169
	global_store_dwordx4 v[140:141], v[86:89], off offset:64
	s_waitcnt vmcnt(20)
	v_permlane16_swap_b32_e32 v170, v172
	v_permlane16_swap_b32_e32 v171, v173
	v_lshlrev_b32_e32 v216, 16, v170
	v_and_b32_e32 v170, 0xffff0000, v170
	v_lshlrev_b32_e32 v217, 16, v171
	v_and_b32_e32 v171, 0xffff0000, v171
	v_fmac_f32_e32 v54, s44, v216
	v_fmac_f32_e32 v55, s44, v170
	v_fmac_f32_e32 v56, s44, v217
	v_fmac_f32_e32 v57, s44, v171
	global_store_dwordx4 v[140:141], v[54:57], off offset:128
	v_lshlrev_b32_e32 v216, 16, v172
	v_and_b32_e32 v172, 0xffff0000, v172
	v_lshlrev_b32_e32 v217, 16, v173
	v_and_b32_e32 v173, 0xffff0000, v173
	v_fmac_f32_e32 v22, s44, v216
	v_fmac_f32_e32 v23, s44, v172
	v_fmac_f32_e32 v24, s44, v217
	v_fmac_f32_e32 v25, s44, v173
	global_store_dwordx4 v[140:141], v[22:25], off offset:192
	v_lshl_add_u64 v[140:141], v[140:141], 0, s[10:11]
	s_waitcnt vmcnt(21)
	v_permlane16_swap_b32_e32 v176, v178
	v_permlane16_swap_b32_e32 v177, v179
	v_lshlrev_b32_e32 v216, 16, v176
	v_and_b32_e32 v176, 0xffff0000, v176
	v_lshlrev_b32_e32 v217, 16, v177
	v_and_b32_e32 v177, 0xffff0000, v177
	v_fmac_f32_e32 v114, s44, v216
	v_fmac_f32_e32 v115, s44, v176
	v_fmac_f32_e32 v116, s44, v217
	v_fmac_f32_e32 v117, s44, v177
	global_store_dwordx4 v[140:141], v[114:117], off offset:0
	v_lshlrev_b32_e32 v216, 16, v178
	v_and_b32_e32 v178, 0xffff0000, v178
	v_lshlrev_b32_e32 v217, 16, v179
	v_and_b32_e32 v179, 0xffff0000, v179
	v_fmac_f32_e32 v82, s44, v216
	v_fmac_f32_e32 v83, s44, v178
	v_fmac_f32_e32 v84, s44, v217
	v_fmac_f32_e32 v85, s44, v179
	global_store_dwordx4 v[140:141], v[82:85], off offset:64
	s_waitcnt vmcnt(22)
; DEVI float blo(unsigned u) { return __uint_as_float(u << 16); }
; DEVI float bhi(unsigned u) { return __uint_as_float(u & 0xffff0000u); }
; DEVI int xcd_first_tile() { return (blockIdx.x & 7) * (gridDim.x >> 3) + (blockIdx.x >> 3); }
;     ...
;         if (EPI == EPI_RESID || EPI == EPI_RESID_ATOMIC) {
;           f32x4 x = a;
;           if (EPI == EPI_RESID || kpart == 0) {
;             const u32x2 xr = *(const u32x2*)((const u16*)(p.ws + WS_XB) + (size_t)row * 1024 + col);
;             x[0] += ALPHA * blo(xr[0]); x[1] += ALPHA * bhi(xr[0]); x[2] += ALPHA * blo(xr[1]); x[3] += ALPHA * bhi(xr[1]);
;           }
;           if (EPI == EPI_RESID) *(f32x4*)((float*)(p.ws + WS_XF) + (size_t)row * 1024 + col) = x;
; DEVI void run_phase(const Params& p, int ph, char* smem) {
;     ...
;       for (int t = xcd_first_tile(); t < 512 + 16 * 2; t += xcd_tile_step()) {
;         if (t < 512) {
;           int mt_, nt_; tile_coords(t, 64, 8, mt_, nt_);
;           gemm_tile256<EPI_RESID>(p, ox, 256, Bt, 256, mt_ * 256, nt_ * 128, nullptr, 0, smem);
	v_permlane16_swap_b32_e32 v180, v182
	v_permlane16_swap_b32_e32 v181, v183
	v_lshlrev_b32_e32 v216, 16, v180
	v_and_b32_e32 v180, 0xffff0000, v180
	v_lshlrev_b32_e32 v217, 16, v181
	v_and_b32_e32 v181, 0xffff0000, v181
	v_fmac_f32_e32 v50, s44, v216
	v_fmac_f32_e32 v51, s44, v180
	v_fmac_f32_e32 v52, s44, v217
	v_fmac_f32_e32 v53, s44, v181
	global_store_dwordx4 v[140:141], v[50:53], off offset:128
	v_lshlrev_b32_e32 v216, 16, v182
	v_and_b32_e32 v182, 0xffff0000, v182
	v_lshlrev_b32_e32 v217, 16, v183
	v_and_b32_e32 v183, 0xffff0000, v183
	v_fmac_f32_e32 v18, s44, v216
	v_fmac_f32_e32 v19, s44, v182
	v_fmac_f32_e32 v20, s44, v217
	v_fmac_f32_e32 v21, s44, v183
	global_store_dwordx4 v[140:141], v[18:21], off offset:192
	v_lshl_add_u64 v[140:141], v[140:141], 0, s[10:11]
	s_waitcnt vmcnt(23)
	v_permlane16_swap_b32_e32 v184, v186
	v_permlane16_swap_b32_e32 v185, v187
	v_lshlrev_b32_e32 v216, 16, v184
	v_and_b32_e32 v184, 0xffff0000, v184
	v_lshlrev_b32_e32 v217, 16, v185
	v_and_b32_e32 v185, 0xffff0000, v185
	v_fmac_f32_e32 v110, s44, v216
	v_fmac_f32_e32 v111, s44, v184
	v_fmac_f32_e32 v112, s44, v217
	v_fmac_f32_e32 v113, s44, v185
	global_store_dwordx4 v[140:141], v[110:113], off offset:0
	v_lshlrev_b32_e32 v216, 16, v186
	v_and_b32_e32 v186, 0xffff0000, v186
	v_lshlrev_b32_e32 v217, 16, v187
	v_and_b32_e32 v187, 0xffff0000, v187
	v_fmac_f32_e32 v78, s44, v216
	v_fmac_f32_e32 v79, s44, v186
	v_fmac_f32_e32 v80, s44, v217
	v_fmac_f32_e32 v81, s44, v187
	global_store_dwordx4 v[140:141], v[78:81], off offset:64
	s_waitcnt vmcnt(24)
	v_permlane16_swap_b32_e32 v188, v190
	v_permlane16_swap_b32_e32 v189, v191
	v_lshlrev_b32_e32 v216, 16, v188
	v_and_b32_e32 v188, 0xffff0000, v188
	v_lshlrev_b32_e32 v217, 16, v189
	v_and_b32_e32 v189, 0xffff0000, v189
	v_fmac_f32_e32 v46, s44, v216
	v_fmac_f32_e32 v47, s44, v188
	v_fmac_f32_e32 v48, s44, v217
	v_fmac_f32_e32 v49, s44, v189
	global_store_dwordx4 v[140:141], v[46:49], off offset:128
	v_lshlrev_b32_e32 v216, 16, v190
	v_and_b32_e32 v190, 0xffff0000, v190
	v_lshlrev_b32_e32 v217, 16, v191
	v_and_b32_e32 v191, 0xffff0000, v191
	v_fmac_f32_e32 v14, s44, v216
	v_fmac_f32_e32 v15, s44, v190
	v_fmac_f32_e32 v16, s44, v217
	v_fmac_f32_e32 v17, s44, v191
	global_store_dwordx4 v[140:141], v[14:17], off offset:192
	v_lshl_add_u64 v[140:141], v[140:141], 0, s[10:11]
	s_waitcnt vmcnt(25)
	v_permlane16_swap_b32_e32 v192, v194
	v_permlane16_swap_b32_e32 v193, v195
	v_lshlrev_b32_e32 v216, 16, v192
	v_and_b32_e32 v192, 0xffff0000, v192
	v_lshlrev_b32_e32 v217, 16, v193
	v_and_b32_e32 v193, 0xffff0000, v193
	v_fmac_f32_e32 v106, s44, v216
	v_fmac_f32_e32 v107, s44, v192
	v_fmac_f32_e32 v108, s44, v217
	v_fmac_f32_e32 v109, s44, v193
	global_store_dwordx4 v[140:141], v[106:109], off offset:0
	v_lshlrev_b32_e32 v216, 16, v194
	v_and_b32_e32 v194, 0xffff0000, v194
	v_lshlrev_b32_e32 v217, 16, v195
	v_and_b32_e32 v195, 0xffff0000, v195
	v_fmac_f32_e32 v74, s44, v216
	v_fmac_f32_e32 v75, s44, v194
	v_fmac_f32_e32 v76, s44, v217
	v_fmac_f32_e32 v77, s44, v195
	global_store_dwordx4 v[140:141], v[74:77], off offset:64
	s_waitcnt vmcnt(26)
	v_permlane16_swap_b32_e32 v196, v198
	v_permlane16_swap_b32_e32 v197, v199
	v_lshlrev_b32_e32 v216, 16, v196
	v_and_b32_e32 v196, 0xffff0000, v196
	v_lshlrev_b32_e32 v217, 16, v197
	v_and_b32_e32 v197, 0xffff0000, v197
	v_fmac_f32_e32 v42, s44, v216
	v_fmac_f32_e32 v43, s44, v196
	v_fmac_f32_e32 v44, s44, v217
	v_fmac_f32_e32 v45, s44, v197
	global_store_dwordx4 v[140:141], v[42:45], off offset:128
	v_lshlrev_b32_e32 v216, 16, v198
	v_and_b32_e32 v198, 0xffff0000, v198
	v_lshlrev_b32_e32 v217, 16, v199
	v_and_b32_e32 v199, 0xffff0000, v199
	v_fmac_f32_e32 v10, s44, v216
	v_fmac_f32_e32 v11, s44, v198
	v_fmac_f32_e32 v12, s44, v217
	v_fmac_f32_e32 v13, s44, v199
	global_store_dwordx4 v[140:141], v[10:13], off offset:192
	v_lshl_add_u64 v[140:141], v[140:141], 0, s[10:11]
	s_waitcnt vmcnt(27)
	v_permlane16_swap_b32_e32 v200, v202
	v_permlane16_swap_b32_e32 v201, v203
	v_lshlrev_b32_e32 v216, 16, v200
	v_and_b32_e32 v200, 0xffff0000, v200
	v_lshlrev_b32_e32 v217, 16, v201
	v_and_b32_e32 v201, 0xffff0000, v201
	v_fmac_f32_e32 v102, s44, v216
	v_fmac_f32_e32 v103, s44, v200
	v_fmac_f32_e32 v104, s44, v217
	v_fmac_f32_e32 v105, s44, v201
	global_store_dwordx4 v[140:141], v[102:105], off offset:0
	v_lshlrev_b32_e32 v216, 16, v202
	v_and_b32_e32 v202, 0xffff0000, v202
	v_lshlrev_b32_e32 v217, 16, v203
	v_and_b32_e32 v203, 0xffff0000, v203
	v_fmac_f32_e32 v70, s44, v216
	v_fmac_f32_e32 v71, s44, v202
	v_fmac_f32_e32 v72, s44, v217
	v_fmac_f32_e32 v73, s44, v203
	global_store_dwordx4 v[140:141], v[70:73], off offset:64
	s_waitcnt vmcnt(28)
	v_permlane16_swap_b32_e32 v204, v206
	v_permlane16_swap_b32_e32 v205, v207
	v_lshlrev_b32_e32 v216, 16, v204
	v_and_b32_e32 v204, 0xffff0000, v204
	v_lshlrev_b32_e32 v217, 16, v205
	v_and_b32_e32 v205, 0xffff0000, v205
	v_fmac_f32_e32 v38, s44, v216
	v_fmac_f32_e32 v39, s44, v204
	v_fmac_f32_e32 v40, s44, v217
	v_fmac_f32_e32 v41, s44, v205
	global_store_dwordx4 v[140:141], v[38:41], off offset:128
	v_lshlrev_b32_e32 v216, 16, v206
	v_and_b32_e32 v206, 0xffff0000, v206
	v_lshlrev_b32_e32 v217, 16, v207
	v_and_b32_e32 v207, 0xffff0000, v207
	v_fmac_f32_e32 v6, s44, v216
	v_fmac_f32_e32 v7, s44, v206
	v_fmac_f32_e32 v8, s44, v217
	v_fmac_f32_e32 v9, s44, v207
	global_store_dwordx4 v[140:141], v[6:9], off offset:192
	v_lshl_add_u64 v[140:141], v[140:141], 0, s[10:11]
	s_waitcnt vmcnt(29)
	v_permlane16_swap_b32_e32 v208, v210
	v_permlane16_swap_b32_e32 v209, v211
	v_lshlrev_b32_e32 v216, 16, v208
	v_and_b32_e32 v208, 0xffff0000, v208
	v_lshlrev_b32_e32 v217, 16, v209
	v_and_b32_e32 v209, 0xffff0000, v209
	v_fmac_f32_e32 v98, s44, v216
	v_fmac_f32_e32 v99, s44, v208
	v_fmac_f32_e32 v100, s44, v217
	v_fmac_f32_e32 v101, s44, v209
	global_store_dwordx4 v[140:141], v[98:101], off offset:0
	v_lshlrev_b32_e32 v216, 16, v210
	v_and_b32_e32 v210, 0xffff0000, v210
	v_lshlrev_b32_e32 v217, 16, v211
	v_and_b32_e32 v211, 0xffff0000, v211
	v_fmac_f32_e32 v66, s44, v216
	v_fmac_f32_e32 v67, s44, v210
	v_fmac_f32_e32 v68, s44, v217
	v_fmac_f32_e32 v69, s44, v211
	global_store_dwordx4 v[140:141], v[66:69], off offset:64
	s_waitcnt vmcnt(30)
	v_permlane16_swap_b32_e32 v212, v214
	v_permlane16_swap_b32_e32 v213, v215
	v_lshlrev_b32_e32 v216, 16, v212
	v_and_b32_e32 v212, 0xffff0000, v212
	v_lshlrev_b32_e32 v217, 16, v213
	v_and_b32_e32 v213, 0xffff0000, v213
	v_fmac_f32_e32 v34, s44, v216
	v_fmac_f32_e32 v35, s44, v212
	v_fmac_f32_e32 v36, s44, v217
	v_fmac_f32_e32 v37, s44, v213
	global_store_dwordx4 v[140:141], v[34:37], off offset:128
	v_lshlrev_b32_e32 v216, 16, v214
	v_and_b32_e32 v214, 0xffff0000, v214
	v_lshlrev_b32_e32 v217, 16, v215
	v_and_b32_e32 v215, 0xffff0000, v215
	v_fmac_f32_e32 v2, s44, v216
	v_fmac_f32_e32 v3, s44, v214
	v_fmac_f32_e32 v4, s44, v217
	v_fmac_f32_e32 v5, s44, v215
	global_store_dwordx4 v[140:141], v[2:5], off offset:192
	v_readlane_b32 s39, v250, 7
	s_cmpk_lg_u32 s39, 0x200
	s_cbranch_scc1 .LBB0_146
; DEVI int xcd_first_tile() { return (blockIdx.x & 7) * (gridDim.x >> 3) + (blockIdx.x >> 3); }
; DEVI void run_phase(const Params& p, int ph, char* smem) {
;     ...
;       for (int t = xcd_first_tile(); t < 512 + 16 * 2; t += xcd_tile_step()) {
;         if (t < 512) {
;           int mt_, nt_; tile_coords(t, 64, 8, mt_, nt_);
;           gemm_tile256<EPI_RESID>(p, ox, 256, Bt, 256, mt_ * 256, nt_ * 128, nullptr, 0, smem);
	v_readlane_b32 s40, v250, 0
	s_lshr_b32 s41, s40, 3
	s_and_b32 s40, s40, 7
	s_mul_i32 s40, s40, 4
	s_add_i32 s40, s40, s41
	s_cmp_lt_u32 s41, 4
	s_cselect_b32 s38, s40, 0x4000
	s_branch .LBB0_146

; #define LAS __attribute__((address_space(3)))
;     ...
;   const int nk = (nk_part < 0) ? (K >> 5) : nk_part;
;   const int lrow = tid >> 2, lpc = tid & 3;
;   const int lch = lpc ^ ((0x78 >> (((lrow >> 2) & 3) * 2)) & 3);
;   const u16* ga = A + (size_t)(m0 + lrow) * lda + kbeg + lch * 8;
;   const u16* gb = Bt + (size_t)(n0 + lrow) * K + kbeg + lch * 8;
;   const size_t ga1 = (size_t)64 * lda, gb1 = (size_t)64 * K;
;   const unsigned lds0 = (unsigned)(uintptr_t)(LAS char*)smem + (unsigned)__builtin_amdgcn_readfirstlane(wid) * 1024u;
;     ...
;   __syncthreads();
;   G2_STAGE(0); G2_STAGE(1);
; DEVI void run_phase(const Params& p, int ph, char* smem) {
;     ...
;           const int u_ = t - 512, tl_ = u_ / 8, q_ = u_ - tl_ * 8;
;           gemm_tile256<EPI_RESID_ATOMIC>(p, mix, 1024, Bt, 1024, (64 + (tl_ & 1)) * 256, (tl_ >> 1) * 128, nullptr, 0, smem, q_ * 128, 4, q_);
.LBB0_758:
	s_cmpk_gt_i32 s39, 0x1ff
	s_mov_b64 s[2:3], -1
	s_cbranch_scc0 .LBB0_812
	s_sub_i32 s43, s39, 512
	s_lshr_b32 s42, s43, 3
	s_and_b32 s98, s43, 7
	s_lshr_b32 s15, s42, 1
	s_and_b32 s42, s42, 1
	s_add_i32 s42, s42, 64
	v_readlane_b32 s2, v250, 5
	v_readlane_b32 s3, v250, 6
	v_readlane_b32 s43, v254, 62
	s_mul_i32 s1, s42, 0x80000
	s_add_u32 s4, s2, s1
	s_addc_u32 s5, s3, 0
	s_add_u32 s4, s4, 0xb580000
	s_addc_u32 s5, s5, 0
	s_mul_i32 s1, s43, 0x200000
	s_mul_i32 s14, s15, 0x40000
	s_add_i32 s1, s1, s14
	s_add_u32 s10, s2, s1
	s_addc_u32 s11, s3, 0
	s_add_u32 s10, s10, 0x15e00000
	s_addc_u32 s11, s11, 0
	s_mul_i32 s1, s98, 256
	s_add_u32 s4, s4, s1
	s_addc_u32 s5, s5, 0
	s_mul_i32 s1, s98, 512
	s_add_u32 s10, s10, s1
	s_addc_u32 s11, s11, 0
	s_movk_i32 s0, 0x78
	v_lshrrev_b32_e32 v0, 2, v145
	v_and_b32_e32 v131, 3, v145
	v_bfe_u32 v136, v145, 4, 2
	v_lshlrev_b32_e32 v136, 1, v136
	v_lshrrev_b32_e64 v136, v136, s0
	v_and_b32_e32 v136, 3, v136
	v_xor_b32_e32 v131, v131, v136
	v_lshlrev_b32_e32 v131, 4, v131
	s_movk_i32 s14, 0x800
	v_mad_u32_u24 v0, v0, s14, v131
	v_bfe_u32 v137, v145, 2, 1
	s_movk_i32 s14, 0x7c0
	v_mul_u32_u24_e32 v136, s14, v137
	v_sub_u32_e32 v136, v0, v136
	v_mov_b32_e32 v137, 0
	v_lshl_add_u64 v[134:135], s[10:11], 0, v[136:137]
	v_bfe_u32 v137, v145, 2, 1
	s_mov_b32 s12, 64
	s_mov_b32 s13, 0
	v_lshl_add_u64 v[132:133], s[4:5], 0, v[0:1]
	v_bfe_u32 v136, v145, 2, 2
	v_lshlrev_b32_e32 v136, 1, v136
	v_lshrrev_b32_e64 v136, v136, s0
	v_and_b32_e32 v136, 3, v136
	v_bfe_u32 v137, v145, 4, 2
	v_xor_b32_e32 v136, v136, v137
	v_lshlrev_b32_e32 v136, 4, v136
	v_and_b32_e32 v131, 15, v145
	v_lshl_or_b32 v136, v131, 6, v136
	v_bfe_u32 v137, v145, 6, 1
	v_lshl_or_b32 v137, v137, 12, v136
	v_lshrrev_b32_e32 v0, 7, v145
	v_lshl_or_b32 v136, v0, 13, v136
	v_and_b32_e32 v140, 1, v131
	v_lshl_or_b32 v131, v0, 7, v131
	v_bfe_u32 v0, v145, 4, 2
	v_lshlrev_b32_e32 v0, 3, v0
	v_bfe_u32 v141, v145, 6, 1
	s_lshl_b32 s1, s42, 19
	s_lshl_b32 s14, s15, 8
	s_add_i32 s1, s1, s14
	s_add_u32 s4, s2, s1
	s_addc_u32 s5, s3, 0
	s_add_u32 s4, s4, 0x4200000
	s_addc_u32 s5, s5, 0
	v_lshlrev_b32_e32 v138, 11, v131
	v_lshl_add_u32 v138, v141, 7, v138
	v_bfe_u32 v139, v145, 4, 1
	v_lshl_add_u32 v138, v139, 5, v138
	v_bfe_u32 v139, v145, 5, 1
	v_lshl_add_u32 v138, v139, 4, v138
	v_mov_b32_e32 v139, 0
	v_lshl_add_u64 v[138:139], s[4:5], 0, v[138:139]
	s_and_b32 s1, s42, 1
	s_lshl_b32 s1, s1, 20
	s_lshl_b32 s14, s98, 21
	s_add_i32 s1, s1, s14
	s_lshl_b32 s14, s15, 9
	s_add_i32 s1, s1, s14
	s_add_u32 s10, s2, s1
	s_addc_u32 s11, s3, 0
	s_add_u32 s10, s10, 0x1dcc0000
	s_addc_u32 s11, s11, 0
	v_lshlrev_b32_e32 v140, 12, v131
	v_lshl_add_u32 v140, v141, 8, v140
	v_lshl_add_u32 v140, v0, 1, v140
	v_mov_b32_e32 v141, 0
	v_lshl_add_u64 v[140:141], s[10:11], 0, v[140:141]
	s_mov_b32 s2, 0x20000
	s_mov_b32 s3, 0
	v_lshrrev_b32_e32 v0, 6, v145
	v_lshlrev_b32_e32 v0, 10, v0
	s_nop 0
	v_readfirstlane_b32 s43, v0
	s_mov_b32 s40, m0
	s_mov_b32 s4, 128
	s_mov_b32 s5, 0
	s_barrier
	s_add_i32 s15, s43, 0x0
	s_mov_b32 m0, s15
	v_lshl_add_u64 v[142:143], v[132:133], 0, s[2:3]
	global_load_lds_dwordx4 v[132:133], off
	s_addk_i32 m0, 0x1000
	s_nop 0
	global_load_lds_dwordx4 v[142:143], off
	v_lshl_add_u64 v[142:143], v[142:143], 0, s[2:3]
	s_addk_i32 m0, 0x1000
	s_nop 0
	global_load_lds_dwordx4 v[142:143], off
	v_lshl_add_u64 v[142:143], v[142:143], 0, s[2:3]
	s_addk_i32 m0, 0x1000
	s_nop 0
	global_load_lds_dwordx4 v[142:143], off
	s_addk_i32 m0, 0x1000
	v_lshl_add_u64 v[142:143], v[134:135], 0, s[2:3]
	s_nop 0
	global_load_lds_dwordx4 v[134:135], off
	s_addk_i32 m0, 0x1000
	v_lshl_add_u64 v[132:133], v[132:133], 0, s[12:13]
	s_nop 0
	global_load_lds_dwordx4 v[142:143], off
	v_lshl_add_u64 v[134:135], v[134:135], 0, s[4:5]
	s_nop 0
	s_add_i32 s15, s43, 0x6000
	s_mov_b32 m0, s15
	v_lshl_add_u64 v[142:143], v[132:133], 0, s[2:3]
	global_load_lds_dwordx4 v[132:133], off
	s_addk_i32 m0, 0x1000
	s_nop 0
	global_load_lds_dwordx4 v[142:143], off
	v_lshl_add_u64 v[142:143], v[142:143], 0, s[2:3]
	s_addk_i32 m0, 0x1000
	s_nop 0
	global_load_lds_dwordx4 v[142:143], off
	v_lshl_add_u64 v[142:143], v[142:143], 0, s[2:3]
	s_addk_i32 m0, 0x1000
	s_nop 0
	global_load_lds_dwordx4 v[142:143], off
	s_addk_i32 m0, 0x1000
	v_lshl_add_u64 v[142:143], v[134:135], 0, s[2:3]
	s_nop 0
	global_load_lds_dwordx4 v[134:135], off
	s_addk_i32 m0, 0x1000
	v_lshl_add_u64 v[132:133], v[132:133], 0, s[12:13]
	s_nop 0
	global_load_lds_dwordx4 v[142:143], off
	v_lshl_add_u64 v[134:135], v[134:135], 0, s[4:5]
	s_nop 0
	s_add_i32 s15, s43, 0xc000
	s_mov_b32 m0, s15
	v_lshl_add_u64 v[142:143], v[132:133], 0, s[2:3]
	global_load_lds_dwordx4 v[132:133], off
	s_addk_i32 m0, 0x1000
	s_nop 0
	global_load_lds_dwordx4 v[142:143], off
	v_lshl_add_u64 v[142:143], v[142:143], 0, s[2:3]
	s_addk_i32 m0, 0x1000
	s_nop 0
	global_load_lds_dwordx4 v[142:143], off
	v_lshl_add_u64 v[142:143], v[142:143], 0, s[2:3]
	s_addk_i32 m0, 0x1000
	s_nop 0
	global_load_lds_dwordx4 v[142:143], off
	s_addk_i32 m0, 0x1000
	v_lshl_add_u64 v[142:143], v[134:135], 0, s[2:3]
	s_nop 0
	global_load_lds_dwordx4 v[134:135], off
	s_addk_i32 m0, 0x1000
	v_lshl_add_u64 v[132:133], v[132:133], 0, s[12:13]
	s_nop 0
	global_load_lds_dwordx4 v[142:143], off
	v_lshl_add_u64 v[134:135], v[134:135], 0, s[4:5]
	s_nop 0
	v_mov_b32_e32 v2, 0
	v_mov_b32_e32 v3, 0
	v_mov_b32_e32 v4, 0
	v_mov_b32_e32 v5, 0
	v_mov_b32_e32 v6, 0
	v_mov_b32_e32 v7, 0
	v_mov_b32_e32 v8, 0
	v_mov_b32_e32 v9, 0
	v_mov_b32_e32 v10, 0
	v_mov_b32_e32 v11, 0
	v_mov_b32_e32 v12, 0
	v_mov_b32_e32 v13, 0
	v_mov_b32_e32 v14, 0
	v_mov_b32_e32 v15, 0
	v_mov_b32_e32 v16, 0
	v_mov_b32_e32 v17, 0
; #define LAS __attribute__((address_space(3)))
;     ...
;   f32x4 acc[4][8];
; #pragma unroll
;   for (int i = 0; i < 4; i++)
; #pragma unroll
;     for (int j = 0; j < 8; j++) acc[i][j] = (f32x4){0.f, 0.f, 0.f, 0.f};
;   const int nk = (nk_part < 0) ? (K >> 5) : nk_part;
;   const int lrow = tid >> 2, lpc = tid & 3;
;   const int lch = lpc ^ ((0x78 >> (((lrow >> 2) & 3) * 2)) & 3);
;   const u16* ga = A + (size_t)(m0 + lrow) * lda + kbeg + lch * 8;
;   const u16* gb = Bt + (size_t)(n0 + lrow) * K + kbeg + lch * 8;
;   const size_t ga1 = (size_t)64 * lda, gb1 = (size_t)64 * K;
;   const unsigned lds0 = (unsigned)(uintptr_t)(LAS char*)smem + (unsigned)__builtin_amdgcn_readfirstlane(wid) * 1024u;
;     ...
;   __syncthreads();
;   G2_STAGE(0); G2_STAGE(1);
;   const int fsw = (0x78 >> (((r16 >> 2) & 3) * 2)) & 3;
;   const int aoff = (wm * 128 + r16) * 64 + ((quad ^ fsw) << 4);
;   const int boff = 16384 + (wn * 64 + r16) * 64 + ((quad ^ fsw) << 4);
;   for (int kt = 0; kt < nk; kt++) {
;     if (kt + 1 < nk) asm volatile("s_waitcnt vmcnt(6)" ::: "memory");
;     else asm volatile("s_waitcnt vmcnt(0)" ::: "memory");
;     __builtin_amdgcn_s_barrier();
;     asm volatile("" ::: "memory");
;     if (kt + 2 < nk) G2_STAGE(kt + 2);
;     const char* cS = smem + (kt % 3) * 24576;
;     bf16x8 xa[8], wb[4];
; #pragma unroll
;     for (int f = 0; f < 8; f++) xa[f] = *(const bf16x8*)(cS + aoff + f * 1024);
; #pragma unroll
;     for (int f = 0; f < 4; f++) wb[f] = *(const bf16x8*)(cS + boff + f * 1024);
; #pragma unroll
;     for (int nf = 0; nf < 4; nf++)
; #pragma unroll
;       for (int mf = 0; mf < 8; mf++)
;         acc[nf][mf] = __builtin_amdgcn_mfma_f32_16x16x32_bf16(wb[nf], xa[mf], acc[nf][mf], 0, 0, 0);
;   }
	v_mov_b32_e32 v18, 0
	v_mov_b32_e32 v19, 0
	v_mov_b32_e32 v20, 0
	v_mov_b32_e32 v21, 0
	v_mov_b32_e32 v22, 0
	v_mov_b32_e32 v23, 0
	v_mov_b32_e32 v24, 0
	v_mov_b32_e32 v25, 0
	v_mov_b32_e32 v26, 0
	v_mov_b32_e32 v27, 0
	v_mov_b32_e32 v28, 0
	v_mov_b32_e32 v29, 0
	v_mov_b32_e32 v30, 0
	v_mov_b32_e32 v31, 0
	v_mov_b32_e32 v32, 0
	v_mov_b32_e32 v33, 0
	v_mov_b32_e32 v34, 0
	v_mov_b32_e32 v35, 0
	v_mov_b32_e32 v36, 0
	v_mov_b32_e32 v37, 0
	v_mov_b32_e32 v38, 0
	v_mov_b32_e32 v39, 0
	v_mov_b32_e32 v40, 0
	v_mov_b32_e32 v41, 0
	v_mov_b32_e32 v42, 0
	v_mov_b32_e32 v43, 0
	v_mov_b32_e32 v44, 0
	v_mov_b32_e32 v45, 0
	v_mov_b32_e32 v46, 0
	v_mov_b32_e32 v47, 0
	v_mov_b32_e32 v48, 0
	v_mov_b32_e32 v49, 0
	v_mov_b32_e32 v50, 0
	v_mov_b32_e32 v51, 0
	v_mov_b32_e32 v52, 0
	v_mov_b32_e32 v53, 0
	v_mov_b32_e32 v54, 0
	v_mov_b32_e32 v55, 0
	v_mov_b32_e32 v56, 0
	v_mov_b32_e32 v57, 0
	v_mov_b32_e32 v58, 0
	v_mov_b32_e32 v59, 0
	v_mov_b32_e32 v60, 0
	v_mov_b32_e32 v61, 0
	v_mov_b32_e32 v62, 0
	v_mov_b32_e32 v63, 0
	v_mov_b32_e32 v64, 0
	v_mov_b32_e32 v65, 0
	v_mov_b32_e32 v66, 0
	v_mov_b32_e32 v67, 0
	v_mov_b32_e32 v68, 0
	v_mov_b32_e32 v69, 0
	v_mov_b32_e32 v70, 0
	v_mov_b32_e32 v71, 0
	v_mov_b32_e32 v72, 0
	v_mov_b32_e32 v73, 0
	v_mov_b32_e32 v74, 0
	v_mov_b32_e32 v75, 0
	v_mov_b32_e32 v76, 0
	v_mov_b32_e32 v77, 0
	v_mov_b32_e32 v78, 0
	v_mov_b32_e32 v79, 0
	v_mov_b32_e32 v80, 0
	v_mov_b32_e32 v81, 0
	v_mov_b32_e32 v82, 0
	v_mov_b32_e32 v83, 0
	v_mov_b32_e32 v84, 0
	v_mov_b32_e32 v85, 0
	v_mov_b32_e32 v86, 0
	v_mov_b32_e32 v87, 0
	v_mov_b32_e32 v88, 0
	v_mov_b32_e32 v89, 0
	v_mov_b32_e32 v90, 0
	v_mov_b32_e32 v91, 0
	v_mov_b32_e32 v92, 0
	v_mov_b32_e32 v93, 0
	v_mov_b32_e32 v94, 0
	v_mov_b32_e32 v95, 0
	v_mov_b32_e32 v96, 0
	v_mov_b32_e32 v97, 0
	v_mov_b32_e32 v98, 0
	v_mov_b32_e32 v99, 0
	v_mov_b32_e32 v100, 0
	v_mov_b32_e32 v101, 0
	v_mov_b32_e32 v102, 0
	v_mov_b32_e32 v103, 0
	v_mov_b32_e32 v104, 0
	v_mov_b32_e32 v105, 0
	v_mov_b32_e32 v106, 0
	v_mov_b32_e32 v107, 0
	v_mov_b32_e32 v108, 0
	v_mov_b32_e32 v109, 0
	v_mov_b32_e32 v110, 0
	v_mov_b32_e32 v111, 0
	v_mov_b32_e32 v112, 0
	v_mov_b32_e32 v113, 0
	v_mov_b32_e32 v114, 0
	v_mov_b32_e32 v115, 0
	v_mov_b32_e32 v116, 0
	v_mov_b32_e32 v117, 0
	v_mov_b32_e32 v118, 0
	v_mov_b32_e32 v119, 0
	v_mov_b32_e32 v120, 0
	v_mov_b32_e32 v121, 0
	v_mov_b32_e32 v122, 0
	v_mov_b32_e32 v123, 0
	v_mov_b32_e32 v124, 0
	v_mov_b32_e32 v125, 0
	v_mov_b32_e32 v126, 0
	v_mov_b32_e32 v127, 0
	v_mov_b32_e32 v128, 0
	v_mov_b32_e32 v129, 0
	s_waitcnt vmcnt(12)
	s_barrier
	ds_read_b128 v[146:149], v136 offset:0
	ds_read_b128 v[152:155], v136 offset:1024
	ds_read_b128 v[156:159], v136 offset:2048
	ds_read_b128 v[162:165], v136 offset:3072
	ds_read_b128 v[166:169], v136 offset:4096
	ds_read_b128 v[170:173], v136 offset:5120
	ds_read_b128 v[176:179], v136 offset:6144
	ds_read_b128 v[180:183], v136 offset:7168
	ds_read_b128 v[184:187], v137 offset:16384
	ds_read_b128 v[188:191], v137 offset:17408
	ds_read_b128 v[192:195], v137 offset:18432
	ds_read_b128 v[196:199], v137 offset:19456
	s_movk_i32 s1, 0x6000
	s_mov_b32 s14, 0
	s_waitcnt vmcnt(6) lgkmcnt(0)
	s_barrier
	s_setprio 1
	v_add_u32_e32 v144, s1, v136
	v_mfma_f32_16x16x32_bf16 v[126:129], v[184:187], v[146:149], v[126:129]
	ds_read_b128 v[200:203], v144 offset:0
	v_mfma_f32_16x16x32_bf16 v[122:125], v[184:187], v[152:155], v[122:125]
	ds_read_b128 v[204:207], v144 offset:1024
	v_mfma_f32_16x16x32_bf16 v[118:121], v[184:187], v[156:159], v[118:121]
	ds_read_b128 v[208:211], v144 offset:2048
	v_mfma_f32_16x16x32_bf16 v[114:117], v[184:187], v[162:165], v[114:117]
	ds_read_b128 v[212:215], v144 offset:3072
	v_mfma_f32_16x16x32_bf16 v[110:113], v[184:187], v[166:169], v[110:113]
	ds_read_b128 v[216:219], v144 offset:4096
	v_mfma_f32_16x16x32_bf16 v[106:109], v[184:187], v[170:173], v[106:109]
	ds_read_b128 v[220:223], v144 offset:5120
	v_mfma_f32_16x16x32_bf16 v[102:105], v[184:187], v[176:179], v[102:105]
	ds_read_b128 v[224:227], v144 offset:6144
	v_mfma_f32_16x16x32_bf16 v[98:101], v[184:187], v[180:183], v[98:101]
	ds_read_b128 v[228:231], v144 offset:7168
	v_mfma_f32_16x16x32_bf16 v[94:97], v[188:191], v[146:149], v[94:97]
	v_add_u32_e32 v144, s1, v137
	v_mfma_f32_16x16x32_bf16 v[90:93], v[188:191], v[152:155], v[90:93]
	v_mfma_f32_16x16x32_bf16 v[86:89], v[188:191], v[156:159], v[86:89]
	ds_read_b128 v[232:235], v144 offset:16384
	v_mfma_f32_16x16x32_bf16 v[82:85], v[188:191], v[162:165], v[82:85]
	ds_read_b128 v[236:239], v144 offset:17408
	v_mfma_f32_16x16x32_bf16 v[78:81], v[188:191], v[166:169], v[78:81]
	ds_read_b128 v[240:243], v144 offset:18432
	v_mfma_f32_16x16x32_bf16 v[74:77], v[188:191], v[170:173], v[74:77]
	ds_read_b128 v[244:247], v144 offset:19456
	s_add_i32 s15, s43, s14
	v_mfma_f32_16x16x32_bf16 v[70:73], v[188:191], v[176:179], v[70:73]
	s_mov_b32 m0, s15
	v_lshl_add_u64 v[142:143], v[132:133], 0, s[2:3]
	v_mfma_f32_16x16x32_bf16 v[66:69], v[188:191], v[180:183], v[66:69]
	global_load_lds_dwordx4 v[132:133], off
	s_addk_i32 m0, 0x1000
	v_mfma_f32_16x16x32_bf16 v[62:65], v[192:195], v[146:149], v[62:65]
	v_mfma_f32_16x16x32_bf16 v[58:61], v[192:195], v[152:155], v[58:61]
	v_mfma_f32_16x16x32_bf16 v[54:57], v[192:195], v[156:159], v[54:57]
	global_load_lds_dwordx4 v[142:143], off
	v_lshl_add_u64 v[142:143], v[142:143], 0, s[2:3]
	s_addk_i32 m0, 0x1000
	v_mfma_f32_16x16x32_bf16 v[50:53], v[192:195], v[162:165], v[50:53]
	v_mfma_f32_16x16x32_bf16 v[46:49], v[192:195], v[166:169], v[46:49]
	v_mfma_f32_16x16x32_bf16 v[42:45], v[192:195], v[170:173], v[42:45]
	global_load_lds_dwordx4 v[142:143], off
	v_lshl_add_u64 v[142:143], v[142:143], 0, s[2:3]
	s_addk_i32 m0, 0x1000
	v_mfma_f32_16x16x32_bf16 v[38:41], v[192:195], v[176:179], v[38:41]
	v_mfma_f32_16x16x32_bf16 v[34:37], v[192:195], v[180:183], v[34:37]
	v_mfma_f32_16x16x32_bf16 v[30:33], v[196:199], v[146:149], v[30:33]
	global_load_lds_dwordx4 v[142:143], off
	s_addk_i32 m0, 0x1000
	v_lshl_add_u64 v[142:143], v[134:135], 0, s[2:3]
	v_mfma_f32_16x16x32_bf16 v[26:29], v[196:199], v[152:155], v[26:29]
	v_mfma_f32_16x16x32_bf16 v[22:25], v[196:199], v[156:159], v[22:25]
	v_mfma_f32_16x16x32_bf16 v[18:21], v[196:199], v[162:165], v[18:21]
	global_load_lds_dwordx4 v[134:135], off
	s_addk_i32 m0, 0x1000
	v_lshl_add_u64 v[132:133], v[132:133], 0, s[12:13]
	v_mfma_f32_16x16x32_bf16 v[14:17], v[196:199], v[166:169], v[14:17]
	v_mfma_f32_16x16x32_bf16 v[10:13], v[196:199], v[170:173], v[10:13]
	v_mfma_f32_16x16x32_bf16 v[6:9], v[196:199], v[176:179], v[6:9]
	global_load_lds_dwordx4 v[142:143], off
	v_lshl_add_u64 v[134:135], v[134:135], 0, s[4:5]
	v_mfma_f32_16x16x32_bf16 v[2:5], v[196:199], v[180:183], v[2:5]
	s_setprio 0
	s_mov_b32 s14, s1
	s_add_i32 s1, s1, 0x6000
	s_cmp_eq_u32 s1, 0x12000
	s_cselect_b32 s1, 0, s1
	s_waitcnt vmcnt(6) lgkmcnt(0)
	s_barrier
;     ...
;   for (int kt = 0; kt < nk; kt++) {
;     if (kt + 1 < nk) asm volatile("s_waitcnt vmcnt(6)" ::: "memory");
;     else asm volatile("s_waitcnt vmcnt(0)" ::: "memory");
;     __builtin_amdgcn_s_barrier();
;     asm volatile("" ::: "memory");
;     if (kt + 2 < nk) G2_STAGE(kt + 2);
;     const char* cS = smem + (kt % 3) * 24576;
;     bf16x8 xa[8], wb[4];
; #pragma unroll
;     for (int f = 0; f < 8; f++) xa[f] = *(const bf16x8*)(cS + aoff + f * 1024);
; #pragma unroll
;     for (int f = 0; f < 4; f++) wb[f] = *(const bf16x8*)(cS + boff + f * 1024);
; #pragma unroll
;     for (int nf = 0; nf < 4; nf++)
; #pragma unroll
;       for (int mf = 0; mf < 8; mf++)
;         acc[nf][mf] = __builtin_amdgcn_mfma_f32_16x16x32_bf16(wb[nf], xa[mf], acc[nf][mf], 0, 0, 0);
;   }
	s_setprio 1
	v_add_u32_e32 v144, s1, v136
	v_mfma_f32_16x16x32_bf16 v[126:129], v[232:235], v[200:203], v[126:129]
	ds_read_b128 v[146:149], v144 offset:0
	v_mfma_f32_16x16x32_bf16 v[122:125], v[232:235], v[204:207], v[122:125]
	ds_read_b128 v[152:155], v144 offset:1024
	v_mfma_f32_16x16x32_bf16 v[118:121], v[232:235], v[208:211], v[118:121]
	ds_read_b128 v[156:159], v144 offset:2048
	v_mfma_f32_16x16x32_bf16 v[114:117], v[232:235], v[212:215], v[114:117]
	ds_read_b128 v[162:165], v144 offset:3072
	v_mfma_f32_16x16x32_bf16 v[110:113], v[232:235], v[216:219], v[110:113]
	ds_read_b128 v[166:169], v144 offset:4096
	v_mfma_f32_16x16x32_bf16 v[106:109], v[232:235], v[220:223], v[106:109]
	ds_read_b128 v[170:173], v144 offset:5120
	v_mfma_f32_16x16x32_bf16 v[102:105], v[232:235], v[224:227], v[102:105]
	ds_read_b128 v[176:179], v144 offset:6144
	v_mfma_f32_16x16x32_bf16 v[98:101], v[232:235], v[228:231], v[98:101]
	ds_read_b128 v[180:183], v144 offset:7168
	v_mfma_f32_16x16x32_bf16 v[94:97], v[236:239], v[200:203], v[94:97]
	v_add_u32_e32 v144, s1, v137
	v_mfma_f32_16x16x32_bf16 v[90:93], v[236:239], v[204:207], v[90:93]
	v_mfma_f32_16x16x32_bf16 v[86:89], v[236:239], v[208:211], v[86:89]
	ds_read_b128 v[184:187], v144 offset:16384
	v_mfma_f32_16x16x32_bf16 v[82:85], v[236:239], v[212:215], v[82:85]
	ds_read_b128 v[188:191], v144 offset:17408
	v_mfma_f32_16x16x32_bf16 v[78:81], v[236:239], v[216:219], v[78:81]
	ds_read_b128 v[192:195], v144 offset:18432
	v_mfma_f32_16x16x32_bf16 v[74:77], v[236:239], v[220:223], v[74:77]
	ds_read_b128 v[196:199], v144 offset:19456
	v_mfma_f32_16x16x32_bf16 v[70:73], v[236:239], v[224:227], v[70:73]
	v_mfma_f32_16x16x32_bf16 v[66:69], v[236:239], v[228:231], v[66:69]
	v_mfma_f32_16x16x32_bf16 v[62:65], v[240:243], v[200:203], v[62:65]
	v_mfma_f32_16x16x32_bf16 v[58:61], v[240:243], v[204:207], v[58:61]
	v_mfma_f32_16x16x32_bf16 v[54:57], v[240:243], v[208:211], v[54:57]
	v_mfma_f32_16x16x32_bf16 v[50:53], v[240:243], v[212:215], v[50:53]
	v_mfma_f32_16x16x32_bf16 v[46:49], v[240:243], v[216:219], v[46:49]
	v_mfma_f32_16x16x32_bf16 v[42:45], v[240:243], v[220:223], v[42:45]
	v_mfma_f32_16x16x32_bf16 v[38:41], v[240:243], v[224:227], v[38:41]
	v_mfma_f32_16x16x32_bf16 v[34:37], v[240:243], v[228:231], v[34:37]
	v_mfma_f32_16x16x32_bf16 v[30:33], v[244:247], v[200:203], v[30:33]
	v_mfma_f32_16x16x32_bf16 v[26:29], v[244:247], v[204:207], v[26:29]
	v_mfma_f32_16x16x32_bf16 v[22:25], v[244:247], v[208:211], v[22:25]
	v_mfma_f32_16x16x32_bf16 v[18:21], v[244:247], v[212:215], v[18:21]
	v_mfma_f32_16x16x32_bf16 v[14:17], v[244:247], v[216:219], v[14:17]
	v_mfma_f32_16x16x32_bf16 v[10:13], v[244:247], v[220:223], v[10:13]
	v_mfma_f32_16x16x32_bf16 v[6:9], v[244:247], v[224:227], v[6:9]
	v_mfma_f32_16x16x32_bf16 v[2:5], v[244:247], v[228:231], v[2:5]
	s_setprio 0
	s_mov_b32 s14, s1
	s_add_i32 s1, s1, 0x6000
	s_cmp_eq_u32 s1, 0x12000
	s_cselect_b32 s1, 0, s1
	s_waitcnt vmcnt(0) lgkmcnt(0)
	s_barrier
	s_setprio 1
	v_add_u32_e32 v144, s1, v136
	v_mfma_f32_16x16x32_bf16 v[126:129], v[184:187], v[146:149], v[126:129]
	ds_read_b128 v[200:203], v144 offset:0
	v_mfma_f32_16x16x32_bf16 v[122:125], v[184:187], v[152:155], v[122:125]
	ds_read_b128 v[204:207], v144 offset:1024
	v_mfma_f32_16x16x32_bf16 v[118:121], v[184:187], v[156:159], v[118:121]
	ds_read_b128 v[208:211], v144 offset:2048
	v_mfma_f32_16x16x32_bf16 v[114:117], v[184:187], v[162:165], v[114:117]
	ds_read_b128 v[212:215], v144 offset:3072
	v_mfma_f32_16x16x32_bf16 v[110:113], v[184:187], v[166:169], v[110:113]
	ds_read_b128 v[216:219], v144 offset:4096
	v_mfma_f32_16x16x32_bf16 v[106:109], v[184:187], v[170:173], v[106:109]
	ds_read_b128 v[220:223], v144 offset:5120
	v_mfma_f32_16x16x32_bf16 v[102:105], v[184:187], v[176:179], v[102:105]
	ds_read_b128 v[224:227], v144 offset:6144
	v_mfma_f32_16x16x32_bf16 v[98:101], v[184:187], v[180:183], v[98:101]
	ds_read_b128 v[228:231], v144 offset:7168
	v_mfma_f32_16x16x32_bf16 v[94:97], v[188:191], v[146:149], v[94:97]
	v_add_u32_e32 v144, s1, v137
	v_mfma_f32_16x16x32_bf16 v[90:93], v[188:191], v[152:155], v[90:93]
	v_mfma_f32_16x16x32_bf16 v[86:89], v[188:191], v[156:159], v[86:89]
	ds_read_b128 v[232:235], v144 offset:16384
	v_mfma_f32_16x16x32_bf16 v[82:85], v[188:191], v[162:165], v[82:85]
	ds_read_b128 v[236:239], v144 offset:17408
	v_mfma_f32_16x16x32_bf16 v[78:81], v[188:191], v[166:169], v[78:81]
	ds_read_b128 v[240:243], v144 offset:18432
	v_mfma_f32_16x16x32_bf16 v[74:77], v[188:191], v[170:173], v[74:77]
	ds_read_b128 v[244:247], v144 offset:19456
	v_mfma_f32_16x16x32_bf16 v[70:73], v[188:191], v[176:179], v[70:73]
	v_mfma_f32_16x16x32_bf16 v[66:69], v[188:191], v[180:183], v[66:69]
	v_mfma_f32_16x16x32_bf16 v[62:65], v[192:195], v[146:149], v[62:65]
	v_mfma_f32_16x16x32_bf16 v[58:61], v[192:195], v[152:155], v[58:61]
	v_mfma_f32_16x16x32_bf16 v[54:57], v[192:195], v[156:159], v[54:57]
	v_mfma_f32_16x16x32_bf16 v[50:53], v[192:195], v[162:165], v[50:53]
	v_mfma_f32_16x16x32_bf16 v[46:49], v[192:195], v[166:169], v[46:49]
	v_mfma_f32_16x16x32_bf16 v[42:45], v[192:195], v[170:173], v[42:45]
	v_mfma_f32_16x16x32_bf16 v[38:41], v[192:195], v[176:179], v[38:41]
	v_mfma_f32_16x16x32_bf16 v[34:37], v[192:195], v[180:183], v[34:37]
	v_mfma_f32_16x16x32_bf16 v[30:33], v[196:199], v[146:149], v[30:33]
	v_mfma_f32_16x16x32_bf16 v[26:29], v[196:199], v[152:155], v[26:29]
	v_mfma_f32_16x16x32_bf16 v[22:25], v[196:199], v[156:159], v[22:25]
	v_mfma_f32_16x16x32_bf16 v[18:21], v[196:199], v[162:165], v[18:21]
	v_mfma_f32_16x16x32_bf16 v[14:17], v[196:199], v[166:169], v[14:17]
	v_mfma_f32_16x16x32_bf16 v[10:13], v[196:199], v[170:173], v[10:13]
	v_mfma_f32_16x16x32_bf16 v[6:9], v[196:199], v[176:179], v[6:9]
	v_mfma_f32_16x16x32_bf16 v[2:5], v[196:199], v[180:183], v[2:5]
	s_setprio 0
	s_mov_b32 s14, s1
	s_add_i32 s1, s1, 0x6000
	s_cmp_eq_u32 s1, 0x12000
	s_cselect_b32 s1, 0, s1
	s_mov_b32 s4, 0x8000
	s_mov_b32 s5, 0
	s_mov_b32 s10, 0x10000
	s_mov_b32 s11, 0
	s_mov_b32 s41, 0x3fd744fd
	s_waitcnt lgkmcnt(0)
; DEVI float blo(unsigned u) { return __uint_as_float(u << 16); }
; DEVI float bhi(unsigned u) { return __uint_as_float(u & 0xffff0000u); }
;     ...
;     for (int nf = 0; nf < 4; nf++)
; #pragma unroll
;       for (int mf = 0; mf < 8; mf++)
;         acc[nf][mf] = __builtin_amdgcn_mfma_f32_16x16x32_bf16(wb[nf], xa[mf], acc[nf][mf], 0, 0, 0);
;     ...
;         if (EPI == EPI_RESID || EPI == EPI_RESID_ATOMIC) {
;           f32x4 x = a;
;           if (EPI == EPI_RESID || kpart == 0) {
;             const u32x2 xr = *(const u32x2*)((const u16*)(p.ws + WS_XB) + (size_t)row * 1024 + col);
;             x[0] += ALPHA * blo(xr[0]); x[1] += ALPHA * bhi(xr[0]); x[2] += ALPHA * blo(xr[1]); x[3] += ALPHA * bhi(xr[1]);
;           }
;           if (EPI == EPI_RESID) *(f32x4*)((float*)(p.ws + WS_XF) + (size_t)row * 1024 + col) = x;
;           else *(f32x4*)((float*)(p.ws + WS_SLAB) + ((size_t)kpart * 512 + (row - T_P)) * 1024 + col) = x;
	v_mfma_f32_16x16x32_bf16 v[126:129], v[232:235], v[200:203], v[126:129]
	v_mfma_f32_16x16x32_bf16 v[122:125], v[232:235], v[204:207], v[122:125]
	v_mfma_f32_16x16x32_bf16 v[118:121], v[232:235], v[208:211], v[118:121]
	v_mfma_f32_16x16x32_bf16 v[114:117], v[232:235], v[212:215], v[114:117]
	v_mfma_f32_16x16x32_bf16 v[110:113], v[232:235], v[216:219], v[110:113]
	v_mfma_f32_16x16x32_bf16 v[106:109], v[232:235], v[220:223], v[106:109]
	v_mfma_f32_16x16x32_bf16 v[102:105], v[232:235], v[224:227], v[102:105]
	v_mfma_f32_16x16x32_bf16 v[98:101], v[232:235], v[228:231], v[98:101]
	v_mfma_f32_16x16x32_bf16 v[94:97], v[236:239], v[200:203], v[94:97]
	v_mfma_f32_16x16x32_bf16 v[90:93], v[236:239], v[204:207], v[90:93]
	v_mfma_f32_16x16x32_bf16 v[86:89], v[236:239], v[208:211], v[86:89]
	v_mfma_f32_16x16x32_bf16 v[82:85], v[236:239], v[212:215], v[82:85]
	v_mfma_f32_16x16x32_bf16 v[78:81], v[236:239], v[216:219], v[78:81]
	v_mfma_f32_16x16x32_bf16 v[74:77], v[236:239], v[220:223], v[74:77]
	v_mfma_f32_16x16x32_bf16 v[70:73], v[236:239], v[224:227], v[70:73]
	v_mfma_f32_16x16x32_bf16 v[66:69], v[236:239], v[228:231], v[66:69]
	v_mfma_f32_16x16x32_bf16 v[62:65], v[240:243], v[200:203], v[62:65]
	v_mfma_f32_16x16x32_bf16 v[58:61], v[240:243], v[204:207], v[58:61]
	v_mfma_f32_16x16x32_bf16 v[54:57], v[240:243], v[208:211], v[54:57]
	v_mfma_f32_16x16x32_bf16 v[50:53], v[240:243], v[212:215], v[50:53]
	v_mfma_f32_16x16x32_bf16 v[46:49], v[240:243], v[216:219], v[46:49]
	v_mfma_f32_16x16x32_bf16 v[42:45], v[240:243], v[220:223], v[42:45]
	v_mfma_f32_16x16x32_bf16 v[38:41], v[240:243], v[224:227], v[38:41]
	v_mfma_f32_16x16x32_bf16 v[34:37], v[240:243], v[228:231], v[34:37]
	v_mfma_f32_16x16x32_bf16 v[30:33], v[244:247], v[200:203], v[30:33]
	v_mfma_f32_16x16x32_bf16 v[26:29], v[244:247], v[204:207], v[26:29]
	v_mfma_f32_16x16x32_bf16 v[22:25], v[244:247], v[208:211], v[22:25]
	v_mfma_f32_16x16x32_bf16 v[18:21], v[244:247], v[212:215], v[18:21]
	v_mfma_f32_16x16x32_bf16 v[14:17], v[244:247], v[216:219], v[14:17]
	v_mfma_f32_16x16x32_bf16 v[10:13], v[244:247], v[220:223], v[10:13]
	v_mfma_f32_16x16x32_bf16 v[6:9], v[244:247], v[224:227], v[6:9]
	v_mfma_f32_16x16x32_bf16 v[2:5], v[244:247], v[228:231], v[2:5]
	s_mov_b32 m0, s40
	s_cmp_eq_u32 s98, 0
	s_cbranch_scc1 .Lta4_first
	s_nop 7
	global_store_dwordx4 v[140:141], v[126:129], off offset:0
	global_store_dwordx4 v[140:141], v[94:97], off offset:64
	global_store_dwordx4 v[140:141], v[62:65], off offset:128
	global_store_dwordx4 v[140:141], v[30:33], off offset:192
	v_lshl_add_u64 v[140:141], v[140:141], 0, s[10:11]
	global_store_dwordx4 v[140:141], v[122:125], off offset:0
	global_store_dwordx4 v[140:141], v[90:93], off offset:64
	global_store_dwordx4 v[140:141], v[58:61], off offset:128
	global_store_dwordx4 v[140:141], v[26:29], off offset:192
	v_lshl_add_u64 v[140:141], v[140:141], 0, s[10:11]
	global_store_dwordx4 v[140:141], v[118:121], off offset:0
	global_store_dwordx4 v[140:141], v[86:89], off offset:64
	global_store_dwordx4 v[140:141], v[54:57], off offset:128
	global_store_dwordx4 v[140:141], v[22:25], off offset:192
	v_lshl_add_u64 v[140:141], v[140:141], 0, s[10:11]
	global_store_dwordx4 v[140:141], v[114:117], off offset:0
	global_store_dwordx4 v[140:141], v[82:85], off offset:64
	global_store_dwordx4 v[140:141], v[50:53], off offset:128
	global_store_dwordx4 v[140:141], v[18:21], off offset:192
	v_lshl_add_u64 v[140:141], v[140:141], 0, s[10:11]
	global_store_dwordx4 v[140:141], v[110:113], off offset:0
	global_store_dwordx4 v[140:141], v[78:81], off offset:64
	global_store_dwordx4 v[140:141], v[46:49], off offset:128
	global_store_dwordx4 v[140:141], v[14:17], off offset:192
	v_lshl_add_u64 v[140:141], v[140:141], 0, s[10:11]
	global_store_dwordx4 v[140:141], v[106:109], off offset:0
	global_store_dwordx4 v[140:141], v[74:77], off offset:64
	global_store_dwordx4 v[140:141], v[42:45], off offset:128
	global_store_dwordx4 v[140:141], v[10:13], off offset:192
	v_lshl_add_u64 v[140:141], v[140:141], 0, s[10:11]
	global_store_dwordx4 v[140:141], v[102:105], off offset:0
	global_store_dwordx4 v[140:141], v[70:73], off offset:64
	global_store_dwordx4 v[140:141], v[38:41], off offset:128
	global_store_dwordx4 v[140:141], v[6:9], off offset:192
	v_lshl_add_u64 v[140:141], v[140:141], 0, s[10:11]
	global_store_dwordx4 v[140:141], v[98:101], off offset:0
	global_store_dwordx4 v[140:141], v[66:69], off offset:64
	global_store_dwordx4 v[140:141], v[34:37], off offset:128
	global_store_dwordx4 v[140:141], v[2:5], off offset:192
	s_branch .LBB0_757

; #define LAS __attribute__((address_space(3)))
;     ...
;   const int nk = (nk_part < 0) ? (K >> 5) : nk_part;
;   const int lrow = tid >> 2, lpc = tid & 3;
;   const int lch = lpc ^ ((0x78 >> (((lrow >> 2) & 3) * 2)) & 3);
;   const u16* ga = A + (size_t)(m0 + lrow) * lda + kbeg + lch * 8;
;   const u16* gb = Bt + (size_t)(n0 + lrow) * K + kbeg + lch * 8;
;   const size_t ga1 = (size_t)64 * lda, gb1 = (size_t)64 * K;
;   const unsigned lds0 = (unsigned)(uintptr_t)(LAS char*)smem + (unsigned)__builtin_amdgcn_readfirstlane(wid) * 1024u;
;     ...
;   __syncthreads();
;   G2_STAGE(0); G2_STAGE(1);
.LBB0_812:
	s_and_b64 vcc, exec, s[2:3]
	s_cbranch_vccz .LBB0_757
	s_lshr_b32 s46, s39, 6
	s_and_b32 s47, s39, 63
	s_lshr_b32 s43, s47, 3
	s_and_b32 s47, s47, 7
	s_lshl_b32 s46, s46, 3
	s_add_i32 s46, s46, s47
	v_readlane_b32 s2, v250, 5
	v_readlane_b32 s3, v250, 6
	v_readlane_b32 s47, v254, 62
	s_mul_i32 s41, s46, 0x80000
	s_add_u32 s4, s2, s41
	s_addc_u32 s5, s3, 0
	s_add_u32 s4, s4, 0xb580000
	s_addc_u32 s5, s5, 0
	s_mul_i32 s41, s47, 0x200000
	s_mul_i32 s42, s43, 0x40000
	s_add_i32 s41, s41, s42
	s_add_u32 s10, s2, s41
	s_addc_u32 s11, s3, 0
	s_add_u32 s10, s10, 0x15e00000
	s_addc_u32 s11, s11, 0
	s_movk_i32 s40, 0x78
	v_lshrrev_b32_e32 v0, 2, v145
	v_and_b32_e32 v131, 3, v145
	v_bfe_u32 v136, v145, 4, 2
	v_lshlrev_b32_e32 v136, 1, v136
	v_lshrrev_b32_e64 v136, v136, s40
	v_and_b32_e32 v136, 3, v136
	v_xor_b32_e32 v131, v131, v136
	v_lshlrev_b32_e32 v131, 4, v131
	s_movk_i32 s42, 0x800
	v_mad_u32_u24 v0, v0, s42, v131
	v_bfe_u32 v137, v145, 2, 1
	s_movk_i32 s42, 0x7c0
	v_mul_u32_u24_e32 v136, s42, v137
	v_sub_u32_e32 v136, v0, v136
	v_mov_b32_e32 v137, 0
	v_lshl_add_u64 v[134:135], s[10:11], 0, v[136:137]
	v_bfe_u32 v137, v145, 2, 1
	s_mov_b32 s12, 64
	s_mov_b32 s13, 0
	v_lshl_add_u64 v[132:133], s[4:5], 0, v[0:1]
	v_bfe_u32 v136, v145, 2, 2
	v_lshlrev_b32_e32 v136, 1, v136
	v_lshrrev_b32_e64 v136, v136, s40
	v_and_b32_e32 v136, 3, v136
	v_bfe_u32 v137, v145, 4, 2
	v_xor_b32_e32 v136, v136, v137
	v_lshlrev_b32_e32 v136, 4, v136
	v_and_b32_e32 v131, 15, v145
	v_lshl_or_b32 v136, v131, 6, v136
	v_bfe_u32 v137, v145, 6, 1
	v_lshl_or_b32 v137, v137, 12, v136
	v_lshrrev_b32_e32 v0, 7, v145
	v_lshl_or_b32 v136, v0, 13, v136
	v_and_b32_e32 v140, 1, v131
	v_lshl_or_b32 v131, v0, 7, v131
	v_bfe_u32 v0, v145, 4, 2
	v_lshlrev_b32_e32 v0, 3, v0
	v_bfe_u32 v141, v145, 6, 1
	s_lshl_b32 s41, s46, 19
	s_lshl_b32 s42, s43, 9
	s_add_i32 s41, s41, s42
	s_add_u32 s4, s2, s41
	s_addc_u32 s5, s3, 0
	s_add_u32 s4, s4, 0x4200000
	s_addc_u32 s5, s5, 0
	v_lshlrev_b32_e32 v138, 11, v131
	v_lshl_add_u32 v138, v141, 8, v138
	v_bfe_u32 v139, v145, 4, 1
	v_lshl_add_u32 v138, v139, 5, v138
	v_bfe_u32 v139, v145, 5, 1
	v_lshl_add_u32 v138, v139, 4, v138
	s_movk_i32 s42, 1984
	v_mul_u32_u24_e32 v139, s42, v140
	v_sub_u32_e32 v138, v138, v139
	v_mov_b32_e32 v139, 0
	v_lshl_add_u64 v[138:139], s[4:5], 0, v[138:139]
	s_lshl_b32 s41, s46, 20
	s_lshl_b32 s42, s43, 9
	s_add_i32 s41, s41, s42
	s_add_u32 s10, s2, s41
	s_addc_u32 s11, s3, 0
	v_lshlrev_b32_e32 v140, 12, v131
	v_lshl_add_u32 v140, v141, 8, v140
	v_lshl_add_u32 v140, v0, 1, v140
	v_mov_b32_e32 v141, 0
	v_lshl_add_u64 v[140:141], s[10:11], 0, v[140:141]
	s_mov_b32 s2, 0x20000
	s_mov_b32 s3, 0
	v_lshrrev_b32_e32 v0, 6, v145
	v_lshlrev_b32_e32 v0, 10, v0
	s_nop 0
	v_readfirstlane_b32 s47, v0
	s_mov_b32 s44, m0
	s_mov_b32 s4, 128
	s_mov_b32 s5, 0
	s_barrier
	s_add_i32 s43, s47, 0x0
	s_mov_b32 m0, s43
	v_lshl_add_u64 v[142:143], v[132:133], 0, s[2:3]
	global_load_lds_dwordx4 v[132:133], off
	s_addk_i32 m0, 0x1000
	s_nop 0
	global_load_lds_dwordx4 v[142:143], off
	v_lshl_add_u64 v[142:143], v[142:143], 0, s[2:3]
	s_addk_i32 m0, 0x1000
	s_nop 0
	global_load_lds_dwordx4 v[142:143], off
	v_lshl_add_u64 v[142:143], v[142:143], 0, s[2:3]
	s_addk_i32 m0, 0x1000
	s_nop 0
	global_load_lds_dwordx4 v[142:143], off
	s_addk_i32 m0, 0x1000
	v_lshl_add_u64 v[142:143], v[134:135], 0, s[2:3]
	s_nop 0
	global_load_lds_dwordx4 v[134:135], off
	s_addk_i32 m0, 0x1000
	v_lshl_add_u64 v[132:133], v[132:133], 0, s[12:13]
	s_nop 0
	global_load_lds_dwordx4 v[142:143], off
	v_lshl_add_u64 v[134:135], v[134:135], 0, s[4:5]
	s_nop 0
	s_add_i32 s43, s47, 0x6000
	s_mov_b32 m0, s43
	v_lshl_add_u64 v[142:143], v[132:133], 0, s[2:3]
	global_load_lds_dwordx4 v[132:133], off
	s_addk_i32 m0, 0x1000
	s_nop 0
	global_load_lds_dwordx4 v[142:143], off
	v_lshl_add_u64 v[142:143], v[142:143], 0, s[2:3]
	s_addk_i32 m0, 0x1000
	s_nop 0
	global_load_lds_dwordx4 v[142:143], off
	v_lshl_add_u64 v[142:143], v[142:143], 0, s[2:3]
	s_addk_i32 m0, 0x1000
	s_nop 0
	global_load_lds_dwordx4 v[142:143], off
	s_addk_i32 m0, 0x1000
	v_lshl_add_u64 v[142:143], v[134:135], 0, s[2:3]
	s_nop 0
	global_load_lds_dwordx4 v[134:135], off
	s_addk_i32 m0, 0x1000
	v_lshl_add_u64 v[132:133], v[132:133], 0, s[12:13]
	s_nop 0
	global_load_lds_dwordx4 v[142:143], off
	v_lshl_add_u64 v[134:135], v[134:135], 0, s[4:5]
	s_nop 0
	s_add_i32 s43, s47, 0xc000
	s_mov_b32 m0, s43
	v_lshl_add_u64 v[142:143], v[132:133], 0, s[2:3]
	global_load_lds_dwordx4 v[132:133], off
	s_addk_i32 m0, 0x1000
	s_nop 0
	global_load_lds_dwordx4 v[142:143], off
	v_lshl_add_u64 v[142:143], v[142:143], 0, s[2:3]
	s_addk_i32 m0, 0x1000
	s_nop 0
	global_load_lds_dwordx4 v[142:143], off
	v_lshl_add_u64 v[142:143], v[142:143], 0, s[2:3]
	s_addk_i32 m0, 0x1000
	s_nop 0
	global_load_lds_dwordx4 v[142:143], off
	s_addk_i32 m0, 0x1000
	v_lshl_add_u64 v[142:143], v[134:135], 0, s[2:3]
	s_nop 0
	global_load_lds_dwordx4 v[134:135], off
	s_addk_i32 m0, 0x1000
	v_lshl_add_u64 v[132:133], v[132:133], 0, s[12:13]
	s_nop 0
	global_load_lds_dwordx4 v[142:143], off
	v_lshl_add_u64 v[134:135], v[134:135], 0, s[4:5]
	s_nop 0
	v_mov_b32_e32 v2, 0
	v_mov_b32_e32 v3, 0
	v_mov_b32_e32 v4, 0
	v_mov_b32_e32 v5, 0
	v_mov_b32_e32 v6, 0
	v_mov_b32_e32 v7, 0
	v_mov_b32_e32 v8, 0
	v_mov_b32_e32 v9, 0
	v_mov_b32_e32 v10, 0
	v_mov_b32_e32 v11, 0
	v_mov_b32_e32 v12, 0
	v_mov_b32_e32 v13, 0
	v_mov_b32_e32 v14, 0
	v_mov_b32_e32 v15, 0
	v_mov_b32_e32 v16, 0
	v_mov_b32_e32 v17, 0
	v_mov_b32_e32 v18, 0
	v_mov_b32_e32 v19, 0
	v_mov_b32_e32 v20, 0
	v_mov_b32_e32 v21, 0
	v_mov_b32_e32 v22, 0
	v_mov_b32_e32 v23, 0
	v_mov_b32_e32 v24, 0
	v_mov_b32_e32 v25, 0
; #define LAS __attribute__((address_space(3)))
;     ...
;   f32x4 acc[4][8];
; #pragma unroll
;   for (int i = 0; i < 4; i++)
; #pragma unroll
;     for (int j = 0; j < 8; j++) acc[i][j] = (f32x4){0.f, 0.f, 0.f, 0.f};
;   const int nk = (nk_part < 0) ? (K >> 5) : nk_part;
;   const int lrow = tid >> 2, lpc = tid & 3;
;   const int lch = lpc ^ ((0x78 >> (((lrow >> 2) & 3) * 2)) & 3);
;   const u16* ga = A + (size_t)(m0 + lrow) * lda + kbeg + lch * 8;
;   const u16* gb = Bt + (size_t)(n0 + lrow) * K + kbeg + lch * 8;
;   const size_t ga1 = (size_t)64 * lda, gb1 = (size_t)64 * K;
;   const unsigned lds0 = (unsigned)(uintptr_t)(LAS char*)smem + (unsigned)__builtin_amdgcn_readfirstlane(wid) * 1024u;
;     ...
;   __syncthreads();
;   G2_STAGE(0); G2_STAGE(1);
;   const int fsw = (0x78 >> (((r16 >> 2) & 3) * 2)) & 3;
;   const int aoff = (wm * 128 + r16) * 64 + ((quad ^ fsw) << 4);
;   const int boff = 16384 + (wn * 64 + r16) * 64 + ((quad ^ fsw) << 4);
;   for (int kt = 0; kt < nk; kt++) {
;     if (kt + 1 < nk) asm volatile("s_waitcnt vmcnt(6)" ::: "memory");
;     else asm volatile("s_waitcnt vmcnt(0)" ::: "memory");
;     __builtin_amdgcn_s_barrier();
;     asm volatile("" ::: "memory");
;     if (kt + 2 < nk) G2_STAGE(kt + 2);
;     const char* cS = smem + (kt % 3) * 24576;
;     bf16x8 xa[8], wb[4];
; #pragma unroll
;     for (int f = 0; f < 8; f++) xa[f] = *(const bf16x8*)(cS + aoff + f * 1024);
; #pragma unroll
;     for (int f = 0; f < 4; f++) wb[f] = *(const bf16x8*)(cS + boff + f * 1024);
; #pragma unroll
;     for (int nf = 0; nf < 4; nf++)
; #pragma unroll
;       for (int mf = 0; mf < 8; mf++)
;         acc[nf][mf] = __builtin_amdgcn_mfma_f32_16x16x32_bf16(wb[nf], xa[mf], acc[nf][mf], 0, 0, 0);
;   }
	v_mov_b32_e32 v26, 0
	v_mov_b32_e32 v27, 0
	v_mov_b32_e32 v28, 0
	v_mov_b32_e32 v29, 0
	v_mov_b32_e32 v30, 0
	v_mov_b32_e32 v31, 0
	v_mov_b32_e32 v32, 0
	v_mov_b32_e32 v33, 0
	v_mov_b32_e32 v34, 0
	v_mov_b32_e32 v35, 0
	v_mov_b32_e32 v36, 0
	v_mov_b32_e32 v37, 0
	v_mov_b32_e32 v38, 0
	v_mov_b32_e32 v39, 0
	v_mov_b32_e32 v40, 0
	v_mov_b32_e32 v41, 0
	v_mov_b32_e32 v42, 0
	v_mov_b32_e32 v43, 0
	v_mov_b32_e32 v44, 0
	v_mov_b32_e32 v45, 0
	v_mov_b32_e32 v46, 0
	v_mov_b32_e32 v47, 0
	v_mov_b32_e32 v48, 0
	v_mov_b32_e32 v49, 0
	v_mov_b32_e32 v50, 0
	v_mov_b32_e32 v51, 0
	v_mov_b32_e32 v52, 0
	v_mov_b32_e32 v53, 0
	v_mov_b32_e32 v54, 0
	v_mov_b32_e32 v55, 0
	v_mov_b32_e32 v56, 0
	v_mov_b32_e32 v57, 0
	v_mov_b32_e32 v58, 0
	v_mov_b32_e32 v59, 0
	v_mov_b32_e32 v60, 0
	v_mov_b32_e32 v61, 0
	v_mov_b32_e32 v62, 0
	v_mov_b32_e32 v63, 0
	v_mov_b32_e32 v64, 0
	v_mov_b32_e32 v65, 0
	v_mov_b32_e32 v66, 0
	v_mov_b32_e32 v67, 0
	v_mov_b32_e32 v68, 0
	v_mov_b32_e32 v69, 0
	v_mov_b32_e32 v70, 0
	v_mov_b32_e32 v71, 0
	v_mov_b32_e32 v72, 0
	v_mov_b32_e32 v73, 0
	v_mov_b32_e32 v74, 0
	v_mov_b32_e32 v75, 0
	v_mov_b32_e32 v76, 0
	v_mov_b32_e32 v77, 0
	v_mov_b32_e32 v78, 0
	v_mov_b32_e32 v79, 0
	v_mov_b32_e32 v80, 0
	v_mov_b32_e32 v81, 0
	v_mov_b32_e32 v82, 0
	v_mov_b32_e32 v83, 0
	v_mov_b32_e32 v84, 0
	v_mov_b32_e32 v85, 0
	v_mov_b32_e32 v86, 0
	v_mov_b32_e32 v87, 0
	v_mov_b32_e32 v88, 0
	v_mov_b32_e32 v89, 0
	v_mov_b32_e32 v90, 0
	v_mov_b32_e32 v91, 0
	v_mov_b32_e32 v92, 0
	v_mov_b32_e32 v93, 0
	v_mov_b32_e32 v94, 0
	v_mov_b32_e32 v95, 0
	v_mov_b32_e32 v96, 0
	v_mov_b32_e32 v97, 0
	v_mov_b32_e32 v98, 0
	v_mov_b32_e32 v99, 0
	v_mov_b32_e32 v100, 0
	v_mov_b32_e32 v101, 0
	v_mov_b32_e32 v102, 0
	v_mov_b32_e32 v103, 0
	v_mov_b32_e32 v104, 0
	v_mov_b32_e32 v105, 0
	v_mov_b32_e32 v106, 0
	v_mov_b32_e32 v107, 0
	v_mov_b32_e32 v108, 0
	v_mov_b32_e32 v109, 0
	v_mov_b32_e32 v110, 0
	v_mov_b32_e32 v111, 0
	v_mov_b32_e32 v112, 0
	v_mov_b32_e32 v113, 0
	v_mov_b32_e32 v114, 0
	v_mov_b32_e32 v115, 0
	v_mov_b32_e32 v116, 0
	v_mov_b32_e32 v117, 0
	v_mov_b32_e32 v118, 0
	v_mov_b32_e32 v119, 0
	v_mov_b32_e32 v120, 0
	v_mov_b32_e32 v121, 0
	v_mov_b32_e32 v122, 0
	v_mov_b32_e32 v123, 0
	v_mov_b32_e32 v124, 0
	v_mov_b32_e32 v125, 0
	v_mov_b32_e32 v126, 0
	v_mov_b32_e32 v127, 0
	v_mov_b32_e32 v128, 0
	v_mov_b32_e32 v129, 0
	s_waitcnt vmcnt(12)
	s_barrier
	ds_read_b128 v[146:149], v136 offset:0
	ds_read_b128 v[152:155], v136 offset:1024
	ds_read_b128 v[156:159], v136 offset:2048
	ds_read_b128 v[162:165], v136 offset:3072
	ds_read_b128 v[166:169], v136 offset:4096
	ds_read_b128 v[170:173], v136 offset:5120
	ds_read_b128 v[176:179], v136 offset:6144
	ds_read_b128 v[180:183], v136 offset:7168
	ds_read_b128 v[184:187], v137 offset:16384
	ds_read_b128 v[188:191], v137 offset:17408
	ds_read_b128 v[192:195], v137 offset:18432
	ds_read_b128 v[196:199], v137 offset:19456
	s_movk_i32 s41, 0x6000
	s_mov_b32 s42, 0
	s_movk_i32 s40, 14
.Lt4_loop:
	s_waitcnt vmcnt(6) lgkmcnt(0)
	s_barrier
	s_setprio 1
	v_add_u32_e32 v144, s41, v136
	v_mfma_f32_16x16x32_bf16 v[126:129], v[184:187], v[146:149], v[126:129]
	ds_read_b128 v[200:203], v144 offset:0
	v_mfma_f32_16x16x32_bf16 v[122:125], v[184:187], v[152:155], v[122:125]
	ds_read_b128 v[204:207], v144 offset:1024
	v_mfma_f32_16x16x32_bf16 v[118:121], v[184:187], v[156:159], v[118:121]
	ds_read_b128 v[208:211], v144 offset:2048
	v_mfma_f32_16x16x32_bf16 v[114:117], v[184:187], v[162:165], v[114:117]
	ds_read_b128 v[212:215], v144 offset:3072
	v_mfma_f32_16x16x32_bf16 v[110:113], v[184:187], v[166:169], v[110:113]
	ds_read_b128 v[216:219], v144 offset:4096
	v_mfma_f32_16x16x32_bf16 v[106:109], v[184:187], v[170:173], v[106:109]
	ds_read_b128 v[220:223], v144 offset:5120
	v_mfma_f32_16x16x32_bf16 v[102:105], v[184:187], v[176:179], v[102:105]
	ds_read_b128 v[224:227], v144 offset:6144
	v_mfma_f32_16x16x32_bf16 v[98:101], v[184:187], v[180:183], v[98:101]
	ds_read_b128 v[228:231], v144 offset:7168
	v_mfma_f32_16x16x32_bf16 v[94:97], v[188:191], v[146:149], v[94:97]
	v_add_u32_e32 v144, s41, v137
	v_mfma_f32_16x16x32_bf16 v[90:93], v[188:191], v[152:155], v[90:93]
	v_mfma_f32_16x16x32_bf16 v[86:89], v[188:191], v[156:159], v[86:89]
	ds_read_b128 v[232:235], v144 offset:16384
	v_mfma_f32_16x16x32_bf16 v[82:85], v[188:191], v[162:165], v[82:85]
	ds_read_b128 v[236:239], v144 offset:17408
	v_mfma_f32_16x16x32_bf16 v[78:81], v[188:191], v[166:169], v[78:81]
	ds_read_b128 v[240:243], v144 offset:18432
	v_mfma_f32_16x16x32_bf16 v[74:77], v[188:191], v[170:173], v[74:77]
	ds_read_b128 v[244:247], v144 offset:19456
	s_add_i32 s43, s47, s42
	v_mfma_f32_16x16x32_bf16 v[70:73], v[188:191], v[176:179], v[70:73]
	s_mov_b32 m0, s43
	v_lshl_add_u64 v[142:143], v[132:133], 0, s[2:3]
	v_mfma_f32_16x16x32_bf16 v[66:69], v[188:191], v[180:183], v[66:69]
	global_load_lds_dwordx4 v[132:133], off
	s_addk_i32 m0, 0x1000
	v_mfma_f32_16x16x32_bf16 v[62:65], v[192:195], v[146:149], v[62:65]
	v_mfma_f32_16x16x32_bf16 v[58:61], v[192:195], v[152:155], v[58:61]
	v_mfma_f32_16x16x32_bf16 v[54:57], v[192:195], v[156:159], v[54:57]
	global_load_lds_dwordx4 v[142:143], off
	v_lshl_add_u64 v[142:143], v[142:143], 0, s[2:3]
	s_addk_i32 m0, 0x1000
	v_mfma_f32_16x16x32_bf16 v[50:53], v[192:195], v[162:165], v[50:53]
	v_mfma_f32_16x16x32_bf16 v[46:49], v[192:195], v[166:169], v[46:49]
	v_mfma_f32_16x16x32_bf16 v[42:45], v[192:195], v[170:173], v[42:45]
	global_load_lds_dwordx4 v[142:143], off
	v_lshl_add_u64 v[142:143], v[142:143], 0, s[2:3]
	s_addk_i32 m0, 0x1000
	v_mfma_f32_16x16x32_bf16 v[38:41], v[192:195], v[176:179], v[38:41]
	v_mfma_f32_16x16x32_bf16 v[34:37], v[192:195], v[180:183], v[34:37]
	v_mfma_f32_16x16x32_bf16 v[30:33], v[196:199], v[146:149], v[30:33]
	global_load_lds_dwordx4 v[142:143], off
	s_addk_i32 m0, 0x1000
	v_lshl_add_u64 v[142:143], v[134:135], 0, s[2:3]
	v_mfma_f32_16x16x32_bf16 v[26:29], v[196:199], v[152:155], v[26:29]
	v_mfma_f32_16x16x32_bf16 v[22:25], v[196:199], v[156:159], v[22:25]
	v_mfma_f32_16x16x32_bf16 v[18:21], v[196:199], v[162:165], v[18:21]
	global_load_lds_dwordx4 v[134:135], off
	s_addk_i32 m0, 0x1000
	v_lshl_add_u64 v[132:133], v[132:133], 0, s[12:13]
	v_mfma_f32_16x16x32_bf16 v[14:17], v[196:199], v[166:169], v[14:17]
	v_mfma_f32_16x16x32_bf16 v[10:13], v[196:199], v[170:173], v[10:13]
	v_mfma_f32_16x16x32_bf16 v[6:9], v[196:199], v[176:179], v[6:9]
	global_load_lds_dwordx4 v[142:143], off
	v_lshl_add_u64 v[134:135], v[134:135], 0, s[4:5]
	v_mfma_f32_16x16x32_bf16 v[2:5], v[196:199], v[180:183], v[2:5]
	s_setprio 0
	s_mov_b32 s42, s41
	s_add_i32 s41, s41, 0x6000
	s_cmp_eq_u32 s41, 0x12000
	s_cselect_b32 s41, 0, s41
	s_waitcnt vmcnt(6) lgkmcnt(0)
	s_barrier
;     ...
;   for (int kt = 0; kt < nk; kt++) {
;     if (kt + 1 < nk) asm volatile("s_waitcnt vmcnt(6)" ::: "memory");
;     else asm volatile("s_waitcnt vmcnt(0)" ::: "memory");
;     __builtin_amdgcn_s_barrier();
;     asm volatile("" ::: "memory");
;     if (kt + 2 < nk) G2_STAGE(kt + 2);
;     const char* cS = smem + (kt % 3) * 24576;
;     bf16x8 xa[8], wb[4];
; #pragma unroll
;     for (int f = 0; f < 8; f++) xa[f] = *(const bf16x8*)(cS + aoff + f * 1024);
; #pragma unroll
;     for (int f = 0; f < 4; f++) wb[f] = *(const bf16x8*)(cS + boff + f * 1024);
; #pragma unroll
;     for (int nf = 0; nf < 4; nf++)
; #pragma unroll
;       for (int mf = 0; mf < 8; mf++)
;         acc[nf][mf] = __builtin_amdgcn_mfma_f32_16x16x32_bf16(wb[nf], xa[mf], acc[nf][mf], 0, 0, 0);
;   }
	s_setprio 1
	v_add_u32_e32 v144, s41, v136
	v_mfma_f32_16x16x32_bf16 v[126:129], v[232:235], v[200:203], v[126:129]
	ds_read_b128 v[146:149], v144 offset:0
	v_mfma_f32_16x16x32_bf16 v[122:125], v[232:235], v[204:207], v[122:125]
	ds_read_b128 v[152:155], v144 offset:1024
	v_mfma_f32_16x16x32_bf16 v[118:121], v[232:235], v[208:211], v[118:121]
	ds_read_b128 v[156:159], v144 offset:2048
	v_mfma_f32_16x16x32_bf16 v[114:117], v[232:235], v[212:215], v[114:117]
	ds_read_b128 v[162:165], v144 offset:3072
	v_mfma_f32_16x16x32_bf16 v[110:113], v[232:235], v[216:219], v[110:113]
	ds_read_b128 v[166:169], v144 offset:4096
	v_mfma_f32_16x16x32_bf16 v[106:109], v[232:235], v[220:223], v[106:109]
	ds_read_b128 v[170:173], v144 offset:5120
	v_mfma_f32_16x16x32_bf16 v[102:105], v[232:235], v[224:227], v[102:105]
	ds_read_b128 v[176:179], v144 offset:6144
	v_mfma_f32_16x16x32_bf16 v[98:101], v[232:235], v[228:231], v[98:101]
	ds_read_b128 v[180:183], v144 offset:7168
	v_mfma_f32_16x16x32_bf16 v[94:97], v[236:239], v[200:203], v[94:97]
	v_add_u32_e32 v144, s41, v137
	v_mfma_f32_16x16x32_bf16 v[90:93], v[236:239], v[204:207], v[90:93]
	v_mfma_f32_16x16x32_bf16 v[86:89], v[236:239], v[208:211], v[86:89]
	ds_read_b128 v[184:187], v144 offset:16384
	v_mfma_f32_16x16x32_bf16 v[82:85], v[236:239], v[212:215], v[82:85]
	ds_read_b128 v[188:191], v144 offset:17408
	v_mfma_f32_16x16x32_bf16 v[78:81], v[236:239], v[216:219], v[78:81]
	ds_read_b128 v[192:195], v144 offset:18432
	v_mfma_f32_16x16x32_bf16 v[74:77], v[236:239], v[220:223], v[74:77]
	ds_read_b128 v[196:199], v144 offset:19456
	s_add_i32 s43, s47, s42
	v_mfma_f32_16x16x32_bf16 v[70:73], v[236:239], v[224:227], v[70:73]
	s_mov_b32 m0, s43
	v_lshl_add_u64 v[142:143], v[132:133], 0, s[2:3]
	v_mfma_f32_16x16x32_bf16 v[66:69], v[236:239], v[228:231], v[66:69]
	global_load_lds_dwordx4 v[132:133], off
	s_addk_i32 m0, 0x1000
	v_mfma_f32_16x16x32_bf16 v[62:65], v[240:243], v[200:203], v[62:65]
	v_mfma_f32_16x16x32_bf16 v[58:61], v[240:243], v[204:207], v[58:61]
	v_mfma_f32_16x16x32_bf16 v[54:57], v[240:243], v[208:211], v[54:57]
	global_load_lds_dwordx4 v[142:143], off
	v_lshl_add_u64 v[142:143], v[142:143], 0, s[2:3]
	s_addk_i32 m0, 0x1000
	v_mfma_f32_16x16x32_bf16 v[50:53], v[240:243], v[212:215], v[50:53]
	v_mfma_f32_16x16x32_bf16 v[46:49], v[240:243], v[216:219], v[46:49]
	v_mfma_f32_16x16x32_bf16 v[42:45], v[240:243], v[220:223], v[42:45]
	global_load_lds_dwordx4 v[142:143], off
	v_lshl_add_u64 v[142:143], v[142:143], 0, s[2:3]
	s_addk_i32 m0, 0x1000
	v_mfma_f32_16x16x32_bf16 v[38:41], v[240:243], v[224:227], v[38:41]
	v_mfma_f32_16x16x32_bf16 v[34:37], v[240:243], v[228:231], v[34:37]
	v_mfma_f32_16x16x32_bf16 v[30:33], v[244:247], v[200:203], v[30:33]
	global_load_lds_dwordx4 v[142:143], off
	s_addk_i32 m0, 0x1000
	v_lshl_add_u64 v[142:143], v[134:135], 0, s[2:3]
	v_mfma_f32_16x16x32_bf16 v[26:29], v[244:247], v[204:207], v[26:29]
	v_mfma_f32_16x16x32_bf16 v[22:25], v[244:247], v[208:211], v[22:25]
	v_mfma_f32_16x16x32_bf16 v[18:21], v[244:247], v[212:215], v[18:21]
	global_load_lds_dwordx4 v[134:135], off
	s_addk_i32 m0, 0x1000
	v_lshl_add_u64 v[132:133], v[132:133], 0, s[12:13]
	v_mfma_f32_16x16x32_bf16 v[14:17], v[244:247], v[216:219], v[14:17]
	v_mfma_f32_16x16x32_bf16 v[10:13], v[244:247], v[220:223], v[10:13]
	v_mfma_f32_16x16x32_bf16 v[6:9], v[244:247], v[224:227], v[6:9]
	global_load_lds_dwordx4 v[142:143], off
	v_lshl_add_u64 v[134:135], v[134:135], 0, s[4:5]
	v_mfma_f32_16x16x32_bf16 v[2:5], v[244:247], v[228:231], v[2:5]
	s_setprio 0
	s_mov_b32 s42, s41
	s_add_i32 s41, s41, 0x6000
	s_cmp_eq_u32 s41, 0x12000
	s_cselect_b32 s41, 0, s41
	s_sub_i32 s40, s40, 1
	s_cmp_lg_u32 s40, 0
	s_cbranch_scc1 .Lt4_loop
	s_waitcnt vmcnt(6) lgkmcnt(0)
	s_barrier
	s_setprio 1
	v_add_u32_e32 v144, s41, v136
	v_mfma_f32_16x16x32_bf16 v[126:129], v[184:187], v[146:149], v[126:129]
	ds_read_b128 v[200:203], v144 offset:0
	v_mfma_f32_16x16x32_bf16 v[122:125], v[184:187], v[152:155], v[122:125]
	ds_read_b128 v[204:207], v144 offset:1024
	v_mfma_f32_16x16x32_bf16 v[118:121], v[184:187], v[156:159], v[118:121]
	ds_read_b128 v[208:211], v144 offset:2048
	v_mfma_f32_16x16x32_bf16 v[114:117], v[184:187], v[162:165], v[114:117]
	ds_read_b128 v[212:215], v144 offset:3072
	v_mfma_f32_16x16x32_bf16 v[110:113], v[184:187], v[166:169], v[110:113]
	ds_read_b128 v[216:219], v144 offset:4096
	v_mfma_f32_16x16x32_bf16 v[106:109], v[184:187], v[170:173], v[106:109]
	ds_read_b128 v[220:223], v144 offset:5120
	v_mfma_f32_16x16x32_bf16 v[102:105], v[184:187], v[176:179], v[102:105]
	ds_read_b128 v[224:227], v144 offset:6144
	v_mfma_f32_16x16x32_bf16 v[98:101], v[184:187], v[180:183], v[98:101]
	ds_read_b128 v[228:231], v144 offset:7168
	v_mfma_f32_16x16x32_bf16 v[94:97], v[188:191], v[146:149], v[94:97]
	v_add_u32_e32 v144, s41, v137
	v_mfma_f32_16x16x32_bf16 v[90:93], v[188:191], v[152:155], v[90:93]
	v_mfma_f32_16x16x32_bf16 v[86:89], v[188:191], v[156:159], v[86:89]
	ds_read_b128 v[232:235], v144 offset:16384
	v_mfma_f32_16x16x32_bf16 v[82:85], v[188:191], v[162:165], v[82:85]
	ds_read_b128 v[236:239], v144 offset:17408
	v_mfma_f32_16x16x32_bf16 v[78:81], v[188:191], v[166:169], v[78:81]
	ds_read_b128 v[240:243], v144 offset:18432
	v_mfma_f32_16x16x32_bf16 v[74:77], v[188:191], v[170:173], v[74:77]
	ds_read_b128 v[244:247], v144 offset:19456
	s_add_i32 s43, s47, s42
	v_mfma_f32_16x16x32_bf16 v[70:73], v[188:191], v[176:179], v[70:73]
	s_mov_b32 m0, s43
	v_lshl_add_u64 v[142:143], v[132:133], 0, s[2:3]
	v_mfma_f32_16x16x32_bf16 v[66:69], v[188:191], v[180:183], v[66:69]
	global_load_lds_dwordx4 v[132:133], off
	s_addk_i32 m0, 0x1000
;     ...
;   for (int kt = 0; kt < nk; kt++) {
;     if (kt + 1 < nk) asm volatile("s_waitcnt vmcnt(6)" ::: "memory");
;     else asm volatile("s_waitcnt vmcnt(0)" ::: "memory");
;     __builtin_amdgcn_s_barrier();
;     asm volatile("" ::: "memory");
;     if (kt + 2 < nk) G2_STAGE(kt + 2);
;     const char* cS = smem + (kt % 3) * 24576;
;     bf16x8 xa[8], wb[4];
; #pragma unroll
;     for (int f = 0; f < 8; f++) xa[f] = *(const bf16x8*)(cS + aoff + f * 1024);
; #pragma unroll
;     for (int f = 0; f < 4; f++) wb[f] = *(const bf16x8*)(cS + boff + f * 1024);
; #pragma unroll
;     for (int nf = 0; nf < 4; nf++)
; #pragma unroll
;       for (int mf = 0; mf < 8; mf++)
;         acc[nf][mf] = __builtin_amdgcn_mfma_f32_16x16x32_bf16(wb[nf], xa[mf], acc[nf][mf], 0, 0, 0);
;   }
	v_mfma_f32_16x16x32_bf16 v[62:65], v[192:195], v[146:149], v[62:65]
	v_mfma_f32_16x16x32_bf16 v[58:61], v[192:195], v[152:155], v[58:61]
	v_mfma_f32_16x16x32_bf16 v[54:57], v[192:195], v[156:159], v[54:57]
	global_load_lds_dwordx4 v[142:143], off
	v_lshl_add_u64 v[142:143], v[142:143], 0, s[2:3]
	s_addk_i32 m0, 0x1000
	v_mfma_f32_16x16x32_bf16 v[50:53], v[192:195], v[162:165], v[50:53]
	v_mfma_f32_16x16x32_bf16 v[46:49], v[192:195], v[166:169], v[46:49]
	v_mfma_f32_16x16x32_bf16 v[42:45], v[192:195], v[170:173], v[42:45]
	global_load_lds_dwordx4 v[142:143], off
	v_lshl_add_u64 v[142:143], v[142:143], 0, s[2:3]
	s_addk_i32 m0, 0x1000
	v_mfma_f32_16x16x32_bf16 v[38:41], v[192:195], v[176:179], v[38:41]
	v_mfma_f32_16x16x32_bf16 v[34:37], v[192:195], v[180:183], v[34:37]
	v_mfma_f32_16x16x32_bf16 v[30:33], v[196:199], v[146:149], v[30:33]
	global_load_lds_dwordx4 v[142:143], off
	s_addk_i32 m0, 0x1000
	v_lshl_add_u64 v[142:143], v[134:135], 0, s[2:3]
	v_mfma_f32_16x16x32_bf16 v[26:29], v[196:199], v[152:155], v[26:29]
	v_mfma_f32_16x16x32_bf16 v[22:25], v[196:199], v[156:159], v[22:25]
	v_mfma_f32_16x16x32_bf16 v[18:21], v[196:199], v[162:165], v[18:21]
	global_load_lds_dwordx4 v[134:135], off
	s_addk_i32 m0, 0x1000
	v_lshl_add_u64 v[132:133], v[132:133], 0, s[12:13]
	v_mfma_f32_16x16x32_bf16 v[14:17], v[196:199], v[166:169], v[14:17]
	v_mfma_f32_16x16x32_bf16 v[10:13], v[196:199], v[170:173], v[10:13]
	v_mfma_f32_16x16x32_bf16 v[6:9], v[196:199], v[176:179], v[6:9]
	global_load_lds_dwordx4 v[142:143], off
	v_lshl_add_u64 v[134:135], v[134:135], 0, s[4:5]
	v_mfma_f32_16x16x32_bf16 v[2:5], v[196:199], v[180:183], v[2:5]
	s_setprio 0
	s_mov_b32 s42, s41
	s_add_i32 s41, s41, 0x6000
	s_cmp_eq_u32 s41, 0x12000
	s_cselect_b32 s41, 0, s41
	s_waitcnt vmcnt(6) lgkmcnt(0)
	s_barrier
	s_setprio 1
	v_add_u32_e32 v144, s41, v136
	v_mfma_f32_16x16x32_bf16 v[126:129], v[232:235], v[200:203], v[126:129]
	ds_read_b128 v[146:149], v144 offset:0
	v_mfma_f32_16x16x32_bf16 v[122:125], v[232:235], v[204:207], v[122:125]
	ds_read_b128 v[152:155], v144 offset:1024
	v_mfma_f32_16x16x32_bf16 v[118:121], v[232:235], v[208:211], v[118:121]
	ds_read_b128 v[156:159], v144 offset:2048
	v_mfma_f32_16x16x32_bf16 v[114:117], v[232:235], v[212:215], v[114:117]
	ds_read_b128 v[162:165], v144 offset:3072
	v_mfma_f32_16x16x32_bf16 v[110:113], v[232:235], v[216:219], v[110:113]
	ds_read_b128 v[166:169], v144 offset:4096
	v_mfma_f32_16x16x32_bf16 v[106:109], v[232:235], v[220:223], v[106:109]
	ds_read_b128 v[170:173], v144 offset:5120
	v_mfma_f32_16x16x32_bf16 v[102:105], v[232:235], v[224:227], v[102:105]
	ds_read_b128 v[176:179], v144 offset:6144
	v_mfma_f32_16x16x32_bf16 v[98:101], v[232:235], v[228:231], v[98:101]
	ds_read_b128 v[180:183], v144 offset:7168
	v_mfma_f32_16x16x32_bf16 v[94:97], v[236:239], v[200:203], v[94:97]
	v_add_u32_e32 v144, s41, v137
	v_mfma_f32_16x16x32_bf16 v[90:93], v[236:239], v[204:207], v[90:93]
	v_mfma_f32_16x16x32_bf16 v[86:89], v[236:239], v[208:211], v[86:89]
	ds_read_b128 v[184:187], v144 offset:16384
	v_mfma_f32_16x16x32_bf16 v[82:85], v[236:239], v[212:215], v[82:85]
	ds_read_b128 v[188:191], v144 offset:17408
	v_mfma_f32_16x16x32_bf16 v[78:81], v[236:239], v[216:219], v[78:81]
	ds_read_b128 v[192:195], v144 offset:18432
	v_mfma_f32_16x16x32_bf16 v[74:77], v[236:239], v[220:223], v[74:77]
	ds_read_b128 v[196:199], v144 offset:19456
	v_mfma_f32_16x16x32_bf16 v[70:73], v[236:239], v[224:227], v[70:73]
	v_mfma_f32_16x16x32_bf16 v[66:69], v[236:239], v[228:231], v[66:69]
	v_mfma_f32_16x16x32_bf16 v[62:65], v[240:243], v[200:203], v[62:65]
	v_mfma_f32_16x16x32_bf16 v[58:61], v[240:243], v[204:207], v[58:61]
	v_mfma_f32_16x16x32_bf16 v[54:57], v[240:243], v[208:211], v[54:57]
	v_mfma_f32_16x16x32_bf16 v[50:53], v[240:243], v[212:215], v[50:53]
	v_mfma_f32_16x16x32_bf16 v[46:49], v[240:243], v[216:219], v[46:49]
	v_mfma_f32_16x16x32_bf16 v[42:45], v[240:243], v[220:223], v[42:45]
	v_mfma_f32_16x16x32_bf16 v[38:41], v[240:243], v[224:227], v[38:41]
	v_mfma_f32_16x16x32_bf16 v[34:37], v[240:243], v[228:231], v[34:37]
	v_mfma_f32_16x16x32_bf16 v[30:33], v[244:247], v[200:203], v[30:33]
	v_mfma_f32_16x16x32_bf16 v[26:29], v[244:247], v[204:207], v[26:29]
	v_mfma_f32_16x16x32_bf16 v[22:25], v[244:247], v[208:211], v[22:25]
	v_mfma_f32_16x16x32_bf16 v[18:21], v[244:247], v[212:215], v[18:21]
	v_mfma_f32_16x16x32_bf16 v[14:17], v[244:247], v[216:219], v[14:17]
	v_mfma_f32_16x16x32_bf16 v[10:13], v[244:247], v[220:223], v[10:13]
	v_mfma_f32_16x16x32_bf16 v[6:9], v[244:247], v[224:227], v[6:9]
	v_mfma_f32_16x16x32_bf16 v[2:5], v[244:247], v[228:231], v[2:5]
	s_setprio 0
	s_mov_b32 s42, s41
	s_add_i32 s41, s41, 0x6000
	s_cmp_eq_u32 s41, 0x12000
	s_cselect_b32 s41, 0, s41
	s_waitcnt vmcnt(0) lgkmcnt(0)
	s_barrier
; DEVI float blo(unsigned u) { return __uint_as_float(u << 16); }
; DEVI float bhi(unsigned u) { return __uint_as_float(u & 0xffff0000u); }
;     ...
;   for (int kt = 0; kt < nk; kt++) {
;     if (kt + 1 < nk) asm volatile("s_waitcnt vmcnt(6)" ::: "memory");
;     else asm volatile("s_waitcnt vmcnt(0)" ::: "memory");
;     __builtin_amdgcn_s_barrier();
;     asm volatile("" ::: "memory");
;     if (kt + 2 < nk) G2_STAGE(kt + 2);
;     const char* cS = smem + (kt % 3) * 24576;
;     bf16x8 xa[8], wb[4];
; #pragma unroll
;     for (int f = 0; f < 8; f++) xa[f] = *(const bf16x8*)(cS + aoff + f * 1024);
; #pragma unroll
;     for (int f = 0; f < 4; f++) wb[f] = *(const bf16x8*)(cS + boff + f * 1024);
; #pragma unroll
;     for (int nf = 0; nf < 4; nf++)
; #pragma unroll
;       for (int mf = 0; mf < 8; mf++)
;         acc[nf][mf] = __builtin_amdgcn_mfma_f32_16x16x32_bf16(wb[nf], xa[mf], acc[nf][mf], 0, 0, 0);
;   }
;     ...
;         if (EPI == EPI_RESID || EPI == EPI_RESID_ATOMIC) {
;           f32x4 x = a;
;           if (EPI == EPI_RESID || kpart == 0) {
;             const u32x2 xr = *(const u32x2*)((const u16*)(p.ws + WS_XB) + (size_t)row * 1024 + col);
;             x[0] += ALPHA * blo(xr[0]); x[1] += ALPHA * bhi(xr[0]); x[2] += ALPHA * blo(xr[1]); x[3] += ALPHA * bhi(xr[1]);
;           }
;           if (EPI == EPI_RESID) *(f32x4*)((float*)(p.ws + WS_XF) + (size_t)row * 1024 + col) = x;
	s_setprio 1
	v_add_u32_e32 v144, s41, v136
	v_mfma_f32_16x16x32_bf16 v[126:129], v[184:187], v[146:149], v[126:129]
	ds_read_b128 v[200:203], v144 offset:0
	v_mfma_f32_16x16x32_bf16 v[122:125], v[184:187], v[152:155], v[122:125]
	ds_read_b128 v[204:207], v144 offset:1024
	v_mfma_f32_16x16x32_bf16 v[118:121], v[184:187], v[156:159], v[118:121]
	ds_read_b128 v[208:211], v144 offset:2048
	v_mfma_f32_16x16x32_bf16 v[114:117], v[184:187], v[162:165], v[114:117]
	ds_read_b128 v[212:215], v144 offset:3072
	v_mfma_f32_16x16x32_bf16 v[110:113], v[184:187], v[166:169], v[110:113]
	ds_read_b128 v[216:219], v144 offset:4096
	v_mfma_f32_16x16x32_bf16 v[106:109], v[184:187], v[170:173], v[106:109]
	ds_read_b128 v[220:223], v144 offset:5120
	v_mfma_f32_16x16x32_bf16 v[102:105], v[184:187], v[176:179], v[102:105]
	ds_read_b128 v[224:227], v144 offset:6144
	v_mfma_f32_16x16x32_bf16 v[98:101], v[184:187], v[180:183], v[98:101]
	ds_read_b128 v[228:231], v144 offset:7168
	v_mfma_f32_16x16x32_bf16 v[94:97], v[188:191], v[146:149], v[94:97]
	v_add_u32_e32 v144, s41, v137
	v_mfma_f32_16x16x32_bf16 v[90:93], v[188:191], v[152:155], v[90:93]
	v_mfma_f32_16x16x32_bf16 v[86:89], v[188:191], v[156:159], v[86:89]
	ds_read_b128 v[232:235], v144 offset:16384
	v_mfma_f32_16x16x32_bf16 v[82:85], v[188:191], v[162:165], v[82:85]
	ds_read_b128 v[236:239], v144 offset:17408
	v_mfma_f32_16x16x32_bf16 v[78:81], v[188:191], v[166:169], v[78:81]
	ds_read_b128 v[240:243], v144 offset:18432
	v_mfma_f32_16x16x32_bf16 v[74:77], v[188:191], v[170:173], v[74:77]
	ds_read_b128 v[244:247], v144 offset:19456
	v_mfma_f32_16x16x32_bf16 v[70:73], v[188:191], v[176:179], v[70:73]
	v_mfma_f32_16x16x32_bf16 v[66:69], v[188:191], v[180:183], v[66:69]
	v_mfma_f32_16x16x32_bf16 v[62:65], v[192:195], v[146:149], v[62:65]
	v_mfma_f32_16x16x32_bf16 v[58:61], v[192:195], v[152:155], v[58:61]
	v_mfma_f32_16x16x32_bf16 v[54:57], v[192:195], v[156:159], v[54:57]
	v_mfma_f32_16x16x32_bf16 v[50:53], v[192:195], v[162:165], v[50:53]
	v_mfma_f32_16x16x32_bf16 v[46:49], v[192:195], v[166:169], v[46:49]
	v_mfma_f32_16x16x32_bf16 v[42:45], v[192:195], v[170:173], v[42:45]
	v_mfma_f32_16x16x32_bf16 v[38:41], v[192:195], v[176:179], v[38:41]
	v_mfma_f32_16x16x32_bf16 v[34:37], v[192:195], v[180:183], v[34:37]
	v_mfma_f32_16x16x32_bf16 v[30:33], v[196:199], v[146:149], v[30:33]
	v_mfma_f32_16x16x32_bf16 v[26:29], v[196:199], v[152:155], v[26:29]
	v_mfma_f32_16x16x32_bf16 v[22:25], v[196:199], v[156:159], v[22:25]
	v_mfma_f32_16x16x32_bf16 v[18:21], v[196:199], v[162:165], v[18:21]
	v_mfma_f32_16x16x32_bf16 v[14:17], v[196:199], v[166:169], v[14:17]
	v_mfma_f32_16x16x32_bf16 v[10:13], v[196:199], v[170:173], v[10:13]
	v_mfma_f32_16x16x32_bf16 v[6:9], v[196:199], v[176:179], v[6:9]
	v_mfma_f32_16x16x32_bf16 v[2:5], v[196:199], v[180:183], v[2:5]
	s_setprio 0
	s_mov_b32 s42, s41
	s_add_i32 s41, s41, 0x6000
	s_cmp_eq_u32 s41, 0x12000
	s_cselect_b32 s41, 0, s41
	s_mov_b32 s4, 0x8000
	s_mov_b32 s5, 0
	s_mov_b32 s10, 0x10000
	s_mov_b32 s11, 0
	s_mov_b32 s45, 0x3fd744fd
	s_waitcnt lgkmcnt(0)
	v_mfma_f32_16x16x32_bf16 v[126:129], v[232:235], v[200:203], v[126:129]
	v_mfma_f32_16x16x32_bf16 v[122:125], v[232:235], v[204:207], v[122:125]
	v_mfma_f32_16x16x32_bf16 v[118:121], v[232:235], v[208:211], v[118:121]
	v_mfma_f32_16x16x32_bf16 v[114:117], v[232:235], v[212:215], v[114:117]
	v_mfma_f32_16x16x32_bf16 v[110:113], v[232:235], v[216:219], v[110:113]
	global_load_dwordx4 v[146:149], v[138:139], off offset:0
	v_mfma_f32_16x16x32_bf16 v[106:109], v[232:235], v[220:223], v[106:109]
	v_mfma_f32_16x16x32_bf16 v[102:105], v[232:235], v[224:227], v[102:105]
	global_load_dwordx4 v[152:155], v[138:139], off offset:128
	v_mfma_f32_16x16x32_bf16 v[98:101], v[232:235], v[228:231], v[98:101]
	v_lshl_add_u64 v[138:139], v[138:139], 0, s[4:5]
	v_mfma_f32_16x16x32_bf16 v[94:97], v[236:239], v[200:203], v[94:97]
	global_load_dwordx4 v[156:159], v[138:139], off offset:0
	v_mfma_f32_16x16x32_bf16 v[90:93], v[236:239], v[204:207], v[90:93]
	v_mfma_f32_16x16x32_bf16 v[86:89], v[236:239], v[208:211], v[86:89]
	global_load_dwordx4 v[162:165], v[138:139], off offset:128
	v_mfma_f32_16x16x32_bf16 v[82:85], v[236:239], v[212:215], v[82:85]
	v_lshl_add_u64 v[138:139], v[138:139], 0, s[4:5]
	v_mfma_f32_16x16x32_bf16 v[78:81], v[236:239], v[216:219], v[78:81]
	global_load_dwordx4 v[166:169], v[138:139], off offset:0
	v_mfma_f32_16x16x32_bf16 v[74:77], v[236:239], v[220:223], v[74:77]
	v_mfma_f32_16x16x32_bf16 v[70:73], v[236:239], v[224:227], v[70:73]
	global_load_dwordx4 v[170:173], v[138:139], off offset:128
	v_mfma_f32_16x16x32_bf16 v[66:69], v[236:239], v[228:231], v[66:69]
	v_lshl_add_u64 v[138:139], v[138:139], 0, s[4:5]
	v_mfma_f32_16x16x32_bf16 v[62:65], v[240:243], v[200:203], v[62:65]
	global_load_dwordx4 v[176:179], v[138:139], off offset:0
	v_mfma_f32_16x16x32_bf16 v[58:61], v[240:243], v[204:207], v[58:61]
	v_mfma_f32_16x16x32_bf16 v[54:57], v[240:243], v[208:211], v[54:57]
	global_load_dwordx4 v[180:183], v[138:139], off offset:128
	v_mfma_f32_16x16x32_bf16 v[50:53], v[240:243], v[212:215], v[50:53]
	v_lshl_add_u64 v[138:139], v[138:139], 0, s[4:5]
	v_mfma_f32_16x16x32_bf16 v[46:49], v[240:243], v[216:219], v[46:49]
	global_load_dwordx4 v[184:187], v[138:139], off offset:0
	v_mfma_f32_16x16x32_bf16 v[42:45], v[240:243], v[220:223], v[42:45]
	v_mfma_f32_16x16x32_bf16 v[38:41], v[240:243], v[224:227], v[38:41]
	global_load_dwordx4 v[188:191], v[138:139], off offset:128
	v_mfma_f32_16x16x32_bf16 v[34:37], v[240:243], v[228:231], v[34:37]
	v_lshl_add_u64 v[138:139], v[138:139], 0, s[4:5]
	v_mfma_f32_16x16x32_bf16 v[30:33], v[244:247], v[200:203], v[30:33]
	global_load_dwordx4 v[192:195], v[138:139], off offset:0
	v_mfma_f32_16x16x32_bf16 v[26:29], v[244:247], v[204:207], v[26:29]
	v_mfma_f32_16x16x32_bf16 v[22:25], v[244:247], v[208:211], v[22:25]
	global_load_dwordx4 v[196:199], v[138:139], off offset:128
	v_mfma_f32_16x16x32_bf16 v[18:21], v[244:247], v[212:215], v[18:21]
	v_lshl_add_u64 v[138:139], v[138:139], 0, s[4:5]
	v_mfma_f32_16x16x32_bf16 v[14:17], v[244:247], v[216:219], v[14:17]
	v_mfma_f32_16x16x32_bf16 v[10:13], v[244:247], v[220:223], v[10:13]
	v_mfma_f32_16x16x32_bf16 v[6:9], v[244:247], v[224:227], v[6:9]
	v_mfma_f32_16x16x32_bf16 v[2:5], v[244:247], v[228:231], v[2:5]
	s_mov_b32 m0, s44
	global_load_dwordx4 v[200:203], v[138:139], off offset:0
	global_load_dwordx4 v[204:207], v[138:139], off offset:128
	v_lshl_add_u64 v[138:139], v[138:139], 0, s[4:5]
	global_load_dwordx4 v[208:211], v[138:139], off offset:0
	global_load_dwordx4 v[212:215], v[138:139], off offset:128
	v_lshl_add_u64 v[138:139], v[138:139], 0, s[4:5]
	s_nop 7
	s_waitcnt vmcnt(15)
; DEVI float blo(unsigned u) { return __uint_as_float(u << 16); }
; DEVI float bhi(unsigned u) { return __uint_as_float(u & 0xffff0000u); }
;     ...
;         if (EPI == EPI_RESID || EPI == EPI_RESID_ATOMIC) {
;           f32x4 x = a;
;           if (EPI == EPI_RESID || kpart == 0) {
;             const u32x2 xr = *(const u32x2*)((const u16*)(p.ws + WS_XB) + (size_t)row * 1024 + col);
;             x[0] += ALPHA * blo(xr[0]); x[1] += ALPHA * bhi(xr[0]); x[2] += ALPHA * blo(xr[1]); x[3] += ALPHA * bhi(xr[1]);
;           }
;           if (EPI == EPI_RESID) *(f32x4*)((float*)(p.ws + WS_XF) + (size_t)row * 1024 + col) = x;
	v_permlane16_swap_b32_e32 v146, v148
	v_permlane16_swap_b32_e32 v147, v149
	v_lshlrev_b32_e32 v216, 16, v146
	v_and_b32_e32 v146, 0xffff0000, v146
	v_lshlrev_b32_e32 v217, 16, v147
	v_and_b32_e32 v147, 0xffff0000, v147
	v_fmac_f32_e32 v126, s45, v216
	v_fmac_f32_e32 v127, s45, v146
	v_fmac_f32_e32 v128, s45, v217
	v_fmac_f32_e32 v129, s45, v147
	global_store_dwordx4 v[140:141], v[126:129], off offset:0
	v_lshlrev_b32_e32 v216, 16, v148
	v_and_b32_e32 v148, 0xffff0000, v148
	v_lshlrev_b32_e32 v217, 16, v149
	v_and_b32_e32 v149, 0xffff0000, v149
	v_fmac_f32_e32 v94, s45, v216
	v_fmac_f32_e32 v95, s45, v148
	v_fmac_f32_e32 v96, s45, v217
	v_fmac_f32_e32 v97, s45, v149
	global_store_dwordx4 v[140:141], v[94:97], off offset:64
	s_waitcnt vmcnt(16)
	v_permlane16_swap_b32_e32 v152, v154
	v_permlane16_swap_b32_e32 v153, v155
	v_lshlrev_b32_e32 v216, 16, v152
	v_and_b32_e32 v152, 0xffff0000, v152
	v_lshlrev_b32_e32 v217, 16, v153
	v_and_b32_e32 v153, 0xffff0000, v153
	v_fmac_f32_e32 v62, s45, v216
	v_fmac_f32_e32 v63, s45, v152
	v_fmac_f32_e32 v64, s45, v217
	v_fmac_f32_e32 v65, s45, v153
	global_store_dwordx4 v[140:141], v[62:65], off offset:128
	v_lshlrev_b32_e32 v216, 16, v154
	v_and_b32_e32 v154, 0xffff0000, v154
	v_lshlrev_b32_e32 v217, 16, v155
	v_and_b32_e32 v155, 0xffff0000, v155
	v_fmac_f32_e32 v30, s45, v216
	v_fmac_f32_e32 v31, s45, v154
	v_fmac_f32_e32 v32, s45, v217
	v_fmac_f32_e32 v33, s45, v155
	global_store_dwordx4 v[140:141], v[30:33], off offset:192
	v_lshl_add_u64 v[140:141], v[140:141], 0, s[10:11]
	s_waitcnt vmcnt(17)
	v_permlane16_swap_b32_e32 v156, v158
	v_permlane16_swap_b32_e32 v157, v159
	v_lshlrev_b32_e32 v216, 16, v156
	v_and_b32_e32 v156, 0xffff0000, v156
	v_lshlrev_b32_e32 v217, 16, v157
	v_and_b32_e32 v157, 0xffff0000, v157
	v_fmac_f32_e32 v122, s45, v216
	v_fmac_f32_e32 v123, s45, v156
	v_fmac_f32_e32 v124, s45, v217
	v_fmac_f32_e32 v125, s45, v157
	global_store_dwordx4 v[140:141], v[122:125], off offset:0
	v_lshlrev_b32_e32 v216, 16, v158
	v_and_b32_e32 v158, 0xffff0000, v158
	v_lshlrev_b32_e32 v217, 16, v159
	v_and_b32_e32 v159, 0xffff0000, v159
	v_fmac_f32_e32 v90, s45, v216
	v_fmac_f32_e32 v91, s45, v158
	v_fmac_f32_e32 v92, s45, v217
	v_fmac_f32_e32 v93, s45, v159
	global_store_dwordx4 v[140:141], v[90:93], off offset:64
	s_waitcnt vmcnt(18)
	v_permlane16_swap_b32_e32 v162, v164
	v_permlane16_swap_b32_e32 v163, v165
	v_lshlrev_b32_e32 v216, 16, v162
	v_and_b32_e32 v162, 0xffff0000, v162
	v_lshlrev_b32_e32 v217, 16, v163
	v_and_b32_e32 v163, 0xffff0000, v163
	v_fmac_f32_e32 v58, s45, v216
	v_fmac_f32_e32 v59, s45, v162
	v_fmac_f32_e32 v60, s45, v217
	v_fmac_f32_e32 v61, s45, v163
	global_store_dwordx4 v[140:141], v[58:61], off offset:128
	v_lshlrev_b32_e32 v216, 16, v164
	v_and_b32_e32 v164, 0xffff0000, v164
	v_lshlrev_b32_e32 v217, 16, v165
	v_and_b32_e32 v165, 0xffff0000, v165
	v_fmac_f32_e32 v26, s45, v216
	v_fmac_f32_e32 v27, s45, v164
	v_fmac_f32_e32 v28, s45, v217
	v_fmac_f32_e32 v29, s45, v165
	global_store_dwordx4 v[140:141], v[26:29], off offset:192
	v_lshl_add_u64 v[140:141], v[140:141], 0, s[10:11]
	s_waitcnt vmcnt(19)
	v_permlane16_swap_b32_e32 v166, v168
	v_permlane16_swap_b32_e32 v167, v169
	v_lshlrev_b32_e32 v216, 16, v166
	v_and_b32_e32 v166, 0xffff0000, v166
	v_lshlrev_b32_e32 v217, 16, v167
	v_and_b32_e32 v167, 0xffff0000, v167
	v_fmac_f32_e32 v118, s45, v216
	v_fmac_f32_e32 v119, s45, v166
	v_fmac_f32_e32 v120, s45, v217
	v_fmac_f32_e32 v121, s45, v167
	global_store_dwordx4 v[140:141], v[118:121], off offset:0
	v_lshlrev_b32_e32 v216, 16, v168
	v_and_b32_e32 v168, 0xffff0000, v168
	v_lshlrev_b32_e32 v217, 16, v169
	v_and_b32_e32 v169, 0xffff0000, v169
	v_fmac_f32_e32 v86, s45, v216
	v_fmac_f32_e32 v87, s45, v168
	v_fmac_f32_e32 v88, s45, v217
	v_fmac_f32_e32 v89, s45, v169
	global_store_dwordx4 v[140:141], v[86:89], off offset:64
	s_waitcnt vmcnt(20)
	v_permlane16_swap_b32_e32 v170, v172
	v_permlane16_swap_b32_e32 v171, v173
	v_lshlrev_b32_e32 v216, 16, v170
	v_and_b32_e32 v170, 0xffff0000, v170
	v_lshlrev_b32_e32 v217, 16, v171
	v_and_b32_e32 v171, 0xffff0000, v171
	v_fmac_f32_e32 v54, s45, v216
	v_fmac_f32_e32 v55, s45, v170
	v_fmac_f32_e32 v56, s45, v217
	v_fmac_f32_e32 v57, s45, v171
	global_store_dwordx4 v[140:141], v[54:57], off offset:128
	v_lshlrev_b32_e32 v216, 16, v172
	v_and_b32_e32 v172, 0xffff0000, v172
	v_lshlrev_b32_e32 v217, 16, v173
	v_and_b32_e32 v173, 0xffff0000, v173
	v_fmac_f32_e32 v22, s45, v216
	v_fmac_f32_e32 v23, s45, v172
	v_fmac_f32_e32 v24, s45, v217
	v_fmac_f32_e32 v25, s45, v173
	global_store_dwordx4 v[140:141], v[22:25], off offset:192
	v_lshl_add_u64 v[140:141], v[140:141], 0, s[10:11]
	s_waitcnt vmcnt(21)
	v_permlane16_swap_b32_e32 v176, v178
	v_permlane16_swap_b32_e32 v177, v179
	v_lshlrev_b32_e32 v216, 16, v176
	v_and_b32_e32 v176, 0xffff0000, v176
	v_lshlrev_b32_e32 v217, 16, v177
	v_and_b32_e32 v177, 0xffff0000, v177
	v_fmac_f32_e32 v114, s45, v216
	v_fmac_f32_e32 v115, s45, v176
	v_fmac_f32_e32 v116, s45, v217
	v_fmac_f32_e32 v117, s45, v177
	global_store_dwordx4 v[140:141], v[114:117], off offset:0
	v_lshlrev_b32_e32 v216, 16, v178
	v_and_b32_e32 v178, 0xffff0000, v178
	v_lshlrev_b32_e32 v217, 16, v179
	v_and_b32_e32 v179, 0xffff0000, v179
	v_fmac_f32_e32 v82, s45, v216
	v_fmac_f32_e32 v83, s45, v178
	v_fmac_f32_e32 v84, s45, v217
	v_fmac_f32_e32 v85, s45, v179
	global_store_dwordx4 v[140:141], v[82:85], off offset:64
	s_waitcnt vmcnt(22)
; DEVI float blo(unsigned u) { return __uint_as_float(u << 16); }
; DEVI float bhi(unsigned u) { return __uint_as_float(u & 0xffff0000u); }
;     ...
;         if (EPI == EPI_RESID || EPI == EPI_RESID_ATOMIC) {
;           f32x4 x = a;
;           if (EPI == EPI_RESID || kpart == 0) {
;             const u32x2 xr = *(const u32x2*)((const u16*)(p.ws + WS_XB) + (size_t)row * 1024 + col);
;             x[0] += ALPHA * blo(xr[0]); x[1] += ALPHA * bhi(xr[0]); x[2] += ALPHA * blo(xr[1]); x[3] += ALPHA * bhi(xr[1]);
;           }
;           if (EPI == EPI_RESID) *(f32x4*)((float*)(p.ws + WS_XF) + (size_t)row * 1024 + col) = x;
	v_permlane16_swap_b32_e32 v180, v182
	v_permlane16_swap_b32_e32 v181, v183
	v_lshlrev_b32_e32 v216, 16, v180
	v_and_b32_e32 v180, 0xffff0000, v180
	v_lshlrev_b32_e32 v217, 16, v181
	v_and_b32_e32 v181, 0xffff0000, v181
	v_fmac_f32_e32 v50, s45, v216
	v_fmac_f32_e32 v51, s45, v180
	v_fmac_f32_e32 v52, s45, v217
	v_fmac_f32_e32 v53, s45, v181
	global_store_dwordx4 v[140:141], v[50:53], off offset:128
	v_lshlrev_b32_e32 v216, 16, v182
	v_and_b32_e32 v182, 0xffff0000, v182
	v_lshlrev_b32_e32 v217, 16, v183
	v_and_b32_e32 v183, 0xffff0000, v183
	v_fmac_f32_e32 v18, s45, v216
	v_fmac_f32_e32 v19, s45, v182
	v_fmac_f32_e32 v20, s45, v217
	v_fmac_f32_e32 v21, s45, v183
	global_store_dwordx4 v[140:141], v[18:21], off offset:192
	v_lshl_add_u64 v[140:141], v[140:141], 0, s[10:11]
	s_waitcnt vmcnt(23)
	v_permlane16_swap_b32_e32 v184, v186
	v_permlane16_swap_b32_e32 v185, v187
	v_lshlrev_b32_e32 v216, 16, v184
	v_and_b32_e32 v184, 0xffff0000, v184
	v_lshlrev_b32_e32 v217, 16, v185
	v_and_b32_e32 v185, 0xffff0000, v185
	v_fmac_f32_e32 v110, s45, v216
	v_fmac_f32_e32 v111, s45, v184
	v_fmac_f32_e32 v112, s45, v217
	v_fmac_f32_e32 v113, s45, v185
	global_store_dwordx4 v[140:141], v[110:113], off offset:0
	v_lshlrev_b32_e32 v216, 16, v186
	v_and_b32_e32 v186, 0xffff0000, v186
	v_lshlrev_b32_e32 v217, 16, v187
	v_and_b32_e32 v187, 0xffff0000, v187
	v_fmac_f32_e32 v78, s45, v216
	v_fmac_f32_e32 v79, s45, v186
	v_fmac_f32_e32 v80, s45, v217
	v_fmac_f32_e32 v81, s45, v187
	global_store_dwordx4 v[140:141], v[78:81], off offset:64
	s_waitcnt vmcnt(24)
	v_permlane16_swap_b32_e32 v188, v190
	v_permlane16_swap_b32_e32 v189, v191
	v_lshlrev_b32_e32 v216, 16, v188
	v_and_b32_e32 v188, 0xffff0000, v188
	v_lshlrev_b32_e32 v217, 16, v189
	v_and_b32_e32 v189, 0xffff0000, v189
	v_fmac_f32_e32 v46, s45, v216
	v_fmac_f32_e32 v47, s45, v188
	v_fmac_f32_e32 v48, s45, v217
	v_fmac_f32_e32 v49, s45, v189
	global_store_dwordx4 v[140:141], v[46:49], off offset:128
	v_lshlrev_b32_e32 v216, 16, v190
	v_and_b32_e32 v190, 0xffff0000, v190
	v_lshlrev_b32_e32 v217, 16, v191
	v_and_b32_e32 v191, 0xffff0000, v191
	v_fmac_f32_e32 v14, s45, v216
	v_fmac_f32_e32 v15, s45, v190
	v_fmac_f32_e32 v16, s45, v217
	v_fmac_f32_e32 v17, s45, v191
	global_store_dwordx4 v[140:141], v[14:17], off offset:192
	v_lshl_add_u64 v[140:141], v[140:141], 0, s[10:11]
	s_waitcnt vmcnt(25)
	v_permlane16_swap_b32_e32 v192, v194
	v_permlane16_swap_b32_e32 v193, v195
	v_lshlrev_b32_e32 v216, 16, v192
	v_and_b32_e32 v192, 0xffff0000, v192
	v_lshlrev_b32_e32 v217, 16, v193
	v_and_b32_e32 v193, 0xffff0000, v193
	v_fmac_f32_e32 v106, s45, v216
	v_fmac_f32_e32 v107, s45, v192
	v_fmac_f32_e32 v108, s45, v217
	v_fmac_f32_e32 v109, s45, v193
	global_store_dwordx4 v[140:141], v[106:109], off offset:0
	v_lshlrev_b32_e32 v216, 16, v194
	v_and_b32_e32 v194, 0xffff0000, v194
	v_lshlrev_b32_e32 v217, 16, v195
	v_and_b32_e32 v195, 0xffff0000, v195
	v_fmac_f32_e32 v74, s45, v216
	v_fmac_f32_e32 v75, s45, v194
	v_fmac_f32_e32 v76, s45, v217
	v_fmac_f32_e32 v77, s45, v195
	global_store_dwordx4 v[140:141], v[74:77], off offset:64
	s_waitcnt vmcnt(26)
	v_permlane16_swap_b32_e32 v196, v198
	v_permlane16_swap_b32_e32 v197, v199
	v_lshlrev_b32_e32 v216, 16, v196
	v_and_b32_e32 v196, 0xffff0000, v196
	v_lshlrev_b32_e32 v217, 16, v197
	v_and_b32_e32 v197, 0xffff0000, v197
	v_fmac_f32_e32 v42, s45, v216
	v_fmac_f32_e32 v43, s45, v196
	v_fmac_f32_e32 v44, s45, v217
	v_fmac_f32_e32 v45, s45, v197
	global_store_dwordx4 v[140:141], v[42:45], off offset:128
	v_lshlrev_b32_e32 v216, 16, v198
	v_and_b32_e32 v198, 0xffff0000, v198
	v_lshlrev_b32_e32 v217, 16, v199
	v_and_b32_e32 v199, 0xffff0000, v199
	v_fmac_f32_e32 v10, s45, v216
	v_fmac_f32_e32 v11, s45, v198
	v_fmac_f32_e32 v12, s45, v217
	v_fmac_f32_e32 v13, s45, v199
	global_store_dwordx4 v[140:141], v[10:13], off offset:192
	v_lshl_add_u64 v[140:141], v[140:141], 0, s[10:11]
	s_waitcnt vmcnt(27)
	v_permlane16_swap_b32_e32 v200, v202
	v_permlane16_swap_b32_e32 v201, v203
	v_lshlrev_b32_e32 v216, 16, v200
	v_and_b32_e32 v200, 0xffff0000, v200
	v_lshlrev_b32_e32 v217, 16, v201
	v_and_b32_e32 v201, 0xffff0000, v201
	v_fmac_f32_e32 v102, s45, v216
	v_fmac_f32_e32 v103, s45, v200
	v_fmac_f32_e32 v104, s45, v217
	v_fmac_f32_e32 v105, s45, v201
	global_store_dwordx4 v[140:141], v[102:105], off offset:0
	v_lshlrev_b32_e32 v216, 16, v202
	v_and_b32_e32 v202, 0xffff0000, v202
	v_lshlrev_b32_e32 v217, 16, v203
	v_and_b32_e32 v203, 0xffff0000, v203
	v_fmac_f32_e32 v70, s45, v216
	v_fmac_f32_e32 v71, s45, v202
	v_fmac_f32_e32 v72, s45, v217
	v_fmac_f32_e32 v73, s45, v203
	global_store_dwordx4 v[140:141], v[70:73], off offset:64
	s_waitcnt vmcnt(28)
	v_permlane16_swap_b32_e32 v204, v206
	v_permlane16_swap_b32_e32 v205, v207
	v_lshlrev_b32_e32 v216, 16, v204
	v_and_b32_e32 v204, 0xffff0000, v204
	v_lshlrev_b32_e32 v217, 16, v205
	v_and_b32_e32 v205, 0xffff0000, v205
	v_fmac_f32_e32 v38, s45, v216
	v_fmac_f32_e32 v39, s45, v204
	v_fmac_f32_e32 v40, s45, v217
	v_fmac_f32_e32 v41, s45, v205
	global_store_dwordx4 v[140:141], v[38:41], off offset:128
	v_lshlrev_b32_e32 v216, 16, v206
	v_and_b32_e32 v206, 0xffff0000, v206
	v_lshlrev_b32_e32 v217, 16, v207
	v_and_b32_e32 v207, 0xffff0000, v207
	v_fmac_f32_e32 v6, s45, v216
	v_fmac_f32_e32 v7, s45, v206
	v_fmac_f32_e32 v8, s45, v217
	v_fmac_f32_e32 v9, s45, v207
	global_store_dwordx4 v[140:141], v[6:9], off offset:192
	v_lshl_add_u64 v[140:141], v[140:141], 0, s[10:11]
	s_waitcnt vmcnt(29)
	v_permlane16_swap_b32_e32 v208, v210
	v_permlane16_swap_b32_e32 v209, v211
	v_lshlrev_b32_e32 v216, 16, v208
	v_and_b32_e32 v208, 0xffff0000, v208
	v_lshlrev_b32_e32 v217, 16, v209
	v_and_b32_e32 v209, 0xffff0000, v209
	v_fmac_f32_e32 v98, s45, v216
	v_fmac_f32_e32 v99, s45, v208
	v_fmac_f32_e32 v100, s45, v217
	v_fmac_f32_e32 v101, s45, v209
	global_store_dwordx4 v[140:141], v[98:101], off offset:0
	v_lshlrev_b32_e32 v216, 16, v210
	v_and_b32_e32 v210, 0xffff0000, v210
	v_lshlrev_b32_e32 v217, 16, v211
	v_and_b32_e32 v211, 0xffff0000, v211
	v_fmac_f32_e32 v66, s45, v216
	v_fmac_f32_e32 v67, s45, v210
	v_fmac_f32_e32 v68, s45, v217
	v_fmac_f32_e32 v69, s45, v211
	global_store_dwordx4 v[140:141], v[66:69], off offset:64
	s_waitcnt vmcnt(30)
	v_permlane16_swap_b32_e32 v212, v214
	v_permlane16_swap_b32_e32 v213, v215
	v_lshlrev_b32_e32 v216, 16, v212
	v_and_b32_e32 v212, 0xffff0000, v212
	v_lshlrev_b32_e32 v217, 16, v213
	v_and_b32_e32 v213, 0xffff0000, v213
	v_fmac_f32_e32 v34, s45, v216
	v_fmac_f32_e32 v35, s45, v212
	v_fmac_f32_e32 v36, s45, v217
	v_fmac_f32_e32 v37, s45, v213
	global_store_dwordx4 v[140:141], v[34:37], off offset:128
	v_lshlrev_b32_e32 v216, 16, v214
	v_and_b32_e32 v214, 0xffff0000, v214
	v_lshlrev_b32_e32 v217, 16, v215
	v_and_b32_e32 v215, 0xffff0000, v215
	v_fmac_f32_e32 v2, s45, v216
	v_fmac_f32_e32 v3, s45, v214
	v_fmac_f32_e32 v4, s45, v217
	v_fmac_f32_e32 v5, s45, v215
	global_store_dwordx4 v[140:141], v[2:5], off offset:192
	v_readlane_b32 s40, v250, 7
	s_cmpk_lg_u32 s40, 0x200
	s_cbranch_scc1 .LBB0_757
; DEVI int xcd_first_tile() { return (blockIdx.x & 7) * (gridDim.x >> 3) + (blockIdx.x >> 3); }
; DEVI void run_phase(const Params& p, int ph, char* smem) {
;     ...
;       for (int t = xcd_first_tile(); t < 512 + 16 * 8; t += xcd_tile_step()) {
;         if (t < 512) {
;           int mt_, nt_; tile_coords(t, 64, 8, mt_, nt_);
;           gemm_tile256<EPI_RESID>(p, mix, 1024, Bt, 1024, mt_ * 256, nt_ * 128, nullptr, 0, smem);
;         } else {
;           const int u_ = t - 512, tl_ = u_ / 8, q_ = u_ - tl_ * 8;
;           gemm_tile256<EPI_RESID_ATOMIC>(p, mix, 1024, Bt, 1024, (64 + (tl_ & 1)) * 256, (tl_ >> 1) * 128, nullptr, 0, smem, q_ * 128, 4, q_);
	v_readlane_b32 s41, v250, 0
	s_lshr_b32 s42, s41, 3
	s_and_b32 s41, s41, 7
	s_mul_i32 s41, s41, 16
	s_add_i32 s41, s41, s42
	s_cmp_lt_u32 s42, 16
	s_cselect_b32 s39, s41, 0x4000
	s_branch .LBB0_757

; #define LAS __attribute__((address_space(3)))
;     ...
;   const int nk = (nk_part < 0) ? (K >> 5) : nk_part;
;   const int lrow = tid >> 2, lpc = tid & 3;
;   const int lch = lpc ^ ((0x78 >> (((lrow >> 2) & 3) * 2)) & 3);
;   const u16* ga = A + (size_t)(m0 + lrow) * lda + kbeg + lch * 8;
;   const u16* gb = Bt + (size_t)(n0 + lrow) * K + kbeg + lch * 8;
;   const size_t ga1 = (size_t)64 * lda, gb1 = (size_t)64 * K;
;   const unsigned lds0 = (unsigned)(uintptr_t)(LAS char*)smem + (unsigned)__builtin_amdgcn_readfirstlane(wid) * 1024u;
;     ...
;   __syncthreads();
;   G2_STAGE(0); G2_STAGE(1);
;   const int fsw = (0x78 >> (((r16 >> 2) & 3) * 2)) & 3;
;   const int aoff = (wm * 128 + r16) * 64 + ((quad ^ fsw) << 4);
;   const int boff = 16384 + (wn * 64 + r16) * 64 + ((quad ^ fsw) << 4);
.Lt0_crd:
	s_cmp_lt_u32 s43, 64
	s_cselect_b32 s42, 1, 0
	v_readlane_b32 s2, v250, 5
	v_readlane_b32 s3, v250, 6
	v_readlane_b32 s44, v254, 62
	s_mul_i32 s38, s43, 0x80000
	s_add_u32 s8, s2, s38
	s_addc_u32 s9, s3, 0
	s_add_u32 s8, s8, 0x4200000
	s_addc_u32 s9, s9, 0
	s_mul_i32 s38, s44, 0x500000
	s_mul_i32 s39, s40, 0x40000
	s_add_i32 s38, s38, s39
	s_add_u32 s10, s2, s38
	s_addc_u32 s11, s3, 0
	s_add_u32 s10, s10, 0x14a00000
	s_addc_u32 s11, s11, 0
	s_movk_i32 s15, 0x78
	v_lshrrev_b32_e32 v0, 2, v145
	v_and_b32_e32 v131, 3, v145
	v_bfe_u32 v136, v145, 4, 2
	v_lshlrev_b32_e32 v136, 1, v136
	v_lshrrev_b32_e64 v136, v136, s15
	v_and_b32_e32 v136, 3, v136
	v_xor_b32_e32 v131, v131, v136
	v_lshlrev_b32_e32 v131, 4, v131
	s_movk_i32 s39, 0x800
	v_mad_u32_u24 v0, v0, s39, v131
	v_bfe_u32 v137, v145, 2, 1
	s_movk_i32 s39, 0x7c0
	v_mul_u32_u24_e32 v136, s39, v137
	v_sub_u32_e32 v136, v0, v136
	v_mov_b32_e32 v137, 0
	v_lshl_add_u64 v[134:135], s[10:11], 0, v[136:137]
	v_bfe_u32 v137, v145, 2, 1
	s_mul_i32 s39, s42, 0x7c0
	v_mul_u32_u24_e32 v136, s39, v137
	v_sub_u32_e32 v0, v0, v136
	s_lshl_b32 s36, s42, 6
	s_add_i32 s36, s36, 64
	s_mov_b32 s37, 0
	v_lshl_add_u64 v[132:133], s[8:9], 0, v[0:1]
	v_bfe_u32 v136, v145, 2, 2
	v_lshlrev_b32_e32 v136, 1, v136
	v_lshrrev_b32_e64 v136, v136, s15
	v_and_b32_e32 v136, 3, v136
	v_bfe_u32 v137, v145, 4, 2
	v_xor_b32_e32 v136, v136, v137
	v_lshlrev_b32_e32 v136, 4, v136
	v_and_b32_e32 v131, 15, v145
	v_lshl_or_b32 v136, v131, 6, v136
	v_bfe_u32 v137, v145, 6, 1
	v_lshl_or_b32 v137, v137, 12, v136
	v_lshrrev_b32_e32 v0, 7, v145
	v_lshl_or_b32 v136, v0, 13, v136
	v_and_b32_e32 v140, 1, v131
	v_lshl_or_b32 v131, v0, 7, v131
	v_bfe_u32 v0, v145, 4, 1
	v_lshlrev_b32_e32 v0, 5, v0
	v_bfe_u32 v141, v145, 5, 1
	v_lshl_or_b32 v0, v141, 4, v0
	v_bfe_u32 v141, v145, 6, 1
	s_mul_i32 s38, s43, 0x140000
	s_lshl_b32 s39, s40, 8
	s_add_i32 s38, s38, s39
	s_add_u32 s10, s2, s38
	s_addc_u32 s11, s3, 0
	s_add_u32 s10, s10, 0x6300000
	s_addc_u32 s11, s11, 0
	s_movk_i32 s39, 5120
	v_mad_u32_u24 v138, v131, s39, v0
	v_lshl_add_u32 v138, v141, 7, v138
	v_mov_b32_e32 v139, 0
	v_lshl_add_u64 v[140:141], s[10:11], 0, v[138:139]
	s_mov_b32 s2, 0x20000
	s_mov_b32 s3, 0
	v_lshrrev_b32_e32 v0, 6, v145
	v_lshlrev_b32_e32 v0, 10, v0
	s_nop 0
	v_readfirstlane_b32 s44, v0
	s_mov_b32 s41, m0
	s_mov_b32 s8, 128
	s_mov_b32 s9, 0
	s_barrier
	s_add_i32 s40, s44, 0x0
	s_mov_b32 m0, s40
	v_lshl_add_u64 v[142:143], v[132:133], 0, s[2:3]
	global_load_lds_dwordx4 v[132:133], off
	s_addk_i32 m0, 0x1000
	s_nop 0
	global_load_lds_dwordx4 v[142:143], off
	v_lshl_add_u64 v[142:143], v[142:143], 0, s[2:3]
	s_addk_i32 m0, 0x1000
	s_nop 0
	global_load_lds_dwordx4 v[142:143], off
	v_lshl_add_u64 v[142:143], v[142:143], 0, s[2:3]
	s_addk_i32 m0, 0x1000
	s_nop 0
	global_load_lds_dwordx4 v[142:143], off
	s_addk_i32 m0, 0x1000
	v_lshl_add_u64 v[142:143], v[134:135], 0, s[2:3]
	s_nop 0
	global_load_lds_dwordx4 v[134:135], off
	s_addk_i32 m0, 0x1000
	v_lshl_add_u64 v[132:133], v[132:133], 0, s[36:37]
	s_nop 0
	global_load_lds_dwordx4 v[142:143], off
	v_lshl_add_u64 v[134:135], v[134:135], 0, s[8:9]
	s_nop 0
	s_add_i32 s40, s44, 0x6000
	s_mov_b32 m0, s40
	v_lshl_add_u64 v[142:143], v[132:133], 0, s[2:3]
	global_load_lds_dwordx4 v[132:133], off
	s_addk_i32 m0, 0x1000
	s_nop 0
	global_load_lds_dwordx4 v[142:143], off
	v_lshl_add_u64 v[142:143], v[142:143], 0, s[2:3]
	s_addk_i32 m0, 0x1000
	s_nop 0
	global_load_lds_dwordx4 v[142:143], off
	v_lshl_add_u64 v[142:143], v[142:143], 0, s[2:3]
	s_addk_i32 m0, 0x1000
	s_nop 0
	global_load_lds_dwordx4 v[142:143], off
	s_addk_i32 m0, 0x1000
	v_lshl_add_u64 v[142:143], v[134:135], 0, s[2:3]
	s_nop 0
	global_load_lds_dwordx4 v[134:135], off
	s_addk_i32 m0, 0x1000
	v_lshl_add_u64 v[132:133], v[132:133], 0, s[36:37]
	s_nop 0
	global_load_lds_dwordx4 v[142:143], off
	v_lshl_add_u64 v[134:135], v[134:135], 0, s[8:9]
	s_nop 0
	s_add_i32 s40, s44, 0xc000
	s_mov_b32 m0, s40
	v_lshl_add_u64 v[142:143], v[132:133], 0, s[2:3]
	global_load_lds_dwordx4 v[132:133], off
	s_addk_i32 m0, 0x1000
	s_nop 0
	global_load_lds_dwordx4 v[142:143], off
	v_lshl_add_u64 v[142:143], v[142:143], 0, s[2:3]
	s_addk_i32 m0, 0x1000
	s_nop 0
	global_load_lds_dwordx4 v[142:143], off
	v_lshl_add_u64 v[142:143], v[142:143], 0, s[2:3]
	s_addk_i32 m0, 0x1000
	s_nop 0
	global_load_lds_dwordx4 v[142:143], off
	s_addk_i32 m0, 0x1000
	v_lshl_add_u64 v[142:143], v[134:135], 0, s[2:3]
	s_nop 0
	global_load_lds_dwordx4 v[134:135], off
	s_addk_i32 m0, 0x1000
	v_lshl_add_u64 v[132:133], v[132:133], 0, s[36:37]
	s_nop 0
	global_load_lds_dwordx4 v[142:143], off
	v_lshl_add_u64 v[134:135], v[134:135], 0, s[8:9]
	s_nop 0
	v_mov_b32_e32 v2, 0
	v_mov_b32_e32 v3, 0
	v_mov_b32_e32 v4, 0
	v_mov_b32_e32 v5, 0
	v_mov_b32_e32 v6, 0
	v_mov_b32_e32 v7, 0
	v_mov_b32_e32 v8, 0
	v_mov_b32_e32 v9, 0
	v_mov_b32_e32 v10, 0
	v_mov_b32_e32 v11, 0
	v_mov_b32_e32 v12, 0
	v_mov_b32_e32 v13, 0
	v_mov_b32_e32 v14, 0
	v_mov_b32_e32 v15, 0
	v_mov_b32_e32 v16, 0
	v_mov_b32_e32 v17, 0
	v_mov_b32_e32 v18, 0
	v_mov_b32_e32 v19, 0
	v_mov_b32_e32 v20, 0
	v_mov_b32_e32 v21, 0
	v_mov_b32_e32 v22, 0
	v_mov_b32_e32 v23, 0
	v_mov_b32_e32 v24, 0
	v_mov_b32_e32 v25, 0
	v_mov_b32_e32 v26, 0
	v_mov_b32_e32 v27, 0
	v_mov_b32_e32 v28, 0
	v_mov_b32_e32 v29, 0
	v_mov_b32_e32 v30, 0
	v_mov_b32_e32 v31, 0
	v_mov_b32_e32 v32, 0
	v_mov_b32_e32 v33, 0
	v_mov_b32_e32 v34, 0
	v_mov_b32_e32 v35, 0
	v_mov_b32_e32 v36, 0
	v_mov_b32_e32 v37, 0
	v_mov_b32_e32 v38, 0
	v_mov_b32_e32 v39, 0
	v_mov_b32_e32 v40, 0
	v_mov_b32_e32 v41, 0
	v_mov_b32_e32 v42, 0
	v_mov_b32_e32 v43, 0
	v_mov_b32_e32 v44, 0
	v_mov_b32_e32 v45, 0
	v_mov_b32_e32 v46, 0
; #define LAS __attribute__((address_space(3)))
;     ...
;   f32x4 acc[4][8];
; #pragma unroll
;   for (int i = 0; i < 4; i++)
; #pragma unroll
;     for (int j = 0; j < 8; j++) acc[i][j] = (f32x4){0.f, 0.f, 0.f, 0.f};
;   const int nk = (nk_part < 0) ? (K >> 5) : nk_part;
;   const int lrow = tid >> 2, lpc = tid & 3;
;   const int lch = lpc ^ ((0x78 >> (((lrow >> 2) & 3) * 2)) & 3);
;   const u16* ga = A + (size_t)(m0 + lrow) * lda + kbeg + lch * 8;
;   const u16* gb = Bt + (size_t)(n0 + lrow) * K + kbeg + lch * 8;
;   const size_t ga1 = (size_t)64 * lda, gb1 = (size_t)64 * K;
;   const unsigned lds0 = (unsigned)(uintptr_t)(LAS char*)smem + (unsigned)__builtin_amdgcn_readfirstlane(wid) * 1024u;
;     ...
;   __syncthreads();
;   G2_STAGE(0); G2_STAGE(1);
;   const int fsw = (0x78 >> (((r16 >> 2) & 3) * 2)) & 3;
;   const int aoff = (wm * 128 + r16) * 64 + ((quad ^ fsw) << 4);
;   const int boff = 16384 + (wn * 64 + r16) * 64 + ((quad ^ fsw) << 4);
;   for (int kt = 0; kt < nk; kt++) {
;     if (kt + 1 < nk) asm volatile("s_waitcnt vmcnt(6)" ::: "memory");
;     else asm volatile("s_waitcnt vmcnt(0)" ::: "memory");
;     __builtin_amdgcn_s_barrier();
;     asm volatile("" ::: "memory");
;     if (kt + 2 < nk) G2_STAGE(kt + 2);
;     const char* cS = smem + (kt % 3) * 24576;
;     bf16x8 xa[8], wb[4];
; #pragma unroll
;     for (int f = 0; f < 8; f++) xa[f] = *(const bf16x8*)(cS + aoff + f * 1024);
; #pragma unroll
;     for (int f = 0; f < 4; f++) wb[f] = *(const bf16x8*)(cS + boff + f * 1024);
; #pragma unroll
;     for (int nf = 0; nf < 4; nf++)
; #pragma unroll
;       for (int mf = 0; mf < 8; mf++)
;         acc[nf][mf] = __builtin_amdgcn_mfma_f32_16x16x32_bf16(wb[nf], xa[mf], acc[nf][mf], 0, 0, 0);
;   }
	v_mov_b32_e32 v47, 0
	v_mov_b32_e32 v48, 0
	v_mov_b32_e32 v49, 0
	v_mov_b32_e32 v50, 0
	v_mov_b32_e32 v51, 0
	v_mov_b32_e32 v52, 0
	v_mov_b32_e32 v53, 0
	v_mov_b32_e32 v54, 0
	v_mov_b32_e32 v55, 0
	v_mov_b32_e32 v56, 0
	v_mov_b32_e32 v57, 0
	v_mov_b32_e32 v58, 0
	v_mov_b32_e32 v59, 0
	v_mov_b32_e32 v60, 0
	v_mov_b32_e32 v61, 0
	v_mov_b32_e32 v62, 0
	v_mov_b32_e32 v63, 0
	v_mov_b32_e32 v64, 0
	v_mov_b32_e32 v65, 0
	v_mov_b32_e32 v66, 0
	v_mov_b32_e32 v67, 0
	v_mov_b32_e32 v68, 0
	v_mov_b32_e32 v69, 0
	v_mov_b32_e32 v70, 0
	v_mov_b32_e32 v71, 0
	v_mov_b32_e32 v72, 0
	v_mov_b32_e32 v73, 0
	v_mov_b32_e32 v74, 0
	v_mov_b32_e32 v75, 0
	v_mov_b32_e32 v76, 0
	v_mov_b32_e32 v77, 0
	v_mov_b32_e32 v78, 0
	v_mov_b32_e32 v79, 0
	v_mov_b32_e32 v80, 0
	v_mov_b32_e32 v81, 0
	v_mov_b32_e32 v82, 0
	v_mov_b32_e32 v83, 0
	v_mov_b32_e32 v84, 0
	v_mov_b32_e32 v85, 0
	v_mov_b32_e32 v86, 0
	v_mov_b32_e32 v87, 0
	v_mov_b32_e32 v88, 0
	v_mov_b32_e32 v89, 0
	v_mov_b32_e32 v90, 0
	v_mov_b32_e32 v91, 0
	v_mov_b32_e32 v92, 0
	v_mov_b32_e32 v93, 0
	v_mov_b32_e32 v94, 0
	v_mov_b32_e32 v95, 0
	v_mov_b32_e32 v96, 0
	v_mov_b32_e32 v97, 0
	v_mov_b32_e32 v98, 0
	v_mov_b32_e32 v99, 0
	v_mov_b32_e32 v100, 0
	v_mov_b32_e32 v101, 0
	v_mov_b32_e32 v102, 0
	v_mov_b32_e32 v103, 0
	v_mov_b32_e32 v104, 0
	v_mov_b32_e32 v105, 0
	v_mov_b32_e32 v106, 0
	v_mov_b32_e32 v107, 0
	v_mov_b32_e32 v108, 0
	v_mov_b32_e32 v109, 0
	v_mov_b32_e32 v110, 0
	v_mov_b32_e32 v111, 0
	v_mov_b32_e32 v112, 0
	v_mov_b32_e32 v113, 0
	v_mov_b32_e32 v114, 0
	v_mov_b32_e32 v115, 0
	v_mov_b32_e32 v116, 0
	v_mov_b32_e32 v117, 0
	v_mov_b32_e32 v118, 0
	v_mov_b32_e32 v119, 0
	v_mov_b32_e32 v120, 0
	v_mov_b32_e32 v121, 0
	v_mov_b32_e32 v122, 0
	v_mov_b32_e32 v123, 0
	v_mov_b32_e32 v124, 0
	v_mov_b32_e32 v125, 0
	v_mov_b32_e32 v126, 0
	v_mov_b32_e32 v127, 0
	v_mov_b32_e32 v128, 0
	v_mov_b32_e32 v129, 0
	s_waitcnt vmcnt(12)
	s_barrier
	ds_read_b128 v[146:149], v136 offset:0
	ds_read_b128 v[152:155], v136 offset:1024
	ds_read_b128 v[156:159], v136 offset:2048
	ds_read_b128 v[162:165], v136 offset:3072
	ds_read_b128 v[166:169], v136 offset:4096
	ds_read_b128 v[170:173], v136 offset:5120
	ds_read_b128 v[176:179], v136 offset:6144
	ds_read_b128 v[180:183], v136 offset:7168
	ds_read_b128 v[184:187], v137 offset:16384
	ds_read_b128 v[188:191], v137 offset:17408
	ds_read_b128 v[192:195], v137 offset:18432
	ds_read_b128 v[196:199], v137 offset:19456
	s_movk_i32 s38, 0x6000
	s_mov_b32 s39, 0
	s_movk_i32 s15, 14
.Lt0_loop:
	s_waitcnt vmcnt(6) lgkmcnt(0)
	s_barrier
	s_setprio 1
	v_add_u32_e32 v144, s38, v136
	v_mfma_f32_16x16x32_bf16 v[126:129], v[184:187], v[146:149], v[126:129]
	ds_read_b128 v[200:203], v144 offset:0
	v_mfma_f32_16x16x32_bf16 v[122:125], v[184:187], v[152:155], v[122:125]
	ds_read_b128 v[204:207], v144 offset:1024
	v_mfma_f32_16x16x32_bf16 v[118:121], v[184:187], v[156:159], v[118:121]
	ds_read_b128 v[208:211], v144 offset:2048
	v_mfma_f32_16x16x32_bf16 v[114:117], v[184:187], v[162:165], v[114:117]
	ds_read_b128 v[212:215], v144 offset:3072
	v_mfma_f32_16x16x32_bf16 v[110:113], v[184:187], v[166:169], v[110:113]
	ds_read_b128 v[216:219], v144 offset:4096
	v_mfma_f32_16x16x32_bf16 v[106:109], v[184:187], v[170:173], v[106:109]
	ds_read_b128 v[220:223], v144 offset:5120
	v_mfma_f32_16x16x32_bf16 v[102:105], v[184:187], v[176:179], v[102:105]
	ds_read_b128 v[224:227], v144 offset:6144
	v_mfma_f32_16x16x32_bf16 v[98:101], v[184:187], v[180:183], v[98:101]
	ds_read_b128 v[228:231], v144 offset:7168
	v_mfma_f32_16x16x32_bf16 v[94:97], v[188:191], v[146:149], v[94:97]
	v_add_u32_e32 v144, s38, v137
	v_mfma_f32_16x16x32_bf16 v[90:93], v[188:191], v[152:155], v[90:93]
	v_mfma_f32_16x16x32_bf16 v[86:89], v[188:191], v[156:159], v[86:89]
	ds_read_b128 v[232:235], v144 offset:16384
	v_mfma_f32_16x16x32_bf16 v[82:85], v[188:191], v[162:165], v[82:85]
	ds_read_b128 v[236:239], v144 offset:17408
	v_mfma_f32_16x16x32_bf16 v[78:81], v[188:191], v[166:169], v[78:81]
	ds_read_b128 v[240:243], v144 offset:18432
	v_mfma_f32_16x16x32_bf16 v[74:77], v[188:191], v[170:173], v[74:77]
	ds_read_b128 v[244:247], v144 offset:19456
	s_add_i32 s40, s44, s39
	v_mfma_f32_16x16x32_bf16 v[70:73], v[188:191], v[176:179], v[70:73]
	s_mov_b32 m0, s40
	v_lshl_add_u64 v[142:143], v[132:133], 0, s[2:3]
	v_mfma_f32_16x16x32_bf16 v[66:69], v[188:191], v[180:183], v[66:69]
	global_load_lds_dwordx4 v[132:133], off
	s_addk_i32 m0, 0x1000
	v_mfma_f32_16x16x32_bf16 v[62:65], v[192:195], v[146:149], v[62:65]
	v_mfma_f32_16x16x32_bf16 v[58:61], v[192:195], v[152:155], v[58:61]
	v_mfma_f32_16x16x32_bf16 v[54:57], v[192:195], v[156:159], v[54:57]
	global_load_lds_dwordx4 v[142:143], off
	v_lshl_add_u64 v[142:143], v[142:143], 0, s[2:3]
	s_addk_i32 m0, 0x1000
	v_mfma_f32_16x16x32_bf16 v[50:53], v[192:195], v[162:165], v[50:53]
	v_mfma_f32_16x16x32_bf16 v[46:49], v[192:195], v[166:169], v[46:49]
	v_mfma_f32_16x16x32_bf16 v[42:45], v[192:195], v[170:173], v[42:45]
	global_load_lds_dwordx4 v[142:143], off
	v_lshl_add_u64 v[142:143], v[142:143], 0, s[2:3]
	s_addk_i32 m0, 0x1000
	v_mfma_f32_16x16x32_bf16 v[38:41], v[192:195], v[176:179], v[38:41]
	v_mfma_f32_16x16x32_bf16 v[34:37], v[192:195], v[180:183], v[34:37]
	v_mfma_f32_16x16x32_bf16 v[30:33], v[196:199], v[146:149], v[30:33]
	global_load_lds_dwordx4 v[142:143], off
	s_addk_i32 m0, 0x1000
	v_lshl_add_u64 v[142:143], v[134:135], 0, s[2:3]
	v_mfma_f32_16x16x32_bf16 v[26:29], v[196:199], v[152:155], v[26:29]
	v_mfma_f32_16x16x32_bf16 v[22:25], v[196:199], v[156:159], v[22:25]
	v_mfma_f32_16x16x32_bf16 v[18:21], v[196:199], v[162:165], v[18:21]
	global_load_lds_dwordx4 v[134:135], off
	s_addk_i32 m0, 0x1000
	v_lshl_add_u64 v[132:133], v[132:133], 0, s[36:37]
	v_mfma_f32_16x16x32_bf16 v[14:17], v[196:199], v[166:169], v[14:17]
	v_mfma_f32_16x16x32_bf16 v[10:13], v[196:199], v[170:173], v[10:13]
	v_mfma_f32_16x16x32_bf16 v[6:9], v[196:199], v[176:179], v[6:9]
	global_load_lds_dwordx4 v[142:143], off
	v_lshl_add_u64 v[134:135], v[134:135], 0, s[8:9]
	v_mfma_f32_16x16x32_bf16 v[2:5], v[196:199], v[180:183], v[2:5]
	s_setprio 0
	s_mov_b32 s39, s38
	s_add_i32 s38, s38, 0x6000
	s_cmp_eq_u32 s38, 0x12000
	s_cselect_b32 s38, 0, s38
	s_waitcnt vmcnt(6) lgkmcnt(0)
	s_barrier
;     ...
;   for (int kt = 0; kt < nk; kt++) {
;     if (kt + 1 < nk) asm volatile("s_waitcnt vmcnt(6)" ::: "memory");
;     else asm volatile("s_waitcnt vmcnt(0)" ::: "memory");
;     __builtin_amdgcn_s_barrier();
;     asm volatile("" ::: "memory");
;     if (kt + 2 < nk) G2_STAGE(kt + 2);
;     const char* cS = smem + (kt % 3) * 24576;
;     bf16x8 xa[8], wb[4];
; #pragma unroll
;     for (int f = 0; f < 8; f++) xa[f] = *(const bf16x8*)(cS + aoff + f * 1024);
; #pragma unroll
;     for (int f = 0; f < 4; f++) wb[f] = *(const bf16x8*)(cS + boff + f * 1024);
; #pragma unroll
;     for (int nf = 0; nf < 4; nf++)
; #pragma unroll
;       for (int mf = 0; mf < 8; mf++)
;         acc[nf][mf] = __builtin_amdgcn_mfma_f32_16x16x32_bf16(wb[nf], xa[mf], acc[nf][mf], 0, 0, 0);
;   }
	s_setprio 1
	v_add_u32_e32 v144, s38, v136
	v_mfma_f32_16x16x32_bf16 v[126:129], v[232:235], v[200:203], v[126:129]
	ds_read_b128 v[146:149], v144 offset:0
	v_mfma_f32_16x16x32_bf16 v[122:125], v[232:235], v[204:207], v[122:125]
	ds_read_b128 v[152:155], v144 offset:1024
	v_mfma_f32_16x16x32_bf16 v[118:121], v[232:235], v[208:211], v[118:121]
	ds_read_b128 v[156:159], v144 offset:2048
	v_mfma_f32_16x16x32_bf16 v[114:117], v[232:235], v[212:215], v[114:117]
	ds_read_b128 v[162:165], v144 offset:3072
	v_mfma_f32_16x16x32_bf16 v[110:113], v[232:235], v[216:219], v[110:113]
	ds_read_b128 v[166:169], v144 offset:4096
	v_mfma_f32_16x16x32_bf16 v[106:109], v[232:235], v[220:223], v[106:109]
	ds_read_b128 v[170:173], v144 offset:5120
	v_mfma_f32_16x16x32_bf16 v[102:105], v[232:235], v[224:227], v[102:105]
	ds_read_b128 v[176:179], v144 offset:6144
	v_mfma_f32_16x16x32_bf16 v[98:101], v[232:235], v[228:231], v[98:101]
	ds_read_b128 v[180:183], v144 offset:7168
	v_mfma_f32_16x16x32_bf16 v[94:97], v[236:239], v[200:203], v[94:97]
	v_add_u32_e32 v144, s38, v137
	v_mfma_f32_16x16x32_bf16 v[90:93], v[236:239], v[204:207], v[90:93]
	v_mfma_f32_16x16x32_bf16 v[86:89], v[236:239], v[208:211], v[86:89]
	ds_read_b128 v[184:187], v144 offset:16384
	v_mfma_f32_16x16x32_bf16 v[82:85], v[236:239], v[212:215], v[82:85]
	ds_read_b128 v[188:191], v144 offset:17408
	v_mfma_f32_16x16x32_bf16 v[78:81], v[236:239], v[216:219], v[78:81]
	ds_read_b128 v[192:195], v144 offset:18432
	v_mfma_f32_16x16x32_bf16 v[74:77], v[236:239], v[220:223], v[74:77]
	ds_read_b128 v[196:199], v144 offset:19456
	s_add_i32 s40, s44, s39
	v_mfma_f32_16x16x32_bf16 v[70:73], v[236:239], v[224:227], v[70:73]
	s_mov_b32 m0, s40
	v_lshl_add_u64 v[142:143], v[132:133], 0, s[2:3]
	v_mfma_f32_16x16x32_bf16 v[66:69], v[236:239], v[228:231], v[66:69]
	global_load_lds_dwordx4 v[132:133], off
	s_addk_i32 m0, 0x1000
	v_mfma_f32_16x16x32_bf16 v[62:65], v[240:243], v[200:203], v[62:65]
	v_mfma_f32_16x16x32_bf16 v[58:61], v[240:243], v[204:207], v[58:61]
	v_mfma_f32_16x16x32_bf16 v[54:57], v[240:243], v[208:211], v[54:57]
	global_load_lds_dwordx4 v[142:143], off
	v_lshl_add_u64 v[142:143], v[142:143], 0, s[2:3]
	s_addk_i32 m0, 0x1000
	v_mfma_f32_16x16x32_bf16 v[50:53], v[240:243], v[212:215], v[50:53]
	v_mfma_f32_16x16x32_bf16 v[46:49], v[240:243], v[216:219], v[46:49]
	v_mfma_f32_16x16x32_bf16 v[42:45], v[240:243], v[220:223], v[42:45]
	global_load_lds_dwordx4 v[142:143], off
	v_lshl_add_u64 v[142:143], v[142:143], 0, s[2:3]
	s_addk_i32 m0, 0x1000
	v_mfma_f32_16x16x32_bf16 v[38:41], v[240:243], v[224:227], v[38:41]
	v_mfma_f32_16x16x32_bf16 v[34:37], v[240:243], v[228:231], v[34:37]
	v_mfma_f32_16x16x32_bf16 v[30:33], v[244:247], v[200:203], v[30:33]
	global_load_lds_dwordx4 v[142:143], off
	s_addk_i32 m0, 0x1000
	v_lshl_add_u64 v[142:143], v[134:135], 0, s[2:3]
	v_mfma_f32_16x16x32_bf16 v[26:29], v[244:247], v[204:207], v[26:29]
	v_mfma_f32_16x16x32_bf16 v[22:25], v[244:247], v[208:211], v[22:25]
	v_mfma_f32_16x16x32_bf16 v[18:21], v[244:247], v[212:215], v[18:21]
	global_load_lds_dwordx4 v[134:135], off
	s_addk_i32 m0, 0x1000
	v_lshl_add_u64 v[132:133], v[132:133], 0, s[36:37]
	v_mfma_f32_16x16x32_bf16 v[14:17], v[244:247], v[216:219], v[14:17]
	v_mfma_f32_16x16x32_bf16 v[10:13], v[244:247], v[220:223], v[10:13]
	v_mfma_f32_16x16x32_bf16 v[6:9], v[244:247], v[224:227], v[6:9]
	global_load_lds_dwordx4 v[142:143], off
	v_lshl_add_u64 v[134:135], v[134:135], 0, s[8:9]
	v_mfma_f32_16x16x32_bf16 v[2:5], v[244:247], v[228:231], v[2:5]
	s_setprio 0
	s_mov_b32 s39, s38
	s_add_i32 s38, s38, 0x6000
	s_cmp_eq_u32 s38, 0x12000
	s_cselect_b32 s38, 0, s38
	s_sub_i32 s15, s15, 1
	s_cmp_lg_u32 s15, 0
	s_cbranch_scc1 .Lt0_loop
	s_waitcnt vmcnt(6) lgkmcnt(0)
	s_barrier
	s_setprio 1
	v_add_u32_e32 v144, s38, v136
	v_mfma_f32_16x16x32_bf16 v[126:129], v[184:187], v[146:149], v[126:129]
	ds_read_b128 v[200:203], v144 offset:0
	v_mfma_f32_16x16x32_bf16 v[122:125], v[184:187], v[152:155], v[122:125]
	ds_read_b128 v[204:207], v144 offset:1024
	v_mfma_f32_16x16x32_bf16 v[118:121], v[184:187], v[156:159], v[118:121]
	ds_read_b128 v[208:211], v144 offset:2048
	v_mfma_f32_16x16x32_bf16 v[114:117], v[184:187], v[162:165], v[114:117]
	ds_read_b128 v[212:215], v144 offset:3072
	v_mfma_f32_16x16x32_bf16 v[110:113], v[184:187], v[166:169], v[110:113]
	ds_read_b128 v[216:219], v144 offset:4096
	v_mfma_f32_16x16x32_bf16 v[106:109], v[184:187], v[170:173], v[106:109]
	ds_read_b128 v[220:223], v144 offset:5120
	v_mfma_f32_16x16x32_bf16 v[102:105], v[184:187], v[176:179], v[102:105]
	ds_read_b128 v[224:227], v144 offset:6144
	v_mfma_f32_16x16x32_bf16 v[98:101], v[184:187], v[180:183], v[98:101]
	ds_read_b128 v[228:231], v144 offset:7168
	v_mfma_f32_16x16x32_bf16 v[94:97], v[188:191], v[146:149], v[94:97]
	v_add_u32_e32 v144, s38, v137
	v_mfma_f32_16x16x32_bf16 v[90:93], v[188:191], v[152:155], v[90:93]
	v_mfma_f32_16x16x32_bf16 v[86:89], v[188:191], v[156:159], v[86:89]
	ds_read_b128 v[232:235], v144 offset:16384
	v_mfma_f32_16x16x32_bf16 v[82:85], v[188:191], v[162:165], v[82:85]
	ds_read_b128 v[236:239], v144 offset:17408
	v_mfma_f32_16x16x32_bf16 v[78:81], v[188:191], v[166:169], v[78:81]
	ds_read_b128 v[240:243], v144 offset:18432
	v_mfma_f32_16x16x32_bf16 v[74:77], v[188:191], v[170:173], v[74:77]
	ds_read_b128 v[244:247], v144 offset:19456
	s_add_i32 s40, s44, s39
	v_mfma_f32_16x16x32_bf16 v[70:73], v[188:191], v[176:179], v[70:73]
	s_mov_b32 m0, s40
	v_lshl_add_u64 v[142:143], v[132:133], 0, s[2:3]
	v_mfma_f32_16x16x32_bf16 v[66:69], v[188:191], v[180:183], v[66:69]
	global_load_lds_dwordx4 v[132:133], off
	s_addk_i32 m0, 0x1000
;     ...
;   for (int kt = 0; kt < nk; kt++) {
;     if (kt + 1 < nk) asm volatile("s_waitcnt vmcnt(6)" ::: "memory");
;     else asm volatile("s_waitcnt vmcnt(0)" ::: "memory");
;     __builtin_amdgcn_s_barrier();
;     asm volatile("" ::: "memory");
;     if (kt + 2 < nk) G2_STAGE(kt + 2);
;     const char* cS = smem + (kt % 3) * 24576;
;     bf16x8 xa[8], wb[4];
; #pragma unroll
;     for (int f = 0; f < 8; f++) xa[f] = *(const bf16x8*)(cS + aoff + f * 1024);
; #pragma unroll
;     for (int f = 0; f < 4; f++) wb[f] = *(const bf16x8*)(cS + boff + f * 1024);
; #pragma unroll
;     for (int nf = 0; nf < 4; nf++)
; #pragma unroll
;       for (int mf = 0; mf < 8; mf++)
;         acc[nf][mf] = __builtin_amdgcn_mfma_f32_16x16x32_bf16(wb[nf], xa[mf], acc[nf][mf], 0, 0, 0);
;   }
	v_mfma_f32_16x16x32_bf16 v[62:65], v[192:195], v[146:149], v[62:65]
	v_mfma_f32_16x16x32_bf16 v[58:61], v[192:195], v[152:155], v[58:61]
	v_mfma_f32_16x16x32_bf16 v[54:57], v[192:195], v[156:159], v[54:57]
	global_load_lds_dwordx4 v[142:143], off
	v_lshl_add_u64 v[142:143], v[142:143], 0, s[2:3]
	s_addk_i32 m0, 0x1000
	v_mfma_f32_16x16x32_bf16 v[50:53], v[192:195], v[162:165], v[50:53]
	v_mfma_f32_16x16x32_bf16 v[46:49], v[192:195], v[166:169], v[46:49]
	v_mfma_f32_16x16x32_bf16 v[42:45], v[192:195], v[170:173], v[42:45]
	global_load_lds_dwordx4 v[142:143], off
	v_lshl_add_u64 v[142:143], v[142:143], 0, s[2:3]
	s_addk_i32 m0, 0x1000
	v_mfma_f32_16x16x32_bf16 v[38:41], v[192:195], v[176:179], v[38:41]
	v_mfma_f32_16x16x32_bf16 v[34:37], v[192:195], v[180:183], v[34:37]
	v_mfma_f32_16x16x32_bf16 v[30:33], v[196:199], v[146:149], v[30:33]
	global_load_lds_dwordx4 v[142:143], off
	s_addk_i32 m0, 0x1000
	v_lshl_add_u64 v[142:143], v[134:135], 0, s[2:3]
	v_mfma_f32_16x16x32_bf16 v[26:29], v[196:199], v[152:155], v[26:29]
	v_mfma_f32_16x16x32_bf16 v[22:25], v[196:199], v[156:159], v[22:25]
	v_mfma_f32_16x16x32_bf16 v[18:21], v[196:199], v[162:165], v[18:21]
	global_load_lds_dwordx4 v[134:135], off
	s_addk_i32 m0, 0x1000
	v_lshl_add_u64 v[132:133], v[132:133], 0, s[36:37]
	v_mfma_f32_16x16x32_bf16 v[14:17], v[196:199], v[166:169], v[14:17]
	v_mfma_f32_16x16x32_bf16 v[10:13], v[196:199], v[170:173], v[10:13]
	v_mfma_f32_16x16x32_bf16 v[6:9], v[196:199], v[176:179], v[6:9]
	global_load_lds_dwordx4 v[142:143], off
	v_lshl_add_u64 v[134:135], v[134:135], 0, s[8:9]
	v_mfma_f32_16x16x32_bf16 v[2:5], v[196:199], v[180:183], v[2:5]
	s_setprio 0
	s_mov_b32 s39, s38
	s_add_i32 s38, s38, 0x6000
	s_cmp_eq_u32 s38, 0x12000
	s_cselect_b32 s38, 0, s38
	s_waitcnt vmcnt(6) lgkmcnt(0)
	s_barrier
	s_setprio 1
	v_add_u32_e32 v144, s38, v136
	v_mfma_f32_16x16x32_bf16 v[126:129], v[232:235], v[200:203], v[126:129]
	ds_read_b128 v[146:149], v144 offset:0
	v_mfma_f32_16x16x32_bf16 v[122:125], v[232:235], v[204:207], v[122:125]
	ds_read_b128 v[152:155], v144 offset:1024
	v_mfma_f32_16x16x32_bf16 v[118:121], v[232:235], v[208:211], v[118:121]
	ds_read_b128 v[156:159], v144 offset:2048
	v_mfma_f32_16x16x32_bf16 v[114:117], v[232:235], v[212:215], v[114:117]
	ds_read_b128 v[162:165], v144 offset:3072
	v_mfma_f32_16x16x32_bf16 v[110:113], v[232:235], v[216:219], v[110:113]
	ds_read_b128 v[166:169], v144 offset:4096
	v_mfma_f32_16x16x32_bf16 v[106:109], v[232:235], v[220:223], v[106:109]
	ds_read_b128 v[170:173], v144 offset:5120
	v_mfma_f32_16x16x32_bf16 v[102:105], v[232:235], v[224:227], v[102:105]
	ds_read_b128 v[176:179], v144 offset:6144
	v_mfma_f32_16x16x32_bf16 v[98:101], v[232:235], v[228:231], v[98:101]
	ds_read_b128 v[180:183], v144 offset:7168
	v_mfma_f32_16x16x32_bf16 v[94:97], v[236:239], v[200:203], v[94:97]
	v_add_u32_e32 v144, s38, v137
	v_mfma_f32_16x16x32_bf16 v[90:93], v[236:239], v[204:207], v[90:93]
	v_mfma_f32_16x16x32_bf16 v[86:89], v[236:239], v[208:211], v[86:89]
	ds_read_b128 v[184:187], v144 offset:16384
	v_mfma_f32_16x16x32_bf16 v[82:85], v[236:239], v[212:215], v[82:85]
	ds_read_b128 v[188:191], v144 offset:17408
	v_mfma_f32_16x16x32_bf16 v[78:81], v[236:239], v[216:219], v[78:81]
	ds_read_b128 v[192:195], v144 offset:18432
	v_mfma_f32_16x16x32_bf16 v[74:77], v[236:239], v[220:223], v[74:77]
	ds_read_b128 v[196:199], v144 offset:19456
	v_mfma_f32_16x16x32_bf16 v[70:73], v[236:239], v[224:227], v[70:73]
	v_mfma_f32_16x16x32_bf16 v[66:69], v[236:239], v[228:231], v[66:69]
	v_mfma_f32_16x16x32_bf16 v[62:65], v[240:243], v[200:203], v[62:65]
	v_mfma_f32_16x16x32_bf16 v[58:61], v[240:243], v[204:207], v[58:61]
	v_mfma_f32_16x16x32_bf16 v[54:57], v[240:243], v[208:211], v[54:57]
	v_mfma_f32_16x16x32_bf16 v[50:53], v[240:243], v[212:215], v[50:53]
	v_mfma_f32_16x16x32_bf16 v[46:49], v[240:243], v[216:219], v[46:49]
	v_mfma_f32_16x16x32_bf16 v[42:45], v[240:243], v[220:223], v[42:45]
	v_mfma_f32_16x16x32_bf16 v[38:41], v[240:243], v[224:227], v[38:41]
	v_mfma_f32_16x16x32_bf16 v[34:37], v[240:243], v[228:231], v[34:37]
	v_mfma_f32_16x16x32_bf16 v[30:33], v[244:247], v[200:203], v[30:33]
	v_mfma_f32_16x16x32_bf16 v[26:29], v[244:247], v[204:207], v[26:29]
	v_mfma_f32_16x16x32_bf16 v[22:25], v[244:247], v[208:211], v[22:25]
	v_mfma_f32_16x16x32_bf16 v[18:21], v[244:247], v[212:215], v[18:21]
	v_mfma_f32_16x16x32_bf16 v[14:17], v[244:247], v[216:219], v[14:17]
	v_mfma_f32_16x16x32_bf16 v[10:13], v[244:247], v[220:223], v[10:13]
	v_mfma_f32_16x16x32_bf16 v[6:9], v[244:247], v[224:227], v[6:9]
	v_mfma_f32_16x16x32_bf16 v[2:5], v[244:247], v[228:231], v[2:5]
	s_setprio 0
	s_mov_b32 s39, s38
	s_add_i32 s38, s38, 0x6000
	s_cmp_eq_u32 s38, 0x12000
	s_cselect_b32 s38, 0, s38
	s_waitcnt vmcnt(0) lgkmcnt(0)
	s_barrier
;     ...
;   for (int kt = 0; kt < nk; kt++) {
;     if (kt + 1 < nk) asm volatile("s_waitcnt vmcnt(6)" ::: "memory");
;     else asm volatile("s_waitcnt vmcnt(0)" ::: "memory");
;     __builtin_amdgcn_s_barrier();
;     asm volatile("" ::: "memory");
;     if (kt + 2 < nk) G2_STAGE(kt + 2);
;     const char* cS = smem + (kt % 3) * 24576;
;     bf16x8 xa[8], wb[4];
; #pragma unroll
;     for (int f = 0; f < 8; f++) xa[f] = *(const bf16x8*)(cS + aoff + f * 1024);
; #pragma unroll
;     for (int f = 0; f < 4; f++) wb[f] = *(const bf16x8*)(cS + boff + f * 1024);
; #pragma unroll
;     for (int nf = 0; nf < 4; nf++)
; #pragma unroll
;       for (int mf = 0; mf < 8; mf++)
;         acc[nf][mf] = __builtin_amdgcn_mfma_f32_16x16x32_bf16(wb[nf], xa[mf], acc[nf][mf], 0, 0, 0);
;   }
	s_setprio 1
	v_add_u32_e32 v144, s38, v136
	v_mfma_f32_16x16x32_bf16 v[126:129], v[184:187], v[146:149], v[126:129]
	ds_read_b128 v[200:203], v144 offset:0
	v_mfma_f32_16x16x32_bf16 v[122:125], v[184:187], v[152:155], v[122:125]
	ds_read_b128 v[204:207], v144 offset:1024
	v_mfma_f32_16x16x32_bf16 v[118:121], v[184:187], v[156:159], v[118:121]
	ds_read_b128 v[208:211], v144 offset:2048
	v_mfma_f32_16x16x32_bf16 v[114:117], v[184:187], v[162:165], v[114:117]
	ds_read_b128 v[212:215], v144 offset:3072
	v_mfma_f32_16x16x32_bf16 v[110:113], v[184:187], v[166:169], v[110:113]
	ds_read_b128 v[216:219], v144 offset:4096
	v_mfma_f32_16x16x32_bf16 v[106:109], v[184:187], v[170:173], v[106:109]
	ds_read_b128 v[220:223], v144 offset:5120
	v_mfma_f32_16x16x32_bf16 v[102:105], v[184:187], v[176:179], v[102:105]
	ds_read_b128 v[224:227], v144 offset:6144
	v_mfma_f32_16x16x32_bf16 v[98:101], v[184:187], v[180:183], v[98:101]
	ds_read_b128 v[228:231], v144 offset:7168
	v_mfma_f32_16x16x32_bf16 v[94:97], v[188:191], v[146:149], v[94:97]
	v_add_u32_e32 v144, s38, v137
	v_mfma_f32_16x16x32_bf16 v[90:93], v[188:191], v[152:155], v[90:93]
	v_mfma_f32_16x16x32_bf16 v[86:89], v[188:191], v[156:159], v[86:89]
	ds_read_b128 v[232:235], v144 offset:16384
	v_mfma_f32_16x16x32_bf16 v[82:85], v[188:191], v[162:165], v[82:85]
	ds_read_b128 v[236:239], v144 offset:17408
	v_mfma_f32_16x16x32_bf16 v[78:81], v[188:191], v[166:169], v[78:81]
	ds_read_b128 v[240:243], v144 offset:18432
	v_mfma_f32_16x16x32_bf16 v[74:77], v[188:191], v[170:173], v[74:77]
	ds_read_b128 v[244:247], v144 offset:19456
	v_mfma_f32_16x16x32_bf16 v[70:73], v[188:191], v[176:179], v[70:73]
	v_mfma_f32_16x16x32_bf16 v[66:69], v[188:191], v[180:183], v[66:69]
	v_mfma_f32_16x16x32_bf16 v[62:65], v[192:195], v[146:149], v[62:65]
	v_mfma_f32_16x16x32_bf16 v[58:61], v[192:195], v[152:155], v[58:61]
	v_mfma_f32_16x16x32_bf16 v[54:57], v[192:195], v[156:159], v[54:57]
	v_mfma_f32_16x16x32_bf16 v[50:53], v[192:195], v[162:165], v[50:53]
	v_mfma_f32_16x16x32_bf16 v[46:49], v[192:195], v[166:169], v[46:49]
	v_mfma_f32_16x16x32_bf16 v[42:45], v[192:195], v[170:173], v[42:45]
	v_mfma_f32_16x16x32_bf16 v[38:41], v[192:195], v[176:179], v[38:41]
	v_mfma_f32_16x16x32_bf16 v[34:37], v[192:195], v[180:183], v[34:37]
	v_mfma_f32_16x16x32_bf16 v[30:33], v[196:199], v[146:149], v[30:33]
	v_mfma_f32_16x16x32_bf16 v[26:29], v[196:199], v[152:155], v[26:29]
	v_mfma_f32_16x16x32_bf16 v[22:25], v[196:199], v[156:159], v[22:25]
	v_mfma_f32_16x16x32_bf16 v[18:21], v[196:199], v[162:165], v[18:21]
	v_mfma_f32_16x16x32_bf16 v[14:17], v[196:199], v[166:169], v[14:17]
	v_mfma_f32_16x16x32_bf16 v[10:13], v[196:199], v[170:173], v[10:13]
	v_mfma_f32_16x16x32_bf16 v[6:9], v[196:199], v[176:179], v[6:9]
	v_mfma_f32_16x16x32_bf16 v[2:5], v[196:199], v[180:183], v[2:5]
	s_setprio 0
	s_mov_b32 s39, s38
	s_add_i32 s38, s38, 0x6000
	s_cmp_eq_u32 s38, 0x12000
	s_cselect_b32 s38, 0, s38
	s_waitcnt lgkmcnt(0)
; DEVI unsigned pack2(float a, float b) { return __builtin_bit_cast(unsigned, __builtin_convertvector((f32x2_t){a, b}, bf16x2_t)); }
; DEVI float blo(unsigned u) { return __uint_as_float(u << 16); }
; DEVI float bhi(unsigned u) { return __uint_as_float(u & 0xffff0000u); }
;     ...
;     for (int nf = 0; nf < 4; nf++)
; #pragma unroll
;       for (int mf = 0; mf < 8; mf++)
;         acc[nf][mf] = __builtin_amdgcn_mfma_f32_16x16x32_bf16(wb[nf], xa[mf], acc[nf][mf], 0, 0, 0);
;     ...
; #pragma unroll
;       for (int nf = 0; nf < 4; nf++) {
;         const int col = n0 + wn * 64 + nf * 16 + quad * 4;
;         f32x4 a = acc[nf][mf];
;         if (EPI == EPI_RESID || EPI == EPI_RESID_ATOMIC) {
;           f32x4 x = a;
;           if (EPI == EPI_RESID || kpart == 0) {
;             const u32x2 xr = *(const u32x2*)((const u16*)(p.ws + WS_XB) + (size_t)row * 1024 + col);
;             x[0] += ALPHA * blo(xr[0]); x[1] += ALPHA * bhi(xr[0]); x[2] += ALPHA * blo(xr[1]); x[3] += ALPHA * bhi(xr[1]);
;           }
;           if (EPI == EPI_RESID) *(f32x4*)((float*)(p.ws + WS_XF) + (size_t)row * 1024 + col) = x;
;           else *(f32x4*)((float*)(p.ws + WS_SLAB) + ((size_t)kpart * 512 + (row - T_P)) * 1024 + col) = x;
;         } else {
;           u32x2 pk; pk[0] = pack2(a[0], a[1]); pk[1] = pack2(a[2], a[3]);
;           *(u32x2*)(outb + (size_t)row * ldc + col) = pk;
;         }
	v_mfma_f32_16x16x32_bf16 v[126:129], v[232:235], v[200:203], v[126:129]
	v_mfma_f32_16x16x32_bf16 v[122:125], v[232:235], v[204:207], v[122:125]
	v_mfma_f32_16x16x32_bf16 v[118:121], v[232:235], v[208:211], v[118:121]
	v_mfma_f32_16x16x32_bf16 v[114:117], v[232:235], v[212:215], v[114:117]
	v_mfma_f32_16x16x32_bf16 v[110:113], v[232:235], v[216:219], v[110:113]
	v_mfma_f32_16x16x32_bf16 v[106:109], v[232:235], v[220:223], v[106:109]
	v_mfma_f32_16x16x32_bf16 v[102:105], v[232:235], v[224:227], v[102:105]
	v_mfma_f32_16x16x32_bf16 v[98:101], v[232:235], v[228:231], v[98:101]
	v_mfma_f32_16x16x32_bf16 v[94:97], v[236:239], v[200:203], v[94:97]
	v_mfma_f32_16x16x32_bf16 v[90:93], v[236:239], v[204:207], v[90:93]
	v_mfma_f32_16x16x32_bf16 v[86:89], v[236:239], v[208:211], v[86:89]
	v_mfma_f32_16x16x32_bf16 v[82:85], v[236:239], v[212:215], v[82:85]
	v_mfma_f32_16x16x32_bf16 v[78:81], v[236:239], v[216:219], v[78:81]
	v_mfma_f32_16x16x32_bf16 v[74:77], v[236:239], v[220:223], v[74:77]
	v_mfma_f32_16x16x32_bf16 v[70:73], v[236:239], v[224:227], v[70:73]
	v_mfma_f32_16x16x32_bf16 v[66:69], v[236:239], v[228:231], v[66:69]
	v_mfma_f32_16x16x32_bf16 v[62:65], v[240:243], v[200:203], v[62:65]
	v_mfma_f32_16x16x32_bf16 v[58:61], v[240:243], v[204:207], v[58:61]
	v_mfma_f32_16x16x32_bf16 v[54:57], v[240:243], v[208:211], v[54:57]
	v_mfma_f32_16x16x32_bf16 v[50:53], v[240:243], v[212:215], v[50:53]
	v_mfma_f32_16x16x32_bf16 v[46:49], v[240:243], v[216:219], v[46:49]
	v_mfma_f32_16x16x32_bf16 v[42:45], v[240:243], v[220:223], v[42:45]
	v_mfma_f32_16x16x32_bf16 v[38:41], v[240:243], v[224:227], v[38:41]
	v_mfma_f32_16x16x32_bf16 v[34:37], v[240:243], v[228:231], v[34:37]
	v_mfma_f32_16x16x32_bf16 v[30:33], v[244:247], v[200:203], v[30:33]
	v_mfma_f32_16x16x32_bf16 v[26:29], v[244:247], v[204:207], v[26:29]
	v_mfma_f32_16x16x32_bf16 v[22:25], v[244:247], v[208:211], v[22:25]
	v_mfma_f32_16x16x32_bf16 v[18:21], v[244:247], v[212:215], v[18:21]
	v_mfma_f32_16x16x32_bf16 v[14:17], v[244:247], v[216:219], v[14:17]
	v_mfma_f32_16x16x32_bf16 v[10:13], v[244:247], v[220:223], v[10:13]
	v_mfma_f32_16x16x32_bf16 v[6:9], v[244:247], v[224:227], v[6:9]
	v_mfma_f32_16x16x32_bf16 v[2:5], v[244:247], v[228:231], v[2:5]
	s_mov_b32 m0, s41
	s_mov_b32 s8, 0x14000
	s_mov_b32 s9, 0
	s_nop 7
	v_cvt_pk_bf16_f32 v126, v126, v127
	v_cvt_pk_bf16_f32 v127, v128, v129
	v_cvt_pk_bf16_f32 v128, v94, v95
	v_cvt_pk_bf16_f32 v129, v96, v97
	v_cvt_pk_bf16_f32 v62, v62, v63
	v_cvt_pk_bf16_f32 v63, v64, v65
	v_cvt_pk_bf16_f32 v64, v30, v31
	v_cvt_pk_bf16_f32 v65, v32, v33
	v_permlane16_swap_b32_e32 v126, v128
	v_permlane16_swap_b32_e32 v127, v129
	v_permlane16_swap_b32_e32 v62, v64
	v_permlane16_swap_b32_e32 v63, v65
	global_store_dwordx4 v[140:141], v[126:129], off offset:0
	global_store_dwordx4 v[140:141], v[62:65], off offset:64
	v_lshl_add_u64 v[140:141], v[140:141], 0, s[8:9]
	v_cvt_pk_bf16_f32 v122, v122, v123
	v_cvt_pk_bf16_f32 v123, v124, v125
	v_cvt_pk_bf16_f32 v124, v90, v91
	v_cvt_pk_bf16_f32 v125, v92, v93
	v_cvt_pk_bf16_f32 v58, v58, v59
	v_cvt_pk_bf16_f32 v59, v60, v61
	v_cvt_pk_bf16_f32 v60, v26, v27
	v_cvt_pk_bf16_f32 v61, v28, v29
	v_permlane16_swap_b32_e32 v122, v124
	v_permlane16_swap_b32_e32 v123, v125
	v_permlane16_swap_b32_e32 v58, v60
	v_permlane16_swap_b32_e32 v59, v61
	global_store_dwordx4 v[140:141], v[122:125], off offset:0
	global_store_dwordx4 v[140:141], v[58:61], off offset:64
	v_lshl_add_u64 v[140:141], v[140:141], 0, s[8:9]
	v_cvt_pk_bf16_f32 v118, v118, v119
	v_cvt_pk_bf16_f32 v119, v120, v121
	v_cvt_pk_bf16_f32 v120, v86, v87
	v_cvt_pk_bf16_f32 v121, v88, v89
	v_cvt_pk_bf16_f32 v54, v54, v55
	v_cvt_pk_bf16_f32 v55, v56, v57
	v_cvt_pk_bf16_f32 v56, v22, v23
	v_cvt_pk_bf16_f32 v57, v24, v25
	v_permlane16_swap_b32_e32 v118, v120
	v_permlane16_swap_b32_e32 v119, v121
	v_permlane16_swap_b32_e32 v54, v56
	v_permlane16_swap_b32_e32 v55, v57
	global_store_dwordx4 v[140:141], v[118:121], off offset:0
	global_store_dwordx4 v[140:141], v[54:57], off offset:64
	v_lshl_add_u64 v[140:141], v[140:141], 0, s[8:9]
	v_cvt_pk_bf16_f32 v114, v114, v115
	v_cvt_pk_bf16_f32 v115, v116, v117
	v_cvt_pk_bf16_f32 v116, v82, v83
	v_cvt_pk_bf16_f32 v117, v84, v85
	v_cvt_pk_bf16_f32 v50, v50, v51
	v_cvt_pk_bf16_f32 v51, v52, v53
	v_cvt_pk_bf16_f32 v52, v18, v19
	v_cvt_pk_bf16_f32 v53, v20, v21
	v_permlane16_swap_b32_e32 v114, v116
	v_permlane16_swap_b32_e32 v115, v117
	v_permlane16_swap_b32_e32 v50, v52
	v_permlane16_swap_b32_e32 v51, v53
	global_store_dwordx4 v[140:141], v[114:117], off offset:0
	global_store_dwordx4 v[140:141], v[50:53], off offset:64
	v_lshl_add_u64 v[140:141], v[140:141], 0, s[8:9]
	v_cvt_pk_bf16_f32 v110, v110, v111
	v_cvt_pk_bf16_f32 v111, v112, v113
	v_cvt_pk_bf16_f32 v112, v78, v79
	v_cvt_pk_bf16_f32 v113, v80, v81
	v_cvt_pk_bf16_f32 v46, v46, v47
	v_cvt_pk_bf16_f32 v47, v48, v49
	v_cvt_pk_bf16_f32 v48, v14, v15
	v_cvt_pk_bf16_f32 v49, v16, v17
	v_permlane16_swap_b32_e32 v110, v112
	v_permlane16_swap_b32_e32 v111, v113
	v_permlane16_swap_b32_e32 v46, v48
	v_permlane16_swap_b32_e32 v47, v49
	global_store_dwordx4 v[140:141], v[110:113], off offset:0
	global_store_dwordx4 v[140:141], v[46:49], off offset:64
	v_lshl_add_u64 v[140:141], v[140:141], 0, s[8:9]
	v_cvt_pk_bf16_f32 v106, v106, v107
	v_cvt_pk_bf16_f32 v107, v108, v109
	v_cvt_pk_bf16_f32 v108, v74, v75
	v_cvt_pk_bf16_f32 v109, v76, v77
	v_cvt_pk_bf16_f32 v42, v42, v43
	v_cvt_pk_bf16_f32 v43, v44, v45
	v_cvt_pk_bf16_f32 v44, v10, v11
	v_cvt_pk_bf16_f32 v45, v12, v13
	v_permlane16_swap_b32_e32 v106, v108
	v_permlane16_swap_b32_e32 v107, v109
	v_permlane16_swap_b32_e32 v42, v44
	v_permlane16_swap_b32_e32 v43, v45
	global_store_dwordx4 v[140:141], v[106:109], off offset:0
	global_store_dwordx4 v[140:141], v[42:45], off offset:64
	v_lshl_add_u64 v[140:141], v[140:141], 0, s[8:9]
	v_cvt_pk_bf16_f32 v102, v102, v103
	v_cvt_pk_bf16_f32 v103, v104, v105
	v_cvt_pk_bf16_f32 v104, v70, v71
	v_cvt_pk_bf16_f32 v105, v72, v73
	v_cvt_pk_bf16_f32 v38, v38, v39
	v_cvt_pk_bf16_f32 v39, v40, v41
	v_cvt_pk_bf16_f32 v40, v6, v7
	v_cvt_pk_bf16_f32 v41, v8, v9
	v_permlane16_swap_b32_e32 v102, v104
	v_permlane16_swap_b32_e32 v103, v105
	v_permlane16_swap_b32_e32 v38, v40
	v_permlane16_swap_b32_e32 v39, v41
	global_store_dwordx4 v[140:141], v[102:105], off offset:0
	global_store_dwordx4 v[140:141], v[38:41], off offset:64
	v_lshl_add_u64 v[140:141], v[140:141], 0, s[8:9]
	v_cvt_pk_bf16_f32 v98, v98, v99
	v_cvt_pk_bf16_f32 v99, v100, v101
	v_cvt_pk_bf16_f32 v100, v66, v67
	v_cvt_pk_bf16_f32 v101, v68, v69
	v_cvt_pk_bf16_f32 v34, v34, v35
	v_cvt_pk_bf16_f32 v35, v36, v37
	v_cvt_pk_bf16_f32 v36, v2, v3
	v_cvt_pk_bf16_f32 v37, v4, v5
	v_permlane16_swap_b32_e32 v98, v100
	v_permlane16_swap_b32_e32 v99, v101
	v_permlane16_swap_b32_e32 v34, v36
	v_permlane16_swap_b32_e32 v35, v37
	global_store_dwordx4 v[140:141], v[98:101], off offset:0
	global_store_dwordx4 v[140:141], v[34:37], off offset:64
	s_branch .LBB0_886
